# peeled first K-iteration with SrcC=0 (no accumulator zeroing), leaner grid barrier (leader posts non-returning add, all poll one word), SwiGLU epilogue math restructured in f32 (fewer VALU ops: g*u*r^
# speedup vs baseline: 1.0273x; 1.0151x over previous
; #define LAS __attribute__((address_space(3)))
; __device__ __forceinline__ float hsum4(f32x4 v) { return (v[0] + v[1]) + (v[2] + v[3]); }
; #define PG8_STAGEA(bufoff, gbase) PG8_STAGE_(bufoff, gbase, voffA)
; template <int EK, int SK = -1>
; __device__ __forceinline__ void gemm_phase(LAS unsigned char* lds, const bf16_t* A, const bf16_t* Bt, int nM, int N, int K, const EpiArgs& E) {
;     ...
;     f32x4 acc[2][2][4][2];
; #pragma unroll
;     for (int a = 0; a < 2; ++a)
; #pragma unroll
;         for (int b = 0; b < 2; ++b)
; #pragma unroll
;             for (int m = 0; m < 4; ++m)
; #pragma unroll
;                 for (int n = 0; n < 2; ++n) acc[a][b][m][n] = (f32x4){0.f, 0.f, 0.f, 0.f};
;     bf16x8 At[4][2], B0[2][2], B1[2][2];
;     const char* cA = (const char*)A + (size_t)cur.pm * tstep; const char* cB = (const char*)Bt + (size_t)cur.pn * tstep;
;     PG8_STAGEB(PG8_SB(0, 0), cB); PG8_STAGEB(PG8_SB(0, 1), cB + hstep); PG8_STAGEA(PG8_SA(0, 0), cA); PG8_STAGEA(PG8_SA(0, 1), cA + hstep);
;     f32x4 tq[4][4]; bool okq[4];
;     if (EK != EK_RES && EK != EK_FINAL) {
; #pragma unroll
;         for (int j = 0; j < 4; ++j) { Unit uu; okq[j] = S.next((tid >> 8) + 2 * j, uu);
;             if (okq[j]) { const f32x4* sp = (const f32x4*)(E.stIn + (size_t)(uu.pm * BM + (tid & 255)) * 16); tq[j][0] = sp[0]; tq[j][1] = sp[1]; tq[j][2] = sp[2]; tq[j][3] = sp[3]; } }
;     }
;     if (SK >= 0) skinny_phase<(SK >= 0 ? SK : 0)>(lds + 32768, (LAS float*)(lds + SRED_OFF), A, Bt, N, K, E);
;     if (EK != EK_RES && EK != EK_FINAL) {
; #pragma unroll
;         for (int j = 0; j < 4; ++j) if (okq[j]) { const float s_ = (hsum4(tq[j][0]) + hsum4(tq[j][1])) + (hsum4(tq[j][2]) + hsum4(tq[j][3]));
;             rtab[((tid >> 8) + 2 * j) * 256 + (tid & 255)] = rsqrtf(s_ * (1.0f / 1024.0f) + EPS); }
;         __syncthreads();
;     }
;     if (wr == 1) PG8_BAR;
;     PG8_WAIT_V(2); PG8_BAR;
;     PG8_STAGEB(PG8_SB(1, 0), cB + kstep); PG8_STAGEA(PG8_SA(1, 0), cA + kstep); PG8_STAGEB(PG8_SB(1, 1), cB + hstep + kstep);
;     PG8_WAIT_V(6); PG8_BAR;
;     ...
; #pragma unroll
;         for (int a = 0; a < 2; ++a)
; #pragma unroll
;             for (int b = 0; b < 2; ++b)
; #pragma unroll
;                 for (int m = 0; m < 4; ++m)
; #pragma unroll
;                     for (int n = 0; n < 2; ++n) acc[a][b][m][n] = (f32x4){0.f, 0.f, 0.f, 0.f};
;         cur = nxt; cA = nA; cB = nB; ++ui;
.LBB0_189:
	v_lshlrev_b32_e32 v2, 1, v90
	v_lshlrev_b32_e32 v4, 2, v91
	v_lshl_or_b32 v3, v91, 6, v2
	s_lshl_b32 s5, s4, 13
	v_and_b32_e32 v5, 32, v4
	v_bitop3_b32 v5, v3, s5, v5 bitop3:0xde
	s_lshl_b32 s5, s52, 5
	v_lshlrev_b32_e32 v3, 6, v0
	s_movk_i32 s6, 0x3c0
	s_and_b32 s5, s5, 0x60
	v_and_or_b32 v2, v3, s6, v2
	v_lshlrev_b32_e32 v3, 2, v0
	s_lshl_b32 s6, s5, 7
	v_and_b32_e32 v3, 32, v3
	s_mov_b64 s[10:11], 0x80
	v_bitop3_b32 v152, s6, v2, v3 bitop3:0xf6
	s_add_i32 m0, s67, 0x18000
	v_lshl_add_u64 v[2:3], v[76:77], 0, s[10:11]
	s_waitcnt vmcnt(2)
	s_barrier
	global_load_lds_dwordx4 v[2:3], off
	v_lshl_add_u64 v[2:3], v[74:75], 0, s[10:11]
	s_add_i32 m0, s67, 0x1a000
	s_add_i32 s52, s67, 0x8000
	s_add_i32 s53, s67, 0xa000
	global_load_lds_dwordx4 v[2:3], off
	v_lshl_add_u64 v[2:3], v[72:73], 0, s[10:11]
	s_mov_b32 m0, s52
	s_add_u32 s12, s78, 0x40080
	global_load_lds_dwordx4 v[2:3], off
	v_lshl_add_u64 v[2:3], v[70:71], 0, s[10:11]
	s_mov_b32 m0, s53
	s_addc_u32 s13, s79, 0
	global_load_lds_dwordx4 v[2:3], off
	s_add_i32 m0, s67, 0x1c000
	v_lshl_add_u64 v[2:3], s[12:13], 0, v[132:133]
	global_load_lds_dwordx4 v[2:3], off
	v_lshl_add_u64 v[2:3], s[12:13], 0, v[136:137]
	s_add_i32 m0, s67, 0x1e000
	v_lshl_or_b32 v1, s4, 6, v91
	global_load_lds_dwordx4 v[2:3], off
	s_lshl_b32 s4, s4, 8
	s_add_i32 s4, s4, 0
	s_add_i32 s4, s4, 0x20010
	v_lshlrev_b32_e32 v2, 8, v0
	v_add_u32_e32 v153, s4, v4
	v_and_b32_e32 v2, 0x18000, v2
	v_lshlrev_b32_e32 v4, 11, v88
	v_or3_b32 v2, v86, v2, v4
	s_mov_b64 s[6:7], 0x40080
	v_add_u32_e32 v2, v2, v87
	v_mov_b32_e32 v3, 0
	v_lshl_add_u64 v[138:139], v[2:3], 0, s[6:7]
	v_lshlrev_b32_e32 v2, 4, v89
	v_and_b32_e32 v2, 0x38000, v2
	s_waitcnt vmcnt(6)
	v_or3_b32 v2, v86, v2, v4
	s_cmpk_lt_u32 s54, 0x100
	v_add_u32_e32 v2, v2, v87
	s_mov_b32 s56, 0
	s_cselect_b64 s[12:13], -1, 0
	v_or_b32_e32 v154, s5, v90
	v_lshl_add_u64 v[140:141], v[2:3], 0, s[6:7]
	v_mov_b64_e32 v[142:143], 0x200
	v_mov_b64_e32 v[144:145], 0x1ff
	s_add_i32 s54, 0, 0x10000
	s_add_i32 s55, 0, 0x14000
	v_add_u32_e32 v155, 0, v5
	v_mov_b32_e32 v2, v3
	s_barrier
	s_branch .LBB0_191
.LBB0_190:
	v_mov_b32_e32 v2, 0
	s_mov_b32 s66, s74
	s_mov_b32 s68, s72
	v_mov_b32_e32 v3, v2
	s_mov_b64 s[70:71], s[80:81]
	s_mov_b32 s56, s57
	s_andn2_b64 vcc, exec, s[4:5]
	s_mov_b64 s[78:79], s[76:77]
	s_cbranch_vccz .LBB0_205

; #define PG8_STAGEA(bufoff, gbase) PG8_STAGE_(bufoff, gbase, voffA)
; #define PG8_STAGEB(bufoff, gbase) PG8_STAGE_(bufoff, gbase, voffB)
; #define PG8_LDA(dst, b, h) do { _Pragma("unroll") for (int m = 0; m < 4; ++m) _Pragma("unroll") for (int k = 0; k < 2; ++k) dst[m][k] = *(const LAS bf16x8*)(lds + PG8_SA(b, h) + aoff + m * 2048 + k * 1024); } while (0)
; #define PG8_LDB(dst, b, h) do { _Pragma("unroll") for (int n = 0; n < 2; ++n) _Pragma("unroll") for (int k = 0; k < 2; ++k) dst[n][k] = *(const LAS bf16x8*)(lds + PG8_SB(b, h) + boff + n * 2048 + k * 1024); } while (0)
; #define PG8_MMA(ai, bj, At, Bt_) do { __builtin_amdgcn_s_setprio(1); _Pragma("unroll") for (int m = 0; m < 4; ++m) _Pragma("unroll") for (int n = 0; n < 2; ++n) _Pragma("unroll") for (int k = 0; k < 2; ++k) \
;         acc[ai][bj][m][n] = __builtin_amdgcn_mfma_f32_16x16x32_bf16(Bt_[n][k], At[m][k], acc[ai][bj][m][n], 0, 0, 0); __builtin_amdgcn_s_setprio(0); } while (0)
; #define PG8_WAIT_V(n) asm volatile("s_waitcnt vmcnt(" #n ")" ::: "memory")
; #define PG8_WAIT_L(n) asm volatile("s_waitcnt lgkmcnt(" #n ")" ::: "memory")
; template <int EK, int SK = -1>
; __device__ __forceinline__ void gemm_phase(LAS unsigned char* lds, const bf16_t* A, const bf16_t* Bt, int nM, int N, int K, const EpiArgs& E) {
;     ...
;     for (;;) {
;         const bool has_next = S.next(ui + 1, nxt);
;         const char* nA = has_next ? (const char*)A + (size_t)nxt.pm * tstep : cA; const char* nB = has_next ? (const char*)Bt + (size_t)nxt.pn * tstep : cB;
;         for (int t = 0; t < nt; t += 2) {
;             const bool last = (t == nt - 2);
;             const char* a1 = cA + (size_t)(t + 1) * kstep;
;             const char* a2 = last ? nA : cA + (size_t)(t + 2) * kstep; const char* b2 = last ? nB : cB + (size_t)(t + 2) * kstep;
;             const char* a3 = a2 + kstep; const char* b3 = b2 + kstep;
;             PG8_LDB(B0, 0, 0); PG8_LDB(B1, 0, 1); PG8_SCHED; PG8_LDA(At, 0, 0); PG8_STAGEA(PG8_SA(1, 1), a1 + hstep);
;             PG8_WAIT_V(8); PG8_WAIT_L(0); PG8_BAR; PG8_MMA(0, 0, At, B0); PG8_MMA(0, 1, At, B1); PG8_BAR; PG8_SCHED;
;             PG8_LDA(At, 0, 1); PG8_STAGEB(PG8_SB(0, 0), b2); PG8_STAGEB(PG8_SB(0, 1), b2 + hstep); PG8_STAGEA(PG8_SA(0, 0), a2);
;             PG8_WAIT_V(8); PG8_WAIT_L(0); PG8_BAR; PG8_MMA(1, 0, At, B0); PG8_MMA(1, 1, At, B1); PG8_BAR; PG8_SCHED;
.LBB0_197:
	s_add_u32 s58, s78, 0x100
	s_addc_u32 s59, s79, 0
	s_ashr_i32 s75, s74, 31
	s_lshl_b64 s[76:77], s[74:75], 19
	s_add_u32 s80, s62, s76
	s_addc_u32 s81, s63, s77
	s_and_b64 s[76:77], s[6:7], exec
	s_cselect_b32 s75, s81, s71
	s_cselect_b32 s90, s80, s70
	s_ashr_i32 s73, s72, 31
	s_lshl_b64 s[76:77], s[72:73], 19
	s_add_u32 s76, s30, s76
	s_addc_u32 s77, s31, s77
	s_and_b64 s[82:83], s[6:7], exec
	s_cselect_b32 s73, s77, s79
	s_cselect_b32 s91, s76, s78
	v_lshl_add_u64 v[146:147], s[70:71], 0, v[138:139]
	v_lshl_add_u64 v[148:149], s[70:71], 0, v[140:141]
	s_mov_b32 s92, -2
	s_mov_b64 s[78:79], 0
	v_add_u32_e32 v150, s54, v152
	ds_read_b128 v[156:159], v150
	ds_read_b128 v[160:163], v150 offset:1024
	ds_read_b128 v[164:167], v150 offset:2048
	ds_read_b128 v[168:171], v150 offset:3072
	v_add_u32_e32 v150, s55, v152
	s_add_u32 s82, s70, s78
	ds_read_b128 v[172:175], v150
	ds_read_b128 v[176:179], v150 offset:1024
	ds_read_b128 v[180:183], v150 offset:2048
	ds_read_b128 v[184:187], v150 offset:3072
	s_addc_u32 s83, s71, s79
	s_add_u32 s82, s82, 0x100
	s_addc_u32 s83, s83, 0
	s_add_u32 s93, s58, s78
	s_addc_u32 s94, s59, s79
	s_cmpk_eq_i32 s78, 0x700
	s_cselect_b32 s85, s75, s83
	s_cselect_b32 s84, s90, s82
	s_cselect_b32 s83, s73, s94
	s_cselect_b32 s82, s91, s93
	v_lshl_add_u64 v[150:151], v[146:147], 0, s[78:79]
	s_add_i32 m0, s67, 0xc000
	ds_read_b128 v[188:191], v155
	ds_read_b128 v[192:195], v155 offset:1024
	ds_read_b128 v[196:199], v155 offset:2048
	ds_read_b128 v[200:203], v155 offset:3072
	ds_read_b128 v[204:207], v155 offset:4096
	ds_read_b128 v[208:211], v155 offset:5120
	ds_read_b128 v[212:215], v155 offset:6144
	ds_read_b128 v[216:219], v155 offset:7168
	global_load_lds_dwordx4 v[150:151], off
	v_lshl_add_u64 v[150:151], v[148:149], 0, s[78:79]
	s_add_i32 m0, s67, 0xe000
	s_nop 0
	global_load_lds_dwordx4 v[150:151], off
	s_waitcnt vmcnt(8)
	s_waitcnt lgkmcnt(0)
	s_barrier
	s_waitcnt lgkmcnt(0)
	v_mfma_f32_16x16x32_bf16 v[110:113], v[156:159], v[188:191], 0
	v_mfma_f32_16x16x32_bf16 v[106:109], v[164:167], v[188:191], 0
	v_mfma_f32_16x16x32_bf16 v[102:105], v[156:159], v[196:199], 0
	v_mfma_f32_16x16x32_bf16 v[98:101], v[164:167], v[196:199], 0
	v_mfma_f32_16x16x32_bf16 v[94:97], v[156:159], v[204:207], 0
	v_mfma_f32_16x16x32_bf16 v[90:93], v[164:167], v[204:207], 0
	v_mfma_f32_16x16x32_bf16 v[86:89], v[156:159], v[212:215], 0
	v_mfma_f32_16x16x32_bf16 v[82:85], v[164:167], v[212:215], 0
	v_mfma_f32_16x16x32_bf16 v[110:113], v[160:163], v[192:195], v[110:113]
	v_mfma_f32_16x16x32_bf16 v[106:109], v[168:171], v[192:195], v[106:109]
	v_mfma_f32_16x16x32_bf16 v[102:105], v[160:163], v[200:203], v[102:105]
	v_mfma_f32_16x16x32_bf16 v[98:101], v[168:171], v[200:203], v[98:101]
	v_mfma_f32_16x16x32_bf16 v[94:97], v[160:163], v[208:211], v[94:97]
	v_mfma_f32_16x16x32_bf16 v[90:93], v[168:171], v[208:211], v[90:93]
	v_mfma_f32_16x16x32_bf16 v[86:89], v[160:163], v[216:219], v[86:89]
	v_mfma_f32_16x16x32_bf16 v[82:85], v[168:171], v[216:219], v[82:85]
	v_mfma_f32_16x16x32_bf16 v[78:81], v[172:175], v[188:191], 0
	v_mfma_f32_16x16x32_bf16 v[74:77], v[180:183], v[188:191], 0
	v_mfma_f32_16x16x32_bf16 v[70:73], v[172:175], v[196:199], 0
	v_mfma_f32_16x16x32_bf16 v[66:69], v[180:183], v[196:199], 0
	v_mfma_f32_16x16x32_bf16 v[62:65], v[172:175], v[204:207], 0
	v_mfma_f32_16x16x32_bf16 v[58:61], v[180:183], v[204:207], 0
	v_mfma_f32_16x16x32_bf16 v[54:57], v[172:175], v[212:215], 0
	v_mfma_f32_16x16x32_bf16 v[50:53], v[180:183], v[212:215], 0
	v_mfma_f32_16x16x32_bf16 v[78:81], v[176:179], v[192:195], v[78:81]
	v_mfma_f32_16x16x32_bf16 v[74:77], v[184:187], v[192:195], v[74:77]
	v_mfma_f32_16x16x32_bf16 v[70:73], v[176:179], v[200:203], v[70:73]
	v_mfma_f32_16x16x32_bf16 v[66:69], v[184:187], v[200:203], v[66:69]
	v_mfma_f32_16x16x32_bf16 v[62:65], v[176:179], v[208:211], v[62:65]
	v_mfma_f32_16x16x32_bf16 v[58:61], v[184:187], v[208:211], v[58:61]
	v_mfma_f32_16x16x32_bf16 v[54:57], v[176:179], v[216:219], v[54:57]
	v_mfma_f32_16x16x32_bf16 v[50:53], v[184:187], v[216:219], v[50:53]
	s_barrier
	s_add_i32 s93, s54, s87
	v_lshl_add_u64 v[150:151], s[82:83], 0, v[132:133]
	s_mov_b32 m0, s93
	ds_read_b128 v[188:191], v155 offset:16384
	ds_read_b128 v[192:195], v155 offset:17408
	ds_read_b128 v[196:199], v155 offset:18432
	ds_read_b128 v[200:203], v155 offset:19456
	ds_read_b128 v[204:207], v155 offset:20480
	ds_read_b128 v[208:211], v155 offset:21504
	ds_read_b128 v[212:215], v155 offset:22528
	ds_read_b128 v[216:219], v155 offset:23552
	global_load_lds_dwordx4 v[150:151], off
	s_add_i32 m0, s93, 0x2000
	s_add_u32 s94, s82, 0x40000
	v_lshl_add_u64 v[220:221], s[82:83], 0, v[136:137]
	s_addc_u32 s95, s83, 0
	s_add_i32 s93, s55, s87
	global_load_lds_dwordx4 v[220:221], off
	v_lshl_add_u64 v[222:223], s[94:95], 0, v[132:133]
	s_mov_b32 m0, s93
	v_lshl_add_u64 v[224:225], s[84:85], 0, v[134:135]
	global_load_lds_dwordx4 v[222:223], off
	v_lshl_add_u64 v[222:223], s[94:95], 0, v[136:137]
	s_add_i32 m0, s93, 0x2000
	s_nop 0
	global_load_lds_dwordx4 v[222:223], off
	v_lshl_add_u64 v[222:223], s[84:85], 0, v[130:131]
	s_mov_b32 m0, s67
	s_nop 0
	global_load_lds_dwordx4 v[222:223], off
	s_mov_b32 m0, s69
	s_nop 0
	global_load_lds_dwordx4 v[224:225], off
	s_waitcnt vmcnt(8)
	s_waitcnt lgkmcnt(0)
	s_barrier
; #define PG8_STAGEA(bufoff, gbase) PG8_STAGE_(bufoff, gbase, voffA)
; #define PG8_LDA(dst, b, h) do { _Pragma("unroll") for (int m = 0; m < 4; ++m) _Pragma("unroll") for (int k = 0; k < 2; ++k) dst[m][k] = *(const LAS bf16x8*)(lds + PG8_SA(b, h) + aoff + m * 2048 + k * 1024); } while (0)
; #define PG8_LDB(dst, b, h) do { _Pragma("unroll") for (int n = 0; n < 2; ++n) _Pragma("unroll") for (int k = 0; k < 2; ++k) dst[n][k] = *(const LAS bf16x8*)(lds + PG8_SB(b, h) + boff + n * 2048 + k * 1024); } while (0)
; #define PG8_MMA(ai, bj, At, Bt_) do { __builtin_amdgcn_s_setprio(1); _Pragma("unroll") for (int m = 0; m < 4; ++m) _Pragma("unroll") for (int n = 0; n < 2; ++n) _Pragma("unroll") for (int k = 0; k < 2; ++k) \
;         acc[ai][bj][m][n] = __builtin_amdgcn_mfma_f32_16x16x32_bf16(Bt_[n][k], At[m][k], acc[ai][bj][m][n], 0, 0, 0); __builtin_amdgcn_s_setprio(0); } while (0)
; #define PG8_WAIT_V(n) asm volatile("s_waitcnt vmcnt(" #n ")" ::: "memory")
; #define PG8_WAIT_L(n) asm volatile("s_waitcnt lgkmcnt(" #n ")" ::: "memory")
; #define PG8_BAR __builtin_amdgcn_s_barrier()
; #define PG8_SCHED __builtin_amdgcn_sched_barrier(0)
; template <int EK, int SK = -1>
; __device__ __forceinline__ void gemm_phase(LAS unsigned char* lds, const bf16_t* A, const bf16_t* Bt, int nM, int N, int K, const EpiArgs& E) {
;     ...
;             PG8_WAIT_V(8); PG8_WAIT_L(0); PG8_BAR; PG8_MMA(1, 0, At, B0); PG8_MMA(1, 1, At, B1); PG8_BAR; PG8_SCHED;
;             PG8_LDB(B0, 1, 0); PG8_LDB(B1, 1, 1); PG8_SCHED; PG8_LDA(At, 1, 0); PG8_STAGEA(PG8_SA(0, 1), a2 + hstep);
;             PG8_WAIT_V(8); PG8_WAIT_L(0); PG8_BAR; PG8_MMA(0, 0, At, B0); PG8_MMA(0, 1, At, B1); PG8_BAR; PG8_SCHED;
	s_waitcnt lgkmcnt(0)
	v_mfma_f32_16x16x32_bf16 v[46:49], v[156:159], v[188:191], 0
	v_mfma_f32_16x16x32_bf16 v[42:45], v[164:167], v[188:191], 0
	v_mfma_f32_16x16x32_bf16 v[38:41], v[156:159], v[196:199], 0
	v_mfma_f32_16x16x32_bf16 v[34:37], v[164:167], v[196:199], 0
	v_mfma_f32_16x16x32_bf16 v[30:33], v[156:159], v[204:207], 0
	v_mfma_f32_16x16x32_bf16 v[26:29], v[164:167], v[204:207], 0
	v_mfma_f32_16x16x32_bf16 v[22:25], v[156:159], v[212:215], 0
	v_mfma_f32_16x16x32_bf16 v[18:21], v[164:167], v[212:215], 0
	v_mfma_f32_16x16x32_bf16 v[46:49], v[160:163], v[192:195], v[46:49]
	v_mfma_f32_16x16x32_bf16 v[42:45], v[168:171], v[192:195], v[42:45]
	v_mfma_f32_16x16x32_bf16 v[38:41], v[160:163], v[200:203], v[38:41]
	v_mfma_f32_16x16x32_bf16 v[34:37], v[168:171], v[200:203], v[34:37]
	v_mfma_f32_16x16x32_bf16 v[30:33], v[160:163], v[208:211], v[30:33]
	v_mfma_f32_16x16x32_bf16 v[26:29], v[168:171], v[208:211], v[26:29]
	v_mfma_f32_16x16x32_bf16 v[22:25], v[160:163], v[216:219], v[22:25]
	v_mfma_f32_16x16x32_bf16 v[18:21], v[168:171], v[216:219], v[18:21]
	v_mfma_f32_16x16x32_bf16 v[14:17], v[172:175], v[188:191], 0
	v_mfma_f32_16x16x32_bf16 v[10:13], v[180:183], v[188:191], 0
	v_mfma_f32_16x16x32_bf16 v[6:9], v[172:175], v[196:199], 0
	v_mfma_f32_16x16x32_bf16 v[2:5], v[180:183], v[196:199], 0
	v_mfma_f32_16x16x32_bf16 v[114:117], v[172:175], v[204:207], 0
	v_mfma_f32_16x16x32_bf16 v[118:121], v[180:183], v[204:207], 0
	v_mfma_f32_16x16x32_bf16 v[122:125], v[172:175], v[212:215], 0
	v_mfma_f32_16x16x32_bf16 v[126:129], v[180:183], v[212:215], 0
	v_mfma_f32_16x16x32_bf16 v[14:17], v[176:179], v[192:195], v[14:17]
	v_mfma_f32_16x16x32_bf16 v[10:13], v[184:187], v[192:195], v[10:13]
	v_mfma_f32_16x16x32_bf16 v[6:9], v[176:179], v[200:203], v[6:9]
	v_mfma_f32_16x16x32_bf16 v[2:5], v[184:187], v[200:203], v[2:5]
	v_mfma_f32_16x16x32_bf16 v[114:117], v[176:179], v[208:211], v[114:117]
	v_mfma_f32_16x16x32_bf16 v[118:121], v[184:187], v[208:211], v[118:121]
	v_mfma_f32_16x16x32_bf16 v[122:125], v[176:179], v[216:219], v[122:125]
	v_mfma_f32_16x16x32_bf16 v[126:129], v[184:187], v[216:219], v[126:129]
	s_barrier
	s_add_i32 s93, 0, 0x18000
	s_add_i32 s94, 0, 0x1c000
	v_add_u32_e32 v168, s93, v152
	v_add_u32_e32 v184, s94, v152
	ds_read_b128 v[156:159], v168
	ds_read_b128 v[160:163], v168 offset:1024
	ds_read_b128 v[164:167], v168 offset:2048
	ds_read_b128 v[168:171], v168 offset:3072
	ds_read_b128 v[172:175], v184
	ds_read_b128 v[176:179], v184 offset:1024
	ds_read_b128 v[180:183], v184 offset:2048
	ds_read_b128 v[184:187], v184 offset:3072
	s_add_u32 s84, s84, 0x40000
	s_addc_u32 s85, s85, 0
	s_mov_b32 m0, s88
	v_lshl_add_u64 v[226:227], s[84:85], 0, v[130:131]
	ds_read_b128 v[188:191], v155 offset:32768
	ds_read_b128 v[192:195], v155 offset:33792
	ds_read_b128 v[196:199], v155 offset:34816
	ds_read_b128 v[200:203], v155 offset:35840
	ds_read_b128 v[204:207], v155 offset:36864
	ds_read_b128 v[208:211], v155 offset:37888
	ds_read_b128 v[212:215], v155 offset:38912
	ds_read_b128 v[216:219], v155 offset:39936
	global_load_lds_dwordx4 v[226:227], off
	v_lshl_add_u64 v[226:227], s[84:85], 0, v[134:135]
	s_mov_b32 m0, s89
	s_nop 0
	global_load_lds_dwordx4 v[226:227], off
	s_waitcnt vmcnt(8)
	s_waitcnt lgkmcnt(0)
	s_barrier
	s_waitcnt lgkmcnt(0)
	v_mfma_f32_16x16x32_bf16 v[110:113], v[156:159], v[188:191], v[110:113]
	v_mfma_f32_16x16x32_bf16 v[106:109], v[164:167], v[188:191], v[106:109]
	v_mfma_f32_16x16x32_bf16 v[102:105], v[156:159], v[196:199], v[102:105]
	v_mfma_f32_16x16x32_bf16 v[98:101], v[164:167], v[196:199], v[98:101]
	v_mfma_f32_16x16x32_bf16 v[94:97], v[156:159], v[204:207], v[94:97]
	v_mfma_f32_16x16x32_bf16 v[90:93], v[164:167], v[204:207], v[90:93]
	v_mfma_f32_16x16x32_bf16 v[86:89], v[156:159], v[212:215], v[86:89]
	v_mfma_f32_16x16x32_bf16 v[82:85], v[164:167], v[212:215], v[82:85]
	v_mfma_f32_16x16x32_bf16 v[110:113], v[160:163], v[192:195], v[110:113]
	v_mfma_f32_16x16x32_bf16 v[106:109], v[168:171], v[192:195], v[106:109]
	v_mfma_f32_16x16x32_bf16 v[102:105], v[160:163], v[200:203], v[102:105]
	v_mfma_f32_16x16x32_bf16 v[98:101], v[168:171], v[200:203], v[98:101]
	v_mfma_f32_16x16x32_bf16 v[94:97], v[160:163], v[208:211], v[94:97]
	v_mfma_f32_16x16x32_bf16 v[90:93], v[168:171], v[208:211], v[90:93]
	v_mfma_f32_16x16x32_bf16 v[86:89], v[160:163], v[216:219], v[86:89]
	v_mfma_f32_16x16x32_bf16 v[82:85], v[168:171], v[216:219], v[82:85]
	v_mfma_f32_16x16x32_bf16 v[78:81], v[172:175], v[188:191], v[78:81]
	v_mfma_f32_16x16x32_bf16 v[74:77], v[180:183], v[188:191], v[74:77]
	v_mfma_f32_16x16x32_bf16 v[70:73], v[172:175], v[196:199], v[70:73]
	v_mfma_f32_16x16x32_bf16 v[66:69], v[180:183], v[196:199], v[66:69]
	v_mfma_f32_16x16x32_bf16 v[62:65], v[172:175], v[204:207], v[62:65]
	v_mfma_f32_16x16x32_bf16 v[58:61], v[180:183], v[204:207], v[58:61]
	v_mfma_f32_16x16x32_bf16 v[54:57], v[172:175], v[212:215], v[54:57]
	v_mfma_f32_16x16x32_bf16 v[50:53], v[180:183], v[212:215], v[50:53]
	v_mfma_f32_16x16x32_bf16 v[78:81], v[176:179], v[192:195], v[78:81]
	v_mfma_f32_16x16x32_bf16 v[74:77], v[184:187], v[192:195], v[74:77]
	v_mfma_f32_16x16x32_bf16 v[70:73], v[176:179], v[200:203], v[70:73]
	v_mfma_f32_16x16x32_bf16 v[66:69], v[184:187], v[200:203], v[66:69]
	v_mfma_f32_16x16x32_bf16 v[62:65], v[176:179], v[208:211], v[62:65]
	v_mfma_f32_16x16x32_bf16 v[58:61], v[184:187], v[208:211], v[58:61]
	v_mfma_f32_16x16x32_bf16 v[54:57], v[176:179], v[216:219], v[54:57]
	v_mfma_f32_16x16x32_bf16 v[50:53], v[184:187], v[216:219], v[50:53]
	s_barrier
; #define PG8_STAGEA(bufoff, gbase) PG8_STAGE_(bufoff, gbase, voffA)
; #define PG8_STAGEB(bufoff, gbase) PG8_STAGE_(bufoff, gbase, voffB)
; #define PG8_LDA(dst, b, h) do { _Pragma("unroll") for (int m = 0; m < 4; ++m) _Pragma("unroll") for (int k = 0; k < 2; ++k) dst[m][k] = *(const LAS bf16x8*)(lds + PG8_SA(b, h) + aoff + m * 2048 + k * 1024); } while (0)
; #define PG8_MMA(ai, bj, At, Bt_) do { __builtin_amdgcn_s_setprio(1); _Pragma("unroll") for (int m = 0; m < 4; ++m) _Pragma("unroll") for (int n = 0; n < 2; ++n) _Pragma("unroll") for (int k = 0; k < 2; ++k) \
;         acc[ai][bj][m][n] = __builtin_amdgcn_mfma_f32_16x16x32_bf16(Bt_[n][k], At[m][k], acc[ai][bj][m][n], 0, 0, 0); __builtin_amdgcn_s_setprio(0); } while (0)
; #define PG8_WAIT_V(n) asm volatile("s_waitcnt vmcnt(" #n ")" ::: "memory")
; #define PG8_WAIT_L(n) asm volatile("s_waitcnt lgkmcnt(" #n ")" ::: "memory")
; #define PG8_BAR __builtin_amdgcn_s_barrier()
; #define PG8_SCHED __builtin_amdgcn_sched_barrier(0)
; template <int EK, int SK = -1>
; __device__ __forceinline__ void gemm_phase(LAS unsigned char* lds, const bf16_t* A, const bf16_t* Bt, int nM, int N, int K, const EpiArgs& E) {
;     ...
;             PG8_LDA(At, 1, 1); PG8_STAGEB(PG8_SB(1, 0), b3); PG8_STAGEB(PG8_SB(1, 1), b3 + hstep); PG8_STAGEA(PG8_SA(1, 0), a3);
;             PG8_WAIT_V(8); PG8_WAIT_L(0); PG8_BAR; PG8_MMA(1, 0, At, B0); PG8_MMA(1, 1, At, B1); PG8_BAR; PG8_SCHED;
;         }
	s_add_i32 s84, s93, s87
	v_lshl_add_u64 v[150:151], v[150:151], 0, s[10:11]
	s_mov_b32 m0, s84
	ds_read_b128 v[188:191], v155 offset:49152
	ds_read_b128 v[192:195], v155 offset:50176
	ds_read_b128 v[196:199], v155 offset:51200
	ds_read_b128 v[200:203], v155 offset:52224
	ds_read_b128 v[204:207], v155 offset:53248
	ds_read_b128 v[208:211], v155 offset:54272
	ds_read_b128 v[212:215], v155 offset:55296
	ds_read_b128 v[216:219], v155 offset:56320
	global_load_lds_dwordx4 v[150:151], off
	s_add_i32 m0, s84, 0x2000
	s_add_u32 s82, s82, 0x40080
	v_lshl_add_u64 v[150:151], v[220:221], 0, s[10:11]
	s_addc_u32 s83, s83, 0
	s_add_i32 s84, s94, s87
	global_load_lds_dwordx4 v[150:151], off
	v_lshl_add_u64 v[150:151], s[82:83], 0, v[132:133]
	s_mov_b32 m0, s84
	s_nop 0
	global_load_lds_dwordx4 v[150:151], off
	v_lshl_add_u64 v[150:151], s[82:83], 0, v[136:137]
	s_add_i32 m0, s84, 0x2000
	s_nop 0
	global_load_lds_dwordx4 v[150:151], off
	v_lshl_add_u64 v[150:151], v[222:223], 0, s[10:11]
	s_mov_b32 m0, s52
	s_nop 0
	global_load_lds_dwordx4 v[150:151], off
	v_lshl_add_u64 v[150:151], v[224:225], 0, s[10:11]
	s_mov_b32 m0, s53
	s_nop 0
	global_load_lds_dwordx4 v[150:151], off
	s_waitcnt vmcnt(8)
	s_waitcnt lgkmcnt(0)
	s_barrier
	s_waitcnt lgkmcnt(0)
	v_mfma_f32_16x16x32_bf16 v[46:49], v[156:159], v[188:191], v[46:49]
	v_mfma_f32_16x16x32_bf16 v[42:45], v[164:167], v[188:191], v[42:45]
	v_mfma_f32_16x16x32_bf16 v[38:41], v[156:159], v[196:199], v[38:41]
	v_mfma_f32_16x16x32_bf16 v[34:37], v[164:167], v[196:199], v[34:37]
	v_mfma_f32_16x16x32_bf16 v[30:33], v[156:159], v[204:207], v[30:33]
	v_mfma_f32_16x16x32_bf16 v[26:29], v[164:167], v[204:207], v[26:29]
	v_mfma_f32_16x16x32_bf16 v[22:25], v[156:159], v[212:215], v[22:25]
	v_mfma_f32_16x16x32_bf16 v[18:21], v[164:167], v[212:215], v[18:21]
	v_mfma_f32_16x16x32_bf16 v[46:49], v[160:163], v[192:195], v[46:49]
	v_mfma_f32_16x16x32_bf16 v[42:45], v[168:171], v[192:195], v[42:45]
	v_mfma_f32_16x16x32_bf16 v[38:41], v[160:163], v[200:203], v[38:41]
	v_mfma_f32_16x16x32_bf16 v[34:37], v[168:171], v[200:203], v[34:37]
	v_mfma_f32_16x16x32_bf16 v[30:33], v[160:163], v[208:211], v[30:33]
	v_mfma_f32_16x16x32_bf16 v[26:29], v[168:171], v[208:211], v[26:29]
	v_mfma_f32_16x16x32_bf16 v[22:25], v[160:163], v[216:219], v[22:25]
	v_mfma_f32_16x16x32_bf16 v[18:21], v[168:171], v[216:219], v[18:21]
	v_mfma_f32_16x16x32_bf16 v[14:17], v[172:175], v[188:191], v[14:17]
	v_mfma_f32_16x16x32_bf16 v[10:13], v[180:183], v[188:191], v[10:13]
	v_mfma_f32_16x16x32_bf16 v[6:9], v[172:175], v[196:199], v[6:9]
	v_mfma_f32_16x16x32_bf16 v[2:5], v[180:183], v[196:199], v[2:5]
	v_mfma_f32_16x16x32_bf16 v[114:117], v[172:175], v[204:207], v[114:117]
	v_mfma_f32_16x16x32_bf16 v[118:121], v[180:183], v[204:207], v[118:121]
	v_mfma_f32_16x16x32_bf16 v[122:125], v[172:175], v[212:215], v[122:125]
	v_mfma_f32_16x16x32_bf16 v[126:129], v[180:183], v[212:215], v[126:129]
	v_mfma_f32_16x16x32_bf16 v[14:17], v[176:179], v[192:195], v[14:17]
	v_mfma_f32_16x16x32_bf16 v[10:13], v[184:187], v[192:195], v[10:13]
	v_mfma_f32_16x16x32_bf16 v[6:9], v[176:179], v[200:203], v[6:9]
	v_mfma_f32_16x16x32_bf16 v[2:5], v[184:187], v[200:203], v[2:5]
	v_mfma_f32_16x16x32_bf16 v[114:117], v[176:179], v[208:211], v[114:117]
	v_mfma_f32_16x16x32_bf16 v[118:121], v[184:187], v[208:211], v[118:121]
	v_mfma_f32_16x16x32_bf16 v[122:125], v[176:179], v[216:219], v[122:125]
	v_mfma_f32_16x16x32_bf16 v[126:129], v[184:187], v[216:219], v[126:129]
	s_barrier
	s_add_i32 s92, s92, 2
	s_add_u32 s78, s78, 0x100
	s_addc_u32 s79, s79, 0
	s_cmp_gt_u32 s92, 13
	s_cbranch_scc0 .LBB0_198
	s_branch .Lmy_kexit_0

; #define PG8_BAR __builtin_amdgcn_s_barrier()
; template <int EK, int SK = -1>
; __device__ __forceinline__ void gemm_phase(LAS unsigned char* lds, const bf16_t* A, const bf16_t* Bt, int nM, int N, int K, const EpiArgs& E) {
;     ...
;         }
;         if (wr == 0) PG8_BAR;
;         if (EK != EK_FINAL) epi_tile<EK>(acc, cur, wr, wc, fr, fq, E, rtab + ui * 256);
.Lmy_kexit_0:
	s_and_b64 vcc, exec, s[12:13]
	s_cbranch_vccz .LBB0_201
	s_barrier

; __device__ __forceinline__ unsigned xb_ld(unsigned* p)              { return __hip_atomic_load(p, __ATOMIC_RELAXED, __HIP_MEMORY_SCOPE_AGENT); }
; __device__ __forceinline__ unsigned xb_add(unsigned* p, unsigned v) { return __hip_atomic_fetch_add(p, v, __ATOMIC_RELAXED, __HIP_MEMORY_SCOPE_AGENT); }
; #define XB_SPIN(cond, bar) do { unsigned _sp = 0; while (cond) { __builtin_amdgcn_s_sleep(1); \
;     if ((++_sp & 255u) == 0u) { if (xb_ld(&(bar)[XB_TMO])) break; if (_sp > XB_SPIN_CAP) { atomicAdd(&(bar)[XB_TMO], 1u); break; } } } } while (0)
; __device__ __forceinline__ void xcd_barrier(const XcdBarrier& b) {
;     asm volatile("s_waitcnt vmcnt(0)" ::: "memory");
;     __syncthreads();
;     if (threadIdx.x == 0) {
;         unsigned* bar = b.bar;
;         __builtin_amdgcn_s_waitcnt(0);
;         unsigned nloc = b.st[0], nx = b.st[1];
;         if (nloc == 0u) { xcd_barrier_complete(bar, b.x, nloc, nx); b.st[0] = nloc; b.st[1] = nx; }
;         const unsigned old = xb_add(&bar[XB_XSUB(b.x)], 1u);
;         const unsigned gen = old / nloc;
;         if (old + 1u == (gen + 1u) * nloc) {
;             __builtin_amdgcn_fence(__ATOMIC_RELEASE, "agent");
;             asm volatile("s_waitcnt vmcnt(0)" ::: "memory");
;             const unsigned og = xb_add(&bar[XB_TOP], 1u);
;             const unsigned tg = og / nx;
;             if (og + 1u == (tg + 1u) * nx) xb_add(&bar[XB_TOPGEN], 1u);
;             else XB_SPIN(xb_ld(&bar[XB_TOPGEN]) == tg, bar);
;             __builtin_amdgcn_fence(__ATOMIC_ACQUIRE, "agent");
;             asm volatile("s_waitcnt vmcnt(0)" ::: "memory");
;         } else {
;             XB_SPIN(xb_ld(&bar[XB_TOPGEN]) == gen, bar);
;             __builtin_amdgcn_fence(__ATOMIC_ACQUIRE, "agent");
;             asm volatile("s_waitcnt vmcnt(0)" ::: "memory");
;         }
;     }
;     __syncthreads();
.Lmy_noinv2:
	s_and_saveexec_b64 s[6:7], vcc
	s_cbranch_execz .LBB0_255
	s_waitcnt vmcnt(0) lgkmcnt(0)
	v_mov_b32_e32 v1, 0x20000
	ds_read2_b32 v[2:3], v1 offset1:1
	s_and_b32 s99, s33, 7
	s_lshl_b32 s99, s99, 8
	s_add_u32 s100, s60, 0xc000
	s_addc_u32 s101, s61, 0
	v_mov_b32_e32 v4, s99
	v_mov_b32_e32 v5, 1
	global_atomic_add v5, v4, v5, s[100:101] sc0
	s_waitcnt lgkmcnt(0)
	v_mul_u32_u24_e32 v6, 1, v2
	v_mul_u32_u24_e32 v7, 1, v3
	s_waitcnt vmcnt(0)
	v_add_u32_e32 v5, 1, v5
	v_cmp_eq_u32_e32 vcc, v5, v6
	s_cbranch_vccz .Lmy_nl1
	buffer_wbl2 sc1
	s_waitcnt vmcnt(0)
	v_mov_b32_e32 v4, 0x800
	v_mov_b32_e32 v5, 1
	global_atomic_add v4, v5, s[100:101]
.Lmy_nl1:
	v_mov_b32_e32 v4, 0x800
	s_mov_b32 s99, 0
.Lmy_poll1:
	global_load_dword v5, v4, s[100:101] sc1
	s_waitcnt vmcnt(0)
	v_cmp_ge_u32_e32 vcc, v5, v7
	s_cbranch_vccnz .Lmy_pdone1
	s_sleep 1
	s_add_i32 s99, s99, 1
	s_cmp_lt_u32 s99, 0x40000
	s_cbranch_scc1 .Lmy_poll1
.Lmy_pdone1:
.LBB0_255:
	s_or_b64 exec, exec, s[6:7]
	s_waitcnt lgkmcnt(0)
	s_barrier

; __device__ __forceinline__ unsigned xb_ld(unsigned* p)              { return __hip_atomic_load(p, __ATOMIC_RELAXED, __HIP_MEMORY_SCOPE_AGENT); }
; __device__ __forceinline__ unsigned xb_add(unsigned* p, unsigned v) { return __hip_atomic_fetch_add(p, v, __ATOMIC_RELAXED, __HIP_MEMORY_SCOPE_AGENT); }
; #define XB_SPIN(cond, bar) do { unsigned _sp = 0; while (cond) { __builtin_amdgcn_s_sleep(1); \
;     if ((++_sp & 255u) == 0u) { if (xb_ld(&(bar)[XB_TMO])) break; if (_sp > XB_SPIN_CAP) { atomicAdd(&(bar)[XB_TMO], 1u); break; } } } } while (0)
; __device__ __forceinline__ void xcd_barrier(const XcdBarrier& b) {
;     asm volatile("s_waitcnt vmcnt(0)" ::: "memory");
;     __syncthreads();
;     if (threadIdx.x == 0) {
;         unsigned* bar = b.bar;
;         __builtin_amdgcn_s_waitcnt(0);
;         unsigned nloc = b.st[0], nx = b.st[1];
;         if (nloc == 0u) { xcd_barrier_complete(bar, b.x, nloc, nx); b.st[0] = nloc; b.st[1] = nx; }
;         const unsigned old = xb_add(&bar[XB_XSUB(b.x)], 1u);
;         const unsigned gen = old / nloc;
;         if (old + 1u == (gen + 1u) * nloc) {
;             __builtin_amdgcn_fence(__ATOMIC_RELEASE, "agent");
;             asm volatile("s_waitcnt vmcnt(0)" ::: "memory");
;             const unsigned og = xb_add(&bar[XB_TOP], 1u);
;             const unsigned tg = og / nx;
;             if (og + 1u == (tg + 1u) * nx) xb_add(&bar[XB_TOPGEN], 1u);
;             else XB_SPIN(xb_ld(&bar[XB_TOPGEN]) == tg, bar);
;             __builtin_amdgcn_fence(__ATOMIC_ACQUIRE, "agent");
;             asm volatile("s_waitcnt vmcnt(0)" ::: "memory");
;         } else {
;             XB_SPIN(xb_ld(&bar[XB_TOPGEN]) == gen, bar);
;             __builtin_amdgcn_fence(__ATOMIC_ACQUIRE, "agent");
;             asm volatile("s_waitcnt vmcnt(0)" ::: "memory");
;         }
;     }
;     __syncthreads();
.Lmy_noinv3:
	s_and_saveexec_b64 s[6:7], vcc
	s_cbranch_execz .LBB0_382
	s_waitcnt vmcnt(0) lgkmcnt(0)
	v_mov_b32_e32 v1, 0x20000
	ds_read2_b32 v[2:3], v1 offset1:1
	s_and_b32 s99, s33, 7
	s_lshl_b32 s99, s99, 8
	s_add_u32 s100, s60, 0xc000
	s_addc_u32 s101, s61, 0
	v_mov_b32_e32 v4, s99
	v_mov_b32_e32 v5, 1
	global_atomic_add v5, v4, v5, s[100:101] sc0
	s_waitcnt lgkmcnt(0)
	v_mul_u32_u24_e32 v6, 2, v2
	v_mul_u32_u24_e32 v7, 2, v3
	s_waitcnt vmcnt(0)
	v_add_u32_e32 v5, 1, v5
	v_cmp_eq_u32_e32 vcc, v5, v6
	s_cbranch_vccz .Lmy_nl2
	buffer_wbl2 sc1
	s_waitcnt vmcnt(0)
	v_mov_b32_e32 v4, 0x800
	v_mov_b32_e32 v5, 1
	global_atomic_add v4, v5, s[100:101]

; #define LAS __attribute__((address_space(3)))
; __device__ __forceinline__ float hsum4(f32x4 v) { return (v[0] + v[1]) + (v[2] + v[3]); }
; #define PG8_STAGEA(bufoff, gbase) PG8_STAGE_(bufoff, gbase, voffA)
; template <int EK, int SK = -1>
; __device__ __forceinline__ void gemm_phase(LAS unsigned char* lds, const bf16_t* A, const bf16_t* Bt, int nM, int N, int K, const EpiArgs& E) {
;     ...
;     f32x4 acc[2][2][4][2];
; #pragma unroll
;     for (int a = 0; a < 2; ++a)
; #pragma unroll
;         for (int b = 0; b < 2; ++b)
; #pragma unroll
;             for (int m = 0; m < 4; ++m)
; #pragma unroll
;                 for (int n = 0; n < 2; ++n) acc[a][b][m][n] = (f32x4){0.f, 0.f, 0.f, 0.f};
;     bf16x8 At[4][2], B0[2][2], B1[2][2];
;     const char* cA = (const char*)A + (size_t)cur.pm * tstep; const char* cB = (const char*)Bt + (size_t)cur.pn * tstep;
;     PG8_STAGEB(PG8_SB(0, 0), cB); PG8_STAGEB(PG8_SB(0, 1), cB + hstep); PG8_STAGEA(PG8_SA(0, 0), cA); PG8_STAGEA(PG8_SA(0, 1), cA + hstep);
;     f32x4 tq[4][4]; bool okq[4];
;     if (EK != EK_RES && EK != EK_FINAL) {
; #pragma unroll
;         for (int j = 0; j < 4; ++j) { Unit uu; okq[j] = S.next((tid >> 8) + 2 * j, uu);
;             if (okq[j]) { const f32x4* sp = (const f32x4*)(E.stIn + (size_t)(uu.pm * BM + (tid & 255)) * 16); tq[j][0] = sp[0]; tq[j][1] = sp[1]; tq[j][2] = sp[2]; tq[j][3] = sp[3]; } }
;     }
;     if (SK >= 0) skinny_phase<(SK >= 0 ? SK : 0)>(lds + 32768, (LAS float*)(lds + SRED_OFF), A, Bt, N, K, E);
;     if (EK != EK_RES && EK != EK_FINAL) {
; #pragma unroll
;         for (int j = 0; j < 4; ++j) if (okq[j]) { const float s_ = (hsum4(tq[j][0]) + hsum4(tq[j][1])) + (hsum4(tq[j][2]) + hsum4(tq[j][3]));
;             rtab[((tid >> 8) + 2 * j) * 256 + (tid & 255)] = rsqrtf(s_ * (1.0f / 1024.0f) + EPS); }
;         __syncthreads();
;     }
;     if (wr == 1) PG8_BAR;
;     PG8_WAIT_V(2); PG8_BAR;
;     PG8_STAGEB(PG8_SB(1, 0), cB + kstep); PG8_STAGEA(PG8_SA(1, 0), cA + kstep); PG8_STAGEB(PG8_SB(1, 1), cB + hstep + kstep);
;     PG8_WAIT_V(6); PG8_BAR;
;     ...
; #pragma unroll
;         for (int a = 0; a < 2; ++a)
; #pragma unroll
;             for (int b = 0; b < 2; ++b)
; #pragma unroll
;                 for (int m = 0; m < 4; ++m)
; #pragma unroll
;                     for (int n = 0; n < 2; ++n) acc[a][b][m][n] = (f32x4){0.f, 0.f, 0.f, 0.f};
;         cur = nxt; cA = nA; cB = nB; ++ui;
.LBB0_404:
	v_bfe_u32 v10, v0, 4, 2
	v_lshlrev_b32_e32 v12, 4, v10
	v_lshl_or_b32 v1, s4, 6, v18
	v_lshl_or_b32 v13, v18, 6, v12
	v_lshlrev_b32_e32 v18, 2, v18
	s_lshl_b32 s4, s4, 13
	v_and_b32_e32 v18, 32, v18
	v_bitop3_b32 v13, v13, s4, v18 bitop3:0xde
	v_lshlrev_b32_e32 v18, 6, v0
	s_movk_i32 s4, 0x3c0
	s_mov_b64 s[68:69], 0x80
	s_and_b32 s91, s53, 3
	v_and_or_b32 v12, v18, s4, v12
	v_lshlrev_b32_e32 v18, 2, v0
	s_add_i32 m0, s15, 0x18000
	v_lshl_add_u64 v[8:9], v[8:9], 0, s[68:69]
	s_lshl_b32 s4, s91, 12
	v_and_b32_e32 v18, 32, v18
	s_ashr_i32 s92, s2, 31
	s_waitcnt vmcnt(2)
	s_barrier
	global_load_lds_dwordx4 v[8:9], off
	v_lshl_add_u64 v[6:7], v[6:7], 0, s[68:69]
	s_add_i32 m0, s15, 0x1a000
	s_add_i32 s93, s15, 0x8000
	s_add_i32 s94, s15, 0xa000
	v_bitop3_b32 v152, s4, v12, v18 bitop3:0xf6
	global_load_lds_dwordx4 v[6:7], off
	v_lshl_add_u64 v[2:3], v[2:3], 0, s[68:69]
	s_mov_b32 m0, s93
	s_add_u32 s4, s80, 0x40080
	global_load_lds_dwordx4 v[2:3], off
	v_lshl_add_u64 v[2:3], v[4:5], 0, s[68:69]
	s_mov_b32 m0, s94
	s_addc_u32 s5, s81, 0
	global_load_lds_dwordx4 v[2:3], off
	s_add_i32 m0, s15, 0x1c000
	v_lshl_add_u64 v[2:3], s[4:5], 0, v[132:133]
	global_load_lds_dwordx4 v[2:3], off
	v_lshl_add_u64 v[2:3], s[4:5], 0, v[136:137]
	s_add_i32 m0, s15, 0x1e000
	v_lshlrev_b32_e32 v4, 11, v16
	global_load_lds_dwordx4 v[2:3], off
	v_lshlrev_b32_e32 v2, 8, v0
	v_and_b32_e32 v2, 0x18000, v2
	v_or3_b32 v2, v14, v2, v4
	s_mov_b64 s[6:7], 0x40080
	v_add_u32_e32 v2, v2, v15
	v_mov_b32_e32 v3, 0
	v_lshl_add_u64 v[138:139], v[2:3], 0, s[6:7]
	v_lshlrev_b32_e32 v2, 4, v17
	v_and_b32_e32 v2, 0x38000, v2
	v_or3_b32 v2, v14, v2, v4
	s_waitcnt vmcnt(6)
	v_add_u32_e32 v2, v2, v15
	v_lshlrev_b32_e32 v11, 3, v10
	s_cmpk_lt_u32 s52, 0x100
	v_lshl_add_u64 v[140:141], v[2:3], 0, s[6:7]
	v_mbcnt_lo_u32_b32 v2, -1, 0
	s_mov_b32 s41, 0
	v_lshl_or_b32 v153, s91, 5, v11
	s_cselect_b64 s[70:71], -1, 0
	v_cmp_eq_u32_e64 s[4:5], 0, v10
	v_mov_b64_e32 v[142:143], 0x100
	v_mov_b64_e32 v[144:145], 0xff
	s_add_i32 s95, 0, 0x10000
	s_add_i32 s96, 0, 0x14000
	v_add_u32_e32 v154, 0, v13
	v_mbcnt_hi_u32_b32 v155, -1, v2
	s_mov_b32 s52, 0
	v_mov_b32_e32 v2, v3
	s_barrier
	s_branch .LBB0_406
.LBB0_405:
	v_mov_b32_e32 v2, 0
	s_mov_b32 s16, s72
	s_mov_b32 s14, s74
	v_mov_b32_e32 v3, v2
	s_mov_b64 s[18:19], s[78:79]
	s_mov_b32 s52, s97
	s_andn2_b64 vcc, exec, s[6:7]
	s_mov_b64 s[80:81], s[76:77]
	s_cbranch_vccz .LBB0_436

; #define PG8_STAGEA(bufoff, gbase) PG8_STAGE_(bufoff, gbase, voffA)
; #define PG8_STAGEB(bufoff, gbase) PG8_STAGE_(bufoff, gbase, voffB)
; #define PG8_LDA(dst, b, h) do { _Pragma("unroll") for (int m = 0; m < 4; ++m) _Pragma("unroll") for (int k = 0; k < 2; ++k) dst[m][k] = *(const LAS bf16x8*)(lds + PG8_SA(b, h) + aoff + m * 2048 + k * 1024); } while (0)
; #define PG8_LDB(dst, b, h) do { _Pragma("unroll") for (int n = 0; n < 2; ++n) _Pragma("unroll") for (int k = 0; k < 2; ++k) dst[n][k] = *(const LAS bf16x8*)(lds + PG8_SB(b, h) + boff + n * 2048 + k * 1024); } while (0)
; #define PG8_MMA(ai, bj, At, Bt_) do { __builtin_amdgcn_s_setprio(1); _Pragma("unroll") for (int m = 0; m < 4; ++m) _Pragma("unroll") for (int n = 0; n < 2; ++n) _Pragma("unroll") for (int k = 0; k < 2; ++k) \
;         acc[ai][bj][m][n] = __builtin_amdgcn_mfma_f32_16x16x32_bf16(Bt_[n][k], At[m][k], acc[ai][bj][m][n], 0, 0, 0); __builtin_amdgcn_s_setprio(0); } while (0)
; #define PG8_WAIT_V(n) asm volatile("s_waitcnt vmcnt(" #n ")" ::: "memory")
; #define PG8_WAIT_L(n) asm volatile("s_waitcnt lgkmcnt(" #n ")" ::: "memory")
; template <int EK, int SK = -1>
; __device__ __forceinline__ void gemm_phase(LAS unsigned char* lds, const bf16_t* A, const bf16_t* Bt, int nM, int N, int K, const EpiArgs& E) {
;     ...
;     for (;;) {
;         const bool has_next = S.next(ui + 1, nxt);
;         const char* nA = has_next ? (const char*)A + (size_t)nxt.pm * tstep : cA; const char* nB = has_next ? (const char*)Bt + (size_t)nxt.pn * tstep : cB;
;         for (int t = 0; t < nt; t += 2) {
;             const bool last = (t == nt - 2);
;             const char* a1 = cA + (size_t)(t + 1) * kstep;
;             const char* a2 = last ? nA : cA + (size_t)(t + 2) * kstep; const char* b2 = last ? nB : cB + (size_t)(t + 2) * kstep;
;             const char* a3 = a2 + kstep; const char* b3 = b2 + kstep;
;             PG8_LDB(B0, 0, 0); PG8_LDB(B1, 0, 1); PG8_SCHED; PG8_LDA(At, 0, 0); PG8_STAGEA(PG8_SA(1, 1), a1 + hstep);
;             PG8_WAIT_V(8); PG8_WAIT_L(0); PG8_BAR; PG8_MMA(0, 0, At, B0); PG8_MMA(0, 1, At, B1); PG8_BAR; PG8_SCHED;
;             PG8_LDA(At, 0, 1); PG8_STAGEB(PG8_SB(0, 0), b2); PG8_STAGEB(PG8_SB(0, 1), b2 + hstep); PG8_STAGEA(PG8_SA(0, 0), a2);
;             PG8_WAIT_V(8); PG8_WAIT_L(0); PG8_BAR; PG8_MMA(1, 0, At, B0); PG8_MMA(1, 1, At, B1); PG8_BAR; PG8_SCHED;
.LBB0_412:
	s_add_u32 s53, s80, 0x100
	s_addc_u32 s54, s81, 0
	s_ashr_i32 s75, s74, 31
	s_lshl_b64 s[56:57], s[74:75], 19
	s_add_u32 s78, s66, s56
	s_addc_u32 s79, s67, s57
	s_and_b64 s[56:57], s[8:9], exec
	s_cselect_b32 s40, s79, s19
	s_cselect_b32 s55, s78, s18
	s_ashr_i32 s73, s72, 31
	s_lshl_b64 s[56:57], s[72:73], 19
	s_add_u32 s76, s86, s56
	s_addc_u32 s77, s87, s57
	s_and_b64 s[56:57], s[8:9], exec
	s_cselect_b32 s56, s77, s81
	s_cselect_b32 s57, s76, s80
	v_lshl_add_u64 v[146:147], s[18:19], 0, v[138:139]
	v_lshl_add_u64 v[148:149], s[18:19], 0, v[140:141]
	s_mov_b32 s58, -2
	s_mov_b64 s[80:81], 0
	v_add_u32_e32 v150, s95, v152
	ds_read_b128 v[156:159], v150
	ds_read_b128 v[160:163], v150 offset:1024
	ds_read_b128 v[164:167], v150 offset:2048
	ds_read_b128 v[168:171], v150 offset:3072
	v_add_u32_e32 v150, s96, v152
	s_add_u32 s59, s18, s80
	ds_read_b128 v[172:175], v150
	ds_read_b128 v[176:179], v150 offset:1024
	ds_read_b128 v[180:183], v150 offset:2048
	ds_read_b128 v[184:187], v150 offset:3072
	s_addc_u32 s73, s19, s81
	s_add_u32 s59, s59, 0x100
	s_addc_u32 s73, s73, 0
	s_add_u32 s75, s53, s80
	s_addc_u32 s82, s54, s81
	s_cmpk_eq_i32 s80, 0x700
	s_cselect_b32 s85, s40, s73
	s_cselect_b32 s84, s55, s59
	s_cselect_b32 s83, s56, s82
	s_cselect_b32 s82, s57, s75
	v_lshl_add_u64 v[150:151], v[146:147], 0, s[80:81]
	s_add_i32 m0, s15, 0xc000
	ds_read_b128 v[188:191], v154
	ds_read_b128 v[192:195], v154 offset:1024
	ds_read_b128 v[196:199], v154 offset:2048
	ds_read_b128 v[200:203], v154 offset:3072
	ds_read_b128 v[204:207], v154 offset:4096
	ds_read_b128 v[208:211], v154 offset:5120
	ds_read_b128 v[212:215], v154 offset:6144
	ds_read_b128 v[216:219], v154 offset:7168
	global_load_lds_dwordx4 v[150:151], off
	v_lshl_add_u64 v[150:151], v[148:149], 0, s[80:81]
	s_add_i32 m0, s15, 0xe000
	s_nop 0
	global_load_lds_dwordx4 v[150:151], off
	s_waitcnt vmcnt(8)
	s_waitcnt lgkmcnt(0)
	s_barrier
	s_waitcnt lgkmcnt(0)
	v_mfma_f32_16x16x32_bf16 v[126:129], v[156:159], v[188:191], 0
	v_mfma_f32_16x16x32_bf16 v[122:125], v[164:167], v[188:191], 0
	v_mfma_f32_16x16x32_bf16 v[118:121], v[156:159], v[196:199], 0
	v_mfma_f32_16x16x32_bf16 v[114:117], v[164:167], v[196:199], 0
	v_mfma_f32_16x16x32_bf16 v[110:113], v[156:159], v[204:207], 0
	v_mfma_f32_16x16x32_bf16 v[106:109], v[164:167], v[204:207], 0
	v_mfma_f32_16x16x32_bf16 v[102:105], v[156:159], v[212:215], 0
	v_mfma_f32_16x16x32_bf16 v[98:101], v[164:167], v[212:215], 0
	v_mfma_f32_16x16x32_bf16 v[126:129], v[160:163], v[192:195], v[126:129]
	v_mfma_f32_16x16x32_bf16 v[122:125], v[168:171], v[192:195], v[122:125]
	v_mfma_f32_16x16x32_bf16 v[118:121], v[160:163], v[200:203], v[118:121]
	v_mfma_f32_16x16x32_bf16 v[114:117], v[168:171], v[200:203], v[114:117]
	v_mfma_f32_16x16x32_bf16 v[110:113], v[160:163], v[208:211], v[110:113]
	v_mfma_f32_16x16x32_bf16 v[106:109], v[168:171], v[208:211], v[106:109]
	v_mfma_f32_16x16x32_bf16 v[102:105], v[160:163], v[216:219], v[102:105]
	v_mfma_f32_16x16x32_bf16 v[98:101], v[168:171], v[216:219], v[98:101]
	v_mfma_f32_16x16x32_bf16 v[94:97], v[172:175], v[188:191], 0
	v_mfma_f32_16x16x32_bf16 v[90:93], v[180:183], v[188:191], 0
	v_mfma_f32_16x16x32_bf16 v[86:89], v[172:175], v[196:199], 0
	v_mfma_f32_16x16x32_bf16 v[82:85], v[180:183], v[196:199], 0
	v_mfma_f32_16x16x32_bf16 v[78:81], v[172:175], v[204:207], 0
	v_mfma_f32_16x16x32_bf16 v[74:77], v[180:183], v[204:207], 0
	v_mfma_f32_16x16x32_bf16 v[70:73], v[172:175], v[212:215], 0
	v_mfma_f32_16x16x32_bf16 v[66:69], v[180:183], v[212:215], 0
	v_mfma_f32_16x16x32_bf16 v[94:97], v[176:179], v[192:195], v[94:97]
	v_mfma_f32_16x16x32_bf16 v[90:93], v[184:187], v[192:195], v[90:93]
	v_mfma_f32_16x16x32_bf16 v[86:89], v[176:179], v[200:203], v[86:89]
	v_mfma_f32_16x16x32_bf16 v[82:85], v[184:187], v[200:203], v[82:85]
	v_mfma_f32_16x16x32_bf16 v[78:81], v[176:179], v[208:211], v[78:81]
	v_mfma_f32_16x16x32_bf16 v[74:77], v[184:187], v[208:211], v[74:77]
	v_mfma_f32_16x16x32_bf16 v[70:73], v[176:179], v[216:219], v[70:73]
	v_mfma_f32_16x16x32_bf16 v[66:69], v[184:187], v[216:219], v[66:69]
	s_barrier
	s_add_i32 s59, s95, s88
	v_lshl_add_u64 v[150:151], s[82:83], 0, v[132:133]
	s_mov_b32 m0, s59
	ds_read_b128 v[188:191], v154 offset:16384
	ds_read_b128 v[192:195], v154 offset:17408
	ds_read_b128 v[196:199], v154 offset:18432
	ds_read_b128 v[200:203], v154 offset:19456
	ds_read_b128 v[204:207], v154 offset:20480
	ds_read_b128 v[208:211], v154 offset:21504
	ds_read_b128 v[212:215], v154 offset:22528
	ds_read_b128 v[216:219], v154 offset:23552
	global_load_lds_dwordx4 v[150:151], off
	s_add_i32 m0, s59, 0x2000
	s_add_u32 vcc_lo, s82, 0x40000
	v_lshl_add_u64 v[220:221], s[82:83], 0, v[136:137]
	s_addc_u32 vcc_hi, s83, 0
	s_add_i32 s59, s96, s88
	global_load_lds_dwordx4 v[220:221], off
	v_lshl_add_u64 v[222:223], vcc, 0, v[132:133]
	s_mov_b32 m0, s59
	v_lshl_add_u64 v[224:225], s[84:85], 0, v[134:135]
	global_load_lds_dwordx4 v[222:223], off
	v_lshl_add_u64 v[222:223], vcc, 0, v[136:137]
	s_add_i32 m0, s59, 0x2000
	s_nop 0
	global_load_lds_dwordx4 v[222:223], off
	v_lshl_add_u64 v[222:223], s[84:85], 0, v[130:131]
	s_mov_b32 m0, s15
	s_nop 0
	global_load_lds_dwordx4 v[222:223], off
	s_mov_b32 m0, s17
	s_nop 0
	global_load_lds_dwordx4 v[224:225], off
	s_waitcnt vmcnt(8)
	s_waitcnt lgkmcnt(0)
	s_barrier
; #define PG8_STAGEA(bufoff, gbase) PG8_STAGE_(bufoff, gbase, voffA)
; #define PG8_LDA(dst, b, h) do { _Pragma("unroll") for (int m = 0; m < 4; ++m) _Pragma("unroll") for (int k = 0; k < 2; ++k) dst[m][k] = *(const LAS bf16x8*)(lds + PG8_SA(b, h) + aoff + m * 2048 + k * 1024); } while (0)
; #define PG8_LDB(dst, b, h) do { _Pragma("unroll") for (int n = 0; n < 2; ++n) _Pragma("unroll") for (int k = 0; k < 2; ++k) dst[n][k] = *(const LAS bf16x8*)(lds + PG8_SB(b, h) + boff + n * 2048 + k * 1024); } while (0)
; #define PG8_MMA(ai, bj, At, Bt_) do { __builtin_amdgcn_s_setprio(1); _Pragma("unroll") for (int m = 0; m < 4; ++m) _Pragma("unroll") for (int n = 0; n < 2; ++n) _Pragma("unroll") for (int k = 0; k < 2; ++k) \
;         acc[ai][bj][m][n] = __builtin_amdgcn_mfma_f32_16x16x32_bf16(Bt_[n][k], At[m][k], acc[ai][bj][m][n], 0, 0, 0); __builtin_amdgcn_s_setprio(0); } while (0)
; #define PG8_WAIT_V(n) asm volatile("s_waitcnt vmcnt(" #n ")" ::: "memory")
; #define PG8_WAIT_L(n) asm volatile("s_waitcnt lgkmcnt(" #n ")" ::: "memory")
; #define PG8_BAR __builtin_amdgcn_s_barrier()
; #define PG8_SCHED __builtin_amdgcn_sched_barrier(0)
; template <int EK, int SK = -1>
; __device__ __forceinline__ void gemm_phase(LAS unsigned char* lds, const bf16_t* A, const bf16_t* Bt, int nM, int N, int K, const EpiArgs& E) {
;     ...
;             PG8_WAIT_V(8); PG8_WAIT_L(0); PG8_BAR; PG8_MMA(1, 0, At, B0); PG8_MMA(1, 1, At, B1); PG8_BAR; PG8_SCHED;
;             PG8_LDB(B0, 1, 0); PG8_LDB(B1, 1, 1); PG8_SCHED; PG8_LDA(At, 1, 0); PG8_STAGEA(PG8_SA(0, 1), a2 + hstep);
;             PG8_WAIT_V(8); PG8_WAIT_L(0); PG8_BAR; PG8_MMA(0, 0, At, B0); PG8_MMA(0, 1, At, B1); PG8_BAR; PG8_SCHED;
	s_waitcnt lgkmcnt(0)
	v_mfma_f32_16x16x32_bf16 v[62:65], v[156:159], v[188:191], 0
	v_mfma_f32_16x16x32_bf16 v[58:61], v[164:167], v[188:191], 0
	v_mfma_f32_16x16x32_bf16 v[54:57], v[156:159], v[196:199], 0
	v_mfma_f32_16x16x32_bf16 v[50:53], v[164:167], v[196:199], 0
	v_mfma_f32_16x16x32_bf16 v[46:49], v[156:159], v[204:207], 0
	v_mfma_f32_16x16x32_bf16 v[42:45], v[164:167], v[204:207], 0
	v_mfma_f32_16x16x32_bf16 v[38:41], v[156:159], v[212:215], 0
	v_mfma_f32_16x16x32_bf16 v[34:37], v[164:167], v[212:215], 0
	v_mfma_f32_16x16x32_bf16 v[62:65], v[160:163], v[192:195], v[62:65]
	v_mfma_f32_16x16x32_bf16 v[58:61], v[168:171], v[192:195], v[58:61]
	v_mfma_f32_16x16x32_bf16 v[54:57], v[160:163], v[200:203], v[54:57]
	v_mfma_f32_16x16x32_bf16 v[50:53], v[168:171], v[200:203], v[50:53]
	v_mfma_f32_16x16x32_bf16 v[46:49], v[160:163], v[208:211], v[46:49]
	v_mfma_f32_16x16x32_bf16 v[42:45], v[168:171], v[208:211], v[42:45]
	v_mfma_f32_16x16x32_bf16 v[38:41], v[160:163], v[216:219], v[38:41]
	v_mfma_f32_16x16x32_bf16 v[34:37], v[168:171], v[216:219], v[34:37]
	v_mfma_f32_16x16x32_bf16 v[30:33], v[172:175], v[188:191], 0
	v_mfma_f32_16x16x32_bf16 v[26:29], v[180:183], v[188:191], 0
	v_mfma_f32_16x16x32_bf16 v[22:25], v[172:175], v[196:199], 0
	v_mfma_f32_16x16x32_bf16 v[18:21], v[180:183], v[196:199], 0
	v_mfma_f32_16x16x32_bf16 v[14:17], v[172:175], v[204:207], 0
	v_mfma_f32_16x16x32_bf16 v[10:13], v[180:183], v[204:207], 0
	v_mfma_f32_16x16x32_bf16 v[6:9], v[172:175], v[212:215], 0
	v_mfma_f32_16x16x32_bf16 v[2:5], v[180:183], v[212:215], 0
	v_mfma_f32_16x16x32_bf16 v[30:33], v[176:179], v[192:195], v[30:33]
	v_mfma_f32_16x16x32_bf16 v[26:29], v[184:187], v[192:195], v[26:29]
	v_mfma_f32_16x16x32_bf16 v[22:25], v[176:179], v[200:203], v[22:25]
	v_mfma_f32_16x16x32_bf16 v[18:21], v[184:187], v[200:203], v[18:21]
	v_mfma_f32_16x16x32_bf16 v[14:17], v[176:179], v[208:211], v[14:17]
	v_mfma_f32_16x16x32_bf16 v[10:13], v[184:187], v[208:211], v[10:13]
	v_mfma_f32_16x16x32_bf16 v[6:9], v[176:179], v[216:219], v[6:9]
	v_mfma_f32_16x16x32_bf16 v[2:5], v[184:187], v[216:219], v[2:5]
	s_barrier
	s_add_i32 s59, 0, 0x18000
	s_add_i32 s73, 0, 0x1c000
	v_add_u32_e32 v168, s59, v152
	v_add_u32_e32 v184, s73, v152
	ds_read_b128 v[156:159], v168
	ds_read_b128 v[160:163], v168 offset:1024
	ds_read_b128 v[164:167], v168 offset:2048
	ds_read_b128 v[168:171], v168 offset:3072
	ds_read_b128 v[172:175], v184
	ds_read_b128 v[176:179], v184 offset:1024
	ds_read_b128 v[180:183], v184 offset:2048
	ds_read_b128 v[184:187], v184 offset:3072
	s_add_u32 s84, s84, 0x40000
	s_addc_u32 s85, s85, 0
	s_mov_b32 m0, s89
	v_lshl_add_u64 v[226:227], s[84:85], 0, v[130:131]
	ds_read_b128 v[188:191], v154 offset:32768
	ds_read_b128 v[192:195], v154 offset:33792
	ds_read_b128 v[196:199], v154 offset:34816
	ds_read_b128 v[200:203], v154 offset:35840
	ds_read_b128 v[204:207], v154 offset:36864
	ds_read_b128 v[208:211], v154 offset:37888
	ds_read_b128 v[212:215], v154 offset:38912
	ds_read_b128 v[216:219], v154 offset:39936
	global_load_lds_dwordx4 v[226:227], off
	v_lshl_add_u64 v[226:227], s[84:85], 0, v[134:135]
	s_mov_b32 m0, s90
	s_nop 0
	global_load_lds_dwordx4 v[226:227], off
	s_waitcnt vmcnt(8)
	s_waitcnt lgkmcnt(0)
	s_barrier
	s_waitcnt lgkmcnt(0)
	v_mfma_f32_16x16x32_bf16 v[126:129], v[156:159], v[188:191], v[126:129]
	v_mfma_f32_16x16x32_bf16 v[122:125], v[164:167], v[188:191], v[122:125]
	v_mfma_f32_16x16x32_bf16 v[118:121], v[156:159], v[196:199], v[118:121]
	v_mfma_f32_16x16x32_bf16 v[114:117], v[164:167], v[196:199], v[114:117]
	v_mfma_f32_16x16x32_bf16 v[110:113], v[156:159], v[204:207], v[110:113]
	v_mfma_f32_16x16x32_bf16 v[106:109], v[164:167], v[204:207], v[106:109]
	v_mfma_f32_16x16x32_bf16 v[102:105], v[156:159], v[212:215], v[102:105]
	v_mfma_f32_16x16x32_bf16 v[98:101], v[164:167], v[212:215], v[98:101]
	v_mfma_f32_16x16x32_bf16 v[126:129], v[160:163], v[192:195], v[126:129]
	v_mfma_f32_16x16x32_bf16 v[122:125], v[168:171], v[192:195], v[122:125]
	v_mfma_f32_16x16x32_bf16 v[118:121], v[160:163], v[200:203], v[118:121]
	v_mfma_f32_16x16x32_bf16 v[114:117], v[168:171], v[200:203], v[114:117]
	v_mfma_f32_16x16x32_bf16 v[110:113], v[160:163], v[208:211], v[110:113]
	v_mfma_f32_16x16x32_bf16 v[106:109], v[168:171], v[208:211], v[106:109]
	v_mfma_f32_16x16x32_bf16 v[102:105], v[160:163], v[216:219], v[102:105]
	v_mfma_f32_16x16x32_bf16 v[98:101], v[168:171], v[216:219], v[98:101]
	v_mfma_f32_16x16x32_bf16 v[94:97], v[172:175], v[188:191], v[94:97]
	v_mfma_f32_16x16x32_bf16 v[90:93], v[180:183], v[188:191], v[90:93]
	v_mfma_f32_16x16x32_bf16 v[86:89], v[172:175], v[196:199], v[86:89]
	v_mfma_f32_16x16x32_bf16 v[82:85], v[180:183], v[196:199], v[82:85]
	v_mfma_f32_16x16x32_bf16 v[78:81], v[172:175], v[204:207], v[78:81]
	v_mfma_f32_16x16x32_bf16 v[74:77], v[180:183], v[204:207], v[74:77]
	v_mfma_f32_16x16x32_bf16 v[70:73], v[172:175], v[212:215], v[70:73]
	v_mfma_f32_16x16x32_bf16 v[66:69], v[180:183], v[212:215], v[66:69]
	v_mfma_f32_16x16x32_bf16 v[94:97], v[176:179], v[192:195], v[94:97]
	v_mfma_f32_16x16x32_bf16 v[90:93], v[184:187], v[192:195], v[90:93]
	v_mfma_f32_16x16x32_bf16 v[86:89], v[176:179], v[200:203], v[86:89]
	v_mfma_f32_16x16x32_bf16 v[82:85], v[184:187], v[200:203], v[82:85]
	v_mfma_f32_16x16x32_bf16 v[78:81], v[176:179], v[208:211], v[78:81]
	v_mfma_f32_16x16x32_bf16 v[74:77], v[184:187], v[208:211], v[74:77]
	v_mfma_f32_16x16x32_bf16 v[70:73], v[176:179], v[216:219], v[70:73]
	v_mfma_f32_16x16x32_bf16 v[66:69], v[184:187], v[216:219], v[66:69]
	s_barrier
; #define PG8_STAGEA(bufoff, gbase) PG8_STAGE_(bufoff, gbase, voffA)
; #define PG8_STAGEB(bufoff, gbase) PG8_STAGE_(bufoff, gbase, voffB)
; #define PG8_LDA(dst, b, h) do { _Pragma("unroll") for (int m = 0; m < 4; ++m) _Pragma("unroll") for (int k = 0; k < 2; ++k) dst[m][k] = *(const LAS bf16x8*)(lds + PG8_SA(b, h) + aoff + m * 2048 + k * 1024); } while (0)
; #define PG8_MMA(ai, bj, At, Bt_) do { __builtin_amdgcn_s_setprio(1); _Pragma("unroll") for (int m = 0; m < 4; ++m) _Pragma("unroll") for (int n = 0; n < 2; ++n) _Pragma("unroll") for (int k = 0; k < 2; ++k) \
;         acc[ai][bj][m][n] = __builtin_amdgcn_mfma_f32_16x16x32_bf16(Bt_[n][k], At[m][k], acc[ai][bj][m][n], 0, 0, 0); __builtin_amdgcn_s_setprio(0); } while (0)
; #define PG8_WAIT_V(n) asm volatile("s_waitcnt vmcnt(" #n ")" ::: "memory")
; #define PG8_WAIT_L(n) asm volatile("s_waitcnt lgkmcnt(" #n ")" ::: "memory")
; #define PG8_BAR __builtin_amdgcn_s_barrier()
; #define PG8_SCHED __builtin_amdgcn_sched_barrier(0)
; template <int EK, int SK = -1>
; __device__ __forceinline__ void gemm_phase(LAS unsigned char* lds, const bf16_t* A, const bf16_t* Bt, int nM, int N, int K, const EpiArgs& E) {
;     ...
;             PG8_LDA(At, 1, 1); PG8_STAGEB(PG8_SB(1, 0), b3); PG8_STAGEB(PG8_SB(1, 1), b3 + hstep); PG8_STAGEA(PG8_SA(1, 0), a3);
;             PG8_WAIT_V(8); PG8_WAIT_L(0); PG8_BAR; PG8_MMA(1, 0, At, B0); PG8_MMA(1, 1, At, B1); PG8_BAR; PG8_SCHED;
;         }
	s_add_i32 s59, s59, s88
	v_lshl_add_u64 v[150:151], v[150:151], 0, s[68:69]
	s_mov_b32 m0, s59
	ds_read_b128 v[188:191], v154 offset:49152
	ds_read_b128 v[192:195], v154 offset:50176
	ds_read_b128 v[196:199], v154 offset:51200
	ds_read_b128 v[200:203], v154 offset:52224
	ds_read_b128 v[204:207], v154 offset:53248
	ds_read_b128 v[208:211], v154 offset:54272
	ds_read_b128 v[212:215], v154 offset:55296
	ds_read_b128 v[216:219], v154 offset:56320
	global_load_lds_dwordx4 v[150:151], off
	s_add_i32 m0, s59, 0x2000
	s_add_u32 s82, s82, 0x40080
	v_lshl_add_u64 v[150:151], v[220:221], 0, s[68:69]
	s_addc_u32 s83, s83, 0
	s_add_i32 s59, s73, s88
	global_load_lds_dwordx4 v[150:151], off
	v_lshl_add_u64 v[150:151], s[82:83], 0, v[132:133]
	s_mov_b32 m0, s59
	s_nop 0
	global_load_lds_dwordx4 v[150:151], off
	v_lshl_add_u64 v[150:151], s[82:83], 0, v[136:137]
	s_add_i32 m0, s59, 0x2000
	s_nop 0
	global_load_lds_dwordx4 v[150:151], off
	v_lshl_add_u64 v[150:151], v[222:223], 0, s[68:69]
	s_mov_b32 m0, s93
	s_nop 0
	global_load_lds_dwordx4 v[150:151], off
	v_lshl_add_u64 v[150:151], v[224:225], 0, s[68:69]
	s_mov_b32 m0, s94
	s_nop 0
	global_load_lds_dwordx4 v[150:151], off
	s_waitcnt vmcnt(8)
	s_waitcnt lgkmcnt(0)
	s_barrier
	s_waitcnt lgkmcnt(0)
	v_mfma_f32_16x16x32_bf16 v[62:65], v[156:159], v[188:191], v[62:65]
	v_mfma_f32_16x16x32_bf16 v[58:61], v[164:167], v[188:191], v[58:61]
	v_mfma_f32_16x16x32_bf16 v[54:57], v[156:159], v[196:199], v[54:57]
	v_mfma_f32_16x16x32_bf16 v[50:53], v[164:167], v[196:199], v[50:53]
	v_mfma_f32_16x16x32_bf16 v[46:49], v[156:159], v[204:207], v[46:49]
	v_mfma_f32_16x16x32_bf16 v[42:45], v[164:167], v[204:207], v[42:45]
	v_mfma_f32_16x16x32_bf16 v[38:41], v[156:159], v[212:215], v[38:41]
	v_mfma_f32_16x16x32_bf16 v[34:37], v[164:167], v[212:215], v[34:37]
	v_mfma_f32_16x16x32_bf16 v[62:65], v[160:163], v[192:195], v[62:65]
	v_mfma_f32_16x16x32_bf16 v[58:61], v[168:171], v[192:195], v[58:61]
	v_mfma_f32_16x16x32_bf16 v[54:57], v[160:163], v[200:203], v[54:57]
	v_mfma_f32_16x16x32_bf16 v[50:53], v[168:171], v[200:203], v[50:53]
	v_mfma_f32_16x16x32_bf16 v[46:49], v[160:163], v[208:211], v[46:49]
	v_mfma_f32_16x16x32_bf16 v[42:45], v[168:171], v[208:211], v[42:45]
	v_mfma_f32_16x16x32_bf16 v[38:41], v[160:163], v[216:219], v[38:41]
	v_mfma_f32_16x16x32_bf16 v[34:37], v[168:171], v[216:219], v[34:37]
	v_mfma_f32_16x16x32_bf16 v[30:33], v[172:175], v[188:191], v[30:33]
	v_mfma_f32_16x16x32_bf16 v[26:29], v[180:183], v[188:191], v[26:29]
	v_mfma_f32_16x16x32_bf16 v[22:25], v[172:175], v[196:199], v[22:25]
	v_mfma_f32_16x16x32_bf16 v[18:21], v[180:183], v[196:199], v[18:21]
	v_mfma_f32_16x16x32_bf16 v[14:17], v[172:175], v[204:207], v[14:17]
	v_mfma_f32_16x16x32_bf16 v[10:13], v[180:183], v[204:207], v[10:13]
	v_mfma_f32_16x16x32_bf16 v[6:9], v[172:175], v[212:215], v[6:9]
	v_mfma_f32_16x16x32_bf16 v[2:5], v[180:183], v[212:215], v[2:5]
	v_mfma_f32_16x16x32_bf16 v[30:33], v[176:179], v[192:195], v[30:33]
	v_mfma_f32_16x16x32_bf16 v[26:29], v[184:187], v[192:195], v[26:29]
	v_mfma_f32_16x16x32_bf16 v[22:25], v[176:179], v[200:203], v[22:25]
	v_mfma_f32_16x16x32_bf16 v[18:21], v[184:187], v[200:203], v[18:21]
	v_mfma_f32_16x16x32_bf16 v[14:17], v[176:179], v[208:211], v[14:17]
	v_mfma_f32_16x16x32_bf16 v[10:13], v[184:187], v[208:211], v[10:13]
	v_mfma_f32_16x16x32_bf16 v[6:9], v[176:179], v[216:219], v[6:9]
	v_mfma_f32_16x16x32_bf16 v[2:5], v[184:187], v[216:219], v[2:5]
	s_barrier
	s_add_i32 s58, s58, 2
	s_add_u32 s80, s80, 0x100
	s_addc_u32 s81, s81, 0
	s_cmp_gt_u32 s58, 13
	s_cbranch_scc0 .LBB0_413
	s_branch .Lmy_kexit_1

; #define PG8_BAR __builtin_amdgcn_s_barrier()
; template <int EK, int SK = -1>
; __device__ __forceinline__ void gemm_phase(LAS unsigned char* lds, const bf16_t* A, const bf16_t* Bt, int nM, int N, int K, const EpiArgs& E) {
;     ...
;         }
;         if (wr == 0) PG8_BAR;
;         if (EK != EK_FINAL) epi_tile<EK>(acc, cur, wr, wc, fr, fq, E, rtab + ui * 256);
.Lmy_kexit_1:
	s_and_b64 vcc, exec, s[70:71]
	s_cbranch_vccz .LBB0_416
	s_barrier

; __device__ __forceinline__ unsigned xb_ld(unsigned* p)              { return __hip_atomic_load(p, __ATOMIC_RELAXED, __HIP_MEMORY_SCOPE_AGENT); }
; __device__ __forceinline__ unsigned xb_add(unsigned* p, unsigned v) { return __hip_atomic_fetch_add(p, v, __ATOMIC_RELAXED, __HIP_MEMORY_SCOPE_AGENT); }
; #define XB_SPIN(cond, bar) do { unsigned _sp = 0; while (cond) { __builtin_amdgcn_s_sleep(1); \
;     if ((++_sp & 255u) == 0u) { if (xb_ld(&(bar)[XB_TMO])) break; if (_sp > XB_SPIN_CAP) { atomicAdd(&(bar)[XB_TMO], 1u); break; } } } } while (0)
; __device__ __forceinline__ void xcd_barrier(const XcdBarrier& b) {
;     asm volatile("s_waitcnt vmcnt(0)" ::: "memory");
;     __syncthreads();
;     if (threadIdx.x == 0) {
;         unsigned* bar = b.bar;
;         __builtin_amdgcn_s_waitcnt(0);
;         unsigned nloc = b.st[0], nx = b.st[1];
;         if (nloc == 0u) { xcd_barrier_complete(bar, b.x, nloc, nx); b.st[0] = nloc; b.st[1] = nx; }
;         const unsigned old = xb_add(&bar[XB_XSUB(b.x)], 1u);
;         const unsigned gen = old / nloc;
;         if (old + 1u == (gen + 1u) * nloc) {
;             __builtin_amdgcn_fence(__ATOMIC_RELEASE, "agent");
;             asm volatile("s_waitcnt vmcnt(0)" ::: "memory");
;             const unsigned og = xb_add(&bar[XB_TOP], 1u);
;             const unsigned tg = og / nx;
;             if (og + 1u == (tg + 1u) * nx) xb_add(&bar[XB_TOPGEN], 1u);
;             else XB_SPIN(xb_ld(&bar[XB_TOPGEN]) == tg, bar);
;             __builtin_amdgcn_fence(__ATOMIC_ACQUIRE, "agent");
;             asm volatile("s_waitcnt vmcnt(0)" ::: "memory");
;         } else {
;             XB_SPIN(xb_ld(&bar[XB_TOPGEN]) == gen, bar);
;             __builtin_amdgcn_fence(__ATOMIC_ACQUIRE, "agent");
;             asm volatile("s_waitcnt vmcnt(0)" ::: "memory");
;         }
;     }
;     __syncthreads();
.Lmy_noinv4:
	s_and_saveexec_b64 s[6:7], vcc
	s_cbranch_execz .LBB0_486
	s_waitcnt vmcnt(0) lgkmcnt(0)
	v_mov_b32_e32 v1, 0x20000
	ds_read2_b32 v[2:3], v1 offset1:1
	s_and_b32 s99, s33, 7
	s_lshl_b32 s99, s99, 8
	s_add_u32 s100, s60, 0xc000
	s_addc_u32 s101, s61, 0
	v_mov_b32_e32 v4, s99
	v_mov_b32_e32 v5, 1
	global_atomic_add v5, v4, v5, s[100:101] sc0
	s_waitcnt lgkmcnt(0)
	v_mul_u32_u24_e32 v6, 3, v2
	v_mul_u32_u24_e32 v7, 3, v3
	s_waitcnt vmcnt(0)
	v_add_u32_e32 v5, 1, v5
	v_cmp_eq_u32_e32 vcc, v5, v6
	s_cbranch_vccz .Lmy_nl3
	buffer_wbl2 sc1
	s_waitcnt vmcnt(0)
	v_mov_b32_e32 v4, 0x800
	v_mov_b32_e32 v5, 1
	global_atomic_add v4, v5, s[100:101]

; #define LAS __attribute__((address_space(3)))
; __device__ __forceinline__ float hsum4(f32x4 v) { return (v[0] + v[1]) + (v[2] + v[3]); }
; #define PG8_STAGEA(bufoff, gbase) PG8_STAGE_(bufoff, gbase, voffA)
; template <int EK, int SK = -1>
; __device__ __forceinline__ void gemm_phase(LAS unsigned char* lds, const bf16_t* A, const bf16_t* Bt, int nM, int N, int K, const EpiArgs& E) {
;     ...
;     f32x4 acc[2][2][4][2];
; #pragma unroll
;     for (int a = 0; a < 2; ++a)
; #pragma unroll
;         for (int b = 0; b < 2; ++b)
; #pragma unroll
;             for (int m = 0; m < 4; ++m)
; #pragma unroll
;                 for (int n = 0; n < 2; ++n) acc[a][b][m][n] = (f32x4){0.f, 0.f, 0.f, 0.f};
;     bf16x8 At[4][2], B0[2][2], B1[2][2];
;     const char* cA = (const char*)A + (size_t)cur.pm * tstep; const char* cB = (const char*)Bt + (size_t)cur.pn * tstep;
;     PG8_STAGEB(PG8_SB(0, 0), cB); PG8_STAGEB(PG8_SB(0, 1), cB + hstep); PG8_STAGEA(PG8_SA(0, 0), cA); PG8_STAGEA(PG8_SA(0, 1), cA + hstep);
;     f32x4 tq[4][4]; bool okq[4];
;     if (EK != EK_RES && EK != EK_FINAL) {
; #pragma unroll
;         for (int j = 0; j < 4; ++j) { Unit uu; okq[j] = S.next((tid >> 8) + 2 * j, uu);
;             if (okq[j]) { const f32x4* sp = (const f32x4*)(E.stIn + (size_t)(uu.pm * BM + (tid & 255)) * 16); tq[j][0] = sp[0]; tq[j][1] = sp[1]; tq[j][2] = sp[2]; tq[j][3] = sp[3]; } }
;     }
;     if (SK >= 0) skinny_phase<(SK >= 0 ? SK : 0)>(lds + 32768, (LAS float*)(lds + SRED_OFF), A, Bt, N, K, E);
;     if (EK != EK_RES && EK != EK_FINAL) {
; #pragma unroll
;         for (int j = 0; j < 4; ++j) if (okq[j]) { const float s_ = (hsum4(tq[j][0]) + hsum4(tq[j][1])) + (hsum4(tq[j][2]) + hsum4(tq[j][3]));
;             rtab[((tid >> 8) + 2 * j) * 256 + (tid & 255)] = rsqrtf(s_ * (1.0f / 1024.0f) + EPS); }
;         __syncthreads();
;     }
;     if (wr == 1) PG8_BAR;
;     PG8_WAIT_V(2); PG8_BAR;
;     PG8_STAGEB(PG8_SB(1, 0), cB + kstep); PG8_STAGEA(PG8_SA(1, 0), cA + kstep); PG8_STAGEB(PG8_SB(1, 1), cB + hstep + kstep);
;     PG8_WAIT_V(6); PG8_BAR;
;     ...
; #pragma unroll
;         for (int a = 0; a < 2; ++a)
; #pragma unroll
;             for (int b = 0; b < 2; ++b)
; #pragma unroll
;                 for (int m = 0; m < 4; ++m)
; #pragma unroll
;                     for (int n = 0; n < 2; ++n) acc[a][b][m][n] = (f32x4){0.f, 0.f, 0.f, 0.f};
;         cur = nxt; cA = nA; cB = nB; ++ui;
.LBB0_529:
	v_lshrrev_b32_e32 v3, 1, v0
	v_and_b32_e32 v2, 15, v0
	v_and_b32_e32 v4, 24, v3
	v_lshlrev_b32_e32 v3, 1, v4
	v_lshlrev_b32_e32 v6, 2, v2
	v_lshl_or_b32 v158, s4, 6, v2
	v_lshl_or_b32 v5, v2, 6, v3
	s_lshl_b32 s5, s4, 13
	v_and_b32_e32 v2, 32, v6
	v_bitop3_b32 v5, v5, s5, v2 bitop3:0xde
	s_lshl_b32 s5, s52, 5
	s_and_b32 s5, s5, 0x60
	v_lshlrev_b32_e32 v2, 6, v0
	s_movk_i32 s6, 0x3c0
	v_and_or_b32 v2, v2, s6, v3
	s_lshl_b32 s6, s5, 7
	v_and_b32_e32 v3, 32, v157
	s_mov_b64 s[10:11], 0x80
	v_bitop3_b32 v159, s6, v2, v3 bitop3:0xf6
	s_add_i32 m0, s15, 0x18000
	v_lshl_add_u64 v[2:3], v[72:73], 0, s[10:11]
	s_waitcnt vmcnt(2)
	s_barrier
	global_load_lds_dwordx4 v[2:3], off
	v_lshl_add_u64 v[2:3], v[70:71], 0, s[10:11]
	s_add_i32 m0, s15, 0x1a000
	s_add_i32 s86, s15, 0x8000
	s_add_i32 s87, s15, 0xa000
	global_load_lds_dwordx4 v[2:3], off
	v_lshl_add_u64 v[2:3], v[68:69], 0, s[10:11]
	s_mov_b32 m0, s86
	s_add_u32 s12, s74, 0x40080
	global_load_lds_dwordx4 v[2:3], off
	v_lshl_add_u64 v[2:3], v[66:67], 0, s[10:11]
	s_mov_b32 m0, s87
	s_addc_u32 s13, s75, 0
	global_load_lds_dwordx4 v[2:3], off
	s_add_i32 m0, s15, 0x1c000
	v_lshl_add_u64 v[2:3], s[12:13], 0, v[132:133]
	global_load_lds_dwordx4 v[2:3], off
	v_lshl_add_u64 v[2:3], s[12:13], 0, v[136:137]
	s_add_i32 m0, s15, 0x1e000
	v_or_b32_e32 v161, s5, v4
	global_load_lds_dwordx4 v[2:3], off
	v_lshlrev_b32_e32 v2, 8, v0
	v_and_b32_e32 v2, 0x18000, v2
	v_lshlrev_b32_e32 v4, 11, v76
	v_or3_b32 v2, v74, v2, v4
	s_mov_b64 s[6:7], 0x40080
	v_add_u32_e32 v2, v2, v75
	v_mov_b32_e32 v3, 0
	s_lshl_b32 s4, s4, 8
	v_lshl_add_u64 v[138:139], v[2:3], 0, s[6:7]
	v_lshlrev_b32_e32 v2, 4, v77
	s_add_i32 s4, s4, 0
	v_and_b32_e32 v2, 0x38000, v2
	s_waitcnt vmcnt(6)
	s_add_i32 s4, s4, 0x20010
	v_or3_b32 v2, v74, v2, v4
	s_cmpk_lt_u32 s53, 0x100
	v_add_u32_e32 v2, v2, v75
	s_mov_b32 s52, 0
	v_add_u32_e32 v160, s4, v6
	s_cselect_b64 s[12:13], -1, 0
	v_lshl_add_u64 v[140:141], v[2:3], 0, s[6:7]
	v_mov_b64_e32 v[142:143], 0x596
	v_mov_b64_e32 v[144:145], 0x595
	s_add_i32 s88, 0, 0x10000
	s_add_i32 s89, 0, 0x14000
	v_add_u32_e32 v162, 0, v5
	s_movk_i32 s90, 0x1600
	v_mov_b32_e32 v2, v3
	s_barrier
	s_branch .LBB0_531
.LBB0_530:
	v_mov_b32_e32 v2, 0
	s_mov_b32 s16, s68
	s_mov_b32 s14, s40
	v_mov_b32_e32 v3, v2
	s_mov_b64 s[38:39], s[72:73]
	s_mov_b32 s52, s53
	s_andn2_b64 vcc, exec, s[4:5]
	s_mov_b64 s[74:75], s[70:71]
	s_cbranch_vccz .LBB0_545

; #define PG8_STAGEA(bufoff, gbase) PG8_STAGE_(bufoff, gbase, voffA)
; #define PG8_STAGEB(bufoff, gbase) PG8_STAGE_(bufoff, gbase, voffB)
; #define PG8_LDA(dst, b, h) do { _Pragma("unroll") for (int m = 0; m < 4; ++m) _Pragma("unroll") for (int k = 0; k < 2; ++k) dst[m][k] = *(const LAS bf16x8*)(lds + PG8_SA(b, h) + aoff + m * 2048 + k * 1024); } while (0)
; #define PG8_LDB(dst, b, h) do { _Pragma("unroll") for (int n = 0; n < 2; ++n) _Pragma("unroll") for (int k = 0; k < 2; ++k) dst[n][k] = *(const LAS bf16x8*)(lds + PG8_SB(b, h) + boff + n * 2048 + k * 1024); } while (0)
; #define PG8_MMA(ai, bj, At, Bt_) do { __builtin_amdgcn_s_setprio(1); _Pragma("unroll") for (int m = 0; m < 4; ++m) _Pragma("unroll") for (int n = 0; n < 2; ++n) _Pragma("unroll") for (int k = 0; k < 2; ++k) \
;         acc[ai][bj][m][n] = __builtin_amdgcn_mfma_f32_16x16x32_bf16(Bt_[n][k], At[m][k], acc[ai][bj][m][n], 0, 0, 0); __builtin_amdgcn_s_setprio(0); } while (0)
; #define PG8_WAIT_V(n) asm volatile("s_waitcnt vmcnt(" #n ")" ::: "memory")
; #define PG8_WAIT_L(n) asm volatile("s_waitcnt lgkmcnt(" #n ")" ::: "memory")
; template <int EK, int SK = -1>
; __device__ __forceinline__ void gemm_phase(LAS unsigned char* lds, const bf16_t* A, const bf16_t* Bt, int nM, int N, int K, const EpiArgs& E) {
;     ...
;     for (;;) {
;         const bool has_next = S.next(ui + 1, nxt);
;         const char* nA = has_next ? (const char*)A + (size_t)nxt.pm * tstep : cA; const char* nB = has_next ? (const char*)Bt + (size_t)nxt.pn * tstep : cB;
;         for (int t = 0; t < nt; t += 2) {
;             const bool last = (t == nt - 2);
;             const char* a1 = cA + (size_t)(t + 1) * kstep;
;             const char* a2 = last ? nA : cA + (size_t)(t + 2) * kstep; const char* b2 = last ? nB : cB + (size_t)(t + 2) * kstep;
;             const char* a3 = a2 + kstep; const char* b3 = b2 + kstep;
;             PG8_LDB(B0, 0, 0); PG8_LDB(B1, 0, 1); PG8_SCHED; PG8_LDA(At, 0, 0); PG8_STAGEA(PG8_SA(1, 1), a1 + hstep);
;             PG8_WAIT_V(8); PG8_WAIT_L(0); PG8_BAR; PG8_MMA(0, 0, At, B0); PG8_MMA(0, 1, At, B1); PG8_BAR; PG8_SCHED;
;             PG8_LDA(At, 0, 1); PG8_STAGEB(PG8_SB(0, 0), b2); PG8_STAGEB(PG8_SB(0, 1), b2 + hstep); PG8_STAGEA(PG8_SA(0, 0), a2);
;             PG8_WAIT_V(8); PG8_WAIT_L(0); PG8_BAR; PG8_MMA(1, 0, At, B0); PG8_MMA(1, 1, At, B1); PG8_BAR; PG8_SCHED;
.LBB0_537:
	s_add_u32 s54, s74, 0x100
	s_addc_u32 s55, s75, 0
	s_ashr_i32 s69, s68, 31
	s_lshl_b64 s[56:57], s[68:69], 19
	s_add_u32 s72, s62, s56
	s_addc_u32 s73, s63, s57
	s_and_b64 s[56:57], s[6:7], exec
	s_cselect_b32 s56, s73, s39
	s_cselect_b32 s57, s72, s38
	s_ashr_i32 s41, s40, 31
	s_lshl_b64 s[58:59], s[40:41], 19
	s_add_u32 s70, s81, s58
	s_addc_u32 s71, s82, s59
	s_and_b64 s[58:59], s[6:7], exec
	s_cselect_b32 s41, s71, s75
	s_cselect_b32 s58, s70, s74
	v_lshl_add_u64 v[146:147], s[38:39], 0, v[138:139]
	v_lshl_add_u64 v[148:149], s[38:39], 0, v[140:141]
	s_mov_b32 s59, -2
	s_mov_b64 s[74:75], 0
	v_add_u32_e32 v154, s88, v159
	ds_read_b128 v[150:153], v154
	ds_read_b128 v[164:167], v154 offset:1024
	ds_read_b128 v[168:171], v154 offset:2048
	ds_read_b128 v[172:175], v154 offset:3072
	v_add_u32_e32 v154, s89, v159
	s_add_u32 s69, s38, s74
	ds_read_b128 v[176:179], v154
	ds_read_b128 v[180:183], v154 offset:1024
	ds_read_b128 v[184:187], v154 offset:2048
	ds_read_b128 v[188:191], v154 offset:3072
	s_addc_u32 s76, s39, s75
	s_add_u32 s69, s69, 0x100
	s_addc_u32 s76, s76, 0
	s_add_u32 s91, s54, s74
	s_addc_u32 s77, s55, s75
	s_cmpk_eq_i32 s74, 0x700
	s_cselect_b32 s79, s56, s76
	s_cselect_b32 s78, s57, s69
	s_cselect_b32 s77, s41, s77
	s_cselect_b32 s76, s58, s91
	v_lshl_add_u64 v[154:155], v[146:147], 0, s[74:75]
	s_add_i32 m0, s15, 0xc000
	ds_read_b128 v[192:195], v162
	ds_read_b128 v[196:199], v162 offset:1024
	ds_read_b128 v[200:203], v162 offset:2048
	ds_read_b128 v[204:207], v162 offset:3072
	ds_read_b128 v[208:211], v162 offset:4096
	ds_read_b128 v[212:215], v162 offset:5120
	ds_read_b128 v[216:219], v162 offset:6144
	ds_read_b128 v[220:223], v162 offset:7168
	global_load_lds_dwordx4 v[154:155], off
	v_lshl_add_u64 v[154:155], v[148:149], 0, s[74:75]
	s_add_i32 m0, s15, 0xe000
	s_nop 0
	global_load_lds_dwordx4 v[154:155], off
	s_waitcnt vmcnt(8)
	s_waitcnt lgkmcnt(0)
	s_barrier
	s_waitcnt lgkmcnt(0)
	v_mfma_f32_16x16x32_bf16 v[110:113], v[150:153], v[192:195], 0
	v_mfma_f32_16x16x32_bf16 v[106:109], v[168:171], v[192:195], 0
	v_mfma_f32_16x16x32_bf16 v[102:105], v[150:153], v[200:203], 0
	v_mfma_f32_16x16x32_bf16 v[98:101], v[168:171], v[200:203], 0
	v_mfma_f32_16x16x32_bf16 v[94:97], v[150:153], v[208:211], 0
	v_mfma_f32_16x16x32_bf16 v[90:93], v[168:171], v[208:211], 0
	v_mfma_f32_16x16x32_bf16 v[86:89], v[150:153], v[216:219], 0
	v_mfma_f32_16x16x32_bf16 v[82:85], v[168:171], v[216:219], 0
	v_mfma_f32_16x16x32_bf16 v[110:113], v[164:167], v[196:199], v[110:113]
	v_mfma_f32_16x16x32_bf16 v[106:109], v[172:175], v[196:199], v[106:109]
	v_mfma_f32_16x16x32_bf16 v[102:105], v[164:167], v[204:207], v[102:105]
	v_mfma_f32_16x16x32_bf16 v[98:101], v[172:175], v[204:207], v[98:101]
	v_mfma_f32_16x16x32_bf16 v[94:97], v[164:167], v[212:215], v[94:97]
	v_mfma_f32_16x16x32_bf16 v[90:93], v[172:175], v[212:215], v[90:93]
	v_mfma_f32_16x16x32_bf16 v[86:89], v[164:167], v[220:223], v[86:89]
	v_mfma_f32_16x16x32_bf16 v[82:85], v[172:175], v[220:223], v[82:85]
	v_mfma_f32_16x16x32_bf16 v[78:81], v[176:179], v[192:195], 0
	v_mfma_f32_16x16x32_bf16 v[74:77], v[184:187], v[192:195], 0
	v_mfma_f32_16x16x32_bf16 v[70:73], v[176:179], v[200:203], 0
	v_mfma_f32_16x16x32_bf16 v[66:69], v[184:187], v[200:203], 0
	v_mfma_f32_16x16x32_bf16 v[62:65], v[176:179], v[208:211], 0
	v_mfma_f32_16x16x32_bf16 v[58:61], v[184:187], v[208:211], 0
	v_mfma_f32_16x16x32_bf16 v[54:57], v[176:179], v[216:219], 0
	v_mfma_f32_16x16x32_bf16 v[50:53], v[184:187], v[216:219], 0
	v_mfma_f32_16x16x32_bf16 v[78:81], v[180:183], v[196:199], v[78:81]
	v_mfma_f32_16x16x32_bf16 v[74:77], v[188:191], v[196:199], v[74:77]
	v_mfma_f32_16x16x32_bf16 v[70:73], v[180:183], v[204:207], v[70:73]
	v_mfma_f32_16x16x32_bf16 v[66:69], v[188:191], v[204:207], v[66:69]
	v_mfma_f32_16x16x32_bf16 v[62:65], v[180:183], v[212:215], v[62:65]
	v_mfma_f32_16x16x32_bf16 v[58:61], v[188:191], v[212:215], v[58:61]
	v_mfma_f32_16x16x32_bf16 v[54:57], v[180:183], v[220:223], v[54:57]
	v_mfma_f32_16x16x32_bf16 v[50:53], v[188:191], v[220:223], v[50:53]
	s_barrier
	s_add_i32 s69, s88, s83
	v_lshl_add_u64 v[154:155], s[76:77], 0, v[132:133]
	s_mov_b32 m0, s69
	ds_read_b128 v[192:195], v162 offset:16384
	ds_read_b128 v[196:199], v162 offset:17408
	ds_read_b128 v[200:203], v162 offset:18432
	ds_read_b128 v[204:207], v162 offset:19456
	ds_read_b128 v[208:211], v162 offset:20480
	ds_read_b128 v[212:215], v162 offset:21504
	ds_read_b128 v[216:219], v162 offset:22528
	ds_read_b128 v[220:223], v162 offset:23552
	global_load_lds_dwordx4 v[154:155], off
	s_add_i32 m0, s69, 0x2000
	s_add_u32 s92, s76, 0x40000
	v_lshl_add_u64 v[224:225], s[76:77], 0, v[136:137]
	s_addc_u32 s93, s77, 0
	s_add_i32 s69, s89, s83
	global_load_lds_dwordx4 v[224:225], off
	v_lshl_add_u64 v[226:227], s[92:93], 0, v[132:133]
	s_mov_b32 m0, s69
	v_lshl_add_u64 v[228:229], s[78:79], 0, v[134:135]
	global_load_lds_dwordx4 v[226:227], off
	v_lshl_add_u64 v[226:227], s[92:93], 0, v[136:137]
	s_add_i32 m0, s69, 0x2000
	s_nop 0
	global_load_lds_dwordx4 v[226:227], off
	v_lshl_add_u64 v[226:227], s[78:79], 0, v[130:131]
	s_mov_b32 m0, s15
	s_nop 0
	global_load_lds_dwordx4 v[226:227], off
	s_mov_b32 m0, s17
	s_nop 0
	global_load_lds_dwordx4 v[228:229], off
	s_waitcnt vmcnt(8)
	s_waitcnt lgkmcnt(0)
	s_barrier
; #define PG8_STAGEA(bufoff, gbase) PG8_STAGE_(bufoff, gbase, voffA)
; #define PG8_LDA(dst, b, h) do { _Pragma("unroll") for (int m = 0; m < 4; ++m) _Pragma("unroll") for (int k = 0; k < 2; ++k) dst[m][k] = *(const LAS bf16x8*)(lds + PG8_SA(b, h) + aoff + m * 2048 + k * 1024); } while (0)
; #define PG8_LDB(dst, b, h) do { _Pragma("unroll") for (int n = 0; n < 2; ++n) _Pragma("unroll") for (int k = 0; k < 2; ++k) dst[n][k] = *(const LAS bf16x8*)(lds + PG8_SB(b, h) + boff + n * 2048 + k * 1024); } while (0)
; #define PG8_MMA(ai, bj, At, Bt_) do { __builtin_amdgcn_s_setprio(1); _Pragma("unroll") for (int m = 0; m < 4; ++m) _Pragma("unroll") for (int n = 0; n < 2; ++n) _Pragma("unroll") for (int k = 0; k < 2; ++k) \
;         acc[ai][bj][m][n] = __builtin_amdgcn_mfma_f32_16x16x32_bf16(Bt_[n][k], At[m][k], acc[ai][bj][m][n], 0, 0, 0); __builtin_amdgcn_s_setprio(0); } while (0)
; #define PG8_WAIT_V(n) asm volatile("s_waitcnt vmcnt(" #n ")" ::: "memory")
; #define PG8_WAIT_L(n) asm volatile("s_waitcnt lgkmcnt(" #n ")" ::: "memory")
; #define PG8_BAR __builtin_amdgcn_s_barrier()
; #define PG8_SCHED __builtin_amdgcn_sched_barrier(0)
; template <int EK, int SK = -1>
; __device__ __forceinline__ void gemm_phase(LAS unsigned char* lds, const bf16_t* A, const bf16_t* Bt, int nM, int N, int K, const EpiArgs& E) {
;     ...
;             PG8_WAIT_V(8); PG8_WAIT_L(0); PG8_BAR; PG8_MMA(1, 0, At, B0); PG8_MMA(1, 1, At, B1); PG8_BAR; PG8_SCHED;
;             PG8_LDB(B0, 1, 0); PG8_LDB(B1, 1, 1); PG8_SCHED; PG8_LDA(At, 1, 0); PG8_STAGEA(PG8_SA(0, 1), a2 + hstep);
;             PG8_WAIT_V(8); PG8_WAIT_L(0); PG8_BAR; PG8_MMA(0, 0, At, B0); PG8_MMA(0, 1, At, B1); PG8_BAR; PG8_SCHED;
	s_waitcnt lgkmcnt(0)
	v_mfma_f32_16x16x32_bf16 v[46:49], v[150:153], v[192:195], 0
	v_mfma_f32_16x16x32_bf16 v[42:45], v[168:171], v[192:195], 0
	v_mfma_f32_16x16x32_bf16 v[38:41], v[150:153], v[200:203], 0
	v_mfma_f32_16x16x32_bf16 v[34:37], v[168:171], v[200:203], 0
	v_mfma_f32_16x16x32_bf16 v[30:33], v[150:153], v[208:211], 0
	v_mfma_f32_16x16x32_bf16 v[26:29], v[168:171], v[208:211], 0
	v_mfma_f32_16x16x32_bf16 v[22:25], v[150:153], v[216:219], 0
	v_mfma_f32_16x16x32_bf16 v[18:21], v[168:171], v[216:219], 0
	v_mfma_f32_16x16x32_bf16 v[46:49], v[164:167], v[196:199], v[46:49]
	v_mfma_f32_16x16x32_bf16 v[42:45], v[172:175], v[196:199], v[42:45]
	v_mfma_f32_16x16x32_bf16 v[38:41], v[164:167], v[204:207], v[38:41]
	v_mfma_f32_16x16x32_bf16 v[34:37], v[172:175], v[204:207], v[34:37]
	v_mfma_f32_16x16x32_bf16 v[30:33], v[164:167], v[212:215], v[30:33]
	v_mfma_f32_16x16x32_bf16 v[26:29], v[172:175], v[212:215], v[26:29]
	v_mfma_f32_16x16x32_bf16 v[22:25], v[164:167], v[220:223], v[22:25]
	v_mfma_f32_16x16x32_bf16 v[18:21], v[172:175], v[220:223], v[18:21]
	v_mfma_f32_16x16x32_bf16 v[14:17], v[176:179], v[192:195], 0
	v_mfma_f32_16x16x32_bf16 v[10:13], v[184:187], v[192:195], 0
	v_mfma_f32_16x16x32_bf16 v[6:9], v[176:179], v[200:203], 0
	v_mfma_f32_16x16x32_bf16 v[2:5], v[184:187], v[200:203], 0
	v_mfma_f32_16x16x32_bf16 v[114:117], v[176:179], v[208:211], 0
	v_mfma_f32_16x16x32_bf16 v[118:121], v[184:187], v[208:211], 0
	v_mfma_f32_16x16x32_bf16 v[122:125], v[176:179], v[216:219], 0
	v_mfma_f32_16x16x32_bf16 v[126:129], v[184:187], v[216:219], 0
	v_mfma_f32_16x16x32_bf16 v[14:17], v[180:183], v[196:199], v[14:17]
	v_mfma_f32_16x16x32_bf16 v[10:13], v[188:191], v[196:199], v[10:13]
	v_mfma_f32_16x16x32_bf16 v[6:9], v[180:183], v[204:207], v[6:9]
	v_mfma_f32_16x16x32_bf16 v[2:5], v[188:191], v[204:207], v[2:5]
	v_mfma_f32_16x16x32_bf16 v[114:117], v[180:183], v[212:215], v[114:117]
	v_mfma_f32_16x16x32_bf16 v[118:121], v[188:191], v[212:215], v[118:121]
	v_mfma_f32_16x16x32_bf16 v[122:125], v[180:183], v[220:223], v[122:125]
	v_mfma_f32_16x16x32_bf16 v[126:129], v[188:191], v[220:223], v[126:129]
	s_barrier
	s_add_i32 s69, 0, 0x18000
	v_add_u32_e32 v163, s69, v159
	s_add_i32 s91, 0, 0x1c000
	ds_read_b128 v[150:153], v163
	ds_read_b128 v[164:167], v163 offset:1024
	ds_read_b128 v[168:171], v163 offset:2048
	ds_read_b128 v[172:175], v163 offset:3072
	v_add_u32_e32 v163, s91, v159
	ds_read_b128 v[176:179], v163
	ds_read_b128 v[180:183], v163 offset:1024
	ds_read_b128 v[184:187], v163 offset:2048
	ds_read_b128 v[188:191], v163 offset:3072
	s_add_u32 s78, s78, 0x40000
	s_addc_u32 s79, s79, 0
	s_mov_b32 m0, s84
	v_lshl_add_u64 v[230:231], s[78:79], 0, v[130:131]
	ds_read_b128 v[192:195], v162 offset:32768
	ds_read_b128 v[196:199], v162 offset:33792
	ds_read_b128 v[200:203], v162 offset:34816
	ds_read_b128 v[204:207], v162 offset:35840
	ds_read_b128 v[208:211], v162 offset:36864
	ds_read_b128 v[212:215], v162 offset:37888
	ds_read_b128 v[216:219], v162 offset:38912
	ds_read_b128 v[220:223], v162 offset:39936
	global_load_lds_dwordx4 v[230:231], off
	v_lshl_add_u64 v[230:231], s[78:79], 0, v[134:135]
	s_mov_b32 m0, s85
	s_nop 0
	global_load_lds_dwordx4 v[230:231], off
	s_waitcnt vmcnt(8)
	s_waitcnt lgkmcnt(0)
	s_barrier
	s_waitcnt lgkmcnt(0)
	v_mfma_f32_16x16x32_bf16 v[110:113], v[150:153], v[192:195], v[110:113]
	v_mfma_f32_16x16x32_bf16 v[106:109], v[168:171], v[192:195], v[106:109]
	v_mfma_f32_16x16x32_bf16 v[102:105], v[150:153], v[200:203], v[102:105]
	v_mfma_f32_16x16x32_bf16 v[98:101], v[168:171], v[200:203], v[98:101]
	v_mfma_f32_16x16x32_bf16 v[94:97], v[150:153], v[208:211], v[94:97]
	v_mfma_f32_16x16x32_bf16 v[90:93], v[168:171], v[208:211], v[90:93]
	v_mfma_f32_16x16x32_bf16 v[86:89], v[150:153], v[216:219], v[86:89]
	v_mfma_f32_16x16x32_bf16 v[82:85], v[168:171], v[216:219], v[82:85]
	v_mfma_f32_16x16x32_bf16 v[110:113], v[164:167], v[196:199], v[110:113]
	v_mfma_f32_16x16x32_bf16 v[106:109], v[172:175], v[196:199], v[106:109]
	v_mfma_f32_16x16x32_bf16 v[102:105], v[164:167], v[204:207], v[102:105]
	v_mfma_f32_16x16x32_bf16 v[98:101], v[172:175], v[204:207], v[98:101]
	v_mfma_f32_16x16x32_bf16 v[94:97], v[164:167], v[212:215], v[94:97]
	v_mfma_f32_16x16x32_bf16 v[90:93], v[172:175], v[212:215], v[90:93]
	v_mfma_f32_16x16x32_bf16 v[86:89], v[164:167], v[220:223], v[86:89]
	v_mfma_f32_16x16x32_bf16 v[82:85], v[172:175], v[220:223], v[82:85]
	v_mfma_f32_16x16x32_bf16 v[78:81], v[176:179], v[192:195], v[78:81]
	v_mfma_f32_16x16x32_bf16 v[74:77], v[184:187], v[192:195], v[74:77]
	v_mfma_f32_16x16x32_bf16 v[70:73], v[176:179], v[200:203], v[70:73]
	v_mfma_f32_16x16x32_bf16 v[66:69], v[184:187], v[200:203], v[66:69]
	v_mfma_f32_16x16x32_bf16 v[62:65], v[176:179], v[208:211], v[62:65]
	v_mfma_f32_16x16x32_bf16 v[58:61], v[184:187], v[208:211], v[58:61]
	v_mfma_f32_16x16x32_bf16 v[54:57], v[176:179], v[216:219], v[54:57]
	v_mfma_f32_16x16x32_bf16 v[50:53], v[184:187], v[216:219], v[50:53]
	v_mfma_f32_16x16x32_bf16 v[78:81], v[180:183], v[196:199], v[78:81]
	v_mfma_f32_16x16x32_bf16 v[74:77], v[188:191], v[196:199], v[74:77]
	v_mfma_f32_16x16x32_bf16 v[70:73], v[180:183], v[204:207], v[70:73]
	v_mfma_f32_16x16x32_bf16 v[66:69], v[188:191], v[204:207], v[66:69]
	v_mfma_f32_16x16x32_bf16 v[62:65], v[180:183], v[212:215], v[62:65]
	v_mfma_f32_16x16x32_bf16 v[58:61], v[188:191], v[212:215], v[58:61]
	v_mfma_f32_16x16x32_bf16 v[54:57], v[180:183], v[220:223], v[54:57]
	v_mfma_f32_16x16x32_bf16 v[50:53], v[188:191], v[220:223], v[50:53]
	s_barrier
; #define PG8_STAGEA(bufoff, gbase) PG8_STAGE_(bufoff, gbase, voffA)
; #define PG8_STAGEB(bufoff, gbase) PG8_STAGE_(bufoff, gbase, voffB)
; #define PG8_LDA(dst, b, h) do { _Pragma("unroll") for (int m = 0; m < 4; ++m) _Pragma("unroll") for (int k = 0; k < 2; ++k) dst[m][k] = *(const LAS bf16x8*)(lds + PG8_SA(b, h) + aoff + m * 2048 + k * 1024); } while (0)
; #define PG8_MMA(ai, bj, At, Bt_) do { __builtin_amdgcn_s_setprio(1); _Pragma("unroll") for (int m = 0; m < 4; ++m) _Pragma("unroll") for (int n = 0; n < 2; ++n) _Pragma("unroll") for (int k = 0; k < 2; ++k) \
;         acc[ai][bj][m][n] = __builtin_amdgcn_mfma_f32_16x16x32_bf16(Bt_[n][k], At[m][k], acc[ai][bj][m][n], 0, 0, 0); __builtin_amdgcn_s_setprio(0); } while (0)
; #define PG8_WAIT_V(n) asm volatile("s_waitcnt vmcnt(" #n ")" ::: "memory")
; #define PG8_WAIT_L(n) asm volatile("s_waitcnt lgkmcnt(" #n ")" ::: "memory")
; #define PG8_BAR __builtin_amdgcn_s_barrier()
; #define PG8_SCHED __builtin_amdgcn_sched_barrier(0)
; template <int EK, int SK = -1>
; __device__ __forceinline__ void gemm_phase(LAS unsigned char* lds, const bf16_t* A, const bf16_t* Bt, int nM, int N, int K, const EpiArgs& E) {
;     ...
;             PG8_LDA(At, 1, 1); PG8_STAGEB(PG8_SB(1, 0), b3); PG8_STAGEB(PG8_SB(1, 1), b3 + hstep); PG8_STAGEA(PG8_SA(1, 0), a3);
;             PG8_WAIT_V(8); PG8_WAIT_L(0); PG8_BAR; PG8_MMA(1, 0, At, B0); PG8_MMA(1, 1, At, B1); PG8_BAR; PG8_SCHED;
;         }
	s_add_i32 s69, s69, s83
	v_lshl_add_u64 v[154:155], v[154:155], 0, s[10:11]
	s_mov_b32 m0, s69
	ds_read_b128 v[192:195], v162 offset:49152
	ds_read_b128 v[196:199], v162 offset:50176
	ds_read_b128 v[200:203], v162 offset:51200
	ds_read_b128 v[204:207], v162 offset:52224
	ds_read_b128 v[208:211], v162 offset:53248
	ds_read_b128 v[212:215], v162 offset:54272
	ds_read_b128 v[216:219], v162 offset:55296
	ds_read_b128 v[220:223], v162 offset:56320
	global_load_lds_dwordx4 v[154:155], off
	s_add_i32 m0, s69, 0x2000
	s_add_u32 s76, s76, 0x40080
	v_lshl_add_u64 v[154:155], v[224:225], 0, s[10:11]
	s_addc_u32 s77, s77, 0
	s_add_i32 s69, s91, s83
	global_load_lds_dwordx4 v[154:155], off
	v_lshl_add_u64 v[154:155], s[76:77], 0, v[132:133]
	s_mov_b32 m0, s69
	s_nop 0
	global_load_lds_dwordx4 v[154:155], off
	v_lshl_add_u64 v[154:155], s[76:77], 0, v[136:137]
	s_add_i32 m0, s69, 0x2000
	s_nop 0
	global_load_lds_dwordx4 v[154:155], off
	v_lshl_add_u64 v[154:155], v[226:227], 0, s[10:11]
	s_mov_b32 m0, s86
	s_nop 0
	global_load_lds_dwordx4 v[154:155], off
	v_lshl_add_u64 v[154:155], v[228:229], 0, s[10:11]
	s_mov_b32 m0, s87
	s_nop 0
	global_load_lds_dwordx4 v[154:155], off
	s_waitcnt vmcnt(8)
	s_waitcnt lgkmcnt(0)
	s_barrier
	s_waitcnt lgkmcnt(0)
	v_mfma_f32_16x16x32_bf16 v[46:49], v[150:153], v[192:195], v[46:49]
	v_mfma_f32_16x16x32_bf16 v[42:45], v[168:171], v[192:195], v[42:45]
	v_mfma_f32_16x16x32_bf16 v[38:41], v[150:153], v[200:203], v[38:41]
	v_mfma_f32_16x16x32_bf16 v[34:37], v[168:171], v[200:203], v[34:37]
	v_mfma_f32_16x16x32_bf16 v[30:33], v[150:153], v[208:211], v[30:33]
	v_mfma_f32_16x16x32_bf16 v[26:29], v[168:171], v[208:211], v[26:29]
	v_mfma_f32_16x16x32_bf16 v[22:25], v[150:153], v[216:219], v[22:25]
	v_mfma_f32_16x16x32_bf16 v[18:21], v[168:171], v[216:219], v[18:21]
	v_mfma_f32_16x16x32_bf16 v[46:49], v[164:167], v[196:199], v[46:49]
	v_mfma_f32_16x16x32_bf16 v[42:45], v[172:175], v[196:199], v[42:45]
	v_mfma_f32_16x16x32_bf16 v[38:41], v[164:167], v[204:207], v[38:41]
	v_mfma_f32_16x16x32_bf16 v[34:37], v[172:175], v[204:207], v[34:37]
	v_mfma_f32_16x16x32_bf16 v[30:33], v[164:167], v[212:215], v[30:33]
	v_mfma_f32_16x16x32_bf16 v[26:29], v[172:175], v[212:215], v[26:29]
	v_mfma_f32_16x16x32_bf16 v[22:25], v[164:167], v[220:223], v[22:25]
	v_mfma_f32_16x16x32_bf16 v[18:21], v[172:175], v[220:223], v[18:21]
	v_mfma_f32_16x16x32_bf16 v[14:17], v[176:179], v[192:195], v[14:17]
	v_mfma_f32_16x16x32_bf16 v[10:13], v[184:187], v[192:195], v[10:13]
	v_mfma_f32_16x16x32_bf16 v[6:9], v[176:179], v[200:203], v[6:9]
	v_mfma_f32_16x16x32_bf16 v[2:5], v[184:187], v[200:203], v[2:5]
	v_mfma_f32_16x16x32_bf16 v[114:117], v[176:179], v[208:211], v[114:117]
	v_mfma_f32_16x16x32_bf16 v[118:121], v[184:187], v[208:211], v[118:121]
	v_mfma_f32_16x16x32_bf16 v[122:125], v[176:179], v[216:219], v[122:125]
	v_mfma_f32_16x16x32_bf16 v[126:129], v[184:187], v[216:219], v[126:129]
	v_mfma_f32_16x16x32_bf16 v[14:17], v[180:183], v[196:199], v[14:17]
	v_mfma_f32_16x16x32_bf16 v[10:13], v[188:191], v[196:199], v[10:13]
	v_mfma_f32_16x16x32_bf16 v[6:9], v[180:183], v[204:207], v[6:9]
	v_mfma_f32_16x16x32_bf16 v[2:5], v[188:191], v[204:207], v[2:5]
	v_mfma_f32_16x16x32_bf16 v[114:117], v[180:183], v[212:215], v[114:117]
	v_mfma_f32_16x16x32_bf16 v[118:121], v[188:191], v[212:215], v[118:121]
	v_mfma_f32_16x16x32_bf16 v[122:125], v[180:183], v[220:223], v[122:125]
	v_mfma_f32_16x16x32_bf16 v[126:129], v[188:191], v[220:223], v[126:129]
	s_barrier
	s_add_i32 s59, s59, 2
	s_add_u32 s74, s74, 0x100
	s_addc_u32 s75, s75, 0
	s_cmp_gt_u32 s59, 13
	s_cbranch_scc0 .LBB0_538
	s_branch .Lmy_kexit_2

; __device__ __forceinline__ float silu1(float g) { return g * __builtin_amdgcn_rcpf(1.0f + __expf(-g)); }
; __device__ __forceinline__ f32x4 swiglu4(f32x4 g, f32x4 u) { return (f32x4){silu1(g[0]) * u[0], silu1(g[1]) * u[1], silu1(g[2]) * u[2], silu1(g[3]) * u[3]}; }
; template <int EK>
; __device__ __forceinline__ void epi_tile(const f32x4 (&acc)[2][2][4][2], const Unit& u, int wr, int wc, int fr, int fq, const EpiArgs& E, const LAS float* rt) {
;     const int rowb = u.pm * BM + wr * 64 + fr;
;     float rr[2][4];
;     if (EK != EK_RES) {
; #pragma unroll
;         for (int ai = 0; ai < 2; ++ai)
; #pragma unroll
;             for (int m = 0; m < 4; ++m) rr[ai][m] = rt[ai * HALF + wr * 64 + m * 16 + fr];
;     }
; #pragma unroll
;     for (int ai = 0; ai < 2; ++ai) {
; #pragma unroll
;         for (int m = 0; m < 4; ++m) {
;             const int row = rowb + ai * HALF + m * 16;
;             if (EK == EK_SCALE) {
;                 const float r = rr[ai][m];
; #pragma unroll
;                 for (int bj = 0; bj < 2; ++bj) { const int col = u.pn * BM + bj * HALF + wc * 32 + fq * 8;
;                     const u32x2 lo = pack4(acc[ai][bj][m][0] * r), hi = pack4(acc[ai][bj][m][1] * r);
;                     *(u32x4*)(E.ob + (size_t)row * E.ldb + col) = (u32x4){lo.x, lo.y, hi.x, hi.y}; }
;             } else if (EK == EK_GELU) {
;                 const float r = rr[ai][m]; float ss = 0.f;
; #pragma unroll
;                 for (int bj = 0; bj < 2; ++bj) { const int col = u.pn * BM + bj * HALF + wc * 32 + fq * 8;
;                     const f32x4 z0 = gelu4(acc[ai][bj][m][0] * r), z1 = gelu4(acc[ai][bj][m][1] * r); ss += dot4(z0) + dot4(z1);
;                     const u32x2 lo = pack4(z0), hi = pack4(z1);
;                     *(u32x4*)(E.ob + (size_t)row * E.ldb + col) = (u32x4){lo.x, lo.y, hi.x, hi.y}; }
;                 if (u.pn >= 4) { ss = quad_sum(ss); if (fq == 0) E.stOut[(size_t)row * 16 + (u.pn - 4) * 4 + wc] = ss; }
;             } else if (EK == EK_SWIGLU) {
;                 const float r = rr[ai][m];
;                 { const int col = u.pn * HALF + wc * 32 + fq * 8;
;                     const u32x2 lo = pack4(swiglu4(acc[ai][0][m][0] * r, acc[ai][1][m][0] * r)), hi = pack4(swiglu4(acc[ai][0][m][1] * r, acc[ai][1][m][1] * r));
;                     *(u32x4*)(E.ob + (size_t)row * DFF + col) = (u32x4){lo.x, lo.y, hi.x, hi.y}; }
.LBB0_541:
	v_lshl_add_u32 v146, s52, 10, v160
	ds_read2_b32 v[168:169], v146 offset1:16
	ds_read2_b32 v[154:155], v146 offset0:32 offset1:48
	ds_read2_b32 v[152:153], v146 offset0:128 offset1:144
	ds_read2_b32 v[146:147], v146 offset0:160 offset1:176
	v_lshl_or_b32 v150, s14, 7, v161
	s_waitcnt lgkmcnt(0)
	v_mul_f32_e32 v180, 0xbfb8aa3b, v168
	v_mul_f32_e32 v181, v168, v168
	v_mul_f32_e32 v182, 0xbfb8aa3b, v169
	v_mul_f32_e32 v183, v169, v169
	v_mul_f32_e32 v184, 0xbfb8aa3b, v154
	v_mul_f32_e32 v185, v154, v154
	v_mul_f32_e32 v186, 0xbfb8aa3b, v155
	v_mul_f32_e32 v187, v155, v155
	v_mul_f32_e32 v188, 0xbfb8aa3b, v152
	v_mul_f32_e32 v189, v152, v152
	v_mul_f32_e32 v190, 0xbfb8aa3b, v153
	v_mul_f32_e32 v191, v153, v153
	v_mul_f32_e32 v192, 0xbfb8aa3b, v146
	v_mul_f32_e32 v193, v146, v146
	v_mul_f32_e32 v194, 0xbfb8aa3b, v147
	v_mul_f32_e32 v195, v147, v147
	s_add_u32 s74, s54, 0xffffff00
	v_lshl_add_u32 v163, s16, 8, v158
	v_ashrrev_i32_e32 v151, 31, v150
	s_addc_u32 s75, s55, -1
	v_mov_b64_e32 v[148:149], s[64:65]
	v_mad_i64_i32 v[170:171], s[54:55], v163, s90, v[148:149]
	v_lshlrev_b64 v[150:151], 1, v[150:151]
	v_lshl_add_u64 v[170:171], v[170:171], 0, v[150:151]
	v_pk_mul_f32 v[196:197], v[110:111], v[180:181] op_sel_hi:[1,0]
	v_pk_mul_f32 v[198:199], v[112:113], v[180:181] op_sel_hi:[1,0]
	v_pk_mul_f32 v[200:201], v[110:111], v[78:79]
	v_exp_f32_e32 v196, v196
	v_exp_f32_e32 v197, v197
	v_exp_f32_e32 v198, v198
	v_exp_f32_e32 v199, v199
	v_pk_mul_f32 v[202:203], v[112:113], v[80:81]
	v_pk_add_f32 v[196:197], v[196:197], 1.0 op_sel_hi:[1,0]
	v_pk_add_f32 v[198:199], v[198:199], 1.0 op_sel_hi:[1,0]
	v_pk_mul_f32 v[200:201], v[200:201], v[180:181] op_sel:[0,1] op_sel_hi:[1,1]
	v_rcp_f32_e32 v196, v196
	v_rcp_f32_e32 v197, v197
	v_rcp_f32_e32 v198, v198
	v_rcp_f32_e32 v199, v199
	v_pk_mul_f32 v[202:203], v[202:203], v[180:181] op_sel:[0,1] op_sel_hi:[1,1]
	v_pk_mul_f32 v[200:201], v[200:201], v[196:197]
	v_pk_mul_f32 v[202:203], v[202:203], v[198:199]
	v_cvt_pk_bf16_f32 v204, v200, v201
	v_cvt_pk_bf16_f32 v205, v202, v203
	v_pk_mul_f32 v[196:197], v[106:107], v[180:181] op_sel_hi:[1,0]
	v_pk_mul_f32 v[198:199], v[108:109], v[180:181] op_sel_hi:[1,0]
	v_pk_mul_f32 v[200:201], v[106:107], v[74:75]
	v_exp_f32_e32 v196, v196
	v_exp_f32_e32 v197, v197
	v_exp_f32_e32 v198, v198
	v_exp_f32_e32 v199, v199
	v_pk_mul_f32 v[202:203], v[108:109], v[76:77]
	v_pk_add_f32 v[196:197], v[196:197], 1.0 op_sel_hi:[1,0]
	v_pk_add_f32 v[198:199], v[198:199], 1.0 op_sel_hi:[1,0]
	v_pk_mul_f32 v[200:201], v[200:201], v[180:181] op_sel:[0,1] op_sel_hi:[1,1]
	v_rcp_f32_e32 v196, v196
	v_rcp_f32_e32 v197, v197
	v_rcp_f32_e32 v198, v198
	v_rcp_f32_e32 v199, v199
	v_pk_mul_f32 v[202:203], v[202:203], v[180:181] op_sel:[0,1] op_sel_hi:[1,1]
	v_pk_mul_f32 v[200:201], v[200:201], v[196:197]
	v_pk_mul_f32 v[202:203], v[202:203], v[198:199]
	v_cvt_pk_bf16_f32 v206, v200, v201
	v_cvt_pk_bf16_f32 v207, v202, v203
	global_store_dwordx4 v[170:171], v[204:207], off
	v_or_b32_e32 v174, 16, v163
	s_andn2_b64 vcc, exec, s[6:7]
	v_mad_i64_i32 v[168:169], s[54:55], v174, s90, v[148:149]
	v_lshl_add_u64 v[168:169], v[168:169], 0, v[150:151]
	v_pk_mul_f32 v[196:197], v[102:103], v[182:183] op_sel_hi:[1,0]
	v_pk_mul_f32 v[198:199], v[104:105], v[182:183] op_sel_hi:[1,0]
	v_pk_mul_f32 v[200:201], v[102:103], v[70:71]
	v_exp_f32_e32 v196, v196
	v_exp_f32_e32 v197, v197
	v_exp_f32_e32 v198, v198
	v_exp_f32_e32 v199, v199
	v_pk_mul_f32 v[202:203], v[104:105], v[72:73]
	v_pk_add_f32 v[196:197], v[196:197], 1.0 op_sel_hi:[1,0]
	v_pk_add_f32 v[198:199], v[198:199], 1.0 op_sel_hi:[1,0]
	v_pk_mul_f32 v[200:201], v[200:201], v[182:183] op_sel:[0,1] op_sel_hi:[1,1]
	v_rcp_f32_e32 v196, v196
	v_rcp_f32_e32 v197, v197
	v_rcp_f32_e32 v198, v198
	v_rcp_f32_e32 v199, v199
	v_pk_mul_f32 v[202:203], v[202:203], v[182:183] op_sel:[0,1] op_sel_hi:[1,1]
	v_pk_mul_f32 v[200:201], v[200:201], v[196:197]
	v_pk_mul_f32 v[202:203], v[202:203], v[198:199]
	v_cvt_pk_bf16_f32 v208, v200, v201
	v_cvt_pk_bf16_f32 v209, v202, v203
	v_pk_mul_f32 v[196:197], v[98:99], v[182:183] op_sel_hi:[1,0]
	v_pk_mul_f32 v[198:199], v[100:101], v[182:183] op_sel_hi:[1,0]
	v_pk_mul_f32 v[200:201], v[98:99], v[66:67]
	v_exp_f32_e32 v196, v196
	v_exp_f32_e32 v197, v197
	v_exp_f32_e32 v198, v198
	v_exp_f32_e32 v199, v199
	v_pk_mul_f32 v[202:203], v[100:101], v[68:69]
	v_pk_add_f32 v[196:197], v[196:197], 1.0 op_sel_hi:[1,0]
	v_pk_add_f32 v[198:199], v[198:199], 1.0 op_sel_hi:[1,0]
	v_pk_mul_f32 v[200:201], v[200:201], v[182:183] op_sel:[0,1] op_sel_hi:[1,1]
	v_rcp_f32_e32 v196, v196
	v_rcp_f32_e32 v197, v197
	v_rcp_f32_e32 v198, v198
	v_rcp_f32_e32 v199, v199
	v_pk_mul_f32 v[202:203], v[202:203], v[182:183] op_sel:[0,1] op_sel_hi:[1,1]
	v_pk_mul_f32 v[200:201], v[200:201], v[196:197]
	v_pk_mul_f32 v[202:203], v[202:203], v[198:199]
	v_cvt_pk_bf16_f32 v210, v200, v201
	v_cvt_pk_bf16_f32 v211, v202, v203
	global_store_dwordx4 v[168:169], v[208:211], off
	v_or_b32_e32 v174, 32, v163
	v_mad_i64_i32 v[168:169], s[54:55], v174, s90, v[148:149]
	v_lshl_add_u64 v[168:169], v[168:169], 0, v[150:151]
	v_pk_mul_f32 v[196:197], v[94:95], v[184:185] op_sel_hi:[1,0]
	v_pk_mul_f32 v[198:199], v[96:97], v[184:185] op_sel_hi:[1,0]
	v_pk_mul_f32 v[200:201], v[94:95], v[62:63]
	v_exp_f32_e32 v196, v196
	v_exp_f32_e32 v197, v197
	v_exp_f32_e32 v198, v198
	v_exp_f32_e32 v199, v199
	v_pk_mul_f32 v[202:203], v[96:97], v[64:65]
	v_pk_add_f32 v[196:197], v[196:197], 1.0 op_sel_hi:[1,0]
	v_pk_add_f32 v[198:199], v[198:199], 1.0 op_sel_hi:[1,0]
	v_pk_mul_f32 v[200:201], v[200:201], v[184:185] op_sel:[0,1] op_sel_hi:[1,1]
	v_rcp_f32_e32 v196, v196
; __device__ __forceinline__ float silu1(float g) { return g * __builtin_amdgcn_rcpf(1.0f + __expf(-g)); }
; __device__ __forceinline__ f32x4 swiglu4(f32x4 g, f32x4 u) { return (f32x4){silu1(g[0]) * u[0], silu1(g[1]) * u[1], silu1(g[2]) * u[2], silu1(g[3]) * u[3]}; }
; template <int EK>
; __device__ __forceinline__ void epi_tile(const f32x4 (&acc)[2][2][4][2], const Unit& u, int wr, int wc, int fr, int fq, const EpiArgs& E, const LAS float* rt) {
;     const int rowb = u.pm * BM + wr * 64 + fr;
;     float rr[2][4];
;     if (EK != EK_RES) {
; #pragma unroll
;         for (int ai = 0; ai < 2; ++ai)
; #pragma unroll
;             for (int m = 0; m < 4; ++m) rr[ai][m] = rt[ai * HALF + wr * 64 + m * 16 + fr];
;     }
; #pragma unroll
;     for (int ai = 0; ai < 2; ++ai) {
; #pragma unroll
;         for (int m = 0; m < 4; ++m) {
;             const int row = rowb + ai * HALF + m * 16;
;             if (EK == EK_SCALE) {
;                 const float r = rr[ai][m];
; #pragma unroll
;                 for (int bj = 0; bj < 2; ++bj) { const int col = u.pn * BM + bj * HALF + wc * 32 + fq * 8;
;                     const u32x2 lo = pack4(acc[ai][bj][m][0] * r), hi = pack4(acc[ai][bj][m][1] * r);
;                     *(u32x4*)(E.ob + (size_t)row * E.ldb + col) = (u32x4){lo.x, lo.y, hi.x, hi.y}; }
;             } else if (EK == EK_GELU) {
;                 const float r = rr[ai][m]; float ss = 0.f;
; #pragma unroll
;                 for (int bj = 0; bj < 2; ++bj) { const int col = u.pn * BM + bj * HALF + wc * 32 + fq * 8;
;                     const f32x4 z0 = gelu4(acc[ai][bj][m][0] * r), z1 = gelu4(acc[ai][bj][m][1] * r); ss += dot4(z0) + dot4(z1);
;                     const u32x2 lo = pack4(z0), hi = pack4(z1);
;                     *(u32x4*)(E.ob + (size_t)row * E.ldb + col) = (u32x4){lo.x, lo.y, hi.x, hi.y}; }
;                 if (u.pn >= 4) { ss = quad_sum(ss); if (fq == 0) E.stOut[(size_t)row * 16 + (u.pn - 4) * 4 + wc] = ss; }
;             } else if (EK == EK_SWIGLU) {
;                 const float r = rr[ai][m];
;                 { const int col = u.pn * HALF + wc * 32 + fq * 8;
;                     const u32x2 lo = pack4(swiglu4(acc[ai][0][m][0] * r, acc[ai][1][m][0] * r)), hi = pack4(swiglu4(acc[ai][0][m][1] * r, acc[ai][1][m][1] * r));
;                     *(u32x4*)(E.ob + (size_t)row * DFF + col) = (u32x4){lo.x, lo.y, hi.x, hi.y}; }
	v_rcp_f32_e32 v197, v197
	v_rcp_f32_e32 v198, v198
	v_rcp_f32_e32 v199, v199
	v_pk_mul_f32 v[202:203], v[202:203], v[184:185] op_sel:[0,1] op_sel_hi:[1,1]
	v_pk_mul_f32 v[200:201], v[200:201], v[196:197]
	v_pk_mul_f32 v[202:203], v[202:203], v[198:199]
	v_cvt_pk_bf16_f32 v204, v200, v201
	v_cvt_pk_bf16_f32 v205, v202, v203
	v_pk_mul_f32 v[196:197], v[90:91], v[184:185] op_sel_hi:[1,0]
	v_pk_mul_f32 v[198:199], v[92:93], v[184:185] op_sel_hi:[1,0]
	v_pk_mul_f32 v[200:201], v[90:91], v[58:59]
	v_exp_f32_e32 v196, v196
	v_exp_f32_e32 v197, v197
	v_exp_f32_e32 v198, v198
	v_exp_f32_e32 v199, v199
	v_pk_mul_f32 v[202:203], v[92:93], v[60:61]
	v_pk_add_f32 v[196:197], v[196:197], 1.0 op_sel_hi:[1,0]
	v_pk_add_f32 v[198:199], v[198:199], 1.0 op_sel_hi:[1,0]
	v_pk_mul_f32 v[200:201], v[200:201], v[184:185] op_sel:[0,1] op_sel_hi:[1,1]
	v_rcp_f32_e32 v196, v196
	v_rcp_f32_e32 v197, v197
	v_rcp_f32_e32 v198, v198
	v_rcp_f32_e32 v199, v199
	v_pk_mul_f32 v[202:203], v[202:203], v[184:185] op_sel:[0,1] op_sel_hi:[1,1]
	v_pk_mul_f32 v[200:201], v[200:201], v[196:197]
	v_pk_mul_f32 v[202:203], v[202:203], v[198:199]
	v_cvt_pk_bf16_f32 v206, v200, v201
	v_cvt_pk_bf16_f32 v207, v202, v203
	global_store_dwordx4 v[168:169], v[204:207], off
	v_or_b32_e32 v172, 48, v163
	v_mad_i64_i32 v[154:155], s[54:55], v172, s90, v[148:149]
	v_lshl_add_u64 v[154:155], v[154:155], 0, v[150:151]
	v_pk_mul_f32 v[196:197], v[86:87], v[186:187] op_sel_hi:[1,0]
	v_pk_mul_f32 v[198:199], v[88:89], v[186:187] op_sel_hi:[1,0]
	v_pk_mul_f32 v[200:201], v[86:87], v[54:55]
	v_exp_f32_e32 v196, v196
	v_exp_f32_e32 v197, v197
	v_exp_f32_e32 v198, v198
	v_exp_f32_e32 v199, v199
	v_pk_mul_f32 v[202:203], v[88:89], v[56:57]
	v_pk_add_f32 v[196:197], v[196:197], 1.0 op_sel_hi:[1,0]
	v_pk_add_f32 v[198:199], v[198:199], 1.0 op_sel_hi:[1,0]
	v_pk_mul_f32 v[200:201], v[200:201], v[186:187] op_sel:[0,1] op_sel_hi:[1,1]
	v_rcp_f32_e32 v196, v196
	v_rcp_f32_e32 v197, v197
	v_rcp_f32_e32 v198, v198
	v_rcp_f32_e32 v199, v199
	v_pk_mul_f32 v[202:203], v[202:203], v[186:187] op_sel:[0,1] op_sel_hi:[1,1]
	v_pk_mul_f32 v[200:201], v[200:201], v[196:197]
	v_pk_mul_f32 v[202:203], v[202:203], v[198:199]
	v_cvt_pk_bf16_f32 v208, v200, v201
	v_cvt_pk_bf16_f32 v209, v202, v203
	v_pk_mul_f32 v[196:197], v[82:83], v[186:187] op_sel_hi:[1,0]
	v_pk_mul_f32 v[198:199], v[84:85], v[186:187] op_sel_hi:[1,0]
	v_pk_mul_f32 v[200:201], v[82:83], v[50:51]
	v_exp_f32_e32 v196, v196
	v_exp_f32_e32 v197, v197
	v_exp_f32_e32 v198, v198
	v_exp_f32_e32 v199, v199
	v_pk_mul_f32 v[202:203], v[84:85], v[52:53]
	v_pk_add_f32 v[196:197], v[196:197], 1.0 op_sel_hi:[1,0]
	v_pk_add_f32 v[198:199], v[198:199], 1.0 op_sel_hi:[1,0]
	v_pk_mul_f32 v[200:201], v[200:201], v[186:187] op_sel:[0,1] op_sel_hi:[1,1]
	v_rcp_f32_e32 v196, v196
	v_rcp_f32_e32 v197, v197
	v_rcp_f32_e32 v198, v198
	v_rcp_f32_e32 v199, v199
	v_pk_mul_f32 v[202:203], v[202:203], v[186:187] op_sel:[0,1] op_sel_hi:[1,1]
	v_pk_mul_f32 v[200:201], v[200:201], v[196:197]
	v_pk_mul_f32 v[202:203], v[202:203], v[198:199]
	v_cvt_pk_bf16_f32 v210, v200, v201
	v_cvt_pk_bf16_f32 v211, v202, v203
	global_store_dwordx4 v[154:155], v[208:211], off
	v_add_u32_e32 v172, 0x80, v163
	v_mad_i64_i32 v[154:155], s[54:55], v172, s90, v[148:149]
	v_lshl_add_u64 v[154:155], v[154:155], 0, v[150:151]
	v_pk_mul_f32 v[196:197], v[46:47], v[188:189] op_sel_hi:[1,0]
	v_pk_mul_f32 v[198:199], v[48:49], v[188:189] op_sel_hi:[1,0]
	v_pk_mul_f32 v[200:201], v[46:47], v[14:15]
	v_exp_f32_e32 v196, v196
	v_exp_f32_e32 v197, v197
	v_exp_f32_e32 v198, v198
	v_exp_f32_e32 v199, v199
	v_pk_mul_f32 v[202:203], v[48:49], v[16:17]
	v_pk_add_f32 v[196:197], v[196:197], 1.0 op_sel_hi:[1,0]
	v_pk_add_f32 v[198:199], v[198:199], 1.0 op_sel_hi:[1,0]
	v_pk_mul_f32 v[200:201], v[200:201], v[188:189] op_sel:[0,1] op_sel_hi:[1,1]
	v_rcp_f32_e32 v196, v196
	v_rcp_f32_e32 v197, v197
	v_rcp_f32_e32 v198, v198
	v_rcp_f32_e32 v199, v199
	v_pk_mul_f32 v[202:203], v[202:203], v[188:189] op_sel:[0,1] op_sel_hi:[1,1]
	v_pk_mul_f32 v[200:201], v[200:201], v[196:197]
	v_pk_mul_f32 v[202:203], v[202:203], v[198:199]
	v_cvt_pk_bf16_f32 v204, v200, v201
	v_cvt_pk_bf16_f32 v205, v202, v203
	v_pk_mul_f32 v[196:197], v[42:43], v[188:189] op_sel_hi:[1,0]
	v_pk_mul_f32 v[198:199], v[44:45], v[188:189] op_sel_hi:[1,0]
	v_pk_mul_f32 v[200:201], v[42:43], v[10:11]
	v_exp_f32_e32 v196, v196
	v_exp_f32_e32 v197, v197
	v_exp_f32_e32 v198, v198
	v_exp_f32_e32 v199, v199
	v_pk_mul_f32 v[202:203], v[44:45], v[12:13]
	v_pk_add_f32 v[196:197], v[196:197], 1.0 op_sel_hi:[1,0]
	v_pk_add_f32 v[198:199], v[198:199], 1.0 op_sel_hi:[1,0]
	v_pk_mul_f32 v[200:201], v[200:201], v[188:189] op_sel:[0,1] op_sel_hi:[1,1]
	v_rcp_f32_e32 v196, v196
	v_rcp_f32_e32 v197, v197
	v_rcp_f32_e32 v198, v198
	v_rcp_f32_e32 v199, v199
	v_pk_mul_f32 v[202:203], v[202:203], v[188:189] op_sel:[0,1] op_sel_hi:[1,1]
	v_pk_mul_f32 v[200:201], v[200:201], v[196:197]
	v_pk_mul_f32 v[202:203], v[202:203], v[198:199]
	v_cvt_pk_bf16_f32 v206, v200, v201
	v_cvt_pk_bf16_f32 v207, v202, v203
	global_store_dwordx4 v[154:155], v[204:207], off
	v_add_u32_e32 v170, 0x90, v163
	v_mad_i64_i32 v[164:165], s[54:55], v170, s90, v[148:149]
	v_lshl_add_u64 v[164:165], v[164:165], 0, v[150:151]
	v_pk_mul_f32 v[196:197], v[38:39], v[190:191] op_sel_hi:[1,0]
	v_pk_mul_f32 v[198:199], v[40:41], v[190:191] op_sel_hi:[1,0]
	v_pk_mul_f32 v[200:201], v[38:39], v[6:7]
	v_exp_f32_e32 v196, v196
	v_exp_f32_e32 v197, v197
	v_exp_f32_e32 v198, v198
	v_exp_f32_e32 v199, v199
; __device__ __forceinline__ float silu1(float g) { return g * __builtin_amdgcn_rcpf(1.0f + __expf(-g)); }
; __device__ __forceinline__ f32x4 swiglu4(f32x4 g, f32x4 u) { return (f32x4){silu1(g[0]) * u[0], silu1(g[1]) * u[1], silu1(g[2]) * u[2], silu1(g[3]) * u[3]}; }
; template <int EK>
; __device__ __forceinline__ void epi_tile(const f32x4 (&acc)[2][2][4][2], const Unit& u, int wr, int wc, int fr, int fq, const EpiArgs& E, const LAS float* rt) {
;     const int rowb = u.pm * BM + wr * 64 + fr;
;     float rr[2][4];
;     if (EK != EK_RES) {
; #pragma unroll
;         for (int ai = 0; ai < 2; ++ai)
; #pragma unroll
;             for (int m = 0; m < 4; ++m) rr[ai][m] = rt[ai * HALF + wr * 64 + m * 16 + fr];
;     }
; #pragma unroll
;     for (int ai = 0; ai < 2; ++ai) {
; #pragma unroll
;         for (int m = 0; m < 4; ++m) {
;             const int row = rowb + ai * HALF + m * 16;
;             if (EK == EK_SCALE) {
;                 const float r = rr[ai][m];
; #pragma unroll
;                 for (int bj = 0; bj < 2; ++bj) { const int col = u.pn * BM + bj * HALF + wc * 32 + fq * 8;
;                     const u32x2 lo = pack4(acc[ai][bj][m][0] * r), hi = pack4(acc[ai][bj][m][1] * r);
;                     *(u32x4*)(E.ob + (size_t)row * E.ldb + col) = (u32x4){lo.x, lo.y, hi.x, hi.y}; }
;             } else if (EK == EK_GELU) {
;                 const float r = rr[ai][m]; float ss = 0.f;
; #pragma unroll
;                 for (int bj = 0; bj < 2; ++bj) { const int col = u.pn * BM + bj * HALF + wc * 32 + fq * 8;
;                     const f32x4 z0 = gelu4(acc[ai][bj][m][0] * r), z1 = gelu4(acc[ai][bj][m][1] * r); ss += dot4(z0) + dot4(z1);
;                     const u32x2 lo = pack4(z0), hi = pack4(z1);
;                     *(u32x4*)(E.ob + (size_t)row * E.ldb + col) = (u32x4){lo.x, lo.y, hi.x, hi.y}; }
;                 if (u.pn >= 4) { ss = quad_sum(ss); if (fq == 0) E.stOut[(size_t)row * 16 + (u.pn - 4) * 4 + wc] = ss; }
;             } else if (EK == EK_SWIGLU) {
;                 const float r = rr[ai][m];
;                 { const int col = u.pn * HALF + wc * 32 + fq * 8;
;                     const u32x2 lo = pack4(swiglu4(acc[ai][0][m][0] * r, acc[ai][1][m][0] * r)), hi = pack4(swiglu4(acc[ai][0][m][1] * r, acc[ai][1][m][1] * r));
;                     *(u32x4*)(E.ob + (size_t)row * DFF + col) = (u32x4){lo.x, lo.y, hi.x, hi.y}; }
	v_pk_mul_f32 v[202:203], v[40:41], v[8:9]
	v_pk_add_f32 v[196:197], v[196:197], 1.0 op_sel_hi:[1,0]
	v_pk_add_f32 v[198:199], v[198:199], 1.0 op_sel_hi:[1,0]
	v_pk_mul_f32 v[200:201], v[200:201], v[190:191] op_sel:[0,1] op_sel_hi:[1,1]
	v_rcp_f32_e32 v196, v196
	v_rcp_f32_e32 v197, v197
	v_rcp_f32_e32 v198, v198
	v_rcp_f32_e32 v199, v199
	v_pk_mul_f32 v[202:203], v[202:203], v[190:191] op_sel:[0,1] op_sel_hi:[1,1]
	v_pk_mul_f32 v[200:201], v[200:201], v[196:197]
	v_pk_mul_f32 v[202:203], v[202:203], v[198:199]
	v_cvt_pk_bf16_f32 v208, v200, v201
	v_cvt_pk_bf16_f32 v209, v202, v203
	v_pk_mul_f32 v[196:197], v[34:35], v[190:191] op_sel_hi:[1,0]
	v_pk_mul_f32 v[198:199], v[36:37], v[190:191] op_sel_hi:[1,0]
	v_pk_mul_f32 v[200:201], v[34:35], v[2:3]
	v_exp_f32_e32 v196, v196
	v_exp_f32_e32 v197, v197
	v_exp_f32_e32 v198, v198
	v_exp_f32_e32 v199, v199
	v_pk_mul_f32 v[202:203], v[36:37], v[4:5]
	v_pk_add_f32 v[196:197], v[196:197], 1.0 op_sel_hi:[1,0]
	v_pk_add_f32 v[198:199], v[198:199], 1.0 op_sel_hi:[1,0]
	v_pk_mul_f32 v[200:201], v[200:201], v[190:191] op_sel:[0,1] op_sel_hi:[1,1]
	v_rcp_f32_e32 v196, v196
	v_rcp_f32_e32 v197, v197
	v_rcp_f32_e32 v198, v198
	v_rcp_f32_e32 v199, v199
	v_pk_mul_f32 v[202:203], v[202:203], v[190:191] op_sel:[0,1] op_sel_hi:[1,1]
	v_pk_mul_f32 v[200:201], v[200:201], v[196:197]
	v_pk_mul_f32 v[202:203], v[202:203], v[198:199]
	v_cvt_pk_bf16_f32 v210, v200, v201
	v_cvt_pk_bf16_f32 v211, v202, v203
	global_store_dwordx4 v[164:165], v[208:211], off
	v_add_u32_e32 v170, 0xa0, v163
	v_add_u32_e32 v163, 0xb0, v163
	v_mad_i64_i32 v[164:165], s[54:55], v170, s90, v[148:149]
	v_lshl_add_u64 v[164:165], v[164:165], 0, v[150:151]
	v_pk_mul_f32 v[196:197], v[30:31], v[192:193] op_sel_hi:[1,0]
	v_pk_mul_f32 v[198:199], v[32:33], v[192:193] op_sel_hi:[1,0]
	v_pk_mul_f32 v[200:201], v[30:31], v[114:115]
	v_exp_f32_e32 v196, v196
	v_exp_f32_e32 v197, v197
	v_exp_f32_e32 v198, v198
	v_exp_f32_e32 v199, v199
	v_pk_mul_f32 v[202:203], v[32:33], v[116:117]
	v_pk_add_f32 v[196:197], v[196:197], 1.0 op_sel_hi:[1,0]
	v_pk_add_f32 v[198:199], v[198:199], 1.0 op_sel_hi:[1,0]
	v_pk_mul_f32 v[200:201], v[200:201], v[192:193] op_sel:[0,1] op_sel_hi:[1,1]
	v_rcp_f32_e32 v196, v196
	v_rcp_f32_e32 v197, v197
	v_rcp_f32_e32 v198, v198
	v_rcp_f32_e32 v199, v199
	v_pk_mul_f32 v[202:203], v[202:203], v[192:193] op_sel:[0,1] op_sel_hi:[1,1]
	v_pk_mul_f32 v[200:201], v[200:201], v[196:197]
	v_pk_mul_f32 v[202:203], v[202:203], v[198:199]
	v_cvt_pk_bf16_f32 v204, v200, v201
	v_cvt_pk_bf16_f32 v205, v202, v203
	v_pk_mul_f32 v[196:197], v[26:27], v[192:193] op_sel_hi:[1,0]
	v_pk_mul_f32 v[198:199], v[28:29], v[192:193] op_sel_hi:[1,0]
	v_pk_mul_f32 v[200:201], v[26:27], v[118:119]
	v_exp_f32_e32 v196, v196
	v_exp_f32_e32 v197, v197
	v_exp_f32_e32 v198, v198
	v_exp_f32_e32 v199, v199
	v_pk_mul_f32 v[202:203], v[28:29], v[120:121]
	v_pk_add_f32 v[196:197], v[196:197], 1.0 op_sel_hi:[1,0]
	v_pk_add_f32 v[198:199], v[198:199], 1.0 op_sel_hi:[1,0]
	v_pk_mul_f32 v[200:201], v[200:201], v[192:193] op_sel:[0,1] op_sel_hi:[1,1]
	v_rcp_f32_e32 v196, v196
	v_rcp_f32_e32 v197, v197
	v_rcp_f32_e32 v198, v198
	v_rcp_f32_e32 v199, v199
	v_pk_mul_f32 v[202:203], v[202:203], v[192:193] op_sel:[0,1] op_sel_hi:[1,1]
	v_pk_mul_f32 v[200:201], v[200:201], v[196:197]
	v_pk_mul_f32 v[202:203], v[202:203], v[198:199]
	v_cvt_pk_bf16_f32 v206, v200, v201
	v_cvt_pk_bf16_f32 v207, v202, v203
	global_store_dwordx4 v[164:165], v[204:207], off
	v_mad_i64_i32 v[146:147], s[54:55], v163, s90, v[148:149]
	v_lshl_add_u64 v[146:147], v[146:147], 0, v[150:151]
	v_pk_mul_f32 v[196:197], v[22:23], v[194:195] op_sel_hi:[1,0]
	v_pk_mul_f32 v[198:199], v[24:25], v[194:195] op_sel_hi:[1,0]
	v_pk_mul_f32 v[200:201], v[22:23], v[122:123]
	v_exp_f32_e32 v196, v196
	v_exp_f32_e32 v197, v197
	v_exp_f32_e32 v198, v198
	v_exp_f32_e32 v199, v199
	v_pk_mul_f32 v[202:203], v[24:25], v[124:125]
	v_pk_add_f32 v[196:197], v[196:197], 1.0 op_sel_hi:[1,0]
	v_pk_add_f32 v[198:199], v[198:199], 1.0 op_sel_hi:[1,0]
	v_pk_mul_f32 v[200:201], v[200:201], v[194:195] op_sel:[0,1] op_sel_hi:[1,1]
	v_rcp_f32_e32 v196, v196
	v_rcp_f32_e32 v197, v197
	v_rcp_f32_e32 v198, v198
	v_rcp_f32_e32 v199, v199
	v_pk_mul_f32 v[202:203], v[202:203], v[194:195] op_sel:[0,1] op_sel_hi:[1,1]
	v_pk_mul_f32 v[200:201], v[200:201], v[196:197]
	v_pk_mul_f32 v[202:203], v[202:203], v[198:199]
	v_cvt_pk_bf16_f32 v208, v200, v201
	v_cvt_pk_bf16_f32 v209, v202, v203
	v_pk_mul_f32 v[196:197], v[18:19], v[194:195] op_sel_hi:[1,0]
	v_pk_mul_f32 v[198:199], v[20:21], v[194:195] op_sel_hi:[1,0]
	v_pk_mul_f32 v[200:201], v[18:19], v[126:127]
	v_exp_f32_e32 v196, v196
	v_exp_f32_e32 v197, v197
	v_exp_f32_e32 v198, v198
	v_exp_f32_e32 v199, v199
	v_pk_mul_f32 v[202:203], v[20:21], v[128:129]
	v_pk_add_f32 v[196:197], v[196:197], 1.0 op_sel_hi:[1,0]
	v_pk_add_f32 v[198:199], v[198:199], 1.0 op_sel_hi:[1,0]
	v_pk_mul_f32 v[200:201], v[200:201], v[194:195] op_sel:[0,1] op_sel_hi:[1,1]
	v_rcp_f32_e32 v196, v196
	v_rcp_f32_e32 v197, v197
	v_rcp_f32_e32 v198, v198
	v_rcp_f32_e32 v199, v199
	v_pk_mul_f32 v[202:203], v[202:203], v[194:195] op_sel:[0,1] op_sel_hi:[1,1]
	v_pk_mul_f32 v[200:201], v[200:201], v[196:197]
	v_pk_mul_f32 v[202:203], v[202:203], v[198:199]
	v_cvt_pk_bf16_f32 v210, v200, v201
	v_cvt_pk_bf16_f32 v211, v202, v203
	global_store_dwordx4 v[146:147], v[208:211], off
	s_cbranch_vccnz .LBB0_544
	s_andn2_b64 vcc, exec, s[8:9]
	s_cbranch_vccnz .LBB0_530
	s_barrier
	s_branch .LBB0_530

; __device__ __forceinline__ unsigned xb_ld(unsigned* p)              { return __hip_atomic_load(p, __ATOMIC_RELAXED, __HIP_MEMORY_SCOPE_AGENT); }
; __device__ __forceinline__ unsigned xb_add(unsigned* p, unsigned v) { return __hip_atomic_fetch_add(p, v, __ATOMIC_RELAXED, __HIP_MEMORY_SCOPE_AGENT); }
; #define XB_SPIN(cond, bar) do { unsigned _sp = 0; while (cond) { __builtin_amdgcn_s_sleep(1); \
;     if ((++_sp & 255u) == 0u) { if (xb_ld(&(bar)[XB_TMO])) break; if (_sp > XB_SPIN_CAP) { atomicAdd(&(bar)[XB_TMO], 1u); break; } } } } while (0)
; __device__ __forceinline__ void xcd_barrier(const XcdBarrier& b) {
;     asm volatile("s_waitcnt vmcnt(0)" ::: "memory");
;     __syncthreads();
;     if (threadIdx.x == 0) {
;         unsigned* bar = b.bar;
;         __builtin_amdgcn_s_waitcnt(0);
;         unsigned nloc = b.st[0], nx = b.st[1];
;         if (nloc == 0u) { xcd_barrier_complete(bar, b.x, nloc, nx); b.st[0] = nloc; b.st[1] = nx; }
;         const unsigned old = xb_add(&bar[XB_XSUB(b.x)], 1u);
;         const unsigned gen = old / nloc;
;         if (old + 1u == (gen + 1u) * nloc) {
;             __builtin_amdgcn_fence(__ATOMIC_RELEASE, "agent");
;             asm volatile("s_waitcnt vmcnt(0)" ::: "memory");
;             const unsigned og = xb_add(&bar[XB_TOP], 1u);
;             const unsigned tg = og / nx;
;             if (og + 1u == (tg + 1u) * nx) xb_add(&bar[XB_TOPGEN], 1u);
;             else XB_SPIN(xb_ld(&bar[XB_TOPGEN]) == tg, bar);
;             __builtin_amdgcn_fence(__ATOMIC_ACQUIRE, "agent");
;             asm volatile("s_waitcnt vmcnt(0)" ::: "memory");
;         } else {
;             XB_SPIN(xb_ld(&bar[XB_TOPGEN]) == gen, bar);
;             __builtin_amdgcn_fence(__ATOMIC_ACQUIRE, "agent");
;             asm volatile("s_waitcnt vmcnt(0)" ::: "memory");
;         }
;     }
;     __syncthreads();
.Lmy_noinv5:
	s_and_saveexec_b64 s[6:7], vcc
	s_cbranch_execz .LBB0_758
	s_waitcnt vmcnt(0) lgkmcnt(0)
	v_mov_b32_e32 v1, 0x20000
	ds_read2_b32 v[2:3], v1 offset1:1
	s_and_b32 s99, s33, 7
	s_lshl_b32 s99, s99, 8
	s_add_u32 s100, s60, 0xc000
	s_addc_u32 s101, s61, 0
	v_mov_b32_e32 v4, s99
	v_mov_b32_e32 v5, 1
	global_atomic_add v5, v4, v5, s[100:101] sc0
	s_waitcnt lgkmcnt(0)
	v_mul_u32_u24_e32 v6, 4, v2
	v_mul_u32_u24_e32 v7, 4, v3
	s_waitcnt vmcnt(0)
	v_add_u32_e32 v5, 1, v5
	v_cmp_eq_u32_e32 vcc, v5, v6
	s_cbranch_vccz .Lmy_nl4
	buffer_wbl2 sc1
	s_waitcnt vmcnt(0)
	v_mov_b32_e32 v4, 0x800
	v_mov_b32_e32 v5, 1
	global_atomic_add v4, v5, s[100:101]

; #define LAS __attribute__((address_space(3)))
; __device__ __forceinline__ float hsum4(f32x4 v) { return (v[0] + v[1]) + (v[2] + v[3]); }
; #define PG8_STAGEA(bufoff, gbase) PG8_STAGE_(bufoff, gbase, voffA)
; template <int EK, int SK = -1>
; __device__ __forceinline__ void gemm_phase(LAS unsigned char* lds, const bf16_t* A, const bf16_t* Bt, int nM, int N, int K, const EpiArgs& E) {
;     ...
;     f32x4 acc[2][2][4][2];
; #pragma unroll
;     for (int a = 0; a < 2; ++a)
; #pragma unroll
;         for (int b = 0; b < 2; ++b)
; #pragma unroll
;             for (int m = 0; m < 4; ++m)
; #pragma unroll
;                 for (int n = 0; n < 2; ++n) acc[a][b][m][n] = (f32x4){0.f, 0.f, 0.f, 0.f};
;     bf16x8 At[4][2], B0[2][2], B1[2][2];
;     const char* cA = (const char*)A + (size_t)cur.pm * tstep; const char* cB = (const char*)Bt + (size_t)cur.pn * tstep;
;     PG8_STAGEB(PG8_SB(0, 0), cB); PG8_STAGEB(PG8_SB(0, 1), cB + hstep); PG8_STAGEA(PG8_SA(0, 0), cA); PG8_STAGEA(PG8_SA(0, 1), cA + hstep);
;     f32x4 tq[4][4]; bool okq[4];
;     if (EK != EK_RES && EK != EK_FINAL) {
; #pragma unroll
;         for (int j = 0; j < 4; ++j) { Unit uu; okq[j] = S.next((tid >> 8) + 2 * j, uu);
;             if (okq[j]) { const f32x4* sp = (const f32x4*)(E.stIn + (size_t)(uu.pm * BM + (tid & 255)) * 16); tq[j][0] = sp[0]; tq[j][1] = sp[1]; tq[j][2] = sp[2]; tq[j][3] = sp[3]; } }
;     }
;     if (SK >= 0) skinny_phase<(SK >= 0 ? SK : 0)>(lds + 32768, (LAS float*)(lds + SRED_OFF), A, Bt, N, K, E);
;     if (EK != EK_RES && EK != EK_FINAL) {
; #pragma unroll
;         for (int j = 0; j < 4; ++j) if (okq[j]) { const float s_ = (hsum4(tq[j][0]) + hsum4(tq[j][1])) + (hsum4(tq[j][2]) + hsum4(tq[j][3]));
;             rtab[((tid >> 8) + 2 * j) * 256 + (tid & 255)] = rsqrtf(s_ * (1.0f / 1024.0f) + EPS); }
;         __syncthreads();
;     }
;     if (wr == 1) PG8_BAR;
;     PG8_WAIT_V(2); PG8_BAR;
;     PG8_STAGEB(PG8_SB(1, 0), cB + kstep); PG8_STAGEA(PG8_SA(1, 0), cA + kstep); PG8_STAGEB(PG8_SB(1, 1), cB + hstep + kstep);
;     PG8_WAIT_V(6); PG8_BAR;
;     ...
; #pragma unroll
;         for (int a = 0; a < 2; ++a)
; #pragma unroll
;             for (int b = 0; b < 2; ++b)
; #pragma unroll
;                 for (int m = 0; m < 4; ++m)
; #pragma unroll
;                     for (int n = 0; n < 2; ++n) acc[a][b][m][n] = (f32x4){0.f, 0.f, 0.f, 0.f};
;         cur = nxt; cA = nA; cB = nB; ++ui;
.LBB0_780:
	v_bfe_u32 v10, v0, 4, 2
	v_lshlrev_b32_e32 v17, 4, v10
	v_lshl_or_b32 v1, s4, 6, v16
	v_lshl_or_b32 v18, v16, 6, v17
	v_lshlrev_b32_e32 v16, 2, v16
	s_lshl_b32 s4, s4, 13
	v_and_b32_e32 v16, 32, v16
	s_and_b32 s59, s22, 3
	v_bitop3_b32 v16, v18, s4, v16 bitop3:0xde
	v_lshlrev_b32_e32 v18, 6, v0
	s_movk_i32 s4, 0x3c0
	s_mov_b64 s[22:23], 0x80
	v_and_or_b32 v17, v18, s4, v17
	v_lshlrev_b32_e32 v18, 2, v0
	s_add_i32 m0, s55, 0x18000
	v_lshl_add_u64 v[8:9], v[8:9], 0, s[22:23]
	s_lshl_b32 s4, s59, 12
	v_and_b32_e32 v18, 32, v18
	s_ashr_i32 s68, s2, 31
	s_waitcnt vmcnt(2)
	s_barrier
	global_load_lds_dwordx4 v[8:9], off
	v_lshl_add_u64 v[6:7], v[6:7], 0, s[22:23]
	s_add_i32 m0, s55, 0x1a000
	s_add_i32 s69, s55, 0x8000
	s_add_i32 s70, s55, 0xa000
	v_bitop3_b32 v152, s4, v17, v18 bitop3:0xf6
	global_load_lds_dwordx4 v[6:7], off
	v_lshl_add_u64 v[2:3], v[2:3], 0, s[22:23]
	s_mov_b32 m0, s69
	s_add_u32 s4, s38, 0xb0080
	global_load_lds_dwordx4 v[2:3], off
	v_lshl_add_u64 v[2:3], v[4:5], 0, s[22:23]
	s_mov_b32 m0, s70
	s_addc_u32 s5, s39, 0
	global_load_lds_dwordx4 v[2:3], off
	s_add_i32 m0, s55, 0x1c000
	v_lshl_add_u64 v[2:3], s[4:5], 0, v[132:133]
	global_load_lds_dwordx4 v[2:3], off
	v_lshl_add_u64 v[2:3], s[4:5], 0, v[136:137]
	s_add_i32 m0, s55, 0x1e000
	s_mov_b64 s[6:7], 0xb0080
	global_load_lds_dwordx4 v[2:3], off
	v_add_u16_e32 v2, v12, v13
	v_lshrrev_b16_e32 v4, 1, v2
	v_add_lshl_u32 v2, v14, v4, 1
	v_mov_b32_e32 v3, 0
	s_waitcnt vmcnt(6)
	v_lshl_add_u64 v[138:139], v[2:3], 0, s[6:7]
	v_add_lshl_u32 v2, v15, v4, 1
	v_lshlrev_b32_e32 v11, 3, v10
	s_cmpk_lt_u32 s26, 0x100
	v_lshl_add_u64 v[140:141], v[2:3], 0, s[6:7]
	v_mbcnt_lo_u32_b32 v2, -1, 0
	s_mov_b32 s21, 0
	v_lshl_or_b32 v153, s59, 5, v11
	s_cselect_b64 s[26:27], -1, 0
	v_cmp_eq_u32_e64 s[4:5], 0, v10
	v_mov_b64_e32 v[142:143], 0x100
	v_mov_b64_e32 v[144:145], 0xff
	s_add_i32 s71, 0, 0x10000
	s_add_i32 s72, 0, 0x14000
	v_add_u32_e32 v154, 0, v16
	v_mbcnt_hi_u32_b32 v155, -1, v2
	s_mov_b32 s75, 0
	v_mov_b32_e32 v2, v3
	s_barrier
	s_branch .LBB0_782
.LBB0_781:
	v_mov_b32_e32 v2, 0
	s_mov_b32 s45, s73
	s_mov_b32 s3, s74
	v_mov_b32_e32 v3, v2
	s_mov_b64 s[14:15], s[36:37]
	s_mov_b32 s75, s76
	s_andn2_b64 vcc, exec, s[6:7]
	s_mov_b64 s[38:39], s[10:11]
	s_cbranch_vccz .LBB0_816

; #define PG8_STAGEA(bufoff, gbase) PG8_STAGE_(bufoff, gbase, voffA)
; #define PG8_STAGEB(bufoff, gbase) PG8_STAGE_(bufoff, gbase, voffB)
; #define PG8_LDA(dst, b, h) do { _Pragma("unroll") for (int m = 0; m < 4; ++m) _Pragma("unroll") for (int k = 0; k < 2; ++k) dst[m][k] = *(const LAS bf16x8*)(lds + PG8_SA(b, h) + aoff + m * 2048 + k * 1024); } while (0)
; #define PG8_LDB(dst, b, h) do { _Pragma("unroll") for (int n = 0; n < 2; ++n) _Pragma("unroll") for (int k = 0; k < 2; ++k) dst[n][k] = *(const LAS bf16x8*)(lds + PG8_SB(b, h) + boff + n * 2048 + k * 1024); } while (0)
; #define PG8_MMA(ai, bj, At, Bt_) do { __builtin_amdgcn_s_setprio(1); _Pragma("unroll") for (int m = 0; m < 4; ++m) _Pragma("unroll") for (int n = 0; n < 2; ++n) _Pragma("unroll") for (int k = 0; k < 2; ++k) \
;         acc[ai][bj][m][n] = __builtin_amdgcn_mfma_f32_16x16x32_bf16(Bt_[n][k], At[m][k], acc[ai][bj][m][n], 0, 0, 0); __builtin_amdgcn_s_setprio(0); } while (0)
; #define PG8_WAIT_V(n) asm volatile("s_waitcnt vmcnt(" #n ")" ::: "memory")
; #define PG8_WAIT_L(n) asm volatile("s_waitcnt lgkmcnt(" #n ")" ::: "memory")
; #define PG8_BAR __builtin_amdgcn_s_barrier()
; template <int EK, int SK = -1>
; __device__ __forceinline__ void gemm_phase(LAS unsigned char* lds, const bf16_t* A, const bf16_t* Bt, int nM, int N, int K, const EpiArgs& E) {
;     ...
;         const bool has_next = S.next(ui + 1, nxt);
;         const char* nA = has_next ? (const char*)A + (size_t)nxt.pm * tstep : cA; const char* nB = has_next ? (const char*)Bt + (size_t)nxt.pn * tstep : cB;
;         for (int t = 0; t < nt; t += 2) {
;             const bool last = (t == nt - 2);
;             const char* a1 = cA + (size_t)(t + 1) * kstep;
;             const char* a2 = last ? nA : cA + (size_t)(t + 2) * kstep; const char* b2 = last ? nB : cB + (size_t)(t + 2) * kstep;
;             const char* a3 = a2 + kstep; const char* b3 = b2 + kstep;
;             PG8_LDB(B0, 0, 0); PG8_LDB(B1, 0, 1); PG8_SCHED; PG8_LDA(At, 0, 0); PG8_STAGEA(PG8_SA(1, 1), a1 + hstep);
;             PG8_WAIT_V(8); PG8_WAIT_L(0); PG8_BAR; PG8_MMA(0, 0, At, B0); PG8_MMA(0, 1, At, B1); PG8_BAR; PG8_SCHED;
;             PG8_LDA(At, 0, 1); PG8_STAGEB(PG8_SB(0, 0), b2); PG8_STAGEB(PG8_SB(0, 1), b2 + hstep); PG8_STAGEA(PG8_SA(0, 0), a2);
;             PG8_WAIT_V(8); PG8_WAIT_L(0); PG8_BAR; PG8_MMA(1, 0, At, B0); PG8_MMA(1, 1, At, B1); PG8_BAR; PG8_SCHED;
.LBB0_792:
	s_add_u32 s77, s38, 0x100
	s_addc_u32 s78, s39, 0
	v_lshl_add_u64 v[146:147], s[14:15], 0, v[138:139]
	v_lshl_add_u64 v[148:149], s[14:15], 0, v[140:141]
	s_mov_b32 s20, -2
	s_mov_b64 s[38:39], 0
	v_add_u32_e32 v150, s71, v152
	ds_read_b128 v[156:159], v150
	ds_read_b128 v[160:163], v150 offset:1024
	ds_read_b128 v[164:167], v150 offset:2048
	ds_read_b128 v[168:171], v150 offset:3072
	v_add_u32_e32 v150, s72, v152
	s_add_u32 s40, s14, s38
	ds_read_b128 v[172:175], v150
	ds_read_b128 v[176:179], v150 offset:1024
	ds_read_b128 v[180:183], v150 offset:2048
	ds_read_b128 v[184:187], v150 offset:3072
	s_addc_u32 s41, s15, s39
	s_add_u32 s40, s40, 0x100
	s_addc_u32 s41, s41, 0
	s_add_u32 s79, s77, s38
	s_addc_u32 s80, s78, s39
	s_cmpk_eq_i32 s38, 0x1500
	s_cselect_b32 s43, s37, s41
	s_cselect_b32 s42, s36, s40
	s_cselect_b32 s41, s11, s80
	s_cselect_b32 s40, s10, s79
	v_lshl_add_u64 v[150:151], v[146:147], 0, s[38:39]
	s_add_i32 m0, s55, 0xc000
	ds_read_b128 v[188:191], v154
	ds_read_b128 v[192:195], v154 offset:1024
	ds_read_b128 v[196:199], v154 offset:2048
	ds_read_b128 v[200:203], v154 offset:3072
	ds_read_b128 v[204:207], v154 offset:4096
	ds_read_b128 v[208:211], v154 offset:5120
	ds_read_b128 v[212:215], v154 offset:6144
	ds_read_b128 v[216:219], v154 offset:7168
	global_load_lds_dwordx4 v[150:151], off
	v_lshl_add_u64 v[150:151], v[148:149], 0, s[38:39]
	s_add_i32 m0, s55, 0xe000
	s_nop 0
	global_load_lds_dwordx4 v[150:151], off
	s_waitcnt vmcnt(8)
	s_waitcnt lgkmcnt(0)
	s_barrier
	s_waitcnt lgkmcnt(0)
	v_mfma_f32_16x16x32_bf16 v[126:129], v[156:159], v[188:191], 0
	v_mfma_f32_16x16x32_bf16 v[122:125], v[164:167], v[188:191], 0
	v_mfma_f32_16x16x32_bf16 v[118:121], v[156:159], v[196:199], 0
	v_mfma_f32_16x16x32_bf16 v[114:117], v[164:167], v[196:199], 0
	v_mfma_f32_16x16x32_bf16 v[110:113], v[156:159], v[204:207], 0
	v_mfma_f32_16x16x32_bf16 v[106:109], v[164:167], v[204:207], 0
	v_mfma_f32_16x16x32_bf16 v[102:105], v[156:159], v[212:215], 0
	v_mfma_f32_16x16x32_bf16 v[98:101], v[164:167], v[212:215], 0
	v_mfma_f32_16x16x32_bf16 v[126:129], v[160:163], v[192:195], v[126:129]
	v_mfma_f32_16x16x32_bf16 v[122:125], v[168:171], v[192:195], v[122:125]
	v_mfma_f32_16x16x32_bf16 v[118:121], v[160:163], v[200:203], v[118:121]
	v_mfma_f32_16x16x32_bf16 v[114:117], v[168:171], v[200:203], v[114:117]
	v_mfma_f32_16x16x32_bf16 v[110:113], v[160:163], v[208:211], v[110:113]
	v_mfma_f32_16x16x32_bf16 v[106:109], v[168:171], v[208:211], v[106:109]
	v_mfma_f32_16x16x32_bf16 v[102:105], v[160:163], v[216:219], v[102:105]
	v_mfma_f32_16x16x32_bf16 v[98:101], v[168:171], v[216:219], v[98:101]
	v_mfma_f32_16x16x32_bf16 v[94:97], v[172:175], v[188:191], 0
	v_mfma_f32_16x16x32_bf16 v[90:93], v[180:183], v[188:191], 0
	v_mfma_f32_16x16x32_bf16 v[86:89], v[172:175], v[196:199], 0
	v_mfma_f32_16x16x32_bf16 v[82:85], v[180:183], v[196:199], 0
	v_mfma_f32_16x16x32_bf16 v[78:81], v[172:175], v[204:207], 0
	v_mfma_f32_16x16x32_bf16 v[74:77], v[180:183], v[204:207], 0
	v_mfma_f32_16x16x32_bf16 v[70:73], v[172:175], v[212:215], 0
	v_mfma_f32_16x16x32_bf16 v[66:69], v[180:183], v[212:215], 0
	v_mfma_f32_16x16x32_bf16 v[94:97], v[176:179], v[192:195], v[94:97]
	v_mfma_f32_16x16x32_bf16 v[90:93], v[184:187], v[192:195], v[90:93]
	v_mfma_f32_16x16x32_bf16 v[86:89], v[176:179], v[200:203], v[86:89]
	v_mfma_f32_16x16x32_bf16 v[82:85], v[184:187], v[200:203], v[82:85]
	v_mfma_f32_16x16x32_bf16 v[78:81], v[176:179], v[208:211], v[78:81]
	v_mfma_f32_16x16x32_bf16 v[74:77], v[184:187], v[208:211], v[74:77]
	v_mfma_f32_16x16x32_bf16 v[70:73], v[176:179], v[216:219], v[70:73]
	v_mfma_f32_16x16x32_bf16 v[66:69], v[184:187], v[216:219], v[66:69]
	s_barrier
	s_add_i32 s79, s71, s54
	v_lshl_add_u64 v[150:151], s[40:41], 0, v[132:133]
	s_mov_b32 m0, s79
	ds_read_b128 v[188:191], v154 offset:16384
	ds_read_b128 v[192:195], v154 offset:17408
	ds_read_b128 v[196:199], v154 offset:18432
	ds_read_b128 v[200:203], v154 offset:19456
	ds_read_b128 v[204:207], v154 offset:20480
	ds_read_b128 v[208:211], v154 offset:21504
	ds_read_b128 v[212:215], v154 offset:22528
	ds_read_b128 v[216:219], v154 offset:23552
	global_load_lds_dwordx4 v[150:151], off
	s_add_i32 m0, s79, 0x2000
	s_add_u32 s80, s40, 0xb0000
	v_lshl_add_u64 v[220:221], s[40:41], 0, v[136:137]
	s_addc_u32 s81, s41, 0
	s_add_i32 s79, s72, s54
	global_load_lds_dwordx4 v[220:221], off
	v_lshl_add_u64 v[222:223], s[80:81], 0, v[132:133]
	s_mov_b32 m0, s79
	v_lshl_add_u64 v[224:225], s[42:43], 0, v[134:135]
	global_load_lds_dwordx4 v[222:223], off
	v_lshl_add_u64 v[222:223], s[80:81], 0, v[136:137]
	s_add_i32 m0, s79, 0x2000
	s_nop 0
	global_load_lds_dwordx4 v[222:223], off
	v_lshl_add_u64 v[222:223], s[42:43], 0, v[130:131]
	s_mov_b32 m0, s55
	s_nop 0
	global_load_lds_dwordx4 v[222:223], off
	s_mov_b32 m0, s56
	s_nop 0
	global_load_lds_dwordx4 v[224:225], off
	s_waitcnt vmcnt(8)
	s_waitcnt lgkmcnt(0)
	s_barrier
; #define PG8_STAGEA(bufoff, gbase) PG8_STAGE_(bufoff, gbase, voffA)
; #define PG8_STAGEB(bufoff, gbase) PG8_STAGE_(bufoff, gbase, voffB)
; #define PG8_LDA(dst, b, h) do { _Pragma("unroll") for (int m = 0; m < 4; ++m) _Pragma("unroll") for (int k = 0; k < 2; ++k) dst[m][k] = *(const LAS bf16x8*)(lds + PG8_SA(b, h) + aoff + m * 2048 + k * 1024); } while (0)
; #define PG8_LDB(dst, b, h) do { _Pragma("unroll") for (int n = 0; n < 2; ++n) _Pragma("unroll") for (int k = 0; k < 2; ++k) dst[n][k] = *(const LAS bf16x8*)(lds + PG8_SB(b, h) + boff + n * 2048 + k * 1024); } while (0)
; #define PG8_MMA(ai, bj, At, Bt_) do { __builtin_amdgcn_s_setprio(1); _Pragma("unroll") for (int m = 0; m < 4; ++m) _Pragma("unroll") for (int n = 0; n < 2; ++n) _Pragma("unroll") for (int k = 0; k < 2; ++k) \
;         acc[ai][bj][m][n] = __builtin_amdgcn_mfma_f32_16x16x32_bf16(Bt_[n][k], At[m][k], acc[ai][bj][m][n], 0, 0, 0); __builtin_amdgcn_s_setprio(0); } while (0)
; #define PG8_WAIT_V(n) asm volatile("s_waitcnt vmcnt(" #n ")" ::: "memory")
; #define PG8_WAIT_L(n) asm volatile("s_waitcnt lgkmcnt(" #n ")" ::: "memory")
; #define PG8_BAR __builtin_amdgcn_s_barrier()
; #define PG8_SCHED __builtin_amdgcn_sched_barrier(0)
; template <int EK, int SK = -1>
; __device__ __forceinline__ void gemm_phase(LAS unsigned char* lds, const bf16_t* A, const bf16_t* Bt, int nM, int N, int K, const EpiArgs& E) {
;     ...
;             PG8_WAIT_V(8); PG8_WAIT_L(0); PG8_BAR; PG8_MMA(1, 0, At, B0); PG8_MMA(1, 1, At, B1); PG8_BAR; PG8_SCHED;
;             PG8_LDB(B0, 1, 0); PG8_LDB(B1, 1, 1); PG8_SCHED; PG8_LDA(At, 1, 0); PG8_STAGEA(PG8_SA(0, 1), a2 + hstep);
;             PG8_WAIT_V(8); PG8_WAIT_L(0); PG8_BAR; PG8_MMA(0, 0, At, B0); PG8_MMA(0, 1, At, B1); PG8_BAR; PG8_SCHED;
;             PG8_LDA(At, 1, 1); PG8_STAGEB(PG8_SB(1, 0), b3); PG8_STAGEB(PG8_SB(1, 1), b3 + hstep); PG8_STAGEA(PG8_SA(1, 0), a3);
	s_waitcnt lgkmcnt(0)
	v_mfma_f32_16x16x32_bf16 v[62:65], v[156:159], v[188:191], 0
	v_mfma_f32_16x16x32_bf16 v[58:61], v[164:167], v[188:191], 0
	v_mfma_f32_16x16x32_bf16 v[54:57], v[156:159], v[196:199], 0
	v_mfma_f32_16x16x32_bf16 v[50:53], v[164:167], v[196:199], 0
	v_mfma_f32_16x16x32_bf16 v[46:49], v[156:159], v[204:207], 0
	v_mfma_f32_16x16x32_bf16 v[42:45], v[164:167], v[204:207], 0
	v_mfma_f32_16x16x32_bf16 v[38:41], v[156:159], v[212:215], 0
	v_mfma_f32_16x16x32_bf16 v[34:37], v[164:167], v[212:215], 0
	v_mfma_f32_16x16x32_bf16 v[62:65], v[160:163], v[192:195], v[62:65]
	v_mfma_f32_16x16x32_bf16 v[58:61], v[168:171], v[192:195], v[58:61]
	v_mfma_f32_16x16x32_bf16 v[54:57], v[160:163], v[200:203], v[54:57]
	v_mfma_f32_16x16x32_bf16 v[50:53], v[168:171], v[200:203], v[50:53]
	v_mfma_f32_16x16x32_bf16 v[46:49], v[160:163], v[208:211], v[46:49]
	v_mfma_f32_16x16x32_bf16 v[42:45], v[168:171], v[208:211], v[42:45]
	v_mfma_f32_16x16x32_bf16 v[38:41], v[160:163], v[216:219], v[38:41]
	v_mfma_f32_16x16x32_bf16 v[34:37], v[168:171], v[216:219], v[34:37]
	v_mfma_f32_16x16x32_bf16 v[30:33], v[172:175], v[188:191], 0
	v_mfma_f32_16x16x32_bf16 v[26:29], v[180:183], v[188:191], 0
	v_mfma_f32_16x16x32_bf16 v[22:25], v[172:175], v[196:199], 0
	v_mfma_f32_16x16x32_bf16 v[18:21], v[180:183], v[196:199], 0
	v_mfma_f32_16x16x32_bf16 v[14:17], v[172:175], v[204:207], 0
	v_mfma_f32_16x16x32_bf16 v[10:13], v[180:183], v[204:207], 0
	v_mfma_f32_16x16x32_bf16 v[6:9], v[172:175], v[212:215], 0
	v_mfma_f32_16x16x32_bf16 v[2:5], v[180:183], v[212:215], 0
	v_mfma_f32_16x16x32_bf16 v[30:33], v[176:179], v[192:195], v[30:33]
	v_mfma_f32_16x16x32_bf16 v[26:29], v[184:187], v[192:195], v[26:29]
	v_mfma_f32_16x16x32_bf16 v[22:25], v[176:179], v[200:203], v[22:25]
	v_mfma_f32_16x16x32_bf16 v[18:21], v[184:187], v[200:203], v[18:21]
	v_mfma_f32_16x16x32_bf16 v[14:17], v[176:179], v[208:211], v[14:17]
	v_mfma_f32_16x16x32_bf16 v[10:13], v[184:187], v[208:211], v[10:13]
	v_mfma_f32_16x16x32_bf16 v[6:9], v[176:179], v[216:219], v[6:9]
	v_mfma_f32_16x16x32_bf16 v[2:5], v[184:187], v[216:219], v[2:5]
	s_barrier
	s_add_i32 s79, 0, 0x18000
	s_add_i32 s80, 0, 0x1c000
	v_add_u32_e32 v168, s79, v152
	v_add_u32_e32 v184, s80, v152
	ds_read_b128 v[156:159], v168
	ds_read_b128 v[160:163], v168 offset:1024
	ds_read_b128 v[164:167], v168 offset:2048
	ds_read_b128 v[168:171], v168 offset:3072
	ds_read_b128 v[172:175], v184
	ds_read_b128 v[176:179], v184 offset:1024
	ds_read_b128 v[180:183], v184 offset:2048
	ds_read_b128 v[184:187], v184 offset:3072
	s_add_u32 s42, s42, 0xb0000
	s_addc_u32 s43, s43, 0
	s_mov_b32 m0, s57
	v_lshl_add_u64 v[226:227], s[42:43], 0, v[130:131]
	ds_read_b128 v[188:191], v154 offset:32768
	ds_read_b128 v[192:195], v154 offset:33792
	ds_read_b128 v[196:199], v154 offset:34816
	ds_read_b128 v[200:203], v154 offset:35840
	ds_read_b128 v[204:207], v154 offset:36864
	ds_read_b128 v[208:211], v154 offset:37888
	ds_read_b128 v[212:215], v154 offset:38912
	ds_read_b128 v[216:219], v154 offset:39936
	global_load_lds_dwordx4 v[226:227], off
	v_lshl_add_u64 v[226:227], s[42:43], 0, v[134:135]
	s_mov_b32 m0, s58
	s_nop 0
	global_load_lds_dwordx4 v[226:227], off
	s_waitcnt vmcnt(8)
	s_waitcnt lgkmcnt(0)
	s_barrier
	s_waitcnt lgkmcnt(0)
	v_mfma_f32_16x16x32_bf16 v[126:129], v[156:159], v[188:191], v[126:129]
	v_mfma_f32_16x16x32_bf16 v[122:125], v[164:167], v[188:191], v[122:125]
	v_mfma_f32_16x16x32_bf16 v[118:121], v[156:159], v[196:199], v[118:121]
	v_mfma_f32_16x16x32_bf16 v[114:117], v[164:167], v[196:199], v[114:117]
	v_mfma_f32_16x16x32_bf16 v[110:113], v[156:159], v[204:207], v[110:113]
	v_mfma_f32_16x16x32_bf16 v[106:109], v[164:167], v[204:207], v[106:109]
	v_mfma_f32_16x16x32_bf16 v[102:105], v[156:159], v[212:215], v[102:105]
	v_mfma_f32_16x16x32_bf16 v[98:101], v[164:167], v[212:215], v[98:101]
	v_mfma_f32_16x16x32_bf16 v[126:129], v[160:163], v[192:195], v[126:129]
	v_mfma_f32_16x16x32_bf16 v[122:125], v[168:171], v[192:195], v[122:125]
	v_mfma_f32_16x16x32_bf16 v[118:121], v[160:163], v[200:203], v[118:121]
	v_mfma_f32_16x16x32_bf16 v[114:117], v[168:171], v[200:203], v[114:117]
	v_mfma_f32_16x16x32_bf16 v[110:113], v[160:163], v[208:211], v[110:113]
	v_mfma_f32_16x16x32_bf16 v[106:109], v[168:171], v[208:211], v[106:109]
	v_mfma_f32_16x16x32_bf16 v[102:105], v[160:163], v[216:219], v[102:105]
	v_mfma_f32_16x16x32_bf16 v[98:101], v[168:171], v[216:219], v[98:101]
	v_mfma_f32_16x16x32_bf16 v[94:97], v[172:175], v[188:191], v[94:97]
	v_mfma_f32_16x16x32_bf16 v[90:93], v[180:183], v[188:191], v[90:93]
	v_mfma_f32_16x16x32_bf16 v[86:89], v[172:175], v[196:199], v[86:89]
	v_mfma_f32_16x16x32_bf16 v[82:85], v[180:183], v[196:199], v[82:85]
	v_mfma_f32_16x16x32_bf16 v[78:81], v[172:175], v[204:207], v[78:81]
	v_mfma_f32_16x16x32_bf16 v[74:77], v[180:183], v[204:207], v[74:77]
	v_mfma_f32_16x16x32_bf16 v[70:73], v[172:175], v[212:215], v[70:73]
	v_mfma_f32_16x16x32_bf16 v[66:69], v[180:183], v[212:215], v[66:69]
	v_mfma_f32_16x16x32_bf16 v[94:97], v[176:179], v[192:195], v[94:97]
	v_mfma_f32_16x16x32_bf16 v[90:93], v[184:187], v[192:195], v[90:93]
	v_mfma_f32_16x16x32_bf16 v[86:89], v[176:179], v[200:203], v[86:89]
	v_mfma_f32_16x16x32_bf16 v[82:85], v[184:187], v[200:203], v[82:85]
	v_mfma_f32_16x16x32_bf16 v[78:81], v[176:179], v[208:211], v[78:81]
	v_mfma_f32_16x16x32_bf16 v[74:77], v[184:187], v[208:211], v[74:77]
	v_mfma_f32_16x16x32_bf16 v[70:73], v[176:179], v[216:219], v[70:73]
	v_mfma_f32_16x16x32_bf16 v[66:69], v[184:187], v[216:219], v[66:69]
	s_barrier
; #define PG8_STAGEA(bufoff, gbase) PG8_STAGE_(bufoff, gbase, voffA)
; #define PG8_STAGEB(bufoff, gbase) PG8_STAGE_(bufoff, gbase, voffB)
; #define PG8_LDA(dst, b, h) do { _Pragma("unroll") for (int m = 0; m < 4; ++m) _Pragma("unroll") for (int k = 0; k < 2; ++k) dst[m][k] = *(const LAS bf16x8*)(lds + PG8_SA(b, h) + aoff + m * 2048 + k * 1024); } while (0)
; #define PG8_MMA(ai, bj, At, Bt_) do { __builtin_amdgcn_s_setprio(1); _Pragma("unroll") for (int m = 0; m < 4; ++m) _Pragma("unroll") for (int n = 0; n < 2; ++n) _Pragma("unroll") for (int k = 0; k < 2; ++k) \
;         acc[ai][bj][m][n] = __builtin_amdgcn_mfma_f32_16x16x32_bf16(Bt_[n][k], At[m][k], acc[ai][bj][m][n], 0, 0, 0); __builtin_amdgcn_s_setprio(0); } while (0)
; #define PG8_WAIT_V(n) asm volatile("s_waitcnt vmcnt(" #n ")" ::: "memory")
; #define PG8_WAIT_L(n) asm volatile("s_waitcnt lgkmcnt(" #n ")" ::: "memory")
; #define PG8_BAR __builtin_amdgcn_s_barrier()
; #define PG8_SCHED __builtin_amdgcn_sched_barrier(0)
; template <int EK, int SK = -1>
; __device__ __forceinline__ void gemm_phase(LAS unsigned char* lds, const bf16_t* A, const bf16_t* Bt, int nM, int N, int K, const EpiArgs& E) {
;     ...
;             PG8_LDA(At, 1, 1); PG8_STAGEB(PG8_SB(1, 0), b3); PG8_STAGEB(PG8_SB(1, 1), b3 + hstep); PG8_STAGEA(PG8_SA(1, 0), a3);
;             PG8_WAIT_V(8); PG8_WAIT_L(0); PG8_BAR; PG8_MMA(1, 0, At, B0); PG8_MMA(1, 1, At, B1); PG8_BAR; PG8_SCHED;
;         }
	s_add_i32 s42, s79, s54
	v_lshl_add_u64 v[150:151], v[150:151], 0, s[22:23]
	s_mov_b32 m0, s42
	ds_read_b128 v[188:191], v154 offset:49152
	ds_read_b128 v[192:195], v154 offset:50176
	ds_read_b128 v[196:199], v154 offset:51200
	ds_read_b128 v[200:203], v154 offset:52224
	ds_read_b128 v[204:207], v154 offset:53248
	ds_read_b128 v[208:211], v154 offset:54272
	ds_read_b128 v[212:215], v154 offset:55296
	ds_read_b128 v[216:219], v154 offset:56320
	global_load_lds_dwordx4 v[150:151], off
	s_add_i32 m0, s42, 0x2000
	s_add_u32 s40, s40, 0xb0080
	v_lshl_add_u64 v[150:151], v[220:221], 0, s[22:23]
	s_addc_u32 s41, s41, 0
	s_add_i32 s42, s80, s54
	global_load_lds_dwordx4 v[150:151], off
	v_lshl_add_u64 v[150:151], s[40:41], 0, v[132:133]
	s_mov_b32 m0, s42
	s_nop 0
	global_load_lds_dwordx4 v[150:151], off
	v_lshl_add_u64 v[150:151], s[40:41], 0, v[136:137]
	s_add_i32 m0, s42, 0x2000
	s_nop 0
	global_load_lds_dwordx4 v[150:151], off
	v_lshl_add_u64 v[150:151], v[222:223], 0, s[22:23]
	s_mov_b32 m0, s69
	s_nop 0
	global_load_lds_dwordx4 v[150:151], off
	v_lshl_add_u64 v[150:151], v[224:225], 0, s[22:23]
	s_mov_b32 m0, s70
	s_nop 0
	global_load_lds_dwordx4 v[150:151], off
	s_waitcnt vmcnt(8)
	s_waitcnt lgkmcnt(0)
	s_barrier
	s_waitcnt lgkmcnt(0)
	v_mfma_f32_16x16x32_bf16 v[62:65], v[156:159], v[188:191], v[62:65]
	v_mfma_f32_16x16x32_bf16 v[58:61], v[164:167], v[188:191], v[58:61]
	v_mfma_f32_16x16x32_bf16 v[54:57], v[156:159], v[196:199], v[54:57]
	v_mfma_f32_16x16x32_bf16 v[50:53], v[164:167], v[196:199], v[50:53]
	v_mfma_f32_16x16x32_bf16 v[46:49], v[156:159], v[204:207], v[46:49]
	v_mfma_f32_16x16x32_bf16 v[42:45], v[164:167], v[204:207], v[42:45]
	v_mfma_f32_16x16x32_bf16 v[38:41], v[156:159], v[212:215], v[38:41]
	v_mfma_f32_16x16x32_bf16 v[34:37], v[164:167], v[212:215], v[34:37]
	v_mfma_f32_16x16x32_bf16 v[62:65], v[160:163], v[192:195], v[62:65]
	v_mfma_f32_16x16x32_bf16 v[58:61], v[168:171], v[192:195], v[58:61]
	v_mfma_f32_16x16x32_bf16 v[54:57], v[160:163], v[200:203], v[54:57]
	v_mfma_f32_16x16x32_bf16 v[50:53], v[168:171], v[200:203], v[50:53]
	v_mfma_f32_16x16x32_bf16 v[46:49], v[160:163], v[208:211], v[46:49]
	v_mfma_f32_16x16x32_bf16 v[42:45], v[168:171], v[208:211], v[42:45]
	v_mfma_f32_16x16x32_bf16 v[38:41], v[160:163], v[216:219], v[38:41]
	v_mfma_f32_16x16x32_bf16 v[34:37], v[168:171], v[216:219], v[34:37]
	v_mfma_f32_16x16x32_bf16 v[30:33], v[172:175], v[188:191], v[30:33]
	v_mfma_f32_16x16x32_bf16 v[26:29], v[180:183], v[188:191], v[26:29]
	v_mfma_f32_16x16x32_bf16 v[22:25], v[172:175], v[196:199], v[22:25]
	v_mfma_f32_16x16x32_bf16 v[18:21], v[180:183], v[196:199], v[18:21]
	v_mfma_f32_16x16x32_bf16 v[14:17], v[172:175], v[204:207], v[14:17]
	v_mfma_f32_16x16x32_bf16 v[10:13], v[180:183], v[204:207], v[10:13]
	v_mfma_f32_16x16x32_bf16 v[6:9], v[172:175], v[212:215], v[6:9]
	v_mfma_f32_16x16x32_bf16 v[2:5], v[180:183], v[212:215], v[2:5]
	v_mfma_f32_16x16x32_bf16 v[30:33], v[176:179], v[192:195], v[30:33]
	v_mfma_f32_16x16x32_bf16 v[26:29], v[184:187], v[192:195], v[26:29]
	v_mfma_f32_16x16x32_bf16 v[22:25], v[176:179], v[200:203], v[22:25]
	v_mfma_f32_16x16x32_bf16 v[18:21], v[184:187], v[200:203], v[18:21]
	v_mfma_f32_16x16x32_bf16 v[14:17], v[176:179], v[208:211], v[14:17]
	v_mfma_f32_16x16x32_bf16 v[10:13], v[184:187], v[208:211], v[10:13]
	v_mfma_f32_16x16x32_bf16 v[6:9], v[176:179], v[216:219], v[6:9]
	v_mfma_f32_16x16x32_bf16 v[2:5], v[184:187], v[216:219], v[2:5]
	s_barrier
	s_add_i32 s20, s20, 2
	s_add_u32 s38, s38, 0x100
	s_addc_u32 s39, s39, 0
	s_cmp_gt_u32 s20, 41
	s_cbranch_scc0 .LBB0_793
	s_branch .Lmy_kexit_3

; #define PG8_BAR __builtin_amdgcn_s_barrier()
; template <int EK, int SK = -1>
; __device__ __forceinline__ void gemm_phase(LAS unsigned char* lds, const bf16_t* A, const bf16_t* Bt, int nM, int N, int K, const EpiArgs& E) {
;     ...
;         }
;         if (wr == 0) PG8_BAR;
;         if (EK != EK_FINAL) epi_tile<EK>(acc, cur, wr, wc, fr, fq, E, rtab + ui * 256);
.Lmy_kexit_3:
	s_and_b64 vcc, exec, s[26:27]
	s_cbranch_vccz .LBB0_796
	s_barrier

; __device__ __forceinline__ unsigned xb_ld(unsigned* p)              { return __hip_atomic_load(p, __ATOMIC_RELAXED, __HIP_MEMORY_SCOPE_AGENT); }
; __device__ __forceinline__ unsigned xb_add(unsigned* p, unsigned v) { return __hip_atomic_fetch_add(p, v, __ATOMIC_RELAXED, __HIP_MEMORY_SCOPE_AGENT); }
; #define XB_SPIN(cond, bar) do { unsigned _sp = 0; while (cond) { __builtin_amdgcn_s_sleep(1); \
;     if ((++_sp & 255u) == 0u) { if (xb_ld(&(bar)[XB_TMO])) break; if (_sp > XB_SPIN_CAP) { atomicAdd(&(bar)[XB_TMO], 1u); break; } } } } while (0)
; __device__ __forceinline__ void xcd_barrier(const XcdBarrier& b) {
;     asm volatile("s_waitcnt vmcnt(0)" ::: "memory");
;     __syncthreads();
;     if (threadIdx.x == 0) {
;         unsigned* bar = b.bar;
;         __builtin_amdgcn_s_waitcnt(0);
;         unsigned nloc = b.st[0], nx = b.st[1];
;         if (nloc == 0u) { xcd_barrier_complete(bar, b.x, nloc, nx); b.st[0] = nloc; b.st[1] = nx; }
;         const unsigned old = xb_add(&bar[XB_XSUB(b.x)], 1u);
;         const unsigned gen = old / nloc;
;         if (old + 1u == (gen + 1u) * nloc) {
;             __builtin_amdgcn_fence(__ATOMIC_RELEASE, "agent");
;             asm volatile("s_waitcnt vmcnt(0)" ::: "memory");
;             const unsigned og = xb_add(&bar[XB_TOP], 1u);
;             const unsigned tg = og / nx;
;             if (og + 1u == (tg + 1u) * nx) xb_add(&bar[XB_TOPGEN], 1u);
;             else XB_SPIN(xb_ld(&bar[XB_TOPGEN]) == tg, bar);
;             __builtin_amdgcn_fence(__ATOMIC_ACQUIRE, "agent");
;             asm volatile("s_waitcnt vmcnt(0)" ::: "memory");
;         } else {
;             XB_SPIN(xb_ld(&bar[XB_TOPGEN]) == gen, bar);
;             __builtin_amdgcn_fence(__ATOMIC_ACQUIRE, "agent");
;             asm volatile("s_waitcnt vmcnt(0)" ::: "memory");
.Lmy_noinv6:
	s_and_saveexec_b64 s[6:7], vcc
	s_cbranch_execz .LBB0_866
	s_waitcnt vmcnt(0) lgkmcnt(0)
	v_mov_b32_e32 v1, 0x20000
	ds_read2_b32 v[2:3], v1 offset1:1
	s_and_b32 s99, s33, 7
	s_lshl_b32 s99, s99, 8
	s_add_u32 s100, s60, 0xc000
	s_addc_u32 s101, s61, 0
	v_mov_b32_e32 v4, s99
	v_mov_b32_e32 v5, 1
	global_atomic_add v5, v4, v5, s[100:101] sc0
	s_waitcnt lgkmcnt(0)
	v_mul_u32_u24_e32 v6, 5, v2
	v_mul_u32_u24_e32 v7, 5, v3
	s_waitcnt vmcnt(0)
	v_add_u32_e32 v5, 1, v5
	v_cmp_eq_u32_e32 vcc, v5, v6
	s_cbranch_vccz .Lmy_nl5
	buffer_wbl2 sc1
	s_waitcnt vmcnt(0)
	v_mov_b32_e32 v4, 0x800
	v_mov_b32_e32 v5, 1
	global_atomic_add v4, v5, s[100:101]

; #define LAS __attribute__((address_space(3)))
; __device__ __forceinline__ float hsum4(f32x4 v) { return (v[0] + v[1]) + (v[2] + v[3]); }
; #define PG8_STAGEA(bufoff, gbase) PG8_STAGE_(bufoff, gbase, voffA)
; template <int EK, int SK = -1>
; __device__ __forceinline__ void gemm_phase(LAS unsigned char* lds, const bf16_t* A, const bf16_t* Bt, int nM, int N, int K, const EpiArgs& E) {
;     ...
;     f32x4 acc[2][2][4][2];
; #pragma unroll
;     for (int a = 0; a < 2; ++a)
; #pragma unroll
;         for (int b = 0; b < 2; ++b)
; #pragma unroll
;             for (int m = 0; m < 4; ++m)
; #pragma unroll
;                 for (int n = 0; n < 2; ++n) acc[a][b][m][n] = (f32x4){0.f, 0.f, 0.f, 0.f};
;     bf16x8 At[4][2], B0[2][2], B1[2][2];
;     const char* cA = (const char*)A + (size_t)cur.pm * tstep; const char* cB = (const char*)Bt + (size_t)cur.pn * tstep;
;     PG8_STAGEB(PG8_SB(0, 0), cB); PG8_STAGEB(PG8_SB(0, 1), cB + hstep); PG8_STAGEA(PG8_SA(0, 0), cA); PG8_STAGEA(PG8_SA(0, 1), cA + hstep);
;     f32x4 tq[4][4]; bool okq[4];
;     if (EK != EK_RES && EK != EK_FINAL) {
; #pragma unroll
;         for (int j = 0; j < 4; ++j) { Unit uu; okq[j] = S.next((tid >> 8) + 2 * j, uu);
;             if (okq[j]) { const f32x4* sp = (const f32x4*)(E.stIn + (size_t)(uu.pm * BM + (tid & 255)) * 16); tq[j][0] = sp[0]; tq[j][1] = sp[1]; tq[j][2] = sp[2]; tq[j][3] = sp[3]; } }
;     }
;     if (SK >= 0) skinny_phase<(SK >= 0 ? SK : 0)>(lds + 32768, (LAS float*)(lds + SRED_OFF), A, Bt, N, K, E);
;     if (EK != EK_RES && EK != EK_FINAL) {
; #pragma unroll
;         for (int j = 0; j < 4; ++j) if (okq[j]) { const float s_ = (hsum4(tq[j][0]) + hsum4(tq[j][1])) + (hsum4(tq[j][2]) + hsum4(tq[j][3]));
;             rtab[((tid >> 8) + 2 * j) * 256 + (tid & 255)] = rsqrtf(s_ * (1.0f / 1024.0f) + EPS); }
;         __syncthreads();
;     }
;     if (wr == 1) PG8_BAR;
;     PG8_WAIT_V(2); PG8_BAR;
;     PG8_STAGEB(PG8_SB(1, 0), cB + kstep); PG8_STAGEA(PG8_SA(1, 0), cA + kstep); PG8_STAGEB(PG8_SB(1, 1), cB + hstep + kstep);
;     PG8_WAIT_V(6); PG8_BAR;
;     ...
;         for (int a = 0; a < 2; ++a)
; #pragma unroll
;             for (int b = 0; b < 2; ++b)
; #pragma unroll
;                 for (int m = 0; m < 4; ++m)
; #pragma unroll
;                     for (int n = 0; n < 2; ++n) acc[a][b][m][n] = (f32x4){0.f, 0.f, 0.f, 0.f};
;         cur = nxt; cA = nA; cB = nB; ++ui;
.LBB0_920:
	v_bfe_u32 v4, v0, 4, 2
	v_lshlrev_b32_e32 v2, 4, v4
	v_lshlrev_b32_e32 v6, 2, v92
	v_lshl_or_b32 v3, v92, 6, v2
	s_lshl_b32 s5, s4, 13
	v_and_b32_e32 v7, 32, v6
	v_bitop3_b32 v7, v3, s5, v7 bitop3:0xde
	v_lshlrev_b32_e32 v3, 6, v0
	s_movk_i32 s5, 0x3c0
	s_and_b32 s59, s59, 3
	v_and_or_b32 v2, v3, s5, v2
	v_lshlrev_b32_e32 v3, 2, v0
	s_lshl_b32 s5, s59, 12
	v_and_b32_e32 v3, 32, v3
	s_mov_b64 s[16:17], 0x80
	v_bitop3_b32 v160, s5, v2, v3 bitop3:0xf6
	s_add_i32 m0, s23, 0x18000
	v_lshl_add_u64 v[2:3], v[76:77], 0, s[16:17]
	s_waitcnt vmcnt(2)
	s_barrier
	global_load_lds_dwordx4 v[2:3], off
	v_lshl_add_u64 v[2:3], v[74:75], 0, s[16:17]
	s_add_i32 m0, s23, 0x1a000
	s_add_i32 s80, s23, 0x8000
	s_add_i32 s81, s23, 0xa000
	global_load_lds_dwordx4 v[2:3], off
	v_lshl_add_u64 v[2:3], v[72:73], 0, s[16:17]
	s_mov_b32 m0, s80
	s_add_u32 s8, s76, 0x40080
	global_load_lds_dwordx4 v[2:3], off
	v_lshl_add_u64 v[2:3], v[70:71], 0, s[16:17]
	s_mov_b32 m0, s81
	s_addc_u32 s9, s77, 0
	global_load_lds_dwordx4 v[2:3], off
	s_add_i32 m0, s23, 0x1c000
	v_lshl_add_u64 v[2:3], s[8:9], 0, v[132:133]
	global_load_lds_dwordx4 v[2:3], off
	v_lshl_add_u64 v[2:3], s[8:9], 0, v[136:137]
	s_add_i32 m0, s23, 0x1e000
	v_lshl_or_b32 v1, s4, 6, v92
	global_load_lds_dwordx4 v[2:3], off
	s_lshl_b32 s4, s4, 8
	s_add_i32 s4, s4, 0
	s_add_i32 s4, s4, 0x20010
	v_lshlrev_b32_e32 v2, 8, v0
	v_lshlrev_b32_e32 v5, 3, v4
	v_add_u32_e32 v161, s4, v6
	v_cmp_eq_u32_e64 s[4:5], 0, v4
	v_and_b32_e32 v2, 0x18000, v2
	v_lshlrev_b32_e32 v4, 11, v90
	v_or3_b32 v2, v88, v2, v4
	s_mov_b64 s[6:7], 0x40080
	v_add_u32_e32 v2, v2, v89
	v_mov_b32_e32 v3, 0
	v_lshl_add_u64 v[138:139], v[2:3], 0, s[6:7]
	v_lshlrev_b32_e32 v2, 4, v91
	v_and_b32_e32 v2, 0x38000, v2
	v_or3_b32 v2, v88, v2, v4
	s_waitcnt vmcnt(6)
	v_add_u32_e32 v2, v2, v89
	s_cmpk_lt_u32 s70, 0x100
	v_lshl_add_u64 v[140:141], v[2:3], 0, s[6:7]
	v_mbcnt_lo_u32_b32 v2, -1, 0
	s_mov_b32 s15, 0
	v_lshl_or_b32 v162, s59, 5, v5
	s_cselect_b64 s[38:39], -1, 0
	v_mov_b64_e32 v[142:143], 0x200
	v_mov_b64_e32 v[144:145], 0x1ff
	s_add_i32 s82, 0, 0x10000
	s_add_i32 s83, 0, 0x14000
	v_add_u32_e32 v163, 0, v7
	s_mov_b32 s40, 0x3e6d3388
	s_mov_b32 s42, 0x3f07dc22
	s_mov_b32 s44, 0xbf3a00e3
	s_mov_b32 s52, 0x3f35f0e3
	s_mov_b32 s54, 0xbe11a98e
	s_mov_b32 s56, 0x3e027906
	s_mov_b32 s58, 0xbf38aa3b
	v_mbcnt_hi_u32_b32 v164, -1, v2
	s_mov_b32 s84, 0
	v_mov_b32_e32 v2, v3
	s_barrier
	s_branch .LBB0_922
.LBB0_921:
	v_mov_b32_e32 v2, 0
	s_mov_b32 s22, s70
	s_mov_b32 s26, s68
	v_mov_b32_e32 v3, v2
	s_mov_b64 s[36:37], s[74:75]
	s_mov_b32 s84, s85
	s_andn2_b64 vcc, exec, s[6:7]
	s_mov_b64 s[76:77], s[72:73]
	s_cbranch_vccz .LBB0_968

; #define PG8_STAGEA(bufoff, gbase) PG8_STAGE_(bufoff, gbase, voffA)
; #define PG8_STAGEB(bufoff, gbase) PG8_STAGE_(bufoff, gbase, voffB)
; #define PG8_LDA(dst, b, h) do { _Pragma("unroll") for (int m = 0; m < 4; ++m) _Pragma("unroll") for (int k = 0; k < 2; ++k) dst[m][k] = *(const LAS bf16x8*)(lds + PG8_SA(b, h) + aoff + m * 2048 + k * 1024); } while (0)
; #define PG8_LDB(dst, b, h) do { _Pragma("unroll") for (int n = 0; n < 2; ++n) _Pragma("unroll") for (int k = 0; k < 2; ++k) dst[n][k] = *(const LAS bf16x8*)(lds + PG8_SB(b, h) + boff + n * 2048 + k * 1024); } while (0)
; #define PG8_MMA(ai, bj, At, Bt_) do { __builtin_amdgcn_s_setprio(1); _Pragma("unroll") for (int m = 0; m < 4; ++m) _Pragma("unroll") for (int n = 0; n < 2; ++n) _Pragma("unroll") for (int k = 0; k < 2; ++k) \
;         acc[ai][bj][m][n] = __builtin_amdgcn_mfma_f32_16x16x32_bf16(Bt_[n][k], At[m][k], acc[ai][bj][m][n], 0, 0, 0); __builtin_amdgcn_s_setprio(0); } while (0)
; #define PG8_WAIT_V(n) asm volatile("s_waitcnt vmcnt(" #n ")" ::: "memory")
; #define PG8_WAIT_L(n) asm volatile("s_waitcnt lgkmcnt(" #n ")" ::: "memory")
; #define PG8_BAR __builtin_amdgcn_s_barrier()
; template <int EK, int SK = -1>
; __device__ __forceinline__ void gemm_phase(LAS unsigned char* lds, const bf16_t* A, const bf16_t* Bt, int nM, int N, int K, const EpiArgs& E) {
;     ...
;         const bool has_next = S.next(ui + 1, nxt);
;         const char* nA = has_next ? (const char*)A + (size_t)nxt.pm * tstep : cA; const char* nB = has_next ? (const char*)Bt + (size_t)nxt.pn * tstep : cB;
;         for (int t = 0; t < nt; t += 2) {
;             const bool last = (t == nt - 2);
;             const char* a1 = cA + (size_t)(t + 1) * kstep;
;             const char* a2 = last ? nA : cA + (size_t)(t + 2) * kstep; const char* b2 = last ? nB : cB + (size_t)(t + 2) * kstep;
;             const char* a3 = a2 + kstep; const char* b3 = b2 + kstep;
;             PG8_LDB(B0, 0, 0); PG8_LDB(B1, 0, 1); PG8_SCHED; PG8_LDA(At, 0, 0); PG8_STAGEA(PG8_SA(1, 1), a1 + hstep);
;             PG8_WAIT_V(8); PG8_WAIT_L(0); PG8_BAR; PG8_MMA(0, 0, At, B0); PG8_MMA(0, 1, At, B1); PG8_BAR; PG8_SCHED;
;             PG8_LDA(At, 0, 1); PG8_STAGEB(PG8_SB(0, 0), b2); PG8_STAGEB(PG8_SB(0, 1), b2 + hstep); PG8_STAGEA(PG8_SA(0, 0), a2);
;             PG8_WAIT_V(8); PG8_WAIT_L(0); PG8_BAR; PG8_MMA(1, 0, At, B0); PG8_MMA(1, 1, At, B1); PG8_BAR; PG8_SCHED;
.LBB0_928:
	s_add_u32 s86, s76, 0x100
	s_addc_u32 s87, s77, 0
	s_ashr_i32 s71, s70, 31
	s_lshl_b64 s[10:11], s[70:71], 19
	s_add_u32 s74, s62, s10
	s_addc_u32 s75, s63, s11
	s_and_b64 s[10:11], s[8:9], exec
	s_cselect_b32 s14, s75, s37
	s_cselect_b32 s71, s74, s36
	s_ashr_i32 s69, s68, 31
	s_lshl_b64 s[10:11], s[68:69], 19
	s_add_u32 s72, s43, s10
	s_addc_u32 s73, s45, s11
	s_and_b64 s[10:11], s[8:9], exec
	s_cselect_b32 s69, s73, s77
	s_cselect_b32 s88, s72, s76
	s_waitcnt lgkmcnt(0)
	v_lshl_add_u64 v[146:147], s[36:37], 0, v[138:139]
	v_lshl_add_u64 v[148:149], s[36:37], 0, v[140:141]
	s_mov_b32 s89, -2
	s_mov_b64 s[10:11], 0
	v_add_u32_e32 v158, s82, v160
	ds_read_b128 v[150:153], v158
	ds_read_b128 v[154:157], v158 offset:1024
	ds_read_b128 v[166:169], v158 offset:2048
	ds_read_b128 v[170:173], v158 offset:3072
	v_add_u32_e32 v158, s83, v160
	s_add_u32 s76, s36, s10
	ds_read_b128 v[174:177], v158
	ds_read_b128 v[178:181], v158 offset:1024
	ds_read_b128 v[182:185], v158 offset:2048
	ds_read_b128 v[186:189], v158 offset:3072
	s_addc_u32 s77, s37, s11
	s_add_u32 s76, s76, 0x100
	s_addc_u32 s77, s77, 0
	s_add_u32 s90, s86, s10
	s_addc_u32 s91, s87, s11
	s_cmpk_eq_i32 s10, 0x700
	s_cselect_b32 s79, s14, s77
	s_cselect_b32 s78, s71, s76
	s_cselect_b32 s77, s69, s91
	s_cselect_b32 s76, s88, s90
	v_lshl_add_u64 v[158:159], v[146:147], 0, s[10:11]
	s_add_i32 m0, s23, 0xc000
	ds_read_b128 v[190:193], v163
	ds_read_b128 v[194:197], v163 offset:1024
	ds_read_b128 v[198:201], v163 offset:2048
	ds_read_b128 v[202:205], v163 offset:3072
	ds_read_b128 v[206:209], v163 offset:4096
	ds_read_b128 v[210:213], v163 offset:5120
	ds_read_b128 v[214:217], v163 offset:6144
	ds_read_b128 v[218:221], v163 offset:7168
	global_load_lds_dwordx4 v[158:159], off
	v_lshl_add_u64 v[158:159], v[148:149], 0, s[10:11]
	s_add_i32 m0, s23, 0xe000
	s_nop 0
	global_load_lds_dwordx4 v[158:159], off
	s_waitcnt vmcnt(8)
	s_waitcnt lgkmcnt(0)
	s_barrier
	s_waitcnt lgkmcnt(0)
	v_mfma_f32_16x16x32_bf16 v[110:113], v[150:153], v[190:193], 0
	v_mfma_f32_16x16x32_bf16 v[106:109], v[166:169], v[190:193], 0
	v_mfma_f32_16x16x32_bf16 v[102:105], v[150:153], v[198:201], 0
	v_mfma_f32_16x16x32_bf16 v[98:101], v[166:169], v[198:201], 0
	v_mfma_f32_16x16x32_bf16 v[94:97], v[150:153], v[206:209], 0
	v_mfma_f32_16x16x32_bf16 v[90:93], v[166:169], v[206:209], 0
	v_mfma_f32_16x16x32_bf16 v[86:89], v[150:153], v[214:217], 0
	v_mfma_f32_16x16x32_bf16 v[82:85], v[166:169], v[214:217], 0
	v_mfma_f32_16x16x32_bf16 v[110:113], v[154:157], v[194:197], v[110:113]
	v_mfma_f32_16x16x32_bf16 v[106:109], v[170:173], v[194:197], v[106:109]
	v_mfma_f32_16x16x32_bf16 v[102:105], v[154:157], v[202:205], v[102:105]
	v_mfma_f32_16x16x32_bf16 v[98:101], v[170:173], v[202:205], v[98:101]
	v_mfma_f32_16x16x32_bf16 v[94:97], v[154:157], v[210:213], v[94:97]
	v_mfma_f32_16x16x32_bf16 v[90:93], v[170:173], v[210:213], v[90:93]
	v_mfma_f32_16x16x32_bf16 v[86:89], v[154:157], v[218:221], v[86:89]
	v_mfma_f32_16x16x32_bf16 v[82:85], v[170:173], v[218:221], v[82:85]
	v_mfma_f32_16x16x32_bf16 v[78:81], v[174:177], v[190:193], 0
	v_mfma_f32_16x16x32_bf16 v[74:77], v[182:185], v[190:193], 0
	v_mfma_f32_16x16x32_bf16 v[70:73], v[174:177], v[198:201], 0
	v_mfma_f32_16x16x32_bf16 v[66:69], v[182:185], v[198:201], 0
	v_mfma_f32_16x16x32_bf16 v[62:65], v[174:177], v[206:209], 0
	v_mfma_f32_16x16x32_bf16 v[58:61], v[182:185], v[206:209], 0
	v_mfma_f32_16x16x32_bf16 v[54:57], v[174:177], v[214:217], 0
	v_mfma_f32_16x16x32_bf16 v[50:53], v[182:185], v[214:217], 0
	v_mfma_f32_16x16x32_bf16 v[78:81], v[178:181], v[194:197], v[78:81]
	v_mfma_f32_16x16x32_bf16 v[74:77], v[186:189], v[194:197], v[74:77]
	v_mfma_f32_16x16x32_bf16 v[70:73], v[178:181], v[202:205], v[70:73]
	v_mfma_f32_16x16x32_bf16 v[66:69], v[186:189], v[202:205], v[66:69]
	v_mfma_f32_16x16x32_bf16 v[62:65], v[178:181], v[210:213], v[62:65]
	v_mfma_f32_16x16x32_bf16 v[58:61], v[186:189], v[210:213], v[58:61]
	v_mfma_f32_16x16x32_bf16 v[54:57], v[178:181], v[218:221], v[54:57]
	v_mfma_f32_16x16x32_bf16 v[50:53], v[186:189], v[218:221], v[50:53]
	s_barrier
	s_add_i32 s90, s82, s53
	v_lshl_add_u64 v[158:159], s[76:77], 0, v[132:133]
	s_mov_b32 m0, s90
	ds_read_b128 v[190:193], v163 offset:16384
	ds_read_b128 v[194:197], v163 offset:17408
	ds_read_b128 v[198:201], v163 offset:18432
	ds_read_b128 v[202:205], v163 offset:19456
	ds_read_b128 v[206:209], v163 offset:20480
	ds_read_b128 v[210:213], v163 offset:21504
	ds_read_b128 v[214:217], v163 offset:22528
	ds_read_b128 v[218:221], v163 offset:23552
	global_load_lds_dwordx4 v[158:159], off
	s_add_i32 m0, s90, 0x2000
	s_add_u32 s90, s76, 0x40000
	v_lshl_add_u64 v[222:223], s[76:77], 0, v[136:137]
	s_addc_u32 s91, s77, 0
	s_add_i32 s92, s83, s53
	global_load_lds_dwordx4 v[222:223], off
	v_lshl_add_u64 v[224:225], s[90:91], 0, v[132:133]
	s_mov_b32 m0, s92
	v_lshl_add_u64 v[226:227], s[78:79], 0, v[134:135]
	global_load_lds_dwordx4 v[224:225], off
	v_lshl_add_u64 v[224:225], s[90:91], 0, v[136:137]
	s_add_i32 m0, s92, 0x2000
	s_nop 0
	global_load_lds_dwordx4 v[224:225], off
	v_lshl_add_u64 v[224:225], s[78:79], 0, v[130:131]
	s_mov_b32 m0, s23
	s_nop 0
	global_load_lds_dwordx4 v[224:225], off
	s_mov_b32 m0, s27
	s_nop 0
	global_load_lds_dwordx4 v[226:227], off
	s_waitcnt vmcnt(8)
	s_waitcnt lgkmcnt(0)
	s_barrier
; #define PG8_STAGEA(bufoff, gbase) PG8_STAGE_(bufoff, gbase, voffA)
; #define PG8_STAGEB(bufoff, gbase) PG8_STAGE_(bufoff, gbase, voffB)
; #define PG8_LDA(dst, b, h) do { _Pragma("unroll") for (int m = 0; m < 4; ++m) _Pragma("unroll") for (int k = 0; k < 2; ++k) dst[m][k] = *(const LAS bf16x8*)(lds + PG8_SA(b, h) + aoff + m * 2048 + k * 1024); } while (0)
; #define PG8_LDB(dst, b, h) do { _Pragma("unroll") for (int n = 0; n < 2; ++n) _Pragma("unroll") for (int k = 0; k < 2; ++k) dst[n][k] = *(const LAS bf16x8*)(lds + PG8_SB(b, h) + boff + n * 2048 + k * 1024); } while (0)
; #define PG8_MMA(ai, bj, At, Bt_) do { __builtin_amdgcn_s_setprio(1); _Pragma("unroll") for (int m = 0; m < 4; ++m) _Pragma("unroll") for (int n = 0; n < 2; ++n) _Pragma("unroll") for (int k = 0; k < 2; ++k) \
;         acc[ai][bj][m][n] = __builtin_amdgcn_mfma_f32_16x16x32_bf16(Bt_[n][k], At[m][k], acc[ai][bj][m][n], 0, 0, 0); __builtin_amdgcn_s_setprio(0); } while (0)
; #define PG8_WAIT_V(n) asm volatile("s_waitcnt vmcnt(" #n ")" ::: "memory")
; #define PG8_WAIT_L(n) asm volatile("s_waitcnt lgkmcnt(" #n ")" ::: "memory")
; #define PG8_BAR __builtin_amdgcn_s_barrier()
; #define PG8_SCHED __builtin_amdgcn_sched_barrier(0)
; template <int EK, int SK = -1>
; __device__ __forceinline__ void gemm_phase(LAS unsigned char* lds, const bf16_t* A, const bf16_t* Bt, int nM, int N, int K, const EpiArgs& E) {
;     ...
;             PG8_WAIT_V(8); PG8_WAIT_L(0); PG8_BAR; PG8_MMA(1, 0, At, B0); PG8_MMA(1, 1, At, B1); PG8_BAR; PG8_SCHED;
;             PG8_LDB(B0, 1, 0); PG8_LDB(B1, 1, 1); PG8_SCHED; PG8_LDA(At, 1, 0); PG8_STAGEA(PG8_SA(0, 1), a2 + hstep);
;             PG8_WAIT_V(8); PG8_WAIT_L(0); PG8_BAR; PG8_MMA(0, 0, At, B0); PG8_MMA(0, 1, At, B1); PG8_BAR; PG8_SCHED;
;             PG8_LDA(At, 1, 1); PG8_STAGEB(PG8_SB(1, 0), b3); PG8_STAGEB(PG8_SB(1, 1), b3 + hstep); PG8_STAGEA(PG8_SA(1, 0), a3);
	s_waitcnt lgkmcnt(0)
	v_mfma_f32_16x16x32_bf16 v[46:49], v[150:153], v[190:193], 0
	v_mfma_f32_16x16x32_bf16 v[42:45], v[166:169], v[190:193], 0
	v_mfma_f32_16x16x32_bf16 v[38:41], v[150:153], v[198:201], 0
	v_mfma_f32_16x16x32_bf16 v[34:37], v[166:169], v[198:201], 0
	v_mfma_f32_16x16x32_bf16 v[30:33], v[150:153], v[206:209], 0
	v_mfma_f32_16x16x32_bf16 v[26:29], v[166:169], v[206:209], 0
	v_mfma_f32_16x16x32_bf16 v[22:25], v[150:153], v[214:217], 0
	v_mfma_f32_16x16x32_bf16 v[18:21], v[166:169], v[214:217], 0
	v_mfma_f32_16x16x32_bf16 v[46:49], v[154:157], v[194:197], v[46:49]
	v_mfma_f32_16x16x32_bf16 v[42:45], v[170:173], v[194:197], v[42:45]
	v_mfma_f32_16x16x32_bf16 v[38:41], v[154:157], v[202:205], v[38:41]
	v_mfma_f32_16x16x32_bf16 v[34:37], v[170:173], v[202:205], v[34:37]
	v_mfma_f32_16x16x32_bf16 v[30:33], v[154:157], v[210:213], v[30:33]
	v_mfma_f32_16x16x32_bf16 v[26:29], v[170:173], v[210:213], v[26:29]
	v_mfma_f32_16x16x32_bf16 v[22:25], v[154:157], v[218:221], v[22:25]
	v_mfma_f32_16x16x32_bf16 v[18:21], v[170:173], v[218:221], v[18:21]
	v_mfma_f32_16x16x32_bf16 v[14:17], v[174:177], v[190:193], 0
	v_mfma_f32_16x16x32_bf16 v[10:13], v[182:185], v[190:193], 0
	v_mfma_f32_16x16x32_bf16 v[6:9], v[174:177], v[198:201], 0
	v_mfma_f32_16x16x32_bf16 v[2:5], v[182:185], v[198:201], 0
	v_mfma_f32_16x16x32_bf16 v[114:117], v[174:177], v[206:209], 0
	v_mfma_f32_16x16x32_bf16 v[118:121], v[182:185], v[206:209], 0
	v_mfma_f32_16x16x32_bf16 v[122:125], v[174:177], v[214:217], 0
	v_mfma_f32_16x16x32_bf16 v[126:129], v[182:185], v[214:217], 0
	v_mfma_f32_16x16x32_bf16 v[14:17], v[178:181], v[194:197], v[14:17]
	v_mfma_f32_16x16x32_bf16 v[10:13], v[186:189], v[194:197], v[10:13]
	v_mfma_f32_16x16x32_bf16 v[6:9], v[178:181], v[202:205], v[6:9]
	v_mfma_f32_16x16x32_bf16 v[2:5], v[186:189], v[202:205], v[2:5]
	v_mfma_f32_16x16x32_bf16 v[114:117], v[178:181], v[210:213], v[114:117]
	v_mfma_f32_16x16x32_bf16 v[118:121], v[186:189], v[210:213], v[118:121]
	v_mfma_f32_16x16x32_bf16 v[122:125], v[178:181], v[218:221], v[122:125]
	v_mfma_f32_16x16x32_bf16 v[126:129], v[186:189], v[218:221], v[126:129]
	s_barrier
	s_add_i32 s90, 0, 0x18000
	v_add_u32_e32 v165, s90, v160
	s_add_i32 s91, 0, 0x1c000
	ds_read_b128 v[150:153], v165
	ds_read_b128 v[154:157], v165 offset:1024
	ds_read_b128 v[166:169], v165 offset:2048
	ds_read_b128 v[170:173], v165 offset:3072
	v_add_u32_e32 v165, s91, v160
	ds_read_b128 v[174:177], v165
	ds_read_b128 v[178:181], v165 offset:1024
	ds_read_b128 v[182:185], v165 offset:2048
	ds_read_b128 v[186:189], v165 offset:3072
	s_add_u32 s78, s78, 0x40000
	s_addc_u32 s79, s79, 0
	s_mov_b32 m0, s55
	v_lshl_add_u64 v[228:229], s[78:79], 0, v[130:131]
	ds_read_b128 v[190:193], v163 offset:32768
	ds_read_b128 v[194:197], v163 offset:33792
	ds_read_b128 v[198:201], v163 offset:34816
	ds_read_b128 v[202:205], v163 offset:35840
	ds_read_b128 v[206:209], v163 offset:36864
	ds_read_b128 v[210:213], v163 offset:37888
	ds_read_b128 v[214:217], v163 offset:38912
	ds_read_b128 v[218:221], v163 offset:39936
	global_load_lds_dwordx4 v[228:229], off
	v_lshl_add_u64 v[228:229], s[78:79], 0, v[134:135]
	s_mov_b32 m0, s57
	s_nop 0
	global_load_lds_dwordx4 v[228:229], off
	s_waitcnt vmcnt(8)
	s_waitcnt lgkmcnt(0)
	s_barrier
	s_waitcnt lgkmcnt(0)
	v_mfma_f32_16x16x32_bf16 v[110:113], v[150:153], v[190:193], v[110:113]
	v_mfma_f32_16x16x32_bf16 v[106:109], v[166:169], v[190:193], v[106:109]
	v_mfma_f32_16x16x32_bf16 v[102:105], v[150:153], v[198:201], v[102:105]
	v_mfma_f32_16x16x32_bf16 v[98:101], v[166:169], v[198:201], v[98:101]
	v_mfma_f32_16x16x32_bf16 v[94:97], v[150:153], v[206:209], v[94:97]
	v_mfma_f32_16x16x32_bf16 v[90:93], v[166:169], v[206:209], v[90:93]
	v_mfma_f32_16x16x32_bf16 v[86:89], v[150:153], v[214:217], v[86:89]
	v_mfma_f32_16x16x32_bf16 v[82:85], v[166:169], v[214:217], v[82:85]
	v_mfma_f32_16x16x32_bf16 v[110:113], v[154:157], v[194:197], v[110:113]
	v_mfma_f32_16x16x32_bf16 v[106:109], v[170:173], v[194:197], v[106:109]
	v_mfma_f32_16x16x32_bf16 v[102:105], v[154:157], v[202:205], v[102:105]
	v_mfma_f32_16x16x32_bf16 v[98:101], v[170:173], v[202:205], v[98:101]
	v_mfma_f32_16x16x32_bf16 v[94:97], v[154:157], v[210:213], v[94:97]
	v_mfma_f32_16x16x32_bf16 v[90:93], v[170:173], v[210:213], v[90:93]
	v_mfma_f32_16x16x32_bf16 v[86:89], v[154:157], v[218:221], v[86:89]
	v_mfma_f32_16x16x32_bf16 v[82:85], v[170:173], v[218:221], v[82:85]
	v_mfma_f32_16x16x32_bf16 v[78:81], v[174:177], v[190:193], v[78:81]
	v_mfma_f32_16x16x32_bf16 v[74:77], v[182:185], v[190:193], v[74:77]
	v_mfma_f32_16x16x32_bf16 v[70:73], v[174:177], v[198:201], v[70:73]
	v_mfma_f32_16x16x32_bf16 v[66:69], v[182:185], v[198:201], v[66:69]
	v_mfma_f32_16x16x32_bf16 v[62:65], v[174:177], v[206:209], v[62:65]
	v_mfma_f32_16x16x32_bf16 v[58:61], v[182:185], v[206:209], v[58:61]
	v_mfma_f32_16x16x32_bf16 v[54:57], v[174:177], v[214:217], v[54:57]
	v_mfma_f32_16x16x32_bf16 v[50:53], v[182:185], v[214:217], v[50:53]
	v_mfma_f32_16x16x32_bf16 v[78:81], v[178:181], v[194:197], v[78:81]
	v_mfma_f32_16x16x32_bf16 v[74:77], v[186:189], v[194:197], v[74:77]
	v_mfma_f32_16x16x32_bf16 v[70:73], v[178:181], v[202:205], v[70:73]
	v_mfma_f32_16x16x32_bf16 v[66:69], v[186:189], v[202:205], v[66:69]
	v_mfma_f32_16x16x32_bf16 v[62:65], v[178:181], v[210:213], v[62:65]
	v_mfma_f32_16x16x32_bf16 v[58:61], v[186:189], v[210:213], v[58:61]
	v_mfma_f32_16x16x32_bf16 v[54:57], v[178:181], v[218:221], v[54:57]
	v_mfma_f32_16x16x32_bf16 v[50:53], v[186:189], v[218:221], v[50:53]
	s_barrier
; #define PG8_STAGEA(bufoff, gbase) PG8_STAGE_(bufoff, gbase, voffA)
; #define PG8_STAGEB(bufoff, gbase) PG8_STAGE_(bufoff, gbase, voffB)
; #define PG8_LDA(dst, b, h) do { _Pragma("unroll") for (int m = 0; m < 4; ++m) _Pragma("unroll") for (int k = 0; k < 2; ++k) dst[m][k] = *(const LAS bf16x8*)(lds + PG8_SA(b, h) + aoff + m * 2048 + k * 1024); } while (0)
; #define PG8_MMA(ai, bj, At, Bt_) do { __builtin_amdgcn_s_setprio(1); _Pragma("unroll") for (int m = 0; m < 4; ++m) _Pragma("unroll") for (int n = 0; n < 2; ++n) _Pragma("unroll") for (int k = 0; k < 2; ++k) \
;         acc[ai][bj][m][n] = __builtin_amdgcn_mfma_f32_16x16x32_bf16(Bt_[n][k], At[m][k], acc[ai][bj][m][n], 0, 0, 0); __builtin_amdgcn_s_setprio(0); } while (0)
; #define PG8_WAIT_V(n) asm volatile("s_waitcnt vmcnt(" #n ")" ::: "memory")
; #define PG8_WAIT_L(n) asm volatile("s_waitcnt lgkmcnt(" #n ")" ::: "memory")
; #define PG8_BAR __builtin_amdgcn_s_barrier()
; #define PG8_SCHED __builtin_amdgcn_sched_barrier(0)
; template <int EK, int SK = -1>
; __device__ __forceinline__ void gemm_phase(LAS unsigned char* lds, const bf16_t* A, const bf16_t* Bt, int nM, int N, int K, const EpiArgs& E) {
;     ...
;             PG8_LDA(At, 1, 1); PG8_STAGEB(PG8_SB(1, 0), b3); PG8_STAGEB(PG8_SB(1, 1), b3 + hstep); PG8_STAGEA(PG8_SA(1, 0), a3);
;             PG8_WAIT_V(8); PG8_WAIT_L(0); PG8_BAR; PG8_MMA(1, 0, At, B0); PG8_MMA(1, 1, At, B1); PG8_BAR; PG8_SCHED;
;         }
	s_add_i32 s78, s90, s53
	v_lshl_add_u64 v[158:159], v[158:159], 0, s[16:17]
	s_mov_b32 m0, s78
	ds_read_b128 v[190:193], v163 offset:49152
	ds_read_b128 v[194:197], v163 offset:50176
	ds_read_b128 v[198:201], v163 offset:51200
	ds_read_b128 v[202:205], v163 offset:52224
	ds_read_b128 v[206:209], v163 offset:53248
	ds_read_b128 v[210:213], v163 offset:54272
	ds_read_b128 v[214:217], v163 offset:55296
	ds_read_b128 v[218:221], v163 offset:56320
	global_load_lds_dwordx4 v[158:159], off
	s_add_i32 m0, s78, 0x2000
	s_add_u32 s76, s76, 0x40080
	v_lshl_add_u64 v[158:159], v[222:223], 0, s[16:17]
	s_addc_u32 s77, s77, 0
	s_add_i32 s78, s91, s53
	global_load_lds_dwordx4 v[158:159], off
	v_lshl_add_u64 v[158:159], s[76:77], 0, v[132:133]
	s_mov_b32 m0, s78
	s_nop 0
	global_load_lds_dwordx4 v[158:159], off
	v_lshl_add_u64 v[158:159], s[76:77], 0, v[136:137]
	s_add_i32 m0, s78, 0x2000
	s_nop 0
	global_load_lds_dwordx4 v[158:159], off
	v_lshl_add_u64 v[158:159], v[224:225], 0, s[16:17]
	s_mov_b32 m0, s80
	s_nop 0
	global_load_lds_dwordx4 v[158:159], off
	v_lshl_add_u64 v[158:159], v[226:227], 0, s[16:17]
	s_mov_b32 m0, s81
	s_nop 0
	global_load_lds_dwordx4 v[158:159], off
	s_waitcnt vmcnt(8)
	s_waitcnt lgkmcnt(0)
	s_barrier
	s_waitcnt lgkmcnt(0)
	v_mfma_f32_16x16x32_bf16 v[46:49], v[150:153], v[190:193], v[46:49]
	v_mfma_f32_16x16x32_bf16 v[42:45], v[166:169], v[190:193], v[42:45]
	v_mfma_f32_16x16x32_bf16 v[38:41], v[150:153], v[198:201], v[38:41]
	v_mfma_f32_16x16x32_bf16 v[34:37], v[166:169], v[198:201], v[34:37]
	v_mfma_f32_16x16x32_bf16 v[30:33], v[150:153], v[206:209], v[30:33]
	v_mfma_f32_16x16x32_bf16 v[26:29], v[166:169], v[206:209], v[26:29]
	v_mfma_f32_16x16x32_bf16 v[22:25], v[150:153], v[214:217], v[22:25]
	v_mfma_f32_16x16x32_bf16 v[18:21], v[166:169], v[214:217], v[18:21]
	v_mfma_f32_16x16x32_bf16 v[46:49], v[154:157], v[194:197], v[46:49]
	v_mfma_f32_16x16x32_bf16 v[42:45], v[170:173], v[194:197], v[42:45]
	v_mfma_f32_16x16x32_bf16 v[38:41], v[154:157], v[202:205], v[38:41]
	v_mfma_f32_16x16x32_bf16 v[34:37], v[170:173], v[202:205], v[34:37]
	v_mfma_f32_16x16x32_bf16 v[30:33], v[154:157], v[210:213], v[30:33]
	v_mfma_f32_16x16x32_bf16 v[26:29], v[170:173], v[210:213], v[26:29]
	v_mfma_f32_16x16x32_bf16 v[22:25], v[154:157], v[218:221], v[22:25]
	v_mfma_f32_16x16x32_bf16 v[18:21], v[170:173], v[218:221], v[18:21]
	v_mfma_f32_16x16x32_bf16 v[14:17], v[174:177], v[190:193], v[14:17]
	v_mfma_f32_16x16x32_bf16 v[10:13], v[182:185], v[190:193], v[10:13]
	v_mfma_f32_16x16x32_bf16 v[6:9], v[174:177], v[198:201], v[6:9]
	v_mfma_f32_16x16x32_bf16 v[2:5], v[182:185], v[198:201], v[2:5]
	v_mfma_f32_16x16x32_bf16 v[114:117], v[174:177], v[206:209], v[114:117]
	v_mfma_f32_16x16x32_bf16 v[118:121], v[182:185], v[206:209], v[118:121]
	v_mfma_f32_16x16x32_bf16 v[122:125], v[174:177], v[214:217], v[122:125]
	v_mfma_f32_16x16x32_bf16 v[126:129], v[182:185], v[214:217], v[126:129]
	v_mfma_f32_16x16x32_bf16 v[14:17], v[178:181], v[194:197], v[14:17]
	v_mfma_f32_16x16x32_bf16 v[10:13], v[186:189], v[194:197], v[10:13]
	v_mfma_f32_16x16x32_bf16 v[6:9], v[178:181], v[202:205], v[6:9]
	v_mfma_f32_16x16x32_bf16 v[2:5], v[186:189], v[202:205], v[2:5]
	v_mfma_f32_16x16x32_bf16 v[114:117], v[178:181], v[210:213], v[114:117]
	v_mfma_f32_16x16x32_bf16 v[118:121], v[186:189], v[210:213], v[118:121]
	v_mfma_f32_16x16x32_bf16 v[122:125], v[178:181], v[218:221], v[122:125]
	v_mfma_f32_16x16x32_bf16 v[126:129], v[186:189], v[218:221], v[126:129]
	s_barrier
	s_add_i32 s89, s89, 2
	s_add_u32 s10, s10, 0x100
	s_addc_u32 s11, s11, 0
	s_cmp_gt_u32 s89, 13
	s_cbranch_scc0 .LBB0_929
	s_branch .Lmy_kexit_4

; #define PG8_BAR __builtin_amdgcn_s_barrier()
; template <int EK, int SK = -1>
; __device__ __forceinline__ void gemm_phase(LAS unsigned char* lds, const bf16_t* A, const bf16_t* Bt, int nM, int N, int K, const EpiArgs& E) {
;     ...
;         }
;         if (wr == 0) PG8_BAR;
;         if (EK != EK_FINAL) epi_tile<EK>(acc, cur, wr, wc, fr, fq, E, rtab + ui * 256);
.Lmy_kexit_4:
	s_and_b64 vcc, exec, s[38:39]
	s_cbranch_vccz .LBB0_932
	s_barrier

; __device__ __forceinline__ unsigned xb_ld(unsigned* p)              { return __hip_atomic_load(p, __ATOMIC_RELAXED, __HIP_MEMORY_SCOPE_AGENT); }
; __device__ __forceinline__ unsigned xb_add(unsigned* p, unsigned v) { return __hip_atomic_fetch_add(p, v, __ATOMIC_RELAXED, __HIP_MEMORY_SCOPE_AGENT); }
; #define XB_SPIN(cond, bar) do { unsigned _sp = 0; while (cond) { __builtin_amdgcn_s_sleep(1); \
;     if ((++_sp & 255u) == 0u) { if (xb_ld(&(bar)[XB_TMO])) break; if (_sp > XB_SPIN_CAP) { atomicAdd(&(bar)[XB_TMO], 1u); break; } } } } while (0)
; __device__ __forceinline__ void xcd_barrier(const XcdBarrier& b) {
;     asm volatile("s_waitcnt vmcnt(0)" ::: "memory");
;     __syncthreads();
;     if (threadIdx.x == 0) {
;         unsigned* bar = b.bar;
;         __builtin_amdgcn_s_waitcnt(0);
;         unsigned nloc = b.st[0], nx = b.st[1];
;         if (nloc == 0u) { xcd_barrier_complete(bar, b.x, nloc, nx); b.st[0] = nloc; b.st[1] = nx; }
;         const unsigned old = xb_add(&bar[XB_XSUB(b.x)], 1u);
;         const unsigned gen = old / nloc;
;         if (old + 1u == (gen + 1u) * nloc) {
;             __builtin_amdgcn_fence(__ATOMIC_RELEASE, "agent");
;             asm volatile("s_waitcnt vmcnt(0)" ::: "memory");
;             const unsigned og = xb_add(&bar[XB_TOP], 1u);
;             const unsigned tg = og / nx;
;             if (og + 1u == (tg + 1u) * nx) xb_add(&bar[XB_TOPGEN], 1u);
;             else XB_SPIN(xb_ld(&bar[XB_TOPGEN]) == tg, bar);
;             __builtin_amdgcn_fence(__ATOMIC_ACQUIRE, "agent");
;             asm volatile("s_waitcnt vmcnt(0)" ::: "memory");
;         } else {
;             XB_SPIN(xb_ld(&bar[XB_TOPGEN]) == gen, bar);
;             __builtin_amdgcn_fence(__ATOMIC_ACQUIRE, "agent");
;             asm volatile("s_waitcnt vmcnt(0)" ::: "memory");
.Lmy_noinv7:
	s_and_saveexec_b64 s[6:7], vcc
	s_cbranch_execz .LBB0_1018
	s_waitcnt vmcnt(0) lgkmcnt(0)
	v_mov_b32_e32 v1, 0x20000
	ds_read2_b32 v[2:3], v1 offset1:1
	s_and_b32 s99, s33, 7
	s_lshl_b32 s99, s99, 8
	s_add_u32 s100, s60, 0xc000
	s_addc_u32 s101, s61, 0
	v_mov_b32_e32 v4, s99
	v_mov_b32_e32 v5, 1
	global_atomic_add v5, v4, v5, s[100:101] sc0
	s_waitcnt lgkmcnt(0)
	v_mul_u32_u24_e32 v6, 6, v2
	v_mul_u32_u24_e32 v7, 6, v3
	s_waitcnt vmcnt(0)
	v_add_u32_e32 v5, 1, v5
	v_cmp_eq_u32_e32 vcc, v5, v6
	s_cbranch_vccz .Lmy_nl6
	buffer_wbl2 sc1
	s_waitcnt vmcnt(0)
	v_mov_b32_e32 v4, 0x800
	v_mov_b32_e32 v5, 1
	global_atomic_add v4, v5, s[100:101]

; __device__ __forceinline__ unsigned xb_ld(unsigned* p)              { return __hip_atomic_load(p, __ATOMIC_RELAXED, __HIP_MEMORY_SCOPE_AGENT); }
; __device__ __forceinline__ unsigned xb_add(unsigned* p, unsigned v) { return __hip_atomic_fetch_add(p, v, __ATOMIC_RELAXED, __HIP_MEMORY_SCOPE_AGENT); }
; #define XB_SPIN(cond, bar) do { unsigned _sp = 0; while (cond) { __builtin_amdgcn_s_sleep(1); \
;     if ((++_sp & 255u) == 0u) { if (xb_ld(&(bar)[XB_TMO])) break; if (_sp > XB_SPIN_CAP) { atomicAdd(&(bar)[XB_TMO], 1u); break; } } } } while (0)
; __device__ __forceinline__ void xcd_barrier(const XcdBarrier& b) {
;     asm volatile("s_waitcnt vmcnt(0)" ::: "memory");
;     __syncthreads();
;     if (threadIdx.x == 0) {
;         unsigned* bar = b.bar;
;         __builtin_amdgcn_s_waitcnt(0);
;         unsigned nloc = b.st[0], nx = b.st[1];
;         if (nloc == 0u) { xcd_barrier_complete(bar, b.x, nloc, nx); b.st[0] = nloc; b.st[1] = nx; }
;         const unsigned old = xb_add(&bar[XB_XSUB(b.x)], 1u);
;         const unsigned gen = old / nloc;
;         if (old + 1u == (gen + 1u) * nloc) {
;             __builtin_amdgcn_fence(__ATOMIC_RELEASE, "agent");
;             asm volatile("s_waitcnt vmcnt(0)" ::: "memory");
;             const unsigned og = xb_add(&bar[XB_TOP], 1u);
;             const unsigned tg = og / nx;
;             if (og + 1u == (tg + 1u) * nx) xb_add(&bar[XB_TOPGEN], 1u);
;             else XB_SPIN(xb_ld(&bar[XB_TOPGEN]) == tg, bar);
;             __builtin_amdgcn_fence(__ATOMIC_ACQUIRE, "agent");
;             asm volatile("s_waitcnt vmcnt(0)" ::: "memory");
;         } else {
;             XB_SPIN(xb_ld(&bar[XB_TOPGEN]) == gen, bar);
;             __builtin_amdgcn_fence(__ATOMIC_ACQUIRE, "agent");
;             asm volatile("s_waitcnt vmcnt(0)" ::: "memory");
.Lmy_noinv8:
	s_and_saveexec_b64 s[6:7], vcc
	s_cbranch_execz .LBB0_1089
	s_waitcnt vmcnt(0) lgkmcnt(0)
	v_mov_b32_e32 v1, 0x20000
	ds_read2_b32 v[2:3], v1 offset1:1
	s_and_b32 s99, s33, 7
	s_lshl_b32 s99, s99, 8
	s_add_u32 s100, s60, 0xc000
	s_addc_u32 s101, s61, 0
	v_mov_b32_e32 v4, s99
	v_mov_b32_e32 v5, 1
	global_atomic_add v5, v4, v5, s[100:101] sc0
	s_waitcnt lgkmcnt(0)
	v_mul_u32_u24_e32 v6, 7, v2
	v_mul_u32_u24_e32 v7, 7, v3
	s_waitcnt vmcnt(0)
	v_add_u32_e32 v5, 1, v5
	v_cmp_eq_u32_e32 vcc, v5, v6
	s_cbranch_vccz .Lmy_nl7
	buffer_wbl2 sc1
	s_waitcnt vmcnt(0)
	v_mov_b32_e32 v4, 0x800
	v_mov_b32_e32 v5, 1
	global_atomic_add v4, v5, s[100:101]

; #define LAS __attribute__((address_space(3)))
; __device__ __forceinline__ float hsum4(f32x4 v) { return (v[0] + v[1]) + (v[2] + v[3]); }
; #define PG8_STAGEA(bufoff, gbase) PG8_STAGE_(bufoff, gbase, voffA)
; template <int EK, int SK = -1>
; __device__ __forceinline__ void gemm_phase(LAS unsigned char* lds, const bf16_t* A, const bf16_t* Bt, int nM, int N, int K, const EpiArgs& E) {
;     ...
;     f32x4 acc[2][2][4][2];
; #pragma unroll
;     for (int a = 0; a < 2; ++a)
; #pragma unroll
;         for (int b = 0; b < 2; ++b)
; #pragma unroll
;             for (int m = 0; m < 4; ++m)
; #pragma unroll
;                 for (int n = 0; n < 2; ++n) acc[a][b][m][n] = (f32x4){0.f, 0.f, 0.f, 0.f};
;     bf16x8 At[4][2], B0[2][2], B1[2][2];
;     const char* cA = (const char*)A + (size_t)cur.pm * tstep; const char* cB = (const char*)Bt + (size_t)cur.pn * tstep;
;     PG8_STAGEB(PG8_SB(0, 0), cB); PG8_STAGEB(PG8_SB(0, 1), cB + hstep); PG8_STAGEA(PG8_SA(0, 0), cA); PG8_STAGEA(PG8_SA(0, 1), cA + hstep);
;     f32x4 tq[4][4]; bool okq[4];
;     if (EK != EK_RES && EK != EK_FINAL) {
; #pragma unroll
;         for (int j = 0; j < 4; ++j) { Unit uu; okq[j] = S.next((tid >> 8) + 2 * j, uu);
;             if (okq[j]) { const f32x4* sp = (const f32x4*)(E.stIn + (size_t)(uu.pm * BM + (tid & 255)) * 16); tq[j][0] = sp[0]; tq[j][1] = sp[1]; tq[j][2] = sp[2]; tq[j][3] = sp[3]; } }
;     }
;     if (SK >= 0) skinny_phase<(SK >= 0 ? SK : 0)>(lds + 32768, (LAS float*)(lds + SRED_OFF), A, Bt, N, K, E);
;     if (EK != EK_RES && EK != EK_FINAL) {
; #pragma unroll
;         for (int j = 0; j < 4; ++j) if (okq[j]) { const float s_ = (hsum4(tq[j][0]) + hsum4(tq[j][1])) + (hsum4(tq[j][2]) + hsum4(tq[j][3]));
;             rtab[((tid >> 8) + 2 * j) * 256 + (tid & 255)] = rsqrtf(s_ * (1.0f / 1024.0f) + EPS); }
;         __syncthreads();
;     }
;     if (wr == 1) PG8_BAR;
;     PG8_WAIT_V(2); PG8_BAR;
;     PG8_STAGEB(PG8_SB(1, 0), cB + kstep); PG8_STAGEA(PG8_SA(1, 0), cA + kstep); PG8_STAGEB(PG8_SB(1, 1), cB + hstep + kstep);
;     PG8_WAIT_V(6); PG8_BAR;
;     ...
;         for (int a = 0; a < 2; ++a)
; #pragma unroll
;             for (int b = 0; b < 2; ++b)
; #pragma unroll
;                 for (int m = 0; m < 4; ++m)
; #pragma unroll
;                     for (int n = 0; n < 2; ++n) acc[a][b][m][n] = (f32x4){0.f, 0.f, 0.f, 0.f};
;         cur = nxt; cA = nA; cB = nB; ++ui;
.LBB0_1111:
	v_bfe_u32 v10, v0, 4, 2
	v_lshlrev_b32_e32 v12, 4, v10
	v_lshl_or_b32 v1, s4, 6, v18
	v_lshl_or_b32 v13, v18, 6, v12
	v_lshlrev_b32_e32 v18, 2, v18
	s_lshl_b32 s4, s4, 13
	v_and_b32_e32 v18, 32, v18
	v_bitop3_b32 v13, v13, s4, v18 bitop3:0xde
	v_lshlrev_b32_e32 v18, 6, v0
	s_movk_i32 s4, 0x3c0
	s_mov_b64 s[26:27], 0x80
	s_and_b32 s57, s37, 3
	v_and_or_b32 v12, v18, s4, v12
	v_lshlrev_b32_e32 v18, 2, v0
	s_add_i32 m0, s15, 0x18000
	v_lshl_add_u64 v[8:9], v[8:9], 0, s[26:27]
	s_lshl_b32 s4, s57, 12
	v_and_b32_e32 v18, 32, v18
	s_ashr_i32 s58, s2, 31
	s_waitcnt vmcnt(2)
	s_barrier
	global_load_lds_dwordx4 v[8:9], off
	v_lshl_add_u64 v[6:7], v[6:7], 0, s[26:27]
	s_add_i32 m0, s15, 0x1a000
	s_add_i32 s59, s15, 0x8000
	s_add_i32 s68, s15, 0xa000
	v_bitop3_b32 v152, s4, v12, v18 bitop3:0xf6
	global_load_lds_dwordx4 v[6:7], off
	v_lshl_add_u64 v[2:3], v[2:3], 0, s[26:27]
	s_mov_b32 m0, s59
	s_add_u32 s4, s46, 0x40080
	global_load_lds_dwordx4 v[2:3], off
	v_lshl_add_u64 v[2:3], v[4:5], 0, s[26:27]
	s_mov_b32 m0, s68
	s_addc_u32 s5, s47, 0
	global_load_lds_dwordx4 v[2:3], off
	s_add_i32 m0, s15, 0x1c000
	v_lshl_add_u64 v[2:3], s[4:5], 0, v[132:133]
	global_load_lds_dwordx4 v[2:3], off
	v_lshl_add_u64 v[2:3], s[4:5], 0, v[136:137]
	s_add_i32 m0, s15, 0x1e000
	v_lshlrev_b32_e32 v4, 11, v16
	global_load_lds_dwordx4 v[2:3], off
	v_lshlrev_b32_e32 v2, 8, v0
	v_and_b32_e32 v2, 0x18000, v2
	v_or3_b32 v2, v14, v2, v4
	s_mov_b64 s[6:7], 0x40080
	v_add_u32_e32 v2, v2, v15
	v_mov_b32_e32 v3, 0
	v_lshl_add_u64 v[138:139], v[2:3], 0, s[6:7]
	v_lshlrev_b32_e32 v2, 4, v17
	v_and_b32_e32 v2, 0x38000, v2
	v_or3_b32 v2, v14, v2, v4
	s_waitcnt vmcnt(6)
	v_add_u32_e32 v2, v2, v15
	v_lshlrev_b32_e32 v11, 3, v10
	s_cmpk_lt_u32 s36, 0x100
	v_lshl_add_u64 v[140:141], v[2:3], 0, s[6:7]
	v_mbcnt_lo_u32_b32 v2, -1, 0
	s_mov_b32 s23, 0
	v_lshl_or_b32 v153, s57, 5, v11
	s_cselect_b64 s[36:37], -1, 0
	v_cmp_eq_u32_e64 s[4:5], 0, v10
	v_mov_b64_e32 v[142:143], 0x100
	v_mov_b64_e32 v[144:145], 0xff
	s_add_i32 s69, 0, 0x10000
	s_add_i32 s70, 0, 0x14000
	v_add_u32_e32 v154, 0, v13
	v_mbcnt_hi_u32_b32 v155, -1, v2
	s_mov_b32 s71, 0
	v_mov_b32_e32 v2, v3
	s_barrier
	s_branch .LBB0_1113
.LBB0_1112:
	v_mov_b32_e32 v2, 0
	s_mov_b32 s16, s38
	s_mov_b32 s14, s40
	v_mov_b32_e32 v3, v2
	s_mov_b64 s[18:19], s[44:45]
	s_mov_b32 s71, s72
	s_andn2_b64 vcc, exec, s[6:7]
	s_mov_b64 s[46:47], s[42:43]
	s_cbranch_vccz .LBB0_1143

; #define PG8_STAGEA(bufoff, gbase) PG8_STAGE_(bufoff, gbase, voffA)
; #define PG8_STAGEB(bufoff, gbase) PG8_STAGE_(bufoff, gbase, voffB)
; #define PG8_LDA(dst, b, h) do { _Pragma("unroll") for (int m = 0; m < 4; ++m) _Pragma("unroll") for (int k = 0; k < 2; ++k) dst[m][k] = *(const LAS bf16x8*)(lds + PG8_SA(b, h) + aoff + m * 2048 + k * 1024); } while (0)
; #define PG8_LDB(dst, b, h) do { _Pragma("unroll") for (int n = 0; n < 2; ++n) _Pragma("unroll") for (int k = 0; k < 2; ++k) dst[n][k] = *(const LAS bf16x8*)(lds + PG8_SB(b, h) + boff + n * 2048 + k * 1024); } while (0)
; #define PG8_MMA(ai, bj, At, Bt_) do { __builtin_amdgcn_s_setprio(1); _Pragma("unroll") for (int m = 0; m < 4; ++m) _Pragma("unroll") for (int n = 0; n < 2; ++n) _Pragma("unroll") for (int k = 0; k < 2; ++k) \
;         acc[ai][bj][m][n] = __builtin_amdgcn_mfma_f32_16x16x32_bf16(Bt_[n][k], At[m][k], acc[ai][bj][m][n], 0, 0, 0); __builtin_amdgcn_s_setprio(0); } while (0)
; #define PG8_WAIT_V(n) asm volatile("s_waitcnt vmcnt(" #n ")" ::: "memory")
; #define PG8_WAIT_L(n) asm volatile("s_waitcnt lgkmcnt(" #n ")" ::: "memory")
; #define PG8_BAR __builtin_amdgcn_s_barrier()
; template <int EK, int SK = -1>
; __device__ __forceinline__ void gemm_phase(LAS unsigned char* lds, const bf16_t* A, const bf16_t* Bt, int nM, int N, int K, const EpiArgs& E) {
;     ...
;         const bool has_next = S.next(ui + 1, nxt);
;         const char* nA = has_next ? (const char*)A + (size_t)nxt.pm * tstep : cA; const char* nB = has_next ? (const char*)Bt + (size_t)nxt.pn * tstep : cB;
;         for (int t = 0; t < nt; t += 2) {
;             const bool last = (t == nt - 2);
;             const char* a1 = cA + (size_t)(t + 1) * kstep;
;             const char* a2 = last ? nA : cA + (size_t)(t + 2) * kstep; const char* b2 = last ? nB : cB + (size_t)(t + 2) * kstep;
;             const char* a3 = a2 + kstep; const char* b3 = b2 + kstep;
;             PG8_LDB(B0, 0, 0); PG8_LDB(B1, 0, 1); PG8_SCHED; PG8_LDA(At, 0, 0); PG8_STAGEA(PG8_SA(1, 1), a1 + hstep);
;             PG8_WAIT_V(8); PG8_WAIT_L(0); PG8_BAR; PG8_MMA(0, 0, At, B0); PG8_MMA(0, 1, At, B1); PG8_BAR; PG8_SCHED;
;             PG8_LDA(At, 0, 1); PG8_STAGEB(PG8_SB(0, 0), b2); PG8_STAGEB(PG8_SB(0, 1), b2 + hstep); PG8_STAGEA(PG8_SA(0, 0), a2);
;             PG8_WAIT_V(8); PG8_WAIT_L(0); PG8_BAR; PG8_MMA(1, 0, At, B0); PG8_MMA(1, 1, At, B1); PG8_BAR; PG8_SCHED;
.LBB0_1119:
	s_add_u32 s73, s46, 0x100
	s_addc_u32 s74, s47, 0
	s_ashr_i32 s41, s40, 31
	s_lshl_b64 s[42:43], s[40:41], 19
	s_add_u32 s44, s66, s42
	s_addc_u32 s45, s67, s43
	s_and_b64 s[42:43], s[8:9], exec
	s_cselect_b32 s22, s45, s19
	s_cselect_b32 s41, s44, s18
	s_ashr_i32 s39, s38, 31
	s_lshl_b64 s[42:43], s[38:39], 19
	s_add_u32 s42, s52, s42
	s_addc_u32 s43, s53, s43
	s_and_b64 s[48:49], s[8:9], exec
	s_cselect_b32 s39, s43, s47
	s_cselect_b32 s75, s42, s46
	v_lshl_add_u64 v[146:147], s[18:19], 0, v[138:139]
	v_lshl_add_u64 v[148:149], s[18:19], 0, v[140:141]
	s_mov_b32 s76, -2
	s_mov_b64 s[46:47], 0
	v_add_u32_e32 v150, s69, v152
	ds_read_b128 v[156:159], v150
	ds_read_b128 v[160:163], v150 offset:1024
	ds_read_b128 v[164:167], v150 offset:2048
	ds_read_b128 v[168:171], v150 offset:3072
	v_add_u32_e32 v150, s70, v152
	s_add_u32 s48, s18, s46
	ds_read_b128 v[172:175], v150
	ds_read_b128 v[176:179], v150 offset:1024
	ds_read_b128 v[180:183], v150 offset:2048
	ds_read_b128 v[184:187], v150 offset:3072
	s_addc_u32 s49, s19, s47
	s_add_u32 s48, s48, 0x100
	s_addc_u32 s49, s49, 0
	s_add_u32 s77, s73, s46
	s_addc_u32 s78, s74, s47
	s_cmpk_eq_i32 s46, 0x700
	s_cselect_b32 s51, s22, s49
	s_cselect_b32 s50, s41, s48
	s_cselect_b32 s49, s39, s78
	s_cselect_b32 s48, s75, s77
	v_lshl_add_u64 v[150:151], v[146:147], 0, s[46:47]
	s_add_i32 m0, s15, 0xc000
	ds_read_b128 v[188:191], v154
	ds_read_b128 v[192:195], v154 offset:1024
	ds_read_b128 v[196:199], v154 offset:2048
	ds_read_b128 v[200:203], v154 offset:3072
	ds_read_b128 v[204:207], v154 offset:4096
	ds_read_b128 v[208:211], v154 offset:5120
	ds_read_b128 v[212:215], v154 offset:6144
	ds_read_b128 v[216:219], v154 offset:7168
	global_load_lds_dwordx4 v[150:151], off
	v_lshl_add_u64 v[150:151], v[148:149], 0, s[46:47]
	s_add_i32 m0, s15, 0xe000
	s_nop 0
	global_load_lds_dwordx4 v[150:151], off
	s_waitcnt vmcnt(8)
	s_waitcnt lgkmcnt(0)
	s_barrier
	s_waitcnt lgkmcnt(0)
	v_mfma_f32_16x16x32_bf16 v[126:129], v[156:159], v[188:191], 0
	v_mfma_f32_16x16x32_bf16 v[122:125], v[164:167], v[188:191], 0
	v_mfma_f32_16x16x32_bf16 v[118:121], v[156:159], v[196:199], 0
	v_mfma_f32_16x16x32_bf16 v[114:117], v[164:167], v[196:199], 0
	v_mfma_f32_16x16x32_bf16 v[110:113], v[156:159], v[204:207], 0
	v_mfma_f32_16x16x32_bf16 v[106:109], v[164:167], v[204:207], 0
	v_mfma_f32_16x16x32_bf16 v[102:105], v[156:159], v[212:215], 0
	v_mfma_f32_16x16x32_bf16 v[98:101], v[164:167], v[212:215], 0
	v_mfma_f32_16x16x32_bf16 v[126:129], v[160:163], v[192:195], v[126:129]
	v_mfma_f32_16x16x32_bf16 v[122:125], v[168:171], v[192:195], v[122:125]
	v_mfma_f32_16x16x32_bf16 v[118:121], v[160:163], v[200:203], v[118:121]
	v_mfma_f32_16x16x32_bf16 v[114:117], v[168:171], v[200:203], v[114:117]
	v_mfma_f32_16x16x32_bf16 v[110:113], v[160:163], v[208:211], v[110:113]
	v_mfma_f32_16x16x32_bf16 v[106:109], v[168:171], v[208:211], v[106:109]
	v_mfma_f32_16x16x32_bf16 v[102:105], v[160:163], v[216:219], v[102:105]
	v_mfma_f32_16x16x32_bf16 v[98:101], v[168:171], v[216:219], v[98:101]
	v_mfma_f32_16x16x32_bf16 v[94:97], v[172:175], v[188:191], 0
	v_mfma_f32_16x16x32_bf16 v[90:93], v[180:183], v[188:191], 0
	v_mfma_f32_16x16x32_bf16 v[86:89], v[172:175], v[196:199], 0
	v_mfma_f32_16x16x32_bf16 v[82:85], v[180:183], v[196:199], 0
	v_mfma_f32_16x16x32_bf16 v[78:81], v[172:175], v[204:207], 0
	v_mfma_f32_16x16x32_bf16 v[74:77], v[180:183], v[204:207], 0
	v_mfma_f32_16x16x32_bf16 v[70:73], v[172:175], v[212:215], 0
	v_mfma_f32_16x16x32_bf16 v[66:69], v[180:183], v[212:215], 0
	v_mfma_f32_16x16x32_bf16 v[94:97], v[176:179], v[192:195], v[94:97]
	v_mfma_f32_16x16x32_bf16 v[90:93], v[184:187], v[192:195], v[90:93]
	v_mfma_f32_16x16x32_bf16 v[86:89], v[176:179], v[200:203], v[86:89]
	v_mfma_f32_16x16x32_bf16 v[82:85], v[184:187], v[200:203], v[82:85]
	v_mfma_f32_16x16x32_bf16 v[78:81], v[176:179], v[208:211], v[78:81]
	v_mfma_f32_16x16x32_bf16 v[74:77], v[184:187], v[208:211], v[74:77]
	v_mfma_f32_16x16x32_bf16 v[70:73], v[176:179], v[216:219], v[70:73]
	v_mfma_f32_16x16x32_bf16 v[66:69], v[184:187], v[216:219], v[66:69]
	s_barrier
	s_add_i32 s77, s69, s54
	v_lshl_add_u64 v[150:151], s[48:49], 0, v[132:133]
	s_mov_b32 m0, s77
	ds_read_b128 v[188:191], v154 offset:16384
	ds_read_b128 v[192:195], v154 offset:17408
	ds_read_b128 v[196:199], v154 offset:18432
	ds_read_b128 v[200:203], v154 offset:19456
	ds_read_b128 v[204:207], v154 offset:20480
	ds_read_b128 v[208:211], v154 offset:21504
	ds_read_b128 v[212:215], v154 offset:22528
	ds_read_b128 v[216:219], v154 offset:23552
	global_load_lds_dwordx4 v[150:151], off
	s_add_i32 m0, s77, 0x2000
	s_add_u32 s78, s48, 0x40000
	v_lshl_add_u64 v[220:221], s[48:49], 0, v[136:137]
	s_addc_u32 s79, s49, 0
	s_add_i32 s77, s70, s54
	global_load_lds_dwordx4 v[220:221], off
	v_lshl_add_u64 v[222:223], s[78:79], 0, v[132:133]
	s_mov_b32 m0, s77
	v_lshl_add_u64 v[224:225], s[50:51], 0, v[134:135]
	global_load_lds_dwordx4 v[222:223], off
	v_lshl_add_u64 v[222:223], s[78:79], 0, v[136:137]
	s_add_i32 m0, s77, 0x2000
	s_nop 0
	global_load_lds_dwordx4 v[222:223], off
	v_lshl_add_u64 v[222:223], s[50:51], 0, v[130:131]
	s_mov_b32 m0, s15
	s_nop 0
	global_load_lds_dwordx4 v[222:223], off
	s_mov_b32 m0, s17
	s_nop 0
	global_load_lds_dwordx4 v[224:225], off
	s_waitcnt vmcnt(8)
	s_waitcnt lgkmcnt(0)
	s_barrier
; #define PG8_STAGEA(bufoff, gbase) PG8_STAGE_(bufoff, gbase, voffA)
; #define PG8_STAGEB(bufoff, gbase) PG8_STAGE_(bufoff, gbase, voffB)
; #define PG8_LDA(dst, b, h) do { _Pragma("unroll") for (int m = 0; m < 4; ++m) _Pragma("unroll") for (int k = 0; k < 2; ++k) dst[m][k] = *(const LAS bf16x8*)(lds + PG8_SA(b, h) + aoff + m * 2048 + k * 1024); } while (0)
; #define PG8_LDB(dst, b, h) do { _Pragma("unroll") for (int n = 0; n < 2; ++n) _Pragma("unroll") for (int k = 0; k < 2; ++k) dst[n][k] = *(const LAS bf16x8*)(lds + PG8_SB(b, h) + boff + n * 2048 + k * 1024); } while (0)
; #define PG8_MMA(ai, bj, At, Bt_) do { __builtin_amdgcn_s_setprio(1); _Pragma("unroll") for (int m = 0; m < 4; ++m) _Pragma("unroll") for (int n = 0; n < 2; ++n) _Pragma("unroll") for (int k = 0; k < 2; ++k) \
;         acc[ai][bj][m][n] = __builtin_amdgcn_mfma_f32_16x16x32_bf16(Bt_[n][k], At[m][k], acc[ai][bj][m][n], 0, 0, 0); __builtin_amdgcn_s_setprio(0); } while (0)
; #define PG8_WAIT_V(n) asm volatile("s_waitcnt vmcnt(" #n ")" ::: "memory")
; #define PG8_WAIT_L(n) asm volatile("s_waitcnt lgkmcnt(" #n ")" ::: "memory")
; #define PG8_BAR __builtin_amdgcn_s_barrier()
; #define PG8_SCHED __builtin_amdgcn_sched_barrier(0)
; template <int EK, int SK = -1>
; __device__ __forceinline__ void gemm_phase(LAS unsigned char* lds, const bf16_t* A, const bf16_t* Bt, int nM, int N, int K, const EpiArgs& E) {
;     ...
;             PG8_WAIT_V(8); PG8_WAIT_L(0); PG8_BAR; PG8_MMA(1, 0, At, B0); PG8_MMA(1, 1, At, B1); PG8_BAR; PG8_SCHED;
;             PG8_LDB(B0, 1, 0); PG8_LDB(B1, 1, 1); PG8_SCHED; PG8_LDA(At, 1, 0); PG8_STAGEA(PG8_SA(0, 1), a2 + hstep);
;             PG8_WAIT_V(8); PG8_WAIT_L(0); PG8_BAR; PG8_MMA(0, 0, At, B0); PG8_MMA(0, 1, At, B1); PG8_BAR; PG8_SCHED;
;             PG8_LDA(At, 1, 1); PG8_STAGEB(PG8_SB(1, 0), b3); PG8_STAGEB(PG8_SB(1, 1), b3 + hstep); PG8_STAGEA(PG8_SA(1, 0), a3);
	s_waitcnt lgkmcnt(0)
	v_mfma_f32_16x16x32_bf16 v[62:65], v[156:159], v[188:191], 0
	v_mfma_f32_16x16x32_bf16 v[58:61], v[164:167], v[188:191], 0
	v_mfma_f32_16x16x32_bf16 v[54:57], v[156:159], v[196:199], 0
	v_mfma_f32_16x16x32_bf16 v[50:53], v[164:167], v[196:199], 0
	v_mfma_f32_16x16x32_bf16 v[46:49], v[156:159], v[204:207], 0
	v_mfma_f32_16x16x32_bf16 v[42:45], v[164:167], v[204:207], 0
	v_mfma_f32_16x16x32_bf16 v[38:41], v[156:159], v[212:215], 0
	v_mfma_f32_16x16x32_bf16 v[34:37], v[164:167], v[212:215], 0
	v_mfma_f32_16x16x32_bf16 v[62:65], v[160:163], v[192:195], v[62:65]
	v_mfma_f32_16x16x32_bf16 v[58:61], v[168:171], v[192:195], v[58:61]
	v_mfma_f32_16x16x32_bf16 v[54:57], v[160:163], v[200:203], v[54:57]
	v_mfma_f32_16x16x32_bf16 v[50:53], v[168:171], v[200:203], v[50:53]
	v_mfma_f32_16x16x32_bf16 v[46:49], v[160:163], v[208:211], v[46:49]
	v_mfma_f32_16x16x32_bf16 v[42:45], v[168:171], v[208:211], v[42:45]
	v_mfma_f32_16x16x32_bf16 v[38:41], v[160:163], v[216:219], v[38:41]
	v_mfma_f32_16x16x32_bf16 v[34:37], v[168:171], v[216:219], v[34:37]
	v_mfma_f32_16x16x32_bf16 v[30:33], v[172:175], v[188:191], 0
	v_mfma_f32_16x16x32_bf16 v[26:29], v[180:183], v[188:191], 0
	v_mfma_f32_16x16x32_bf16 v[22:25], v[172:175], v[196:199], 0
	v_mfma_f32_16x16x32_bf16 v[18:21], v[180:183], v[196:199], 0
	v_mfma_f32_16x16x32_bf16 v[14:17], v[172:175], v[204:207], 0
	v_mfma_f32_16x16x32_bf16 v[10:13], v[180:183], v[204:207], 0
	v_mfma_f32_16x16x32_bf16 v[6:9], v[172:175], v[212:215], 0
	v_mfma_f32_16x16x32_bf16 v[2:5], v[180:183], v[212:215], 0
	v_mfma_f32_16x16x32_bf16 v[30:33], v[176:179], v[192:195], v[30:33]
	v_mfma_f32_16x16x32_bf16 v[26:29], v[184:187], v[192:195], v[26:29]
	v_mfma_f32_16x16x32_bf16 v[22:25], v[176:179], v[200:203], v[22:25]
	v_mfma_f32_16x16x32_bf16 v[18:21], v[184:187], v[200:203], v[18:21]
	v_mfma_f32_16x16x32_bf16 v[14:17], v[176:179], v[208:211], v[14:17]
	v_mfma_f32_16x16x32_bf16 v[10:13], v[184:187], v[208:211], v[10:13]
	v_mfma_f32_16x16x32_bf16 v[6:9], v[176:179], v[216:219], v[6:9]
	v_mfma_f32_16x16x32_bf16 v[2:5], v[184:187], v[216:219], v[2:5]
	s_barrier
	s_add_i32 s77, 0, 0x18000
	s_add_i32 s78, 0, 0x1c000
	v_add_u32_e32 v168, s77, v152
	v_add_u32_e32 v184, s78, v152
	ds_read_b128 v[156:159], v168
	ds_read_b128 v[160:163], v168 offset:1024
	ds_read_b128 v[164:167], v168 offset:2048
	ds_read_b128 v[168:171], v168 offset:3072
	ds_read_b128 v[172:175], v184
	ds_read_b128 v[176:179], v184 offset:1024
	ds_read_b128 v[180:183], v184 offset:2048
	ds_read_b128 v[184:187], v184 offset:3072
	s_add_u32 s50, s50, 0x40000
	s_addc_u32 s51, s51, 0
	s_mov_b32 m0, s55
	v_lshl_add_u64 v[226:227], s[50:51], 0, v[130:131]
	ds_read_b128 v[188:191], v154 offset:32768
	ds_read_b128 v[192:195], v154 offset:33792
	ds_read_b128 v[196:199], v154 offset:34816
	ds_read_b128 v[200:203], v154 offset:35840
	ds_read_b128 v[204:207], v154 offset:36864
	ds_read_b128 v[208:211], v154 offset:37888
	ds_read_b128 v[212:215], v154 offset:38912
	ds_read_b128 v[216:219], v154 offset:39936
	global_load_lds_dwordx4 v[226:227], off
	v_lshl_add_u64 v[226:227], s[50:51], 0, v[134:135]
	s_mov_b32 m0, s56
	s_nop 0
	global_load_lds_dwordx4 v[226:227], off
	s_waitcnt vmcnt(8)
	s_waitcnt lgkmcnt(0)
	s_barrier
	s_waitcnt lgkmcnt(0)
	v_mfma_f32_16x16x32_bf16 v[126:129], v[156:159], v[188:191], v[126:129]
	v_mfma_f32_16x16x32_bf16 v[122:125], v[164:167], v[188:191], v[122:125]
	v_mfma_f32_16x16x32_bf16 v[118:121], v[156:159], v[196:199], v[118:121]
	v_mfma_f32_16x16x32_bf16 v[114:117], v[164:167], v[196:199], v[114:117]
	v_mfma_f32_16x16x32_bf16 v[110:113], v[156:159], v[204:207], v[110:113]
	v_mfma_f32_16x16x32_bf16 v[106:109], v[164:167], v[204:207], v[106:109]
	v_mfma_f32_16x16x32_bf16 v[102:105], v[156:159], v[212:215], v[102:105]
	v_mfma_f32_16x16x32_bf16 v[98:101], v[164:167], v[212:215], v[98:101]
	v_mfma_f32_16x16x32_bf16 v[126:129], v[160:163], v[192:195], v[126:129]
	v_mfma_f32_16x16x32_bf16 v[122:125], v[168:171], v[192:195], v[122:125]
	v_mfma_f32_16x16x32_bf16 v[118:121], v[160:163], v[200:203], v[118:121]
	v_mfma_f32_16x16x32_bf16 v[114:117], v[168:171], v[200:203], v[114:117]
	v_mfma_f32_16x16x32_bf16 v[110:113], v[160:163], v[208:211], v[110:113]
	v_mfma_f32_16x16x32_bf16 v[106:109], v[168:171], v[208:211], v[106:109]
	v_mfma_f32_16x16x32_bf16 v[102:105], v[160:163], v[216:219], v[102:105]
	v_mfma_f32_16x16x32_bf16 v[98:101], v[168:171], v[216:219], v[98:101]
	v_mfma_f32_16x16x32_bf16 v[94:97], v[172:175], v[188:191], v[94:97]
	v_mfma_f32_16x16x32_bf16 v[90:93], v[180:183], v[188:191], v[90:93]
	v_mfma_f32_16x16x32_bf16 v[86:89], v[172:175], v[196:199], v[86:89]
	v_mfma_f32_16x16x32_bf16 v[82:85], v[180:183], v[196:199], v[82:85]
	v_mfma_f32_16x16x32_bf16 v[78:81], v[172:175], v[204:207], v[78:81]
	v_mfma_f32_16x16x32_bf16 v[74:77], v[180:183], v[204:207], v[74:77]
	v_mfma_f32_16x16x32_bf16 v[70:73], v[172:175], v[212:215], v[70:73]
	v_mfma_f32_16x16x32_bf16 v[66:69], v[180:183], v[212:215], v[66:69]
	v_mfma_f32_16x16x32_bf16 v[94:97], v[176:179], v[192:195], v[94:97]
	v_mfma_f32_16x16x32_bf16 v[90:93], v[184:187], v[192:195], v[90:93]
	v_mfma_f32_16x16x32_bf16 v[86:89], v[176:179], v[200:203], v[86:89]
	v_mfma_f32_16x16x32_bf16 v[82:85], v[184:187], v[200:203], v[82:85]
	v_mfma_f32_16x16x32_bf16 v[78:81], v[176:179], v[208:211], v[78:81]
	v_mfma_f32_16x16x32_bf16 v[74:77], v[184:187], v[208:211], v[74:77]
	v_mfma_f32_16x16x32_bf16 v[70:73], v[176:179], v[216:219], v[70:73]
	v_mfma_f32_16x16x32_bf16 v[66:69], v[184:187], v[216:219], v[66:69]
	s_barrier
; #define PG8_STAGEA(bufoff, gbase) PG8_STAGE_(bufoff, gbase, voffA)
; #define PG8_STAGEB(bufoff, gbase) PG8_STAGE_(bufoff, gbase, voffB)
; #define PG8_LDA(dst, b, h) do { _Pragma("unroll") for (int m = 0; m < 4; ++m) _Pragma("unroll") for (int k = 0; k < 2; ++k) dst[m][k] = *(const LAS bf16x8*)(lds + PG8_SA(b, h) + aoff + m * 2048 + k * 1024); } while (0)
; #define PG8_MMA(ai, bj, At, Bt_) do { __builtin_amdgcn_s_setprio(1); _Pragma("unroll") for (int m = 0; m < 4; ++m) _Pragma("unroll") for (int n = 0; n < 2; ++n) _Pragma("unroll") for (int k = 0; k < 2; ++k) \
;         acc[ai][bj][m][n] = __builtin_amdgcn_mfma_f32_16x16x32_bf16(Bt_[n][k], At[m][k], acc[ai][bj][m][n], 0, 0, 0); __builtin_amdgcn_s_setprio(0); } while (0)
; #define PG8_WAIT_V(n) asm volatile("s_waitcnt vmcnt(" #n ")" ::: "memory")
; #define PG8_WAIT_L(n) asm volatile("s_waitcnt lgkmcnt(" #n ")" ::: "memory")
; #define PG8_BAR __builtin_amdgcn_s_barrier()
; #define PG8_SCHED __builtin_amdgcn_sched_barrier(0)
; template <int EK, int SK = -1>
; __device__ __forceinline__ void gemm_phase(LAS unsigned char* lds, const bf16_t* A, const bf16_t* Bt, int nM, int N, int K, const EpiArgs& E) {
;     ...
;             PG8_LDA(At, 1, 1); PG8_STAGEB(PG8_SB(1, 0), b3); PG8_STAGEB(PG8_SB(1, 1), b3 + hstep); PG8_STAGEA(PG8_SA(1, 0), a3);
;             PG8_WAIT_V(8); PG8_WAIT_L(0); PG8_BAR; PG8_MMA(1, 0, At, B0); PG8_MMA(1, 1, At, B1); PG8_BAR; PG8_SCHED;
;         }
	s_add_i32 s50, s77, s54
	v_lshl_add_u64 v[150:151], v[150:151], 0, s[26:27]
	s_mov_b32 m0, s50
	ds_read_b128 v[188:191], v154 offset:49152
	ds_read_b128 v[192:195], v154 offset:50176
	ds_read_b128 v[196:199], v154 offset:51200
	ds_read_b128 v[200:203], v154 offset:52224
	ds_read_b128 v[204:207], v154 offset:53248
	ds_read_b128 v[208:211], v154 offset:54272
	ds_read_b128 v[212:215], v154 offset:55296
	ds_read_b128 v[216:219], v154 offset:56320
	global_load_lds_dwordx4 v[150:151], off
	s_add_i32 m0, s50, 0x2000
	s_add_u32 s48, s48, 0x40080
	v_lshl_add_u64 v[150:151], v[220:221], 0, s[26:27]
	s_addc_u32 s49, s49, 0
	s_add_i32 s50, s78, s54
	global_load_lds_dwordx4 v[150:151], off
	v_lshl_add_u64 v[150:151], s[48:49], 0, v[132:133]
	s_mov_b32 m0, s50
	s_nop 0
	global_load_lds_dwordx4 v[150:151], off
	v_lshl_add_u64 v[150:151], s[48:49], 0, v[136:137]
	s_add_i32 m0, s50, 0x2000
	s_nop 0
	global_load_lds_dwordx4 v[150:151], off
	v_lshl_add_u64 v[150:151], v[222:223], 0, s[26:27]
	s_mov_b32 m0, s59
	s_nop 0
	global_load_lds_dwordx4 v[150:151], off
	v_lshl_add_u64 v[150:151], v[224:225], 0, s[26:27]
	s_mov_b32 m0, s68
	s_nop 0
	global_load_lds_dwordx4 v[150:151], off
	s_waitcnt vmcnt(8)
	s_waitcnt lgkmcnt(0)
	s_barrier
	s_waitcnt lgkmcnt(0)
	v_mfma_f32_16x16x32_bf16 v[62:65], v[156:159], v[188:191], v[62:65]
	v_mfma_f32_16x16x32_bf16 v[58:61], v[164:167], v[188:191], v[58:61]
	v_mfma_f32_16x16x32_bf16 v[54:57], v[156:159], v[196:199], v[54:57]
	v_mfma_f32_16x16x32_bf16 v[50:53], v[164:167], v[196:199], v[50:53]
	v_mfma_f32_16x16x32_bf16 v[46:49], v[156:159], v[204:207], v[46:49]
	v_mfma_f32_16x16x32_bf16 v[42:45], v[164:167], v[204:207], v[42:45]
	v_mfma_f32_16x16x32_bf16 v[38:41], v[156:159], v[212:215], v[38:41]
	v_mfma_f32_16x16x32_bf16 v[34:37], v[164:167], v[212:215], v[34:37]
	v_mfma_f32_16x16x32_bf16 v[62:65], v[160:163], v[192:195], v[62:65]
	v_mfma_f32_16x16x32_bf16 v[58:61], v[168:171], v[192:195], v[58:61]
	v_mfma_f32_16x16x32_bf16 v[54:57], v[160:163], v[200:203], v[54:57]
	v_mfma_f32_16x16x32_bf16 v[50:53], v[168:171], v[200:203], v[50:53]
	v_mfma_f32_16x16x32_bf16 v[46:49], v[160:163], v[208:211], v[46:49]
	v_mfma_f32_16x16x32_bf16 v[42:45], v[168:171], v[208:211], v[42:45]
	v_mfma_f32_16x16x32_bf16 v[38:41], v[160:163], v[216:219], v[38:41]
	v_mfma_f32_16x16x32_bf16 v[34:37], v[168:171], v[216:219], v[34:37]
	v_mfma_f32_16x16x32_bf16 v[30:33], v[172:175], v[188:191], v[30:33]
	v_mfma_f32_16x16x32_bf16 v[26:29], v[180:183], v[188:191], v[26:29]
	v_mfma_f32_16x16x32_bf16 v[22:25], v[172:175], v[196:199], v[22:25]
	v_mfma_f32_16x16x32_bf16 v[18:21], v[180:183], v[196:199], v[18:21]
	v_mfma_f32_16x16x32_bf16 v[14:17], v[172:175], v[204:207], v[14:17]
	v_mfma_f32_16x16x32_bf16 v[10:13], v[180:183], v[204:207], v[10:13]
	v_mfma_f32_16x16x32_bf16 v[6:9], v[172:175], v[212:215], v[6:9]
	v_mfma_f32_16x16x32_bf16 v[2:5], v[180:183], v[212:215], v[2:5]
	v_mfma_f32_16x16x32_bf16 v[30:33], v[176:179], v[192:195], v[30:33]
	v_mfma_f32_16x16x32_bf16 v[26:29], v[184:187], v[192:195], v[26:29]
	v_mfma_f32_16x16x32_bf16 v[22:25], v[176:179], v[200:203], v[22:25]
	v_mfma_f32_16x16x32_bf16 v[18:21], v[184:187], v[200:203], v[18:21]
	v_mfma_f32_16x16x32_bf16 v[14:17], v[176:179], v[208:211], v[14:17]
	v_mfma_f32_16x16x32_bf16 v[10:13], v[184:187], v[208:211], v[10:13]
	v_mfma_f32_16x16x32_bf16 v[6:9], v[176:179], v[216:219], v[6:9]
	v_mfma_f32_16x16x32_bf16 v[2:5], v[184:187], v[216:219], v[2:5]
	s_barrier
	s_add_i32 s76, s76, 2
	s_add_u32 s46, s46, 0x100
	s_addc_u32 s47, s47, 0
	s_cmp_gt_u32 s76, 13
	s_cbranch_scc0 .LBB0_1120
	s_branch .Lmy_kexit_5

; #define PG8_BAR __builtin_amdgcn_s_barrier()
; template <int EK, int SK = -1>
; __device__ __forceinline__ void gemm_phase(LAS unsigned char* lds, const bf16_t* A, const bf16_t* Bt, int nM, int N, int K, const EpiArgs& E) {
;     ...
;         }
;         if (wr == 0) PG8_BAR;
;         if (EK != EK_FINAL) epi_tile<EK>(acc, cur, wr, wc, fr, fq, E, rtab + ui * 256);
.Lmy_kexit_5:
	s_and_b64 vcc, exec, s[36:37]
	s_cbranch_vccz .LBB0_1123
	s_barrier

; __device__ __forceinline__ unsigned xb_ld(unsigned* p)              { return __hip_atomic_load(p, __ATOMIC_RELAXED, __HIP_MEMORY_SCOPE_AGENT); }
; __device__ __forceinline__ unsigned xb_add(unsigned* p, unsigned v) { return __hip_atomic_fetch_add(p, v, __ATOMIC_RELAXED, __HIP_MEMORY_SCOPE_AGENT); }
; #define XB_SPIN(cond, bar) do { unsigned _sp = 0; while (cond) { __builtin_amdgcn_s_sleep(1); \
;     if ((++_sp & 255u) == 0u) { if (xb_ld(&(bar)[XB_TMO])) break; if (_sp > XB_SPIN_CAP) { atomicAdd(&(bar)[XB_TMO], 1u); break; } } } } while (0)
; __device__ __forceinline__ void xcd_barrier(const XcdBarrier& b) {
;     asm volatile("s_waitcnt vmcnt(0)" ::: "memory");
;     __syncthreads();
;     if (threadIdx.x == 0) {
;         unsigned* bar = b.bar;
;         __builtin_amdgcn_s_waitcnt(0);
;         unsigned nloc = b.st[0], nx = b.st[1];
;         if (nloc == 0u) { xcd_barrier_complete(bar, b.x, nloc, nx); b.st[0] = nloc; b.st[1] = nx; }
;         const unsigned old = xb_add(&bar[XB_XSUB(b.x)], 1u);
;         const unsigned gen = old / nloc;
;         if (old + 1u == (gen + 1u) * nloc) {
;             __builtin_amdgcn_fence(__ATOMIC_RELEASE, "agent");
;             asm volatile("s_waitcnt vmcnt(0)" ::: "memory");
;             const unsigned og = xb_add(&bar[XB_TOP], 1u);
;             const unsigned tg = og / nx;
;             if (og + 1u == (tg + 1u) * nx) xb_add(&bar[XB_TOPGEN], 1u);
;             else XB_SPIN(xb_ld(&bar[XB_TOPGEN]) == tg, bar);
;             __builtin_amdgcn_fence(__ATOMIC_ACQUIRE, "agent");
;             asm volatile("s_waitcnt vmcnt(0)" ::: "memory");
;         } else {
;             XB_SPIN(xb_ld(&bar[XB_TOPGEN]) == gen, bar);
;             __builtin_amdgcn_fence(__ATOMIC_ACQUIRE, "agent");
;             asm volatile("s_waitcnt vmcnt(0)" ::: "memory");
.Lmy_noinv9:
	s_and_saveexec_b64 s[6:7], vcc
	s_cbranch_execz .LBB0_1193
	s_waitcnt vmcnt(0) lgkmcnt(0)
	v_mov_b32_e32 v1, 0x20000
	ds_read2_b32 v[2:3], v1 offset1:1
	s_and_b32 s99, s33, 7
	s_lshl_b32 s99, s99, 8
	s_add_u32 s100, s60, 0xc000
	s_addc_u32 s101, s61, 0
	v_mov_b32_e32 v4, s99
	v_mov_b32_e32 v5, 1
	global_atomic_add v5, v4, v5, s[100:101] sc0
	s_waitcnt lgkmcnt(0)
	v_mul_u32_u24_e32 v6, 8, v2
	v_mul_u32_u24_e32 v7, 8, v3
	s_waitcnt vmcnt(0)
	v_add_u32_e32 v5, 1, v5
	v_cmp_eq_u32_e32 vcc, v5, v6
	s_cbranch_vccz .Lmy_nl8
	buffer_wbl2 sc1
	s_waitcnt vmcnt(0)
	v_mov_b32_e32 v4, 0x800
	v_mov_b32_e32 v5, 1
	global_atomic_add v4, v5, s[100:101]

; #define LAS __attribute__((address_space(3)))
; __device__ __forceinline__ float hsum4(f32x4 v) { return (v[0] + v[1]) + (v[2] + v[3]); }
; #define PG8_STAGEA(bufoff, gbase) PG8_STAGE_(bufoff, gbase, voffA)
; template <int EK, int SK = -1>
; __device__ __forceinline__ void gemm_phase(LAS unsigned char* lds, const bf16_t* A, const bf16_t* Bt, int nM, int N, int K, const EpiArgs& E) {
;     ...
;     f32x4 acc[2][2][4][2];
; #pragma unroll
;     for (int a = 0; a < 2; ++a)
; #pragma unroll
;         for (int b = 0; b < 2; ++b)
; #pragma unroll
;             for (int m = 0; m < 4; ++m)
; #pragma unroll
;                 for (int n = 0; n < 2; ++n) acc[a][b][m][n] = (f32x4){0.f, 0.f, 0.f, 0.f};
;     bf16x8 At[4][2], B0[2][2], B1[2][2];
;     const char* cA = (const char*)A + (size_t)cur.pm * tstep; const char* cB = (const char*)Bt + (size_t)cur.pn * tstep;
;     PG8_STAGEB(PG8_SB(0, 0), cB); PG8_STAGEB(PG8_SB(0, 1), cB + hstep); PG8_STAGEA(PG8_SA(0, 0), cA); PG8_STAGEA(PG8_SA(0, 1), cA + hstep);
;     f32x4 tq[4][4]; bool okq[4];
;     if (EK != EK_RES && EK != EK_FINAL) {
; #pragma unroll
;         for (int j = 0; j < 4; ++j) { Unit uu; okq[j] = S.next((tid >> 8) + 2 * j, uu);
;             if (okq[j]) { const f32x4* sp = (const f32x4*)(E.stIn + (size_t)(uu.pm * BM + (tid & 255)) * 16); tq[j][0] = sp[0]; tq[j][1] = sp[1]; tq[j][2] = sp[2]; tq[j][3] = sp[3]; } }
;     }
;     if (SK >= 0) skinny_phase<(SK >= 0 ? SK : 0)>(lds + 32768, (LAS float*)(lds + SRED_OFF), A, Bt, N, K, E);
;     if (EK != EK_RES && EK != EK_FINAL) {
; #pragma unroll
;         for (int j = 0; j < 4; ++j) if (okq[j]) { const float s_ = (hsum4(tq[j][0]) + hsum4(tq[j][1])) + (hsum4(tq[j][2]) + hsum4(tq[j][3]));
;             rtab[((tid >> 8) + 2 * j) * 256 + (tid & 255)] = rsqrtf(s_ * (1.0f / 1024.0f) + EPS); }
;         __syncthreads();
;     }
;     if (wr == 1) PG8_BAR;
;     PG8_WAIT_V(2); PG8_BAR;
;     PG8_STAGEB(PG8_SB(1, 0), cB + kstep); PG8_STAGEA(PG8_SA(1, 0), cA + kstep); PG8_STAGEB(PG8_SB(1, 1), cB + hstep + kstep);
;     PG8_WAIT_V(6); PG8_BAR;
;     ...
;         for (int a = 0; a < 2; ++a)
; #pragma unroll
;             for (int b = 0; b < 2; ++b)
; #pragma unroll
;                 for (int m = 0; m < 4; ++m)
; #pragma unroll
;                     for (int n = 0; n < 2; ++n) acc[a][b][m][n] = (f32x4){0.f, 0.f, 0.f, 0.f};
;         cur = nxt; cA = nA; cB = nB; ++ui;
.LBB0_1236:
	v_and_b32_e32 v2, 15, v0
	v_lshlrev_b32_e32 v3, 1, v78
	v_lshlrev_b32_e32 v5, 2, v2
	v_lshl_or_b32 v1, s4, 6, v2
	v_lshl_or_b32 v4, v2, 6, v3
	s_lshl_b32 s5, s4, 13
	v_and_b32_e32 v2, 32, v5
	v_bitop3_b32 v4, v4, s5, v2 bitop3:0xde
	s_lshl_b32 s5, s27, 5
	v_lshlrev_b32_e32 v2, 6, v0
	s_movk_i32 s6, 0x3c0
	s_and_b32 s5, s5, 0x60
	v_and_or_b32 v2, v2, s6, v3
	v_lshlrev_b32_e32 v3, 2, v0
	s_lshl_b32 s6, s5, 7
	v_and_b32_e32 v3, 32, v3
	s_mov_b64 s[10:11], 0x80
	v_bitop3_b32 v156, s6, v2, v3 bitop3:0xf6
	s_add_i32 m0, s17, 0x18000
	v_lshl_add_u64 v[2:3], v[72:73], 0, s[10:11]
	s_waitcnt vmcnt(2)
	s_barrier
	global_load_lds_dwordx4 v[2:3], off
	v_lshl_add_u64 v[2:3], v[70:71], 0, s[10:11]
	s_add_i32 m0, s17, 0x1a000
	s_add_i32 s52, s17, 0x8000
	s_add_i32 s53, s17, 0xa000
	global_load_lds_dwordx4 v[2:3], off
	v_lshl_add_u64 v[2:3], v[68:69], 0, s[10:11]
	s_mov_b32 m0, s52
	s_add_u32 s12, s40, 0x40080
	global_load_lds_dwordx4 v[2:3], off
	v_lshl_add_u64 v[2:3], v[66:67], 0, s[10:11]
	s_mov_b32 m0, s53
	s_addc_u32 s13, s41, 0
	global_load_lds_dwordx4 v[2:3], off
	s_add_i32 m0, s17, 0x1c000
	v_lshl_add_u64 v[2:3], s[12:13], 0, v[132:133]
	global_load_lds_dwordx4 v[2:3], off
	v_lshl_add_u64 v[2:3], s[12:13], 0, v[136:137]
	s_add_i32 m0, s17, 0x1e000
	s_lshl_b32 s4, s4, 8
	global_load_lds_dwordx4 v[2:3], off
	s_add_i32 s4, s4, 0
	s_add_i32 s4, s4, 0x20010
	v_lshlrev_b32_e32 v2, 8, v0
	v_add_u32_e32 v157, s4, v5
	v_and_b32_e32 v2, 0x18000, v2
	v_lshlrev_b32_e32 v5, 11, v76
	v_or3_b32 v2, v74, v2, v5
	s_mov_b64 s[6:7], 0x40080
	v_add_u32_e32 v2, v2, v75
	v_mov_b32_e32 v3, 0
	v_lshl_add_u64 v[138:139], v[2:3], 0, s[6:7]
	v_lshlrev_b32_e32 v2, 4, v77
	v_and_b32_e32 v2, 0x38000, v2
	s_waitcnt vmcnt(6)
	v_or3_b32 v2, v74, v2, v5
	s_cmpk_lt_u32 s26, 0x100
	v_add_u32_e32 v2, v2, v75
	s_mov_b32 s57, 0
	s_cselect_b64 s[12:13], -1, 0
	v_or_b32_e32 v158, s5, v78
	v_lshl_add_u64 v[140:141], v[2:3], 0, s[6:7]
	v_mov_b64_e32 v[142:143], 0x596
	v_mov_b64_e32 v[144:145], 0x595
	s_add_i32 s54, 0, 0x10000
	s_add_i32 s55, 0, 0x14000
	v_add_u32_e32 v159, 0, v4
	s_movk_i32 s56, 0x1600
	v_mov_b32_e32 v2, v3
	s_barrier
	s_branch .LBB0_1238
.LBB0_1237:
	v_mov_b32_e32 v2, 0
	s_mov_b32 s18, s26
	s_mov_b32 s16, s22
	v_mov_b32_e32 v3, v2
	s_mov_b64 s[20:21], s[38:39]
	s_mov_b32 s57, s58
	s_andn2_b64 vcc, exec, s[4:5]
	s_mov_b64 s[40:41], s[36:37]
	s_cbranch_vccz .LBB0_1252

; #define PG8_STAGEA(bufoff, gbase) PG8_STAGE_(bufoff, gbase, voffA)
; #define PG8_STAGEB(bufoff, gbase) PG8_STAGE_(bufoff, gbase, voffB)
; #define PG8_LDA(dst, b, h) do { _Pragma("unroll") for (int m = 0; m < 4; ++m) _Pragma("unroll") for (int k = 0; k < 2; ++k) dst[m][k] = *(const LAS bf16x8*)(lds + PG8_SA(b, h) + aoff + m * 2048 + k * 1024); } while (0)
; #define PG8_LDB(dst, b, h) do { _Pragma("unroll") for (int n = 0; n < 2; ++n) _Pragma("unroll") for (int k = 0; k < 2; ++k) dst[n][k] = *(const LAS bf16x8*)(lds + PG8_SB(b, h) + boff + n * 2048 + k * 1024); } while (0)
; #define PG8_MMA(ai, bj, At, Bt_) do { __builtin_amdgcn_s_setprio(1); _Pragma("unroll") for (int m = 0; m < 4; ++m) _Pragma("unroll") for (int n = 0; n < 2; ++n) _Pragma("unroll") for (int k = 0; k < 2; ++k) \
;         acc[ai][bj][m][n] = __builtin_amdgcn_mfma_f32_16x16x32_bf16(Bt_[n][k], At[m][k], acc[ai][bj][m][n], 0, 0, 0); __builtin_amdgcn_s_setprio(0); } while (0)
; #define PG8_WAIT_V(n) asm volatile("s_waitcnt vmcnt(" #n ")" ::: "memory")
; #define PG8_WAIT_L(n) asm volatile("s_waitcnt lgkmcnt(" #n ")" ::: "memory")
; #define PG8_BAR __builtin_amdgcn_s_barrier()
; template <int EK, int SK = -1>
; __device__ __forceinline__ void gemm_phase(LAS unsigned char* lds, const bf16_t* A, const bf16_t* Bt, int nM, int N, int K, const EpiArgs& E) {
;     ...
;         const bool has_next = S.next(ui + 1, nxt);
;         const char* nA = has_next ? (const char*)A + (size_t)nxt.pm * tstep : cA; const char* nB = has_next ? (const char*)Bt + (size_t)nxt.pn * tstep : cB;
;         for (int t = 0; t < nt; t += 2) {
;             const bool last = (t == nt - 2);
;             const char* a1 = cA + (size_t)(t + 1) * kstep;
;             const char* a2 = last ? nA : cA + (size_t)(t + 2) * kstep; const char* b2 = last ? nB : cB + (size_t)(t + 2) * kstep;
;             const char* a3 = a2 + kstep; const char* b3 = b2 + kstep;
;             PG8_LDB(B0, 0, 0); PG8_LDB(B1, 0, 1); PG8_SCHED; PG8_LDA(At, 0, 0); PG8_STAGEA(PG8_SA(1, 1), a1 + hstep);
;             PG8_WAIT_V(8); PG8_WAIT_L(0); PG8_BAR; PG8_MMA(0, 0, At, B0); PG8_MMA(0, 1, At, B1); PG8_BAR; PG8_SCHED;
;             PG8_LDA(At, 0, 1); PG8_STAGEB(PG8_SB(0, 0), b2); PG8_STAGEB(PG8_SB(0, 1), b2 + hstep); PG8_STAGEA(PG8_SA(0, 0), a2);
;             PG8_WAIT_V(8); PG8_WAIT_L(0); PG8_BAR; PG8_MMA(1, 0, At, B0); PG8_MMA(1, 1, At, B1); PG8_BAR; PG8_SCHED;
.LBB0_1244:
	s_add_u32 s59, s40, 0x100
	s_addc_u32 s66, s41, 0
	s_ashr_i32 s27, s26, 31
	s_lshl_b64 s[36:37], s[26:27], 19
	s_add_u32 s38, s62, s36
	s_addc_u32 s39, s63, s37
	s_and_b64 s[36:37], s[6:7], exec
	s_cselect_b32 s27, s39, s21
	s_cselect_b32 s67, s38, s20
	s_ashr_i32 s23, s22, 31
	s_lshl_b64 s[36:37], s[22:23], 19
	s_add_u32 s36, s47, s36
	s_addc_u32 s37, s48, s37
	s_and_b64 s[42:43], s[6:7], exec
	s_cselect_b32 s23, s37, s41
	s_cselect_b32 s68, s36, s40
	v_lshl_add_u64 v[146:147], s[20:21], 0, v[138:139]
	v_lshl_add_u64 v[148:149], s[20:21], 0, v[140:141]
	s_mov_b32 s69, -2
	s_mov_b64 s[40:41], 0
	v_add_u32_e32 v154, s54, v156
	ds_read_b128 v[150:153], v154
	ds_read_b128 v[160:163], v154 offset:1024
	ds_read_b128 v[164:167], v154 offset:2048
	ds_read_b128 v[168:171], v154 offset:3072
	v_add_u32_e32 v154, s55, v156
	s_add_u32 s42, s20, s40
	ds_read_b128 v[172:175], v154
	ds_read_b128 v[176:179], v154 offset:1024
	ds_read_b128 v[180:183], v154 offset:2048
	ds_read_b128 v[184:187], v154 offset:3072
	s_addc_u32 s43, s21, s41
	s_add_u32 s42, s42, 0x100
	s_addc_u32 s43, s43, 0
	s_add_u32 s70, s59, s40
	s_addc_u32 s71, s66, s41
	s_cmpk_eq_i32 s40, 0x700
	s_cselect_b32 s45, s27, s43
	s_cselect_b32 s44, s67, s42
	s_cselect_b32 s43, s23, s71
	s_cselect_b32 s42, s68, s70
	v_lshl_add_u64 v[154:155], v[146:147], 0, s[40:41]
	s_add_i32 m0, s17, 0xc000
	ds_read_b128 v[188:191], v159
	ds_read_b128 v[192:195], v159 offset:1024
	ds_read_b128 v[196:199], v159 offset:2048
	ds_read_b128 v[200:203], v159 offset:3072
	ds_read_b128 v[204:207], v159 offset:4096
	ds_read_b128 v[208:211], v159 offset:5120
	ds_read_b128 v[212:215], v159 offset:6144
	ds_read_b128 v[216:219], v159 offset:7168
	global_load_lds_dwordx4 v[154:155], off
	v_lshl_add_u64 v[154:155], v[148:149], 0, s[40:41]
	s_add_i32 m0, s17, 0xe000
	s_nop 0
	global_load_lds_dwordx4 v[154:155], off
	s_waitcnt vmcnt(8)
	s_waitcnt lgkmcnt(0)
	s_barrier
	s_waitcnt lgkmcnt(0)
	v_mfma_f32_16x16x32_bf16 v[110:113], v[150:153], v[188:191], 0
	v_mfma_f32_16x16x32_bf16 v[106:109], v[164:167], v[188:191], 0
	v_mfma_f32_16x16x32_bf16 v[102:105], v[150:153], v[196:199], 0
	v_mfma_f32_16x16x32_bf16 v[98:101], v[164:167], v[196:199], 0
	v_mfma_f32_16x16x32_bf16 v[94:97], v[150:153], v[204:207], 0
	v_mfma_f32_16x16x32_bf16 v[90:93], v[164:167], v[204:207], 0
	v_mfma_f32_16x16x32_bf16 v[86:89], v[150:153], v[212:215], 0
	v_mfma_f32_16x16x32_bf16 v[82:85], v[164:167], v[212:215], 0
	v_mfma_f32_16x16x32_bf16 v[110:113], v[160:163], v[192:195], v[110:113]
	v_mfma_f32_16x16x32_bf16 v[106:109], v[168:171], v[192:195], v[106:109]
	v_mfma_f32_16x16x32_bf16 v[102:105], v[160:163], v[200:203], v[102:105]
	v_mfma_f32_16x16x32_bf16 v[98:101], v[168:171], v[200:203], v[98:101]
	v_mfma_f32_16x16x32_bf16 v[94:97], v[160:163], v[208:211], v[94:97]
	v_mfma_f32_16x16x32_bf16 v[90:93], v[168:171], v[208:211], v[90:93]
	v_mfma_f32_16x16x32_bf16 v[86:89], v[160:163], v[216:219], v[86:89]
	v_mfma_f32_16x16x32_bf16 v[82:85], v[168:171], v[216:219], v[82:85]
	v_mfma_f32_16x16x32_bf16 v[78:81], v[172:175], v[188:191], 0
	v_mfma_f32_16x16x32_bf16 v[74:77], v[180:183], v[188:191], 0
	v_mfma_f32_16x16x32_bf16 v[70:73], v[172:175], v[196:199], 0
	v_mfma_f32_16x16x32_bf16 v[66:69], v[180:183], v[196:199], 0
	v_mfma_f32_16x16x32_bf16 v[62:65], v[172:175], v[204:207], 0
	v_mfma_f32_16x16x32_bf16 v[58:61], v[180:183], v[204:207], 0
	v_mfma_f32_16x16x32_bf16 v[54:57], v[172:175], v[212:215], 0
	v_mfma_f32_16x16x32_bf16 v[50:53], v[180:183], v[212:215], 0
	v_mfma_f32_16x16x32_bf16 v[78:81], v[176:179], v[192:195], v[78:81]
	v_mfma_f32_16x16x32_bf16 v[74:77], v[184:187], v[192:195], v[74:77]
	v_mfma_f32_16x16x32_bf16 v[70:73], v[176:179], v[200:203], v[70:73]
	v_mfma_f32_16x16x32_bf16 v[66:69], v[184:187], v[200:203], v[66:69]
	v_mfma_f32_16x16x32_bf16 v[62:65], v[176:179], v[208:211], v[62:65]
	v_mfma_f32_16x16x32_bf16 v[58:61], v[184:187], v[208:211], v[58:61]
	v_mfma_f32_16x16x32_bf16 v[54:57], v[176:179], v[216:219], v[54:57]
	v_mfma_f32_16x16x32_bf16 v[50:53], v[184:187], v[216:219], v[50:53]
	s_barrier
	s_add_i32 s70, s54, s49
	v_lshl_add_u64 v[154:155], s[42:43], 0, v[132:133]
	s_mov_b32 m0, s70
	ds_read_b128 v[188:191], v159 offset:16384
	ds_read_b128 v[192:195], v159 offset:17408
	ds_read_b128 v[196:199], v159 offset:18432
	ds_read_b128 v[200:203], v159 offset:19456
	ds_read_b128 v[204:207], v159 offset:20480
	ds_read_b128 v[208:211], v159 offset:21504
	ds_read_b128 v[212:215], v159 offset:22528
	ds_read_b128 v[216:219], v159 offset:23552
	global_load_lds_dwordx4 v[154:155], off
	s_add_i32 m0, s70, 0x2000
	s_add_u32 s70, s42, 0x40000
	v_lshl_add_u64 v[220:221], s[42:43], 0, v[136:137]
	s_addc_u32 s71, s43, 0
	s_add_i32 s72, s55, s49
	global_load_lds_dwordx4 v[220:221], off
	v_lshl_add_u64 v[222:223], s[70:71], 0, v[132:133]
	s_mov_b32 m0, s72
	v_lshl_add_u64 v[224:225], s[44:45], 0, v[134:135]
	global_load_lds_dwordx4 v[222:223], off
	v_lshl_add_u64 v[222:223], s[70:71], 0, v[136:137]
	s_add_i32 m0, s72, 0x2000
	s_nop 0
	global_load_lds_dwordx4 v[222:223], off
	v_lshl_add_u64 v[222:223], s[44:45], 0, v[130:131]
	s_mov_b32 m0, s17
	s_nop 0
	global_load_lds_dwordx4 v[222:223], off
	s_mov_b32 m0, s19
	s_nop 0
	global_load_lds_dwordx4 v[224:225], off
	s_waitcnt vmcnt(8)
	s_waitcnt lgkmcnt(0)
	s_barrier
; #define PG8_STAGEA(bufoff, gbase) PG8_STAGE_(bufoff, gbase, voffA)
; #define PG8_STAGEB(bufoff, gbase) PG8_STAGE_(bufoff, gbase, voffB)
; #define PG8_LDA(dst, b, h) do { _Pragma("unroll") for (int m = 0; m < 4; ++m) _Pragma("unroll") for (int k = 0; k < 2; ++k) dst[m][k] = *(const LAS bf16x8*)(lds + PG8_SA(b, h) + aoff + m * 2048 + k * 1024); } while (0)
; #define PG8_LDB(dst, b, h) do { _Pragma("unroll") for (int n = 0; n < 2; ++n) _Pragma("unroll") for (int k = 0; k < 2; ++k) dst[n][k] = *(const LAS bf16x8*)(lds + PG8_SB(b, h) + boff + n * 2048 + k * 1024); } while (0)
; #define PG8_MMA(ai, bj, At, Bt_) do { __builtin_amdgcn_s_setprio(1); _Pragma("unroll") for (int m = 0; m < 4; ++m) _Pragma("unroll") for (int n = 0; n < 2; ++n) _Pragma("unroll") for (int k = 0; k < 2; ++k) \
;         acc[ai][bj][m][n] = __builtin_amdgcn_mfma_f32_16x16x32_bf16(Bt_[n][k], At[m][k], acc[ai][bj][m][n], 0, 0, 0); __builtin_amdgcn_s_setprio(0); } while (0)
; #define PG8_WAIT_V(n) asm volatile("s_waitcnt vmcnt(" #n ")" ::: "memory")
; #define PG8_WAIT_L(n) asm volatile("s_waitcnt lgkmcnt(" #n ")" ::: "memory")
; #define PG8_BAR __builtin_amdgcn_s_barrier()
; #define PG8_SCHED __builtin_amdgcn_sched_barrier(0)
; template <int EK, int SK = -1>
; __device__ __forceinline__ void gemm_phase(LAS unsigned char* lds, const bf16_t* A, const bf16_t* Bt, int nM, int N, int K, const EpiArgs& E) {
;     ...
;             PG8_WAIT_V(8); PG8_WAIT_L(0); PG8_BAR; PG8_MMA(1, 0, At, B0); PG8_MMA(1, 1, At, B1); PG8_BAR; PG8_SCHED;
;             PG8_LDB(B0, 1, 0); PG8_LDB(B1, 1, 1); PG8_SCHED; PG8_LDA(At, 1, 0); PG8_STAGEA(PG8_SA(0, 1), a2 + hstep);
;             PG8_WAIT_V(8); PG8_WAIT_L(0); PG8_BAR; PG8_MMA(0, 0, At, B0); PG8_MMA(0, 1, At, B1); PG8_BAR; PG8_SCHED;
;             PG8_LDA(At, 1, 1); PG8_STAGEB(PG8_SB(1, 0), b3); PG8_STAGEB(PG8_SB(1, 1), b3 + hstep); PG8_STAGEA(PG8_SA(1, 0), a3);
	s_waitcnt lgkmcnt(0)
	v_mfma_f32_16x16x32_bf16 v[46:49], v[150:153], v[188:191], 0
	v_mfma_f32_16x16x32_bf16 v[42:45], v[164:167], v[188:191], 0
	v_mfma_f32_16x16x32_bf16 v[38:41], v[150:153], v[196:199], 0
	v_mfma_f32_16x16x32_bf16 v[34:37], v[164:167], v[196:199], 0
	v_mfma_f32_16x16x32_bf16 v[30:33], v[150:153], v[204:207], 0
	v_mfma_f32_16x16x32_bf16 v[26:29], v[164:167], v[204:207], 0
	v_mfma_f32_16x16x32_bf16 v[22:25], v[150:153], v[212:215], 0
	v_mfma_f32_16x16x32_bf16 v[18:21], v[164:167], v[212:215], 0
	v_mfma_f32_16x16x32_bf16 v[46:49], v[160:163], v[192:195], v[46:49]
	v_mfma_f32_16x16x32_bf16 v[42:45], v[168:171], v[192:195], v[42:45]
	v_mfma_f32_16x16x32_bf16 v[38:41], v[160:163], v[200:203], v[38:41]
	v_mfma_f32_16x16x32_bf16 v[34:37], v[168:171], v[200:203], v[34:37]
	v_mfma_f32_16x16x32_bf16 v[30:33], v[160:163], v[208:211], v[30:33]
	v_mfma_f32_16x16x32_bf16 v[26:29], v[168:171], v[208:211], v[26:29]
	v_mfma_f32_16x16x32_bf16 v[22:25], v[160:163], v[216:219], v[22:25]
	v_mfma_f32_16x16x32_bf16 v[18:21], v[168:171], v[216:219], v[18:21]
	v_mfma_f32_16x16x32_bf16 v[14:17], v[172:175], v[188:191], 0
	v_mfma_f32_16x16x32_bf16 v[10:13], v[180:183], v[188:191], 0
	v_mfma_f32_16x16x32_bf16 v[6:9], v[172:175], v[196:199], 0
	v_mfma_f32_16x16x32_bf16 v[2:5], v[180:183], v[196:199], 0
	v_mfma_f32_16x16x32_bf16 v[114:117], v[172:175], v[204:207], 0
	v_mfma_f32_16x16x32_bf16 v[118:121], v[180:183], v[204:207], 0
	v_mfma_f32_16x16x32_bf16 v[122:125], v[172:175], v[212:215], 0
	v_mfma_f32_16x16x32_bf16 v[126:129], v[180:183], v[212:215], 0
	v_mfma_f32_16x16x32_bf16 v[14:17], v[176:179], v[192:195], v[14:17]
	v_mfma_f32_16x16x32_bf16 v[10:13], v[184:187], v[192:195], v[10:13]
	v_mfma_f32_16x16x32_bf16 v[6:9], v[176:179], v[200:203], v[6:9]
	v_mfma_f32_16x16x32_bf16 v[2:5], v[184:187], v[200:203], v[2:5]
	v_mfma_f32_16x16x32_bf16 v[114:117], v[176:179], v[208:211], v[114:117]
	v_mfma_f32_16x16x32_bf16 v[118:121], v[184:187], v[208:211], v[118:121]
	v_mfma_f32_16x16x32_bf16 v[122:125], v[176:179], v[216:219], v[122:125]
	v_mfma_f32_16x16x32_bf16 v[126:129], v[184:187], v[216:219], v[126:129]
	s_barrier
	s_add_i32 s70, 0, 0x18000
	s_add_i32 s71, 0, 0x1c000
	v_add_u32_e32 v168, s70, v156
	v_add_u32_e32 v184, s71, v156
	ds_read_b128 v[150:153], v168
	ds_read_b128 v[160:163], v168 offset:1024
	ds_read_b128 v[164:167], v168 offset:2048
	ds_read_b128 v[168:171], v168 offset:3072
	ds_read_b128 v[172:175], v184
	ds_read_b128 v[176:179], v184 offset:1024
	ds_read_b128 v[180:183], v184 offset:2048
	ds_read_b128 v[184:187], v184 offset:3072
	s_add_u32 s44, s44, 0x40000
	s_addc_u32 s45, s45, 0
	s_mov_b32 m0, s50
	v_lshl_add_u64 v[226:227], s[44:45], 0, v[130:131]
	ds_read_b128 v[188:191], v159 offset:32768
	ds_read_b128 v[192:195], v159 offset:33792
	ds_read_b128 v[196:199], v159 offset:34816
	ds_read_b128 v[200:203], v159 offset:35840
	ds_read_b128 v[204:207], v159 offset:36864
	ds_read_b128 v[208:211], v159 offset:37888
	ds_read_b128 v[212:215], v159 offset:38912
	ds_read_b128 v[216:219], v159 offset:39936
	global_load_lds_dwordx4 v[226:227], off
	v_lshl_add_u64 v[226:227], s[44:45], 0, v[134:135]
	s_mov_b32 m0, s51
	s_nop 0
	global_load_lds_dwordx4 v[226:227], off
	s_waitcnt vmcnt(8)
	s_waitcnt lgkmcnt(0)
	s_barrier
	s_waitcnt lgkmcnt(0)
	v_mfma_f32_16x16x32_bf16 v[110:113], v[150:153], v[188:191], v[110:113]
	v_mfma_f32_16x16x32_bf16 v[106:109], v[164:167], v[188:191], v[106:109]
	v_mfma_f32_16x16x32_bf16 v[102:105], v[150:153], v[196:199], v[102:105]
	v_mfma_f32_16x16x32_bf16 v[98:101], v[164:167], v[196:199], v[98:101]
	v_mfma_f32_16x16x32_bf16 v[94:97], v[150:153], v[204:207], v[94:97]
	v_mfma_f32_16x16x32_bf16 v[90:93], v[164:167], v[204:207], v[90:93]
	v_mfma_f32_16x16x32_bf16 v[86:89], v[150:153], v[212:215], v[86:89]
	v_mfma_f32_16x16x32_bf16 v[82:85], v[164:167], v[212:215], v[82:85]
	v_mfma_f32_16x16x32_bf16 v[110:113], v[160:163], v[192:195], v[110:113]
	v_mfma_f32_16x16x32_bf16 v[106:109], v[168:171], v[192:195], v[106:109]
	v_mfma_f32_16x16x32_bf16 v[102:105], v[160:163], v[200:203], v[102:105]
	v_mfma_f32_16x16x32_bf16 v[98:101], v[168:171], v[200:203], v[98:101]
	v_mfma_f32_16x16x32_bf16 v[94:97], v[160:163], v[208:211], v[94:97]
	v_mfma_f32_16x16x32_bf16 v[90:93], v[168:171], v[208:211], v[90:93]
	v_mfma_f32_16x16x32_bf16 v[86:89], v[160:163], v[216:219], v[86:89]
	v_mfma_f32_16x16x32_bf16 v[82:85], v[168:171], v[216:219], v[82:85]
	v_mfma_f32_16x16x32_bf16 v[78:81], v[172:175], v[188:191], v[78:81]
	v_mfma_f32_16x16x32_bf16 v[74:77], v[180:183], v[188:191], v[74:77]
	v_mfma_f32_16x16x32_bf16 v[70:73], v[172:175], v[196:199], v[70:73]
	v_mfma_f32_16x16x32_bf16 v[66:69], v[180:183], v[196:199], v[66:69]
	v_mfma_f32_16x16x32_bf16 v[62:65], v[172:175], v[204:207], v[62:65]
	v_mfma_f32_16x16x32_bf16 v[58:61], v[180:183], v[204:207], v[58:61]
	v_mfma_f32_16x16x32_bf16 v[54:57], v[172:175], v[212:215], v[54:57]
	v_mfma_f32_16x16x32_bf16 v[50:53], v[180:183], v[212:215], v[50:53]
	v_mfma_f32_16x16x32_bf16 v[78:81], v[176:179], v[192:195], v[78:81]
	v_mfma_f32_16x16x32_bf16 v[74:77], v[184:187], v[192:195], v[74:77]
	v_mfma_f32_16x16x32_bf16 v[70:73], v[176:179], v[200:203], v[70:73]
	v_mfma_f32_16x16x32_bf16 v[66:69], v[184:187], v[200:203], v[66:69]
	v_mfma_f32_16x16x32_bf16 v[62:65], v[176:179], v[208:211], v[62:65]
	v_mfma_f32_16x16x32_bf16 v[58:61], v[184:187], v[208:211], v[58:61]
	v_mfma_f32_16x16x32_bf16 v[54:57], v[176:179], v[216:219], v[54:57]
	v_mfma_f32_16x16x32_bf16 v[50:53], v[184:187], v[216:219], v[50:53]
	s_barrier
; #define PG8_STAGEA(bufoff, gbase) PG8_STAGE_(bufoff, gbase, voffA)
; #define PG8_STAGEB(bufoff, gbase) PG8_STAGE_(bufoff, gbase, voffB)
; #define PG8_LDA(dst, b, h) do { _Pragma("unroll") for (int m = 0; m < 4; ++m) _Pragma("unroll") for (int k = 0; k < 2; ++k) dst[m][k] = *(const LAS bf16x8*)(lds + PG8_SA(b, h) + aoff + m * 2048 + k * 1024); } while (0)
; #define PG8_MMA(ai, bj, At, Bt_) do { __builtin_amdgcn_s_setprio(1); _Pragma("unroll") for (int m = 0; m < 4; ++m) _Pragma("unroll") for (int n = 0; n < 2; ++n) _Pragma("unroll") for (int k = 0; k < 2; ++k) \
;         acc[ai][bj][m][n] = __builtin_amdgcn_mfma_f32_16x16x32_bf16(Bt_[n][k], At[m][k], acc[ai][bj][m][n], 0, 0, 0); __builtin_amdgcn_s_setprio(0); } while (0)
; #define PG8_WAIT_V(n) asm volatile("s_waitcnt vmcnt(" #n ")" ::: "memory")
; #define PG8_WAIT_L(n) asm volatile("s_waitcnt lgkmcnt(" #n ")" ::: "memory")
; #define PG8_BAR __builtin_amdgcn_s_barrier()
; #define PG8_SCHED __builtin_amdgcn_sched_barrier(0)
; template <int EK, int SK = -1>
; __device__ __forceinline__ void gemm_phase(LAS unsigned char* lds, const bf16_t* A, const bf16_t* Bt, int nM, int N, int K, const EpiArgs& E) {
;     ...
;             PG8_LDA(At, 1, 1); PG8_STAGEB(PG8_SB(1, 0), b3); PG8_STAGEB(PG8_SB(1, 1), b3 + hstep); PG8_STAGEA(PG8_SA(1, 0), a3);
;             PG8_WAIT_V(8); PG8_WAIT_L(0); PG8_BAR; PG8_MMA(1, 0, At, B0); PG8_MMA(1, 1, At, B1); PG8_BAR; PG8_SCHED;
;         }
	s_add_i32 s44, s70, s49
	v_lshl_add_u64 v[154:155], v[154:155], 0, s[10:11]
	s_mov_b32 m0, s44
	ds_read_b128 v[188:191], v159 offset:49152
	ds_read_b128 v[192:195], v159 offset:50176
	ds_read_b128 v[196:199], v159 offset:51200
	ds_read_b128 v[200:203], v159 offset:52224
	ds_read_b128 v[204:207], v159 offset:53248
	ds_read_b128 v[208:211], v159 offset:54272
	ds_read_b128 v[212:215], v159 offset:55296
	ds_read_b128 v[216:219], v159 offset:56320
	global_load_lds_dwordx4 v[154:155], off
	s_add_i32 m0, s44, 0x2000
	s_add_u32 s42, s42, 0x40080
	v_lshl_add_u64 v[154:155], v[220:221], 0, s[10:11]
	s_addc_u32 s43, s43, 0
	s_add_i32 s44, s71, s49
	global_load_lds_dwordx4 v[154:155], off
	v_lshl_add_u64 v[154:155], s[42:43], 0, v[132:133]
	s_mov_b32 m0, s44
	s_nop 0
	global_load_lds_dwordx4 v[154:155], off
	v_lshl_add_u64 v[154:155], s[42:43], 0, v[136:137]
	s_add_i32 m0, s44, 0x2000
	s_nop 0
	global_load_lds_dwordx4 v[154:155], off
	v_lshl_add_u64 v[154:155], v[222:223], 0, s[10:11]
	s_mov_b32 m0, s52
	s_nop 0
	global_load_lds_dwordx4 v[154:155], off
	v_lshl_add_u64 v[154:155], v[224:225], 0, s[10:11]
	s_mov_b32 m0, s53
	s_nop 0
	global_load_lds_dwordx4 v[154:155], off
	s_waitcnt vmcnt(8)
	s_waitcnt lgkmcnt(0)
	s_barrier
	s_waitcnt lgkmcnt(0)
	v_mfma_f32_16x16x32_bf16 v[46:49], v[150:153], v[188:191], v[46:49]
	v_mfma_f32_16x16x32_bf16 v[42:45], v[164:167], v[188:191], v[42:45]
	v_mfma_f32_16x16x32_bf16 v[38:41], v[150:153], v[196:199], v[38:41]
	v_mfma_f32_16x16x32_bf16 v[34:37], v[164:167], v[196:199], v[34:37]
	v_mfma_f32_16x16x32_bf16 v[30:33], v[150:153], v[204:207], v[30:33]
	v_mfma_f32_16x16x32_bf16 v[26:29], v[164:167], v[204:207], v[26:29]
	v_mfma_f32_16x16x32_bf16 v[22:25], v[150:153], v[212:215], v[22:25]
	v_mfma_f32_16x16x32_bf16 v[18:21], v[164:167], v[212:215], v[18:21]
	v_mfma_f32_16x16x32_bf16 v[46:49], v[160:163], v[192:195], v[46:49]
	v_mfma_f32_16x16x32_bf16 v[42:45], v[168:171], v[192:195], v[42:45]
	v_mfma_f32_16x16x32_bf16 v[38:41], v[160:163], v[200:203], v[38:41]
	v_mfma_f32_16x16x32_bf16 v[34:37], v[168:171], v[200:203], v[34:37]
	v_mfma_f32_16x16x32_bf16 v[30:33], v[160:163], v[208:211], v[30:33]
	v_mfma_f32_16x16x32_bf16 v[26:29], v[168:171], v[208:211], v[26:29]
	v_mfma_f32_16x16x32_bf16 v[22:25], v[160:163], v[216:219], v[22:25]
	v_mfma_f32_16x16x32_bf16 v[18:21], v[168:171], v[216:219], v[18:21]
	v_mfma_f32_16x16x32_bf16 v[14:17], v[172:175], v[188:191], v[14:17]
	v_mfma_f32_16x16x32_bf16 v[10:13], v[180:183], v[188:191], v[10:13]
	v_mfma_f32_16x16x32_bf16 v[6:9], v[172:175], v[196:199], v[6:9]
	v_mfma_f32_16x16x32_bf16 v[2:5], v[180:183], v[196:199], v[2:5]
	v_mfma_f32_16x16x32_bf16 v[114:117], v[172:175], v[204:207], v[114:117]
	v_mfma_f32_16x16x32_bf16 v[118:121], v[180:183], v[204:207], v[118:121]
	v_mfma_f32_16x16x32_bf16 v[122:125], v[172:175], v[212:215], v[122:125]
	v_mfma_f32_16x16x32_bf16 v[126:129], v[180:183], v[212:215], v[126:129]
	v_mfma_f32_16x16x32_bf16 v[14:17], v[176:179], v[192:195], v[14:17]
	v_mfma_f32_16x16x32_bf16 v[10:13], v[184:187], v[192:195], v[10:13]
	v_mfma_f32_16x16x32_bf16 v[6:9], v[176:179], v[200:203], v[6:9]
	v_mfma_f32_16x16x32_bf16 v[2:5], v[184:187], v[200:203], v[2:5]
	v_mfma_f32_16x16x32_bf16 v[114:117], v[176:179], v[208:211], v[114:117]
	v_mfma_f32_16x16x32_bf16 v[118:121], v[184:187], v[208:211], v[118:121]
	v_mfma_f32_16x16x32_bf16 v[122:125], v[176:179], v[216:219], v[122:125]
	v_mfma_f32_16x16x32_bf16 v[126:129], v[184:187], v[216:219], v[126:129]
	s_barrier
	s_add_i32 s69, s69, 2
	s_add_u32 s40, s40, 0x100
	s_addc_u32 s41, s41, 0
	s_cmp_gt_u32 s69, 13
	s_cbranch_scc0 .LBB0_1245
	s_branch .Lmy_kexit_6

; __device__ __forceinline__ u32x2 pack4(f32x4 v) { u32x2 w; w.x = cvt_pk_bf16(v[0], v[1]); w.y = cvt_pk_bf16(v[2], v[3]); return w; }
; __device__ __forceinline__ float silu1(float g) { return g * __builtin_amdgcn_rcpf(1.0f + __expf(-g)); }
; __device__ __forceinline__ f32x4 swiglu4(f32x4 g, f32x4 u) { return (f32x4){silu1(g[0]) * u[0], silu1(g[1]) * u[1], silu1(g[2]) * u[2], silu1(g[3]) * u[3]}; }
; template <int EK>
; __device__ __forceinline__ void epi_tile(const f32x4 (&acc)[2][2][4][2], const Unit& u, int wr, int wc, int fr, int fq, const EpiArgs& E, const LAS float* rt) {
;     ...
;             } else if (EK == EK_SWIGLU) {
;                 const float r = rr[ai][m];
;                 { const int col = u.pn * HALF + wc * 32 + fq * 8;
;                     const u32x2 lo = pack4(swiglu4(acc[ai][0][m][0] * r, acc[ai][1][m][0] * r)), hi = pack4(swiglu4(acc[ai][0][m][1] * r, acc[ai][1][m][1] * r));
;                     *(u32x4*)(E.ob + (size_t)row * DFF + col) = (u32x4){lo.x, lo.y, hi.x, hi.y}; }
.LBB0_1248:
	v_lshl_add_u32 v146, s57, 10, v157
	ds_read2_b32 v[166:167], v146 offset1:16
	ds_read2_b32 v[154:155], v146 offset0:32 offset1:48
	ds_read2_b32 v[152:153], v146 offset0:128 offset1:144
	ds_read2_b32 v[146:147], v146 offset0:160 offset1:176
	v_lshl_or_b32 v150, s16, 7, v158
	s_waitcnt lgkmcnt(0)
	v_mul_f32_e32 v180, 0xbfb8aa3b, v166
	v_mul_f32_e32 v181, v166, v166
	v_mul_f32_e32 v182, 0xbfb8aa3b, v167
	v_mul_f32_e32 v183, v167, v167
	v_mul_f32_e32 v184, 0xbfb8aa3b, v154
	v_mul_f32_e32 v185, v154, v154
	v_mul_f32_e32 v186, 0xbfb8aa3b, v155
	v_mul_f32_e32 v187, v155, v155
	v_mul_f32_e32 v188, 0xbfb8aa3b, v152
	v_mul_f32_e32 v189, v152, v152
	v_mul_f32_e32 v190, 0xbfb8aa3b, v153
	v_mul_f32_e32 v191, v153, v153
	v_mul_f32_e32 v192, 0xbfb8aa3b, v146
	v_mul_f32_e32 v193, v146, v146
	v_mul_f32_e32 v194, 0xbfb8aa3b, v147
	v_mul_f32_e32 v195, v147, v147
	v_lshl_add_u32 v160, s18, 8, v1
	v_ashrrev_i32_e32 v151, 31, v150
	v_lshlrev_b64 v[150:151], 1, v[150:151]
	s_add_u32 s40, s59, 0xffffff00
	v_or_b32_e32 v172, 16, v160
	s_addc_u32 s41, s66, -1
	v_mov_b64_e32 v[148:149], s[64:65]
	v_mad_i64_i32 v[168:169], s[42:43], v160, s56, v[148:149]
	v_lshl_add_u64 v[168:169], v[168:169], 0, v[150:151]
	v_pk_mul_f32 v[196:197], v[110:111], v[180:181] op_sel_hi:[1,0]
	v_pk_mul_f32 v[198:199], v[112:113], v[180:181] op_sel_hi:[1,0]
	v_pk_mul_f32 v[200:201], v[110:111], v[78:79]
	v_exp_f32_e32 v196, v196
	v_exp_f32_e32 v197, v197
	v_exp_f32_e32 v198, v198
	v_exp_f32_e32 v199, v199
	v_pk_mul_f32 v[202:203], v[112:113], v[80:81]
	v_pk_add_f32 v[196:197], v[196:197], 1.0 op_sel_hi:[1,0]
	v_pk_add_f32 v[198:199], v[198:199], 1.0 op_sel_hi:[1,0]
	v_pk_mul_f32 v[200:201], v[200:201], v[180:181] op_sel:[0,1] op_sel_hi:[1,1]
	v_rcp_f32_e32 v196, v196
	v_rcp_f32_e32 v197, v197
	v_rcp_f32_e32 v198, v198
	v_rcp_f32_e32 v199, v199
	v_pk_mul_f32 v[202:203], v[202:203], v[180:181] op_sel:[0,1] op_sel_hi:[1,1]
	v_pk_mul_f32 v[200:201], v[200:201], v[196:197]
	v_pk_mul_f32 v[202:203], v[202:203], v[198:199]
	v_cvt_pk_bf16_f32 v204, v200, v201
	v_cvt_pk_bf16_f32 v205, v202, v203
	v_pk_mul_f32 v[196:197], v[106:107], v[180:181] op_sel_hi:[1,0]
	v_pk_mul_f32 v[198:199], v[108:109], v[180:181] op_sel_hi:[1,0]
	v_pk_mul_f32 v[200:201], v[106:107], v[74:75]
	v_exp_f32_e32 v196, v196
	v_exp_f32_e32 v197, v197
	v_exp_f32_e32 v198, v198
	v_exp_f32_e32 v199, v199
	v_pk_mul_f32 v[202:203], v[108:109], v[76:77]
	v_pk_add_f32 v[196:197], v[196:197], 1.0 op_sel_hi:[1,0]
	v_pk_add_f32 v[198:199], v[198:199], 1.0 op_sel_hi:[1,0]
	v_pk_mul_f32 v[200:201], v[200:201], v[180:181] op_sel:[0,1] op_sel_hi:[1,1]
	v_rcp_f32_e32 v196, v196
	v_rcp_f32_e32 v197, v197
	v_rcp_f32_e32 v198, v198
	v_rcp_f32_e32 v199, v199
	v_pk_mul_f32 v[202:203], v[202:203], v[180:181] op_sel:[0,1] op_sel_hi:[1,1]
	v_pk_mul_f32 v[200:201], v[200:201], v[196:197]
	v_pk_mul_f32 v[202:203], v[202:203], v[198:199]
	v_cvt_pk_bf16_f32 v206, v200, v201
	v_cvt_pk_bf16_f32 v207, v202, v203
	global_store_dwordx4 v[168:169], v[204:207], off
	s_andn2_b64 vcc, exec, s[6:7]
	v_mad_i64_i32 v[166:167], s[42:43], v172, s56, v[148:149]
	v_lshl_add_u64 v[166:167], v[166:167], 0, v[150:151]
	v_pk_mul_f32 v[196:197], v[102:103], v[182:183] op_sel_hi:[1,0]
	v_pk_mul_f32 v[198:199], v[104:105], v[182:183] op_sel_hi:[1,0]
	v_pk_mul_f32 v[200:201], v[102:103], v[70:71]
	v_exp_f32_e32 v196, v196
	v_exp_f32_e32 v197, v197
	v_exp_f32_e32 v198, v198
	v_exp_f32_e32 v199, v199
	v_pk_mul_f32 v[202:203], v[104:105], v[72:73]
	v_pk_add_f32 v[196:197], v[196:197], 1.0 op_sel_hi:[1,0]
	v_pk_add_f32 v[198:199], v[198:199], 1.0 op_sel_hi:[1,0]
	v_pk_mul_f32 v[200:201], v[200:201], v[182:183] op_sel:[0,1] op_sel_hi:[1,1]
	v_rcp_f32_e32 v196, v196
	v_rcp_f32_e32 v197, v197
	v_rcp_f32_e32 v198, v198
	v_rcp_f32_e32 v199, v199
	v_pk_mul_f32 v[202:203], v[202:203], v[182:183] op_sel:[0,1] op_sel_hi:[1,1]
	v_pk_mul_f32 v[200:201], v[200:201], v[196:197]
	v_pk_mul_f32 v[202:203], v[202:203], v[198:199]
	v_cvt_pk_bf16_f32 v208, v200, v201
	v_cvt_pk_bf16_f32 v209, v202, v203
	v_pk_mul_f32 v[196:197], v[98:99], v[182:183] op_sel_hi:[1,0]
	v_pk_mul_f32 v[198:199], v[100:101], v[182:183] op_sel_hi:[1,0]
	v_pk_mul_f32 v[200:201], v[98:99], v[66:67]
	v_exp_f32_e32 v196, v196
	v_exp_f32_e32 v197, v197
	v_exp_f32_e32 v198, v198
	v_exp_f32_e32 v199, v199
	v_pk_mul_f32 v[202:203], v[100:101], v[68:69]
	v_pk_add_f32 v[196:197], v[196:197], 1.0 op_sel_hi:[1,0]
	v_pk_add_f32 v[198:199], v[198:199], 1.0 op_sel_hi:[1,0]
	v_pk_mul_f32 v[200:201], v[200:201], v[182:183] op_sel:[0,1] op_sel_hi:[1,1]
	v_rcp_f32_e32 v196, v196
	v_rcp_f32_e32 v197, v197
	v_rcp_f32_e32 v198, v198
	v_rcp_f32_e32 v199, v199
	v_pk_mul_f32 v[202:203], v[202:203], v[182:183] op_sel:[0,1] op_sel_hi:[1,1]
	v_pk_mul_f32 v[200:201], v[200:201], v[196:197]
	v_pk_mul_f32 v[202:203], v[202:203], v[198:199]
	v_cvt_pk_bf16_f32 v210, v200, v201
	v_cvt_pk_bf16_f32 v211, v202, v203
	global_store_dwordx4 v[166:167], v[208:211], off
	v_or_b32_e32 v172, 32, v160
	v_mad_i64_i32 v[166:167], s[42:43], v172, s56, v[148:149]
	v_lshl_add_u64 v[166:167], v[166:167], 0, v[150:151]
	v_pk_mul_f32 v[196:197], v[94:95], v[184:185] op_sel_hi:[1,0]
	v_pk_mul_f32 v[198:199], v[96:97], v[184:185] op_sel_hi:[1,0]
	v_pk_mul_f32 v[200:201], v[94:95], v[62:63]
	v_exp_f32_e32 v196, v196
	v_exp_f32_e32 v197, v197
	v_exp_f32_e32 v198, v198
	v_exp_f32_e32 v199, v199
	v_pk_mul_f32 v[202:203], v[96:97], v[64:65]
	v_pk_add_f32 v[196:197], v[196:197], 1.0 op_sel_hi:[1,0]
	v_pk_add_f32 v[198:199], v[198:199], 1.0 op_sel_hi:[1,0]
	v_pk_mul_f32 v[200:201], v[200:201], v[184:185] op_sel:[0,1] op_sel_hi:[1,1]
	v_rcp_f32_e32 v196, v196
; __device__ __forceinline__ u32x2 pack4(f32x4 v) { u32x2 w; w.x = cvt_pk_bf16(v[0], v[1]); w.y = cvt_pk_bf16(v[2], v[3]); return w; }
; __device__ __forceinline__ float silu1(float g) { return g * __builtin_amdgcn_rcpf(1.0f + __expf(-g)); }
; __device__ __forceinline__ f32x4 swiglu4(f32x4 g, f32x4 u) { return (f32x4){silu1(g[0]) * u[0], silu1(g[1]) * u[1], silu1(g[2]) * u[2], silu1(g[3]) * u[3]}; }
; template <int EK>
; __device__ __forceinline__ void epi_tile(const f32x4 (&acc)[2][2][4][2], const Unit& u, int wr, int wc, int fr, int fq, const EpiArgs& E, const LAS float* rt) {
;     ...
;             } else if (EK == EK_SWIGLU) {
;                 const float r = rr[ai][m];
;                 { const int col = u.pn * HALF + wc * 32 + fq * 8;
;                     const u32x2 lo = pack4(swiglu4(acc[ai][0][m][0] * r, acc[ai][1][m][0] * r)), hi = pack4(swiglu4(acc[ai][0][m][1] * r, acc[ai][1][m][1] * r));
;                     *(u32x4*)(E.ob + (size_t)row * DFF + col) = (u32x4){lo.x, lo.y, hi.x, hi.y}; }
	v_rcp_f32_e32 v197, v197
	v_rcp_f32_e32 v198, v198
	v_rcp_f32_e32 v199, v199
	v_pk_mul_f32 v[202:203], v[202:203], v[184:185] op_sel:[0,1] op_sel_hi:[1,1]
	v_pk_mul_f32 v[200:201], v[200:201], v[196:197]
	v_pk_mul_f32 v[202:203], v[202:203], v[198:199]
	v_cvt_pk_bf16_f32 v204, v200, v201
	v_cvt_pk_bf16_f32 v205, v202, v203
	v_pk_mul_f32 v[196:197], v[90:91], v[184:185] op_sel_hi:[1,0]
	v_pk_mul_f32 v[198:199], v[92:93], v[184:185] op_sel_hi:[1,0]
	v_pk_mul_f32 v[200:201], v[90:91], v[58:59]
	v_exp_f32_e32 v196, v196
	v_exp_f32_e32 v197, v197
	v_exp_f32_e32 v198, v198
	v_exp_f32_e32 v199, v199
	v_pk_mul_f32 v[202:203], v[92:93], v[60:61]
	v_pk_add_f32 v[196:197], v[196:197], 1.0 op_sel_hi:[1,0]
	v_pk_add_f32 v[198:199], v[198:199], 1.0 op_sel_hi:[1,0]
	v_pk_mul_f32 v[200:201], v[200:201], v[184:185] op_sel:[0,1] op_sel_hi:[1,1]
	v_rcp_f32_e32 v196, v196
	v_rcp_f32_e32 v197, v197
	v_rcp_f32_e32 v198, v198
	v_rcp_f32_e32 v199, v199
	v_pk_mul_f32 v[202:203], v[202:203], v[184:185] op_sel:[0,1] op_sel_hi:[1,1]
	v_pk_mul_f32 v[200:201], v[200:201], v[196:197]
	v_pk_mul_f32 v[202:203], v[202:203], v[198:199]
	v_cvt_pk_bf16_f32 v206, v200, v201
	v_cvt_pk_bf16_f32 v207, v202, v203
	global_store_dwordx4 v[166:167], v[204:207], off
	v_or_b32_e32 v161, 48, v160
	v_mad_i64_i32 v[154:155], s[42:43], v161, s56, v[148:149]
	v_lshl_add_u64 v[154:155], v[154:155], 0, v[150:151]
	v_pk_mul_f32 v[196:197], v[86:87], v[186:187] op_sel_hi:[1,0]
	v_pk_mul_f32 v[198:199], v[88:89], v[186:187] op_sel_hi:[1,0]
	v_pk_mul_f32 v[200:201], v[86:87], v[54:55]
	v_exp_f32_e32 v196, v196
	v_exp_f32_e32 v197, v197
	v_exp_f32_e32 v198, v198
	v_exp_f32_e32 v199, v199
	v_pk_mul_f32 v[202:203], v[88:89], v[56:57]
	v_pk_add_f32 v[196:197], v[196:197], 1.0 op_sel_hi:[1,0]
	v_pk_add_f32 v[198:199], v[198:199], 1.0 op_sel_hi:[1,0]
	v_pk_mul_f32 v[200:201], v[200:201], v[186:187] op_sel:[0,1] op_sel_hi:[1,1]
	v_rcp_f32_e32 v196, v196
	v_rcp_f32_e32 v197, v197
	v_rcp_f32_e32 v198, v198
	v_rcp_f32_e32 v199, v199
	v_pk_mul_f32 v[202:203], v[202:203], v[186:187] op_sel:[0,1] op_sel_hi:[1,1]
	v_pk_mul_f32 v[200:201], v[200:201], v[196:197]
	v_pk_mul_f32 v[202:203], v[202:203], v[198:199]
	v_cvt_pk_bf16_f32 v208, v200, v201
	v_cvt_pk_bf16_f32 v209, v202, v203
	v_pk_mul_f32 v[196:197], v[82:83], v[186:187] op_sel_hi:[1,0]
	v_pk_mul_f32 v[198:199], v[84:85], v[186:187] op_sel_hi:[1,0]
	v_pk_mul_f32 v[200:201], v[82:83], v[50:51]
	v_exp_f32_e32 v196, v196
	v_exp_f32_e32 v197, v197
	v_exp_f32_e32 v198, v198
	v_exp_f32_e32 v199, v199
	v_pk_mul_f32 v[202:203], v[84:85], v[52:53]
	v_pk_add_f32 v[196:197], v[196:197], 1.0 op_sel_hi:[1,0]
	v_pk_add_f32 v[198:199], v[198:199], 1.0 op_sel_hi:[1,0]
	v_pk_mul_f32 v[200:201], v[200:201], v[186:187] op_sel:[0,1] op_sel_hi:[1,1]
	v_rcp_f32_e32 v196, v196
	v_rcp_f32_e32 v197, v197
	v_rcp_f32_e32 v198, v198
	v_rcp_f32_e32 v199, v199
	v_pk_mul_f32 v[202:203], v[202:203], v[186:187] op_sel:[0,1] op_sel_hi:[1,1]
	v_pk_mul_f32 v[200:201], v[200:201], v[196:197]
	v_pk_mul_f32 v[202:203], v[202:203], v[198:199]
	v_cvt_pk_bf16_f32 v210, v200, v201
	v_cvt_pk_bf16_f32 v211, v202, v203
	global_store_dwordx4 v[154:155], v[208:211], off
	v_add_u32_e32 v170, 0x80, v160
	v_mad_i64_i32 v[154:155], s[42:43], v170, s56, v[148:149]
	v_lshl_add_u64 v[154:155], v[154:155], 0, v[150:151]
	v_pk_mul_f32 v[196:197], v[46:47], v[188:189] op_sel_hi:[1,0]
	v_pk_mul_f32 v[198:199], v[48:49], v[188:189] op_sel_hi:[1,0]
	v_pk_mul_f32 v[200:201], v[46:47], v[14:15]
	v_exp_f32_e32 v196, v196
	v_exp_f32_e32 v197, v197
	v_exp_f32_e32 v198, v198
	v_exp_f32_e32 v199, v199
	v_pk_mul_f32 v[202:203], v[48:49], v[16:17]
	v_pk_add_f32 v[196:197], v[196:197], 1.0 op_sel_hi:[1,0]
	v_pk_add_f32 v[198:199], v[198:199], 1.0 op_sel_hi:[1,0]
	v_pk_mul_f32 v[200:201], v[200:201], v[188:189] op_sel:[0,1] op_sel_hi:[1,1]
	v_rcp_f32_e32 v196, v196
	v_rcp_f32_e32 v197, v197
	v_rcp_f32_e32 v198, v198
	v_rcp_f32_e32 v199, v199
	v_pk_mul_f32 v[202:203], v[202:203], v[188:189] op_sel:[0,1] op_sel_hi:[1,1]
	v_pk_mul_f32 v[200:201], v[200:201], v[196:197]
	v_pk_mul_f32 v[202:203], v[202:203], v[198:199]
	v_cvt_pk_bf16_f32 v204, v200, v201
	v_cvt_pk_bf16_f32 v205, v202, v203
	v_pk_mul_f32 v[196:197], v[42:43], v[188:189] op_sel_hi:[1,0]
	v_pk_mul_f32 v[198:199], v[44:45], v[188:189] op_sel_hi:[1,0]
	v_pk_mul_f32 v[200:201], v[42:43], v[10:11]
	v_exp_f32_e32 v196, v196
	v_exp_f32_e32 v197, v197
	v_exp_f32_e32 v198, v198
	v_exp_f32_e32 v199, v199
	v_pk_mul_f32 v[202:203], v[44:45], v[12:13]
	v_pk_add_f32 v[196:197], v[196:197], 1.0 op_sel_hi:[1,0]
	v_pk_add_f32 v[198:199], v[198:199], 1.0 op_sel_hi:[1,0]
	v_pk_mul_f32 v[200:201], v[200:201], v[188:189] op_sel:[0,1] op_sel_hi:[1,1]
	v_rcp_f32_e32 v196, v196
	v_rcp_f32_e32 v197, v197
	v_rcp_f32_e32 v198, v198
	v_rcp_f32_e32 v199, v199
	v_pk_mul_f32 v[202:203], v[202:203], v[188:189] op_sel:[0,1] op_sel_hi:[1,1]
	v_pk_mul_f32 v[200:201], v[200:201], v[196:197]
	v_pk_mul_f32 v[202:203], v[202:203], v[198:199]
	v_cvt_pk_bf16_f32 v206, v200, v201
	v_cvt_pk_bf16_f32 v207, v202, v203
	global_store_dwordx4 v[154:155], v[204:207], off
	v_add_u32_e32 v161, 0x90, v160
	v_mad_i64_i32 v[162:163], s[42:43], v161, s56, v[148:149]
	v_lshl_add_u64 v[162:163], v[162:163], 0, v[150:151]
	v_pk_mul_f32 v[196:197], v[38:39], v[190:191] op_sel_hi:[1,0]
	v_pk_mul_f32 v[198:199], v[40:41], v[190:191] op_sel_hi:[1,0]
	v_pk_mul_f32 v[200:201], v[38:39], v[6:7]
	v_exp_f32_e32 v196, v196
	v_exp_f32_e32 v197, v197
	v_exp_f32_e32 v198, v198
	v_exp_f32_e32 v199, v199
; __device__ __forceinline__ u32x2 pack4(f32x4 v) { u32x2 w; w.x = cvt_pk_bf16(v[0], v[1]); w.y = cvt_pk_bf16(v[2], v[3]); return w; }
; __device__ __forceinline__ float silu1(float g) { return g * __builtin_amdgcn_rcpf(1.0f + __expf(-g)); }
; __device__ __forceinline__ f32x4 swiglu4(f32x4 g, f32x4 u) { return (f32x4){silu1(g[0]) * u[0], silu1(g[1]) * u[1], silu1(g[2]) * u[2], silu1(g[3]) * u[3]}; }
; template <int EK>
; __device__ __forceinline__ void epi_tile(const f32x4 (&acc)[2][2][4][2], const Unit& u, int wr, int wc, int fr, int fq, const EpiArgs& E, const LAS float* rt) {
;     ...
;             } else if (EK == EK_SWIGLU) {
;                 const float r = rr[ai][m];
;                 { const int col = u.pn * HALF + wc * 32 + fq * 8;
;                     const u32x2 lo = pack4(swiglu4(acc[ai][0][m][0] * r, acc[ai][1][m][0] * r)), hi = pack4(swiglu4(acc[ai][0][m][1] * r, acc[ai][1][m][1] * r));
;                     *(u32x4*)(E.ob + (size_t)row * DFF + col) = (u32x4){lo.x, lo.y, hi.x, hi.y}; }
	v_pk_mul_f32 v[202:203], v[40:41], v[8:9]
	v_pk_add_f32 v[196:197], v[196:197], 1.0 op_sel_hi:[1,0]
	v_pk_add_f32 v[198:199], v[198:199], 1.0 op_sel_hi:[1,0]
	v_pk_mul_f32 v[200:201], v[200:201], v[190:191] op_sel:[0,1] op_sel_hi:[1,1]
	v_rcp_f32_e32 v196, v196
	v_rcp_f32_e32 v197, v197
	v_rcp_f32_e32 v198, v198
	v_rcp_f32_e32 v199, v199
	v_pk_mul_f32 v[202:203], v[202:203], v[190:191] op_sel:[0,1] op_sel_hi:[1,1]
	v_pk_mul_f32 v[200:201], v[200:201], v[196:197]
	v_pk_mul_f32 v[202:203], v[202:203], v[198:199]
	v_cvt_pk_bf16_f32 v208, v200, v201
	v_cvt_pk_bf16_f32 v209, v202, v203
	v_pk_mul_f32 v[196:197], v[34:35], v[190:191] op_sel_hi:[1,0]
	v_pk_mul_f32 v[198:199], v[36:37], v[190:191] op_sel_hi:[1,0]
	v_pk_mul_f32 v[200:201], v[34:35], v[2:3]
	v_exp_f32_e32 v196, v196
	v_exp_f32_e32 v197, v197
	v_exp_f32_e32 v198, v198
	v_exp_f32_e32 v199, v199
	v_pk_mul_f32 v[202:203], v[36:37], v[4:5]
	v_pk_add_f32 v[196:197], v[196:197], 1.0 op_sel_hi:[1,0]
	v_pk_add_f32 v[198:199], v[198:199], 1.0 op_sel_hi:[1,0]
	v_pk_mul_f32 v[200:201], v[200:201], v[190:191] op_sel:[0,1] op_sel_hi:[1,1]
	v_rcp_f32_e32 v196, v196
	v_rcp_f32_e32 v197, v197
	v_rcp_f32_e32 v198, v198
	v_rcp_f32_e32 v199, v199
	v_pk_mul_f32 v[202:203], v[202:203], v[190:191] op_sel:[0,1] op_sel_hi:[1,1]
	v_pk_mul_f32 v[200:201], v[200:201], v[196:197]
	v_pk_mul_f32 v[202:203], v[202:203], v[198:199]
	v_cvt_pk_bf16_f32 v210, v200, v201
	v_cvt_pk_bf16_f32 v211, v202, v203
	global_store_dwordx4 v[162:163], v[208:211], off
	v_add_u32_e32 v168, 0xa0, v160
	v_mad_i64_i32 v[162:163], s[42:43], v168, s56, v[148:149]
	v_lshl_add_u64 v[162:163], v[162:163], 0, v[150:151]
	v_pk_mul_f32 v[196:197], v[30:31], v[192:193] op_sel_hi:[1,0]
	v_pk_mul_f32 v[198:199], v[32:33], v[192:193] op_sel_hi:[1,0]
	v_pk_mul_f32 v[200:201], v[30:31], v[114:115]
	v_exp_f32_e32 v196, v196
	v_exp_f32_e32 v197, v197
	v_exp_f32_e32 v198, v198
	v_exp_f32_e32 v199, v199
	v_pk_mul_f32 v[202:203], v[32:33], v[116:117]
	v_pk_add_f32 v[196:197], v[196:197], 1.0 op_sel_hi:[1,0]
	v_pk_add_f32 v[198:199], v[198:199], 1.0 op_sel_hi:[1,0]
	v_pk_mul_f32 v[200:201], v[200:201], v[192:193] op_sel:[0,1] op_sel_hi:[1,1]
	v_rcp_f32_e32 v196, v196
	v_rcp_f32_e32 v197, v197
	v_rcp_f32_e32 v198, v198
	v_rcp_f32_e32 v199, v199
	v_pk_mul_f32 v[202:203], v[202:203], v[192:193] op_sel:[0,1] op_sel_hi:[1,1]
	v_pk_mul_f32 v[200:201], v[200:201], v[196:197]
	v_pk_mul_f32 v[202:203], v[202:203], v[198:199]
	v_cvt_pk_bf16_f32 v204, v200, v201
	v_cvt_pk_bf16_f32 v205, v202, v203
	v_pk_mul_f32 v[196:197], v[26:27], v[192:193] op_sel_hi:[1,0]
	v_pk_mul_f32 v[198:199], v[28:29], v[192:193] op_sel_hi:[1,0]
	v_pk_mul_f32 v[200:201], v[26:27], v[118:119]
	v_exp_f32_e32 v196, v196
	v_exp_f32_e32 v197, v197
	v_exp_f32_e32 v198, v198
	v_exp_f32_e32 v199, v199
	v_pk_mul_f32 v[202:203], v[28:29], v[120:121]
	v_pk_add_f32 v[196:197], v[196:197], 1.0 op_sel_hi:[1,0]
	v_pk_add_f32 v[198:199], v[198:199], 1.0 op_sel_hi:[1,0]
	v_pk_mul_f32 v[200:201], v[200:201], v[192:193] op_sel:[0,1] op_sel_hi:[1,1]
	v_rcp_f32_e32 v196, v196
	v_rcp_f32_e32 v197, v197
	v_rcp_f32_e32 v198, v198
	v_rcp_f32_e32 v199, v199
	v_pk_mul_f32 v[202:203], v[202:203], v[192:193] op_sel:[0,1] op_sel_hi:[1,1]
	v_pk_mul_f32 v[200:201], v[200:201], v[196:197]
	v_pk_mul_f32 v[202:203], v[202:203], v[198:199]
	v_cvt_pk_bf16_f32 v206, v200, v201
	v_cvt_pk_bf16_f32 v207, v202, v203
	global_store_dwordx4 v[162:163], v[204:207], off
	v_add_u32_e32 v164, 0xb0, v160
	v_mad_i64_i32 v[146:147], s[42:43], v164, s56, v[148:149]
	v_lshl_add_u64 v[146:147], v[146:147], 0, v[150:151]
	v_pk_mul_f32 v[196:197], v[22:23], v[194:195] op_sel_hi:[1,0]
	v_pk_mul_f32 v[198:199], v[24:25], v[194:195] op_sel_hi:[1,0]
	v_pk_mul_f32 v[200:201], v[22:23], v[122:123]
	v_exp_f32_e32 v196, v196
	v_exp_f32_e32 v197, v197
	v_exp_f32_e32 v198, v198
	v_exp_f32_e32 v199, v199
	v_pk_mul_f32 v[202:203], v[24:25], v[124:125]
	v_pk_add_f32 v[196:197], v[196:197], 1.0 op_sel_hi:[1,0]
	v_pk_add_f32 v[198:199], v[198:199], 1.0 op_sel_hi:[1,0]
	v_pk_mul_f32 v[200:201], v[200:201], v[194:195] op_sel:[0,1] op_sel_hi:[1,1]
	v_rcp_f32_e32 v196, v196
	v_rcp_f32_e32 v197, v197
	v_rcp_f32_e32 v198, v198
	v_rcp_f32_e32 v199, v199
	v_pk_mul_f32 v[202:203], v[202:203], v[194:195] op_sel:[0,1] op_sel_hi:[1,1]
	v_pk_mul_f32 v[200:201], v[200:201], v[196:197]
	v_pk_mul_f32 v[202:203], v[202:203], v[198:199]
	v_cvt_pk_bf16_f32 v208, v200, v201
	v_cvt_pk_bf16_f32 v209, v202, v203
	v_pk_mul_f32 v[196:197], v[18:19], v[194:195] op_sel_hi:[1,0]
	v_pk_mul_f32 v[198:199], v[20:21], v[194:195] op_sel_hi:[1,0]
	v_pk_mul_f32 v[200:201], v[18:19], v[126:127]
	v_exp_f32_e32 v196, v196
	v_exp_f32_e32 v197, v197
	v_exp_f32_e32 v198, v198
	v_exp_f32_e32 v199, v199
	v_pk_mul_f32 v[202:203], v[20:21], v[128:129]
	v_pk_add_f32 v[196:197], v[196:197], 1.0 op_sel_hi:[1,0]
	v_pk_add_f32 v[198:199], v[198:199], 1.0 op_sel_hi:[1,0]
	v_pk_mul_f32 v[200:201], v[200:201], v[194:195] op_sel:[0,1] op_sel_hi:[1,1]
	v_rcp_f32_e32 v196, v196
	v_rcp_f32_e32 v197, v197
	v_rcp_f32_e32 v198, v198
	v_rcp_f32_e32 v199, v199
	v_pk_mul_f32 v[202:203], v[202:203], v[194:195] op_sel:[0,1] op_sel_hi:[1,1]
	v_pk_mul_f32 v[200:201], v[200:201], v[196:197]
	v_pk_mul_f32 v[202:203], v[202:203], v[198:199]
	v_cvt_pk_bf16_f32 v210, v200, v201
	v_cvt_pk_bf16_f32 v211, v202, v203
	global_store_dwordx4 v[146:147], v[208:211], off
	s_cbranch_vccnz .LBB0_1251
	s_andn2_b64 vcc, exec, s[8:9]
	s_cbranch_vccnz .LBB0_1237
	s_barrier
	s_branch .LBB0_1237

; __device__ __forceinline__ unsigned xb_ld(unsigned* p)              { return __hip_atomic_load(p, __ATOMIC_RELAXED, __HIP_MEMORY_SCOPE_AGENT); }
; __device__ __forceinline__ unsigned xb_add(unsigned* p, unsigned v) { return __hip_atomic_fetch_add(p, v, __ATOMIC_RELAXED, __HIP_MEMORY_SCOPE_AGENT); }
; #define XB_SPIN(cond, bar) do { unsigned _sp = 0; while (cond) { __builtin_amdgcn_s_sleep(1); \
;     if ((++_sp & 255u) == 0u) { if (xb_ld(&(bar)[XB_TMO])) break; if (_sp > XB_SPIN_CAP) { atomicAdd(&(bar)[XB_TMO], 1u); break; } } } } while (0)
; __device__ __forceinline__ void xcd_barrier(const XcdBarrier& b) {
;     asm volatile("s_waitcnt vmcnt(0)" ::: "memory");
;     __syncthreads();
;     if (threadIdx.x == 0) {
;         unsigned* bar = b.bar;
;         __builtin_amdgcn_s_waitcnt(0);
;         unsigned nloc = b.st[0], nx = b.st[1];
;         if (nloc == 0u) { xcd_barrier_complete(bar, b.x, nloc, nx); b.st[0] = nloc; b.st[1] = nx; }
;         const unsigned old = xb_add(&bar[XB_XSUB(b.x)], 1u);
;         const unsigned gen = old / nloc;
;         if (old + 1u == (gen + 1u) * nloc) {
;             __builtin_amdgcn_fence(__ATOMIC_RELEASE, "agent");
;             asm volatile("s_waitcnt vmcnt(0)" ::: "memory");
;             const unsigned og = xb_add(&bar[XB_TOP], 1u);
;             const unsigned tg = og / nx;
;             if (og + 1u == (tg + 1u) * nx) xb_add(&bar[XB_TOPGEN], 1u);
;             else XB_SPIN(xb_ld(&bar[XB_TOPGEN]) == tg, bar);
;             __builtin_amdgcn_fence(__ATOMIC_ACQUIRE, "agent");
;             asm volatile("s_waitcnt vmcnt(0)" ::: "memory");
;         } else {
;             XB_SPIN(xb_ld(&bar[XB_TOPGEN]) == gen, bar);
;             __builtin_amdgcn_fence(__ATOMIC_ACQUIRE, "agent");
;             asm volatile("s_waitcnt vmcnt(0)" ::: "memory");
.Lmy_noinv10:
	s_and_saveexec_b64 s[6:7], vcc
	s_cbranch_execz .LBB0_1302
	s_waitcnt vmcnt(0) lgkmcnt(0)
	v_mov_b32_e32 v1, 0x20000
	ds_read2_b32 v[2:3], v1 offset1:1
	s_and_b32 s99, s33, 7
	s_lshl_b32 s99, s99, 8
	s_add_u32 s100, s60, 0xc000
	s_addc_u32 s101, s61, 0
	v_mov_b32_e32 v4, s99
	v_mov_b32_e32 v5, 1
	global_atomic_add v5, v4, v5, s[100:101] sc0
	s_waitcnt lgkmcnt(0)
	v_mul_u32_u24_e32 v6, 9, v2
	v_mul_u32_u24_e32 v7, 9, v3
	s_waitcnt vmcnt(0)
	v_add_u32_e32 v5, 1, v5
	v_cmp_eq_u32_e32 vcc, v5, v6
	s_cbranch_vccz .Lmy_nl9
	buffer_wbl2 sc1
	s_waitcnt vmcnt(0)
	v_mov_b32_e32 v4, 0x800
	v_mov_b32_e32 v5, 1
	global_atomic_add v4, v5, s[100:101]

; #define LAS __attribute__((address_space(3)))
; __device__ __forceinline__ float hsum4(f32x4 v) { return (v[0] + v[1]) + (v[2] + v[3]); }
; #define PG8_STAGEA(bufoff, gbase) PG8_STAGE_(bufoff, gbase, voffA)
; template <int EK, int SK = -1>
; __device__ __forceinline__ void gemm_phase(LAS unsigned char* lds, const bf16_t* A, const bf16_t* Bt, int nM, int N, int K, const EpiArgs& E) {
;     ...
;     f32x4 acc[2][2][4][2];
; #pragma unroll
;     for (int a = 0; a < 2; ++a)
; #pragma unroll
;         for (int b = 0; b < 2; ++b)
; #pragma unroll
;             for (int m = 0; m < 4; ++m)
; #pragma unroll
;                 for (int n = 0; n < 2; ++n) acc[a][b][m][n] = (f32x4){0.f, 0.f, 0.f, 0.f};
;     bf16x8 At[4][2], B0[2][2], B1[2][2];
;     const char* cA = (const char*)A + (size_t)cur.pm * tstep; const char* cB = (const char*)Bt + (size_t)cur.pn * tstep;
;     PG8_STAGEB(PG8_SB(0, 0), cB); PG8_STAGEB(PG8_SB(0, 1), cB + hstep); PG8_STAGEA(PG8_SA(0, 0), cA); PG8_STAGEA(PG8_SA(0, 1), cA + hstep);
;     f32x4 tq[4][4]; bool okq[4];
;     if (EK != EK_RES && EK != EK_FINAL) {
; #pragma unroll
;         for (int j = 0; j < 4; ++j) { Unit uu; okq[j] = S.next((tid >> 8) + 2 * j, uu);
;             if (okq[j]) { const f32x4* sp = (const f32x4*)(E.stIn + (size_t)(uu.pm * BM + (tid & 255)) * 16); tq[j][0] = sp[0]; tq[j][1] = sp[1]; tq[j][2] = sp[2]; tq[j][3] = sp[3]; } }
;     }
;     if (SK >= 0) skinny_phase<(SK >= 0 ? SK : 0)>(lds + 32768, (LAS float*)(lds + SRED_OFF), A, Bt, N, K, E);
;     if (EK != EK_RES && EK != EK_FINAL) {
; #pragma unroll
;         for (int j = 0; j < 4; ++j) if (okq[j]) { const float s_ = (hsum4(tq[j][0]) + hsum4(tq[j][1])) + (hsum4(tq[j][2]) + hsum4(tq[j][3]));
;             rtab[((tid >> 8) + 2 * j) * 256 + (tid & 255)] = rsqrtf(s_ * (1.0f / 1024.0f) + EPS); }
;         __syncthreads();
;     }
;     if (wr == 1) PG8_BAR;
;     PG8_WAIT_V(2); PG8_BAR;
;     PG8_STAGEB(PG8_SB(1, 0), cB + kstep); PG8_STAGEA(PG8_SA(1, 0), cA + kstep); PG8_STAGEB(PG8_SB(1, 1), cB + hstep + kstep);
;     PG8_WAIT_V(6); PG8_BAR;
;     ...
;         for (int a = 0; a < 2; ++a)
; #pragma unroll
;             for (int b = 0; b < 2; ++b)
; #pragma unroll
;                 for (int m = 0; m < 4; ++m)
; #pragma unroll
;                     for (int n = 0; n < 2; ++n) acc[a][b][m][n] = (f32x4){0.f, 0.f, 0.f, 0.f};
;         cur = nxt; cA = nA; cB = nB; ++ui;
.LBB0_1325:
	v_bfe_u32 v10, v0, 4, 2
	v_lshlrev_b32_e32 v17, 4, v10
	v_lshl_or_b32 v1, s0, 6, v16
	v_lshl_or_b32 v18, v16, 6, v17
	v_lshlrev_b32_e32 v16, 2, v16
	s_lshl_b32 s0, s0, 13
	v_and_b32_e32 v16, 32, v16
	s_and_b32 s57, s36, 3
	v_bitop3_b32 v16, v18, s0, v16 bitop3:0xde
	v_lshlrev_b32_e32 v18, 6, v0
	s_movk_i32 s0, 0x3c0
	s_mov_b64 s[36:37], 0x80
	v_and_or_b32 v17, v18, s0, v17
	v_lshlrev_b32_e32 v18, 2, v0
	s_add_i32 m0, s53, 0x18000
	v_lshl_add_u64 v[8:9], v[8:9], 0, s[36:37]
	s_lshl_b32 s0, s57, 12
	v_and_b32_e32 v18, 32, v18
	s_ashr_i32 s58, s2, 31
	s_waitcnt vmcnt(2)
	s_barrier
	global_load_lds_dwordx4 v[8:9], off
	v_lshl_add_u64 v[6:7], v[6:7], 0, s[36:37]
	s_add_i32 m0, s53, 0x1a000
	s_add_i32 s59, s53, 0x8000
	s_add_i32 s66, s53, 0xa000
	v_bitop3_b32 v152, s0, v17, v18 bitop3:0xf6
	global_load_lds_dwordx4 v[6:7], off
	v_lshl_add_u64 v[2:3], v[2:3], 0, s[36:37]
	s_mov_b32 m0, s59
	s_add_u32 s0, s42, 0xb0080
	global_load_lds_dwordx4 v[2:3], off
	v_lshl_add_u64 v[2:3], v[4:5], 0, s[36:37]
	s_mov_b32 m0, s66
	s_addc_u32 s1, s43, 0
	global_load_lds_dwordx4 v[2:3], off
	s_add_i32 m0, s53, 0x1c000
	v_lshl_add_u64 v[2:3], s[0:1], 0, v[132:133]
	global_load_lds_dwordx4 v[2:3], off
	v_lshl_add_u64 v[2:3], s[0:1], 0, v[136:137]
	s_add_i32 m0, s53, 0x1e000
	s_mov_b64 s[4:5], 0xb0080
	global_load_lds_dwordx4 v[2:3], off
	v_add_u16_e32 v2, v12, v13
	v_lshrrev_b16_e32 v4, 1, v2
	v_add_lshl_u32 v2, v14, v4, 1
	v_mov_b32_e32 v3, 0
	s_waitcnt vmcnt(6)
	v_lshl_add_u64 v[138:139], v[2:3], 0, s[4:5]
	v_add_lshl_u32 v2, v15, v4, 1
	v_lshlrev_b32_e32 v11, 3, v10
	s_cmpk_lt_u32 s38, 0x100
	v_lshl_add_u64 v[140:141], v[2:3], 0, s[4:5]
	v_mbcnt_lo_u32_b32 v2, -1, 0
	s_mov_b32 s27, 0
	v_lshl_or_b32 v153, s57, 5, v11
	s_cselect_b64 s[38:39], -1, 0
	v_cmp_eq_u32_e64 s[0:1], 0, v10
	v_mov_b64_e32 v[142:143], 0x100
	v_mov_b64_e32 v[144:145], 0xff
	s_add_i32 s67, 0, 0x10000
	s_add_i32 s68, 0, 0x14000
	v_add_u32_e32 v154, 0, v16
	v_mbcnt_hi_u32_b32 v155, -1, v2
	s_mov_b32 s71, 0
	v_mov_b32_e32 v2, v3
	s_barrier
	s_branch .LBB0_1327
.LBB0_1326:
	v_mov_b32_e32 v2, 0
	s_mov_b32 s51, s69
	s_mov_b32 s50, s70
	v_mov_b32_e32 v3, v2
	s_mov_b64 s[20:21], s[40:41]
	s_mov_b32 s71, s72
	s_andn2_b64 vcc, exec, s[4:5]
	s_mov_b64 s[42:43], s[8:9]
	s_cbranch_vccz .LBB0_1361

; #define PG8_STAGEA(bufoff, gbase) PG8_STAGE_(bufoff, gbase, voffA)
; #define PG8_STAGEB(bufoff, gbase) PG8_STAGE_(bufoff, gbase, voffB)
; #define PG8_LDA(dst, b, h) do { _Pragma("unroll") for (int m = 0; m < 4; ++m) _Pragma("unroll") for (int k = 0; k < 2; ++k) dst[m][k] = *(const LAS bf16x8*)(lds + PG8_SA(b, h) + aoff + m * 2048 + k * 1024); } while (0)
; #define PG8_LDB(dst, b, h) do { _Pragma("unroll") for (int n = 0; n < 2; ++n) _Pragma("unroll") for (int k = 0; k < 2; ++k) dst[n][k] = *(const LAS bf16x8*)(lds + PG8_SB(b, h) + boff + n * 2048 + k * 1024); } while (0)
; #define PG8_MMA(ai, bj, At, Bt_) do { __builtin_amdgcn_s_setprio(1); _Pragma("unroll") for (int m = 0; m < 4; ++m) _Pragma("unroll") for (int n = 0; n < 2; ++n) _Pragma("unroll") for (int k = 0; k < 2; ++k) \
;         acc[ai][bj][m][n] = __builtin_amdgcn_mfma_f32_16x16x32_bf16(Bt_[n][k], At[m][k], acc[ai][bj][m][n], 0, 0, 0); __builtin_amdgcn_s_setprio(0); } while (0)
; #define PG8_WAIT_V(n) asm volatile("s_waitcnt vmcnt(" #n ")" ::: "memory")
; #define PG8_WAIT_L(n) asm volatile("s_waitcnt lgkmcnt(" #n ")" ::: "memory")
; #define PG8_BAR __builtin_amdgcn_s_barrier()
; template <int EK, int SK = -1>
; __device__ __forceinline__ void gemm_phase(LAS unsigned char* lds, const bf16_t* A, const bf16_t* Bt, int nM, int N, int K, const EpiArgs& E) {
;     ...
;         const bool has_next = S.next(ui + 1, nxt);
;         const char* nA = has_next ? (const char*)A + (size_t)nxt.pm * tstep : cA; const char* nB = has_next ? (const char*)Bt + (size_t)nxt.pn * tstep : cB;
;         for (int t = 0; t < nt; t += 2) {
;             const bool last = (t == nt - 2);
;             const char* a1 = cA + (size_t)(t + 1) * kstep;
;             const char* a2 = last ? nA : cA + (size_t)(t + 2) * kstep; const char* b2 = last ? nB : cB + (size_t)(t + 2) * kstep;
;             const char* a3 = a2 + kstep; const char* b3 = b2 + kstep;
;             PG8_LDB(B0, 0, 0); PG8_LDB(B1, 0, 1); PG8_SCHED; PG8_LDA(At, 0, 0); PG8_STAGEA(PG8_SA(1, 1), a1 + hstep);
;             PG8_WAIT_V(8); PG8_WAIT_L(0); PG8_BAR; PG8_MMA(0, 0, At, B0); PG8_MMA(0, 1, At, B1); PG8_BAR; PG8_SCHED;
;             PG8_LDA(At, 0, 1); PG8_STAGEB(PG8_SB(0, 0), b2); PG8_STAGEB(PG8_SB(0, 1), b2 + hstep); PG8_STAGEA(PG8_SA(0, 0), a2);
;             PG8_WAIT_V(8); PG8_WAIT_L(0); PG8_BAR; PG8_MMA(1, 0, At, B0); PG8_MMA(1, 1, At, B1); PG8_BAR; PG8_SCHED;
.LBB0_1337:
	s_add_u32 s73, s42, 0x100
	s_addc_u32 s74, s43, 0
	s_waitcnt lgkmcnt(0)
	v_lshl_add_u64 v[146:147], s[20:21], 0, v[138:139]
	v_lshl_add_u64 v[148:149], s[20:21], 0, v[140:141]
	s_mov_b32 s26, -2
	s_mov_b64 s[42:43], 0
	v_add_u32_e32 v150, s67, v152
	ds_read_b128 v[156:159], v150
	ds_read_b128 v[160:163], v150 offset:1024
	ds_read_b128 v[164:167], v150 offset:2048
	ds_read_b128 v[168:171], v150 offset:3072
	v_add_u32_e32 v150, s68, v152
	s_add_u32 s44, s20, s42
	ds_read_b128 v[172:175], v150
	ds_read_b128 v[176:179], v150 offset:1024
	ds_read_b128 v[180:183], v150 offset:2048
	ds_read_b128 v[184:187], v150 offset:3072
	s_addc_u32 s45, s21, s43
	s_add_u32 s44, s44, 0x100
	s_addc_u32 s45, s45, 0
	s_add_u32 s75, s73, s42
	s_addc_u32 s76, s74, s43
	s_cmpk_eq_i32 s42, 0x1500
	s_cselect_b32 s47, s41, s45
	s_cselect_b32 s46, s40, s44
	s_cselect_b32 s45, s9, s76
	s_cselect_b32 s44, s8, s75
	v_lshl_add_u64 v[150:151], v[146:147], 0, s[42:43]
	s_add_i32 m0, s53, 0xc000
	ds_read_b128 v[188:191], v154
	ds_read_b128 v[192:195], v154 offset:1024
	ds_read_b128 v[196:199], v154 offset:2048
	ds_read_b128 v[200:203], v154 offset:3072
	ds_read_b128 v[204:207], v154 offset:4096
	ds_read_b128 v[208:211], v154 offset:5120
	ds_read_b128 v[212:215], v154 offset:6144
	ds_read_b128 v[216:219], v154 offset:7168
	global_load_lds_dwordx4 v[150:151], off
	v_lshl_add_u64 v[150:151], v[148:149], 0, s[42:43]
	s_add_i32 m0, s53, 0xe000
	s_nop 0
	global_load_lds_dwordx4 v[150:151], off
	s_waitcnt vmcnt(8)
	s_waitcnt lgkmcnt(0)
	s_barrier
	s_waitcnt lgkmcnt(0)
	v_mfma_f32_16x16x32_bf16 v[126:129], v[156:159], v[188:191], 0
	v_mfma_f32_16x16x32_bf16 v[122:125], v[164:167], v[188:191], 0
	v_mfma_f32_16x16x32_bf16 v[118:121], v[156:159], v[196:199], 0
	v_mfma_f32_16x16x32_bf16 v[114:117], v[164:167], v[196:199], 0
	v_mfma_f32_16x16x32_bf16 v[110:113], v[156:159], v[204:207], 0
	v_mfma_f32_16x16x32_bf16 v[106:109], v[164:167], v[204:207], 0
	v_mfma_f32_16x16x32_bf16 v[102:105], v[156:159], v[212:215], 0
	v_mfma_f32_16x16x32_bf16 v[98:101], v[164:167], v[212:215], 0
	v_mfma_f32_16x16x32_bf16 v[126:129], v[160:163], v[192:195], v[126:129]
	v_mfma_f32_16x16x32_bf16 v[122:125], v[168:171], v[192:195], v[122:125]
	v_mfma_f32_16x16x32_bf16 v[118:121], v[160:163], v[200:203], v[118:121]
	v_mfma_f32_16x16x32_bf16 v[114:117], v[168:171], v[200:203], v[114:117]
	v_mfma_f32_16x16x32_bf16 v[110:113], v[160:163], v[208:211], v[110:113]
	v_mfma_f32_16x16x32_bf16 v[106:109], v[168:171], v[208:211], v[106:109]
	v_mfma_f32_16x16x32_bf16 v[102:105], v[160:163], v[216:219], v[102:105]
	v_mfma_f32_16x16x32_bf16 v[98:101], v[168:171], v[216:219], v[98:101]
	v_mfma_f32_16x16x32_bf16 v[94:97], v[172:175], v[188:191], 0
	v_mfma_f32_16x16x32_bf16 v[90:93], v[180:183], v[188:191], 0
	v_mfma_f32_16x16x32_bf16 v[86:89], v[172:175], v[196:199], 0
	v_mfma_f32_16x16x32_bf16 v[82:85], v[180:183], v[196:199], 0
	v_mfma_f32_16x16x32_bf16 v[78:81], v[172:175], v[204:207], 0
	v_mfma_f32_16x16x32_bf16 v[74:77], v[180:183], v[204:207], 0
	v_mfma_f32_16x16x32_bf16 v[70:73], v[172:175], v[212:215], 0
	v_mfma_f32_16x16x32_bf16 v[66:69], v[180:183], v[212:215], 0
	v_mfma_f32_16x16x32_bf16 v[94:97], v[176:179], v[192:195], v[94:97]
	v_mfma_f32_16x16x32_bf16 v[90:93], v[184:187], v[192:195], v[90:93]
	v_mfma_f32_16x16x32_bf16 v[86:89], v[176:179], v[200:203], v[86:89]
	v_mfma_f32_16x16x32_bf16 v[82:85], v[184:187], v[200:203], v[82:85]
	v_mfma_f32_16x16x32_bf16 v[78:81], v[176:179], v[208:211], v[78:81]
	v_mfma_f32_16x16x32_bf16 v[74:77], v[184:187], v[208:211], v[74:77]
	v_mfma_f32_16x16x32_bf16 v[70:73], v[176:179], v[216:219], v[70:73]
	v_mfma_f32_16x16x32_bf16 v[66:69], v[184:187], v[216:219], v[66:69]
	s_barrier
	s_add_i32 s75, s67, s52
	v_lshl_add_u64 v[150:151], s[44:45], 0, v[132:133]
	s_mov_b32 m0, s75
	ds_read_b128 v[188:191], v154 offset:16384
	ds_read_b128 v[192:195], v154 offset:17408
	ds_read_b128 v[196:199], v154 offset:18432
	ds_read_b128 v[200:203], v154 offset:19456
	ds_read_b128 v[204:207], v154 offset:20480
	ds_read_b128 v[208:211], v154 offset:21504
	ds_read_b128 v[212:215], v154 offset:22528
	ds_read_b128 v[216:219], v154 offset:23552
	global_load_lds_dwordx4 v[150:151], off
	s_add_i32 m0, s75, 0x2000
	s_add_u32 s76, s44, 0xb0000
	v_lshl_add_u64 v[220:221], s[44:45], 0, v[136:137]
	s_addc_u32 s77, s45, 0
	s_add_i32 s75, s68, s52
	global_load_lds_dwordx4 v[220:221], off
	v_lshl_add_u64 v[222:223], s[76:77], 0, v[132:133]
	s_mov_b32 m0, s75
	v_lshl_add_u64 v[224:225], s[46:47], 0, v[134:135]
	global_load_lds_dwordx4 v[222:223], off
	v_lshl_add_u64 v[222:223], s[76:77], 0, v[136:137]
	s_add_i32 m0, s75, 0x2000
	s_nop 0
	global_load_lds_dwordx4 v[222:223], off
	v_lshl_add_u64 v[222:223], s[46:47], 0, v[130:131]
	s_mov_b32 m0, s53
	s_nop 0
	global_load_lds_dwordx4 v[222:223], off
	s_mov_b32 m0, s54
	s_nop 0
	global_load_lds_dwordx4 v[224:225], off
	s_waitcnt vmcnt(8)
	s_waitcnt lgkmcnt(0)
	s_barrier
; #define PG8_STAGEA(bufoff, gbase) PG8_STAGE_(bufoff, gbase, voffA)
; #define PG8_STAGEB(bufoff, gbase) PG8_STAGE_(bufoff, gbase, voffB)
; #define PG8_LDA(dst, b, h) do { _Pragma("unroll") for (int m = 0; m < 4; ++m) _Pragma("unroll") for (int k = 0; k < 2; ++k) dst[m][k] = *(const LAS bf16x8*)(lds + PG8_SA(b, h) + aoff + m * 2048 + k * 1024); } while (0)
; #define PG8_LDB(dst, b, h) do { _Pragma("unroll") for (int n = 0; n < 2; ++n) _Pragma("unroll") for (int k = 0; k < 2; ++k) dst[n][k] = *(const LAS bf16x8*)(lds + PG8_SB(b, h) + boff + n * 2048 + k * 1024); } while (0)
; #define PG8_MMA(ai, bj, At, Bt_) do { __builtin_amdgcn_s_setprio(1); _Pragma("unroll") for (int m = 0; m < 4; ++m) _Pragma("unroll") for (int n = 0; n < 2; ++n) _Pragma("unroll") for (int k = 0; k < 2; ++k) \
;         acc[ai][bj][m][n] = __builtin_amdgcn_mfma_f32_16x16x32_bf16(Bt_[n][k], At[m][k], acc[ai][bj][m][n], 0, 0, 0); __builtin_amdgcn_s_setprio(0); } while (0)
; #define PG8_WAIT_V(n) asm volatile("s_waitcnt vmcnt(" #n ")" ::: "memory")
; #define PG8_WAIT_L(n) asm volatile("s_waitcnt lgkmcnt(" #n ")" ::: "memory")
; #define PG8_BAR __builtin_amdgcn_s_barrier()
; #define PG8_SCHED __builtin_amdgcn_sched_barrier(0)
; template <int EK, int SK = -1>
; __device__ __forceinline__ void gemm_phase(LAS unsigned char* lds, const bf16_t* A, const bf16_t* Bt, int nM, int N, int K, const EpiArgs& E) {
;     ...
;             PG8_WAIT_V(8); PG8_WAIT_L(0); PG8_BAR; PG8_MMA(1, 0, At, B0); PG8_MMA(1, 1, At, B1); PG8_BAR; PG8_SCHED;
;             PG8_LDB(B0, 1, 0); PG8_LDB(B1, 1, 1); PG8_SCHED; PG8_LDA(At, 1, 0); PG8_STAGEA(PG8_SA(0, 1), a2 + hstep);
;             PG8_WAIT_V(8); PG8_WAIT_L(0); PG8_BAR; PG8_MMA(0, 0, At, B0); PG8_MMA(0, 1, At, B1); PG8_BAR; PG8_SCHED;
;             PG8_LDA(At, 1, 1); PG8_STAGEB(PG8_SB(1, 0), b3); PG8_STAGEB(PG8_SB(1, 1), b3 + hstep); PG8_STAGEA(PG8_SA(1, 0), a3);
	s_waitcnt lgkmcnt(0)
	v_mfma_f32_16x16x32_bf16 v[62:65], v[156:159], v[188:191], 0
	v_mfma_f32_16x16x32_bf16 v[58:61], v[164:167], v[188:191], 0
	v_mfma_f32_16x16x32_bf16 v[54:57], v[156:159], v[196:199], 0
	v_mfma_f32_16x16x32_bf16 v[50:53], v[164:167], v[196:199], 0
	v_mfma_f32_16x16x32_bf16 v[46:49], v[156:159], v[204:207], 0
	v_mfma_f32_16x16x32_bf16 v[42:45], v[164:167], v[204:207], 0
	v_mfma_f32_16x16x32_bf16 v[38:41], v[156:159], v[212:215], 0
	v_mfma_f32_16x16x32_bf16 v[34:37], v[164:167], v[212:215], 0
	v_mfma_f32_16x16x32_bf16 v[62:65], v[160:163], v[192:195], v[62:65]
	v_mfma_f32_16x16x32_bf16 v[58:61], v[168:171], v[192:195], v[58:61]
	v_mfma_f32_16x16x32_bf16 v[54:57], v[160:163], v[200:203], v[54:57]
	v_mfma_f32_16x16x32_bf16 v[50:53], v[168:171], v[200:203], v[50:53]
	v_mfma_f32_16x16x32_bf16 v[46:49], v[160:163], v[208:211], v[46:49]
	v_mfma_f32_16x16x32_bf16 v[42:45], v[168:171], v[208:211], v[42:45]
	v_mfma_f32_16x16x32_bf16 v[38:41], v[160:163], v[216:219], v[38:41]
	v_mfma_f32_16x16x32_bf16 v[34:37], v[168:171], v[216:219], v[34:37]
	v_mfma_f32_16x16x32_bf16 v[30:33], v[172:175], v[188:191], 0
	v_mfma_f32_16x16x32_bf16 v[26:29], v[180:183], v[188:191], 0
	v_mfma_f32_16x16x32_bf16 v[22:25], v[172:175], v[196:199], 0
	v_mfma_f32_16x16x32_bf16 v[18:21], v[180:183], v[196:199], 0
	v_mfma_f32_16x16x32_bf16 v[14:17], v[172:175], v[204:207], 0
	v_mfma_f32_16x16x32_bf16 v[10:13], v[180:183], v[204:207], 0
	v_mfma_f32_16x16x32_bf16 v[6:9], v[172:175], v[212:215], 0
	v_mfma_f32_16x16x32_bf16 v[2:5], v[180:183], v[212:215], 0
	v_mfma_f32_16x16x32_bf16 v[30:33], v[176:179], v[192:195], v[30:33]
	v_mfma_f32_16x16x32_bf16 v[26:29], v[184:187], v[192:195], v[26:29]
	v_mfma_f32_16x16x32_bf16 v[22:25], v[176:179], v[200:203], v[22:25]
	v_mfma_f32_16x16x32_bf16 v[18:21], v[184:187], v[200:203], v[18:21]
	v_mfma_f32_16x16x32_bf16 v[14:17], v[176:179], v[208:211], v[14:17]
	v_mfma_f32_16x16x32_bf16 v[10:13], v[184:187], v[208:211], v[10:13]
	v_mfma_f32_16x16x32_bf16 v[6:9], v[176:179], v[216:219], v[6:9]
	v_mfma_f32_16x16x32_bf16 v[2:5], v[184:187], v[216:219], v[2:5]
	s_barrier
	s_add_i32 s75, 0, 0x18000
	s_add_i32 s76, 0, 0x1c000
	v_add_u32_e32 v168, s75, v152
	v_add_u32_e32 v184, s76, v152
	ds_read_b128 v[156:159], v168
	ds_read_b128 v[160:163], v168 offset:1024
	ds_read_b128 v[164:167], v168 offset:2048
	ds_read_b128 v[168:171], v168 offset:3072
	ds_read_b128 v[172:175], v184
	ds_read_b128 v[176:179], v184 offset:1024
	ds_read_b128 v[180:183], v184 offset:2048
	ds_read_b128 v[184:187], v184 offset:3072
	s_add_u32 s46, s46, 0xb0000
	s_addc_u32 s47, s47, 0
	s_mov_b32 m0, s55
	v_lshl_add_u64 v[226:227], s[46:47], 0, v[130:131]
	ds_read_b128 v[188:191], v154 offset:32768
	ds_read_b128 v[192:195], v154 offset:33792
	ds_read_b128 v[196:199], v154 offset:34816
	ds_read_b128 v[200:203], v154 offset:35840
	ds_read_b128 v[204:207], v154 offset:36864
	ds_read_b128 v[208:211], v154 offset:37888
	ds_read_b128 v[212:215], v154 offset:38912
	ds_read_b128 v[216:219], v154 offset:39936
	global_load_lds_dwordx4 v[226:227], off
	v_lshl_add_u64 v[226:227], s[46:47], 0, v[134:135]
	s_mov_b32 m0, s56
	s_nop 0
	global_load_lds_dwordx4 v[226:227], off
	s_waitcnt vmcnt(8)
	s_waitcnt lgkmcnt(0)
	s_barrier
	s_waitcnt lgkmcnt(0)
	v_mfma_f32_16x16x32_bf16 v[126:129], v[156:159], v[188:191], v[126:129]
	v_mfma_f32_16x16x32_bf16 v[122:125], v[164:167], v[188:191], v[122:125]
	v_mfma_f32_16x16x32_bf16 v[118:121], v[156:159], v[196:199], v[118:121]
	v_mfma_f32_16x16x32_bf16 v[114:117], v[164:167], v[196:199], v[114:117]
	v_mfma_f32_16x16x32_bf16 v[110:113], v[156:159], v[204:207], v[110:113]
	v_mfma_f32_16x16x32_bf16 v[106:109], v[164:167], v[204:207], v[106:109]
	v_mfma_f32_16x16x32_bf16 v[102:105], v[156:159], v[212:215], v[102:105]
	v_mfma_f32_16x16x32_bf16 v[98:101], v[164:167], v[212:215], v[98:101]
	v_mfma_f32_16x16x32_bf16 v[126:129], v[160:163], v[192:195], v[126:129]
	v_mfma_f32_16x16x32_bf16 v[122:125], v[168:171], v[192:195], v[122:125]
	v_mfma_f32_16x16x32_bf16 v[118:121], v[160:163], v[200:203], v[118:121]
	v_mfma_f32_16x16x32_bf16 v[114:117], v[168:171], v[200:203], v[114:117]
	v_mfma_f32_16x16x32_bf16 v[110:113], v[160:163], v[208:211], v[110:113]
	v_mfma_f32_16x16x32_bf16 v[106:109], v[168:171], v[208:211], v[106:109]
	v_mfma_f32_16x16x32_bf16 v[102:105], v[160:163], v[216:219], v[102:105]
	v_mfma_f32_16x16x32_bf16 v[98:101], v[168:171], v[216:219], v[98:101]
	v_mfma_f32_16x16x32_bf16 v[94:97], v[172:175], v[188:191], v[94:97]
	v_mfma_f32_16x16x32_bf16 v[90:93], v[180:183], v[188:191], v[90:93]
	v_mfma_f32_16x16x32_bf16 v[86:89], v[172:175], v[196:199], v[86:89]
	v_mfma_f32_16x16x32_bf16 v[82:85], v[180:183], v[196:199], v[82:85]
	v_mfma_f32_16x16x32_bf16 v[78:81], v[172:175], v[204:207], v[78:81]
	v_mfma_f32_16x16x32_bf16 v[74:77], v[180:183], v[204:207], v[74:77]
	v_mfma_f32_16x16x32_bf16 v[70:73], v[172:175], v[212:215], v[70:73]
	v_mfma_f32_16x16x32_bf16 v[66:69], v[180:183], v[212:215], v[66:69]
	v_mfma_f32_16x16x32_bf16 v[94:97], v[176:179], v[192:195], v[94:97]
	v_mfma_f32_16x16x32_bf16 v[90:93], v[184:187], v[192:195], v[90:93]
	v_mfma_f32_16x16x32_bf16 v[86:89], v[176:179], v[200:203], v[86:89]
	v_mfma_f32_16x16x32_bf16 v[82:85], v[184:187], v[200:203], v[82:85]
	v_mfma_f32_16x16x32_bf16 v[78:81], v[176:179], v[208:211], v[78:81]
	v_mfma_f32_16x16x32_bf16 v[74:77], v[184:187], v[208:211], v[74:77]
	v_mfma_f32_16x16x32_bf16 v[70:73], v[176:179], v[216:219], v[70:73]
	v_mfma_f32_16x16x32_bf16 v[66:69], v[184:187], v[216:219], v[66:69]
	s_barrier
; #define PG8_STAGEA(bufoff, gbase) PG8_STAGE_(bufoff, gbase, voffA)
; #define PG8_STAGEB(bufoff, gbase) PG8_STAGE_(bufoff, gbase, voffB)
; #define PG8_LDA(dst, b, h) do { _Pragma("unroll") for (int m = 0; m < 4; ++m) _Pragma("unroll") for (int k = 0; k < 2; ++k) dst[m][k] = *(const LAS bf16x8*)(lds + PG8_SA(b, h) + aoff + m * 2048 + k * 1024); } while (0)
; #define PG8_MMA(ai, bj, At, Bt_) do { __builtin_amdgcn_s_setprio(1); _Pragma("unroll") for (int m = 0; m < 4; ++m) _Pragma("unroll") for (int n = 0; n < 2; ++n) _Pragma("unroll") for (int k = 0; k < 2; ++k) \
;         acc[ai][bj][m][n] = __builtin_amdgcn_mfma_f32_16x16x32_bf16(Bt_[n][k], At[m][k], acc[ai][bj][m][n], 0, 0, 0); __builtin_amdgcn_s_setprio(0); } while (0)
; #define PG8_WAIT_V(n) asm volatile("s_waitcnt vmcnt(" #n ")" ::: "memory")
; #define PG8_WAIT_L(n) asm volatile("s_waitcnt lgkmcnt(" #n ")" ::: "memory")
; #define PG8_BAR __builtin_amdgcn_s_barrier()
; #define PG8_SCHED __builtin_amdgcn_sched_barrier(0)
; template <int EK, int SK = -1>
; __device__ __forceinline__ void gemm_phase(LAS unsigned char* lds, const bf16_t* A, const bf16_t* Bt, int nM, int N, int K, const EpiArgs& E) {
;     ...
;             PG8_LDA(At, 1, 1); PG8_STAGEB(PG8_SB(1, 0), b3); PG8_STAGEB(PG8_SB(1, 1), b3 + hstep); PG8_STAGEA(PG8_SA(1, 0), a3);
;             PG8_WAIT_V(8); PG8_WAIT_L(0); PG8_BAR; PG8_MMA(1, 0, At, B0); PG8_MMA(1, 1, At, B1); PG8_BAR; PG8_SCHED;
;         }
	s_add_i32 s46, s75, s52
	v_lshl_add_u64 v[150:151], v[150:151], 0, s[36:37]
	s_mov_b32 m0, s46
	ds_read_b128 v[188:191], v154 offset:49152
	ds_read_b128 v[192:195], v154 offset:50176
	ds_read_b128 v[196:199], v154 offset:51200
	ds_read_b128 v[200:203], v154 offset:52224
	ds_read_b128 v[204:207], v154 offset:53248
	ds_read_b128 v[208:211], v154 offset:54272
	ds_read_b128 v[212:215], v154 offset:55296
	ds_read_b128 v[216:219], v154 offset:56320
	global_load_lds_dwordx4 v[150:151], off
	s_add_i32 m0, s46, 0x2000
	s_add_u32 s44, s44, 0xb0080
	v_lshl_add_u64 v[150:151], v[220:221], 0, s[36:37]
	s_addc_u32 s45, s45, 0
	s_add_i32 s46, s76, s52
	global_load_lds_dwordx4 v[150:151], off
	v_lshl_add_u64 v[150:151], s[44:45], 0, v[132:133]
	s_mov_b32 m0, s46
	s_nop 0
	global_load_lds_dwordx4 v[150:151], off
	v_lshl_add_u64 v[150:151], s[44:45], 0, v[136:137]
	s_add_i32 m0, s46, 0x2000
	s_nop 0
	global_load_lds_dwordx4 v[150:151], off
	v_lshl_add_u64 v[150:151], v[222:223], 0, s[36:37]
	s_mov_b32 m0, s59
	s_nop 0
	global_load_lds_dwordx4 v[150:151], off
	v_lshl_add_u64 v[150:151], v[224:225], 0, s[36:37]
	s_mov_b32 m0, s66
	s_nop 0
	global_load_lds_dwordx4 v[150:151], off
	s_waitcnt vmcnt(8)
	s_waitcnt lgkmcnt(0)
	s_barrier
	s_waitcnt lgkmcnt(0)
	v_mfma_f32_16x16x32_bf16 v[62:65], v[156:159], v[188:191], v[62:65]
	v_mfma_f32_16x16x32_bf16 v[58:61], v[164:167], v[188:191], v[58:61]
	v_mfma_f32_16x16x32_bf16 v[54:57], v[156:159], v[196:199], v[54:57]
	v_mfma_f32_16x16x32_bf16 v[50:53], v[164:167], v[196:199], v[50:53]
	v_mfma_f32_16x16x32_bf16 v[46:49], v[156:159], v[204:207], v[46:49]
	v_mfma_f32_16x16x32_bf16 v[42:45], v[164:167], v[204:207], v[42:45]
	v_mfma_f32_16x16x32_bf16 v[38:41], v[156:159], v[212:215], v[38:41]
	v_mfma_f32_16x16x32_bf16 v[34:37], v[164:167], v[212:215], v[34:37]
	v_mfma_f32_16x16x32_bf16 v[62:65], v[160:163], v[192:195], v[62:65]
	v_mfma_f32_16x16x32_bf16 v[58:61], v[168:171], v[192:195], v[58:61]
	v_mfma_f32_16x16x32_bf16 v[54:57], v[160:163], v[200:203], v[54:57]
	v_mfma_f32_16x16x32_bf16 v[50:53], v[168:171], v[200:203], v[50:53]
	v_mfma_f32_16x16x32_bf16 v[46:49], v[160:163], v[208:211], v[46:49]
	v_mfma_f32_16x16x32_bf16 v[42:45], v[168:171], v[208:211], v[42:45]
	v_mfma_f32_16x16x32_bf16 v[38:41], v[160:163], v[216:219], v[38:41]
	v_mfma_f32_16x16x32_bf16 v[34:37], v[168:171], v[216:219], v[34:37]
	v_mfma_f32_16x16x32_bf16 v[30:33], v[172:175], v[188:191], v[30:33]
	v_mfma_f32_16x16x32_bf16 v[26:29], v[180:183], v[188:191], v[26:29]
	v_mfma_f32_16x16x32_bf16 v[22:25], v[172:175], v[196:199], v[22:25]
	v_mfma_f32_16x16x32_bf16 v[18:21], v[180:183], v[196:199], v[18:21]
	v_mfma_f32_16x16x32_bf16 v[14:17], v[172:175], v[204:207], v[14:17]
	v_mfma_f32_16x16x32_bf16 v[10:13], v[180:183], v[204:207], v[10:13]
	v_mfma_f32_16x16x32_bf16 v[6:9], v[172:175], v[212:215], v[6:9]
	v_mfma_f32_16x16x32_bf16 v[2:5], v[180:183], v[212:215], v[2:5]
	v_mfma_f32_16x16x32_bf16 v[30:33], v[176:179], v[192:195], v[30:33]
	v_mfma_f32_16x16x32_bf16 v[26:29], v[184:187], v[192:195], v[26:29]
	v_mfma_f32_16x16x32_bf16 v[22:25], v[176:179], v[200:203], v[22:25]
	v_mfma_f32_16x16x32_bf16 v[18:21], v[184:187], v[200:203], v[18:21]
	v_mfma_f32_16x16x32_bf16 v[14:17], v[176:179], v[208:211], v[14:17]
	v_mfma_f32_16x16x32_bf16 v[10:13], v[184:187], v[208:211], v[10:13]
	v_mfma_f32_16x16x32_bf16 v[6:9], v[176:179], v[216:219], v[6:9]
	v_mfma_f32_16x16x32_bf16 v[2:5], v[184:187], v[216:219], v[2:5]
	s_barrier
	s_add_i32 s26, s26, 2
	s_add_u32 s42, s42, 0x100
	s_addc_u32 s43, s43, 0
	s_cmp_gt_u32 s26, 41
	s_cbranch_scc0 .LBB0_1338
	s_branch .Lmy_kexit_7

; #define LAS __attribute__((address_space(3)))
; __device__ __forceinline__ float hsum4(f32x4 v) { return (v[0] + v[1]) + (v[2] + v[3]); }
; #define PG8_STAGEA(bufoff, gbase) PG8_STAGE_(bufoff, gbase, voffA)
; #define PG8_STAGEB(bufoff, gbase) PG8_STAGE_(bufoff, gbase, voffB)
; #define PG8_WAIT_V(n) asm volatile("s_waitcnt vmcnt(" #n ")" ::: "memory")
; #define PG8_BAR __builtin_amdgcn_s_barrier()
; template <int EK, int SK = -1>
; __device__ __forceinline__ void gemm_phase(LAS unsigned char* lds, const bf16_t* A, const bf16_t* Bt, int nM, int N, int K, const EpiArgs& E) {
;     ...
;     f32x4 acc[2][2][4][2];
; #pragma unroll
;     for (int a = 0; a < 2; ++a)
; #pragma unroll
;         for (int b = 0; b < 2; ++b)
; #pragma unroll
;             for (int m = 0; m < 4; ++m)
; #pragma unroll
;                 for (int n = 0; n < 2; ++n) acc[a][b][m][n] = (f32x4){0.f, 0.f, 0.f, 0.f};
;     bf16x8 At[4][2], B0[2][2], B1[2][2];
;     const char* cA = (const char*)A + (size_t)cur.pm * tstep; const char* cB = (const char*)Bt + (size_t)cur.pn * tstep;
;     PG8_STAGEB(PG8_SB(0, 0), cB); PG8_STAGEB(PG8_SB(0, 1), cB + hstep); PG8_STAGEA(PG8_SA(0, 0), cA); PG8_STAGEA(PG8_SA(0, 1), cA + hstep);
;     f32x4 tq[4][4]; bool okq[4];
;     if (EK != EK_RES && EK != EK_FINAL) {
; #pragma unroll
;         for (int j = 0; j < 4; ++j) { Unit uu; okq[j] = S.next((tid >> 8) + 2 * j, uu);
;             if (okq[j]) { const f32x4* sp = (const f32x4*)(E.stIn + (size_t)(uu.pm * BM + (tid & 255)) * 16); tq[j][0] = sp[0]; tq[j][1] = sp[1]; tq[j][2] = sp[2]; tq[j][3] = sp[3]; } }
;     }
;     if (SK >= 0) skinny_phase<(SK >= 0 ? SK : 0)>(lds + 32768, (LAS float*)(lds + SRED_OFF), A, Bt, N, K, E);
;     if (EK != EK_RES && EK != EK_FINAL) {
; #pragma unroll
;         for (int j = 0; j < 4; ++j) if (okq[j]) { const float s_ = (hsum4(tq[j][0]) + hsum4(tq[j][1])) + (hsum4(tq[j][2]) + hsum4(tq[j][3]));
;             rtab[((tid >> 8) + 2 * j) * 256 + (tid & 255)] = rsqrtf(s_ * (1.0f / 1024.0f) + EPS); }
;         __syncthreads();
;     }
;     if (wr == 1) PG8_BAR;
;     PG8_WAIT_V(2); PG8_BAR;
;     PG8_STAGEB(PG8_SB(1, 0), cB + kstep); PG8_STAGEA(PG8_SA(1, 0), cA + kstep); PG8_STAGEB(PG8_SB(1, 1), cB + hstep + kstep);
;     PG8_WAIT_V(6); PG8_BAR;
.LBB0_1387:
	v_bfe_u32 v153, v0, 4, 2
	v_lshlrev_b32_e32 v10, 4, v153
	v_lshlrev_b32_e32 v151, 2, v1
	s_lshl_b32 s47, s0, 6
	v_lshl_or_b32 v11, v1, 6, v10
	s_lshl_b32 s0, s0, 13
	v_and_b32_e32 v16, 32, v151
	s_mov_b64 s[22:23], 0x80
	s_and_b32 s50, s39, 3
	v_bitop3_b32 v11, v11, s0, v16 bitop3:0xde
	v_lshlrev_b32_e32 v16, 6, v0
	s_movk_i32 s0, 0x3c0
	s_add_i32 m0, s53, 0x18000
	v_lshl_add_u64 v[8:9], v[8:9], 0, s[22:23]
	v_and_or_b32 v10, v16, s0, v10
	s_lshl_b32 s0, s50, 12
	s_ashr_i32 s57, s2, 31
	s_waitcnt vmcnt(2)
	s_barrier
	global_load_lds_dwordx4 v[8:9], off
	v_lshl_add_u64 v[6:7], v[6:7], 0, s[22:23]
	s_add_i32 m0, s53, 0x1a000
	s_add_i32 s58, s53, 0x8000
	s_add_i32 s59, s53, 0xa000
	global_load_lds_dwordx4 v[6:7], off
	v_lshl_add_u64 v[2:3], v[2:3], 0, s[22:23]
	s_mov_b32 m0, s58
	s_add_u32 s4, s40, 0xb0080
	global_load_lds_dwordx4 v[2:3], off
	v_lshl_add_u64 v[2:3], v[4:5], 0, s[22:23]
	s_mov_b32 m0, s59
	s_addc_u32 s5, s41, 0
	global_load_lds_dwordx4 v[2:3], off
	s_add_i32 m0, s53, 0x1c000
	v_lshl_add_u64 v[2:3], s[4:5], 0, v[132:133]
	global_load_lds_dwordx4 v[2:3], off
	v_lshl_add_u64 v[2:3], s[4:5], 0, v[136:137]
	s_add_i32 m0, s53, 0x1e000
	v_lshlrev_b32_e32 v16, 2, v0
	global_load_lds_dwordx4 v[2:3], off
	v_add_u16_e32 v2, v12, v13
	v_and_b32_e32 v16, 32, v16
	v_lshrrev_b16_e32 v4, 1, v2
	v_bitop3_b32 v154, s0, v10, v16 bitop3:0xf6
	s_mov_b64 s[0:1], 0xb0080
	s_waitcnt vmcnt(6)
	v_add_lshl_u32 v2, v14, v4, 1
	v_mov_b32_e32 v3, 0
	s_cmpk_lt_u32 s38, 0x100
	v_lshl_add_u64 v[138:139], v[2:3], 0, s[0:1]
	v_add_lshl_u32 v2, v15, v4, 1
	s_mov_b32 s70, 0
	s_cselect_b64 s[26:27], -1, 0
	v_lshl_add_u64 v[140:141], v[2:3], 0, s[0:1]
	v_mov_b64_e32 v[142:143], 0x100
	v_mov_b64_e32 v[144:145], 0xff
	s_add_i32 s66, 0, 0x10000
	s_add_i32 s67, 0, 0x14000
	v_add_u32_e32 v155, 0, v11
	v_mov_b32_e32 v2, v3
	v_pk_mov_b32 v[4:5], v[2:3], v[2:3]
	v_pk_mov_b32 v[6:7], v[2:3], v[2:3]
	v_pk_mov_b32 v[8:9], v[2:3], v[2:3]
	v_pk_mov_b32 v[18:19], v[2:3], v[2:3]
	v_pk_mov_b32 v[20:21], v[2:3], v[2:3]
	v_pk_mov_b32 v[22:23], v[2:3], v[2:3]
	v_pk_mov_b32 v[24:25], v[2:3], v[2:3]
	v_pk_mov_b32 v[34:35], v[2:3], v[2:3]
	v_pk_mov_b32 v[36:37], v[2:3], v[2:3]
	v_pk_mov_b32 v[38:39], v[2:3], v[2:3]
	v_pk_mov_b32 v[40:41], v[2:3], v[2:3]
	v_pk_mov_b32 v[50:51], v[2:3], v[2:3]
	v_pk_mov_b32 v[52:53], v[2:3], v[2:3]
	v_pk_mov_b32 v[54:55], v[2:3], v[2:3]
	v_pk_mov_b32 v[56:57], v[2:3], v[2:3]
	v_pk_mov_b32 v[10:11], v[2:3], v[2:3]
	v_pk_mov_b32 v[12:13], v[2:3], v[2:3]
	v_pk_mov_b32 v[14:15], v[2:3], v[2:3]
	v_pk_mov_b32 v[16:17], v[2:3], v[2:3]
	v_pk_mov_b32 v[26:27], v[2:3], v[2:3]
	v_pk_mov_b32 v[28:29], v[2:3], v[2:3]
	v_pk_mov_b32 v[30:31], v[2:3], v[2:3]
	v_pk_mov_b32 v[32:33], v[2:3], v[2:3]
	v_pk_mov_b32 v[42:43], v[2:3], v[2:3]
	v_pk_mov_b32 v[44:45], v[2:3], v[2:3]
	v_pk_mov_b32 v[46:47], v[2:3], v[2:3]
	v_pk_mov_b32 v[48:49], v[2:3], v[2:3]
	v_pk_mov_b32 v[58:59], v[2:3], v[2:3]
	v_pk_mov_b32 v[60:61], v[2:3], v[2:3]
	v_pk_mov_b32 v[62:63], v[2:3], v[2:3]
	v_pk_mov_b32 v[64:65], v[2:3], v[2:3]
	v_pk_mov_b32 v[66:67], v[2:3], v[2:3]
	v_pk_mov_b32 v[68:69], v[2:3], v[2:3]
	v_pk_mov_b32 v[70:71], v[2:3], v[2:3]
	v_pk_mov_b32 v[72:73], v[2:3], v[2:3]
	v_pk_mov_b32 v[82:83], v[2:3], v[2:3]
	v_pk_mov_b32 v[84:85], v[2:3], v[2:3]
	v_pk_mov_b32 v[86:87], v[2:3], v[2:3]
	v_pk_mov_b32 v[88:89], v[2:3], v[2:3]
	v_pk_mov_b32 v[98:99], v[2:3], v[2:3]
	v_pk_mov_b32 v[100:101], v[2:3], v[2:3]
	v_pk_mov_b32 v[102:103], v[2:3], v[2:3]
	v_pk_mov_b32 v[104:105], v[2:3], v[2:3]
	v_pk_mov_b32 v[114:115], v[2:3], v[2:3]
	v_pk_mov_b32 v[116:117], v[2:3], v[2:3]
	v_pk_mov_b32 v[118:119], v[2:3], v[2:3]
	v_pk_mov_b32 v[120:121], v[2:3], v[2:3]
	v_pk_mov_b32 v[74:75], v[2:3], v[2:3]
	v_pk_mov_b32 v[76:77], v[2:3], v[2:3]
	v_pk_mov_b32 v[78:79], v[2:3], v[2:3]
	v_pk_mov_b32 v[80:81], v[2:3], v[2:3]
	v_pk_mov_b32 v[90:91], v[2:3], v[2:3]
	v_pk_mov_b32 v[92:93], v[2:3], v[2:3]
	v_pk_mov_b32 v[94:95], v[2:3], v[2:3]
	v_pk_mov_b32 v[96:97], v[2:3], v[2:3]
	v_pk_mov_b32 v[106:107], v[2:3], v[2:3]
	v_pk_mov_b32 v[108:109], v[2:3], v[2:3]
	v_pk_mov_b32 v[110:111], v[2:3], v[2:3]
	v_pk_mov_b32 v[112:113], v[2:3], v[2:3]
	v_pk_mov_b32 v[122:123], v[2:3], v[2:3]
	v_pk_mov_b32 v[124:125], v[2:3], v[2:3]
	v_pk_mov_b32 v[126:127], v[2:3], v[2:3]
	v_pk_mov_b32 v[128:129], v[2:3], v[2:3]
	s_barrier
	s_branch .LBB0_1390

; #define PG8_BAR __builtin_amdgcn_s_barrier()
; template <int EK, int SK = -1>
; __device__ __forceinline__ void gemm_phase(LAS unsigned char* lds, const bf16_t* A, const bf16_t* Bt, int nM, int N, int K, const EpiArgs& E) {
;     ...
;         if (!has_next) break;
; #pragma unroll
;         for (int a = 0; a < 2; ++a)
; #pragma unroll
;             for (int b = 0; b < 2; ++b)
; #pragma unroll
;                 for (int m = 0; m < 4; ++m)
; #pragma unroll
;                     for (int n = 0; n < 2; ++n) acc[a][b][m][n] = (f32x4){0.f, 0.f, 0.f, 0.f};
;         cur = nxt; cA = nA; cB = nB; ++ui;
;         if (wr == 1) PG8_BAR;
.LBB0_1407:
	v_mov_b32_e32 v2, 0
	s_mov_b32 s51, s68
	s_mov_b32 s46, s69
	v_mov_b32_e32 v3, v2
	v_pk_mov_b32 v[4:5], v[2:3], v[2:3]
	v_pk_mov_b32 v[6:7], v[2:3], v[2:3]
	v_pk_mov_b32 v[8:9], v[2:3], v[2:3]
	v_pk_mov_b32 v[18:19], v[2:3], v[2:3]
	v_pk_mov_b32 v[20:21], v[2:3], v[2:3]
	v_pk_mov_b32 v[22:23], v[2:3], v[2:3]
	v_pk_mov_b32 v[24:25], v[2:3], v[2:3]
	v_pk_mov_b32 v[34:35], v[2:3], v[2:3]
	v_pk_mov_b32 v[36:37], v[2:3], v[2:3]
	v_pk_mov_b32 v[38:39], v[2:3], v[2:3]
	v_pk_mov_b32 v[40:41], v[2:3], v[2:3]
	v_pk_mov_b32 v[50:51], v[2:3], v[2:3]
	v_pk_mov_b32 v[52:53], v[2:3], v[2:3]
	v_pk_mov_b32 v[54:55], v[2:3], v[2:3]
	v_pk_mov_b32 v[56:57], v[2:3], v[2:3]
	v_pk_mov_b32 v[10:11], v[2:3], v[2:3]
	v_pk_mov_b32 v[12:13], v[2:3], v[2:3]
	v_pk_mov_b32 v[14:15], v[2:3], v[2:3]
	v_pk_mov_b32 v[16:17], v[2:3], v[2:3]
	v_pk_mov_b32 v[26:27], v[2:3], v[2:3]
	v_pk_mov_b32 v[28:29], v[2:3], v[2:3]
	v_pk_mov_b32 v[30:31], v[2:3], v[2:3]
	v_pk_mov_b32 v[32:33], v[2:3], v[2:3]
	v_pk_mov_b32 v[42:43], v[2:3], v[2:3]
	v_pk_mov_b32 v[44:45], v[2:3], v[2:3]
	v_pk_mov_b32 v[46:47], v[2:3], v[2:3]
	v_pk_mov_b32 v[48:49], v[2:3], v[2:3]
	v_pk_mov_b32 v[58:59], v[2:3], v[2:3]
	v_pk_mov_b32 v[60:61], v[2:3], v[2:3]
	v_pk_mov_b32 v[62:63], v[2:3], v[2:3]
	v_pk_mov_b32 v[64:65], v[2:3], v[2:3]
	v_pk_mov_b32 v[66:67], v[2:3], v[2:3]
	v_pk_mov_b32 v[68:69], v[2:3], v[2:3]
	v_pk_mov_b32 v[70:71], v[2:3], v[2:3]
	v_pk_mov_b32 v[72:73], v[2:3], v[2:3]
	v_pk_mov_b32 v[82:83], v[2:3], v[2:3]
	v_pk_mov_b32 v[84:85], v[2:3], v[2:3]
	v_pk_mov_b32 v[86:87], v[2:3], v[2:3]
	v_pk_mov_b32 v[88:89], v[2:3], v[2:3]
	v_pk_mov_b32 v[98:99], v[2:3], v[2:3]
	v_pk_mov_b32 v[100:101], v[2:3], v[2:3]
	v_pk_mov_b32 v[102:103], v[2:3], v[2:3]
	v_pk_mov_b32 v[104:105], v[2:3], v[2:3]
	v_pk_mov_b32 v[114:115], v[2:3], v[2:3]
	v_pk_mov_b32 v[116:117], v[2:3], v[2:3]
	v_pk_mov_b32 v[118:119], v[2:3], v[2:3]
	v_pk_mov_b32 v[120:121], v[2:3], v[2:3]
	v_pk_mov_b32 v[74:75], v[2:3], v[2:3]
	v_pk_mov_b32 v[76:77], v[2:3], v[2:3]
	v_pk_mov_b32 v[78:79], v[2:3], v[2:3]
	v_pk_mov_b32 v[80:81], v[2:3], v[2:3]
	v_pk_mov_b32 v[90:91], v[2:3], v[2:3]
	v_pk_mov_b32 v[92:93], v[2:3], v[2:3]
	v_pk_mov_b32 v[94:95], v[2:3], v[2:3]
	v_pk_mov_b32 v[96:97], v[2:3], v[2:3]
	v_pk_mov_b32 v[106:107], v[2:3], v[2:3]
	v_pk_mov_b32 v[108:109], v[2:3], v[2:3]
	v_pk_mov_b32 v[110:111], v[2:3], v[2:3]
	v_pk_mov_b32 v[112:113], v[2:3], v[2:3]
	v_pk_mov_b32 v[122:123], v[2:3], v[2:3]
	v_pk_mov_b32 v[124:125], v[2:3], v[2:3]
	v_pk_mov_b32 v[126:127], v[2:3], v[2:3]
	v_pk_mov_b32 v[128:129], v[2:3], v[2:3]
	s_andn2_b64 vcc, exec, s[0:1]
	s_cbranch_vccnz .LBB0_1389

; __global__ void __launch_bounds__(512, 2) mega_fwd(Params p) {
	.amdhsa_kernel _Z8mega_fwd6Params
		.amdhsa_group_segment_fixed_size 0
		.amdhsa_private_segment_fixed_size 0
		.amdhsa_kernarg_size 440
		.amdhsa_user_sgpr_count 2
		.amdhsa_user_sgpr_dispatch_ptr 0
		.amdhsa_user_sgpr_queue_ptr 0
		.amdhsa_user_sgpr_kernarg_segment_ptr 1
		.amdhsa_user_sgpr_dispatch_id 0
		.amdhsa_user_sgpr_kernarg_preload_length 0
		.amdhsa_user_sgpr_kernarg_preload_offset 0
		.amdhsa_user_sgpr_private_segment_size 0
		.amdhsa_uses_dynamic_stack 0
		.amdhsa_enable_private_segment 0
		.amdhsa_system_sgpr_workgroup_id_x 1
		.amdhsa_system_sgpr_workgroup_id_y 0
		.amdhsa_system_sgpr_workgroup_id_z 0
		.amdhsa_system_sgpr_workgroup_info 0
		.amdhsa_system_vgpr_workitem_id 0
		.amdhsa_next_free_vgpr 232
		.amdhsa_next_free_sgpr 102
		.amdhsa_accum_offset 232
		.amdhsa_reserve_vcc 1
		.amdhsa_float_round_mode_32 0
		.amdhsa_float_round_mode_16_64 0
		.amdhsa_float_denorm_mode_32 3
		.amdhsa_float_denorm_mode_16_64 3
		.amdhsa_dx10_clamp 1
		.amdhsa_ieee_mode 1
		.amdhsa_fp16_overflow 0
		.amdhsa_tg_split 0
		.amdhsa_exception_fp_ieee_invalid_op 0
		.amdhsa_exception_fp_denorm_src 0
		.amdhsa_exception_fp_ieee_div_zero 0
		.amdhsa_exception_fp_ieee_overflow 0
		.amdhsa_exception_fp_ieee_underflow 0
		.amdhsa_exception_fp_ieee_inexact 0
		.amdhsa_exception_int_div_zero 0
	.end_amdhsa_kernel

; __global__ void __launch_bounds__(512, 2) mega_fwd(Params p) {
amdhsa.kernels:
  - .agpr_count:     0
    .args:
      - .offset:         0
        .size:           184
        .value_kind:     by_value
      - .offset:         184
        .size:           4
        .value_kind:     hidden_block_count_x
      - .offset:         188
        .size:           4
        .value_kind:     hidden_block_count_y
      - .offset:         192
        .size:           4
        .value_kind:     hidden_block_count_z
      - .offset:         196
        .size:           2
        .value_kind:     hidden_group_size_x
      - .offset:         198
        .size:           2
        .value_kind:     hidden_group_size_y
      - .offset:         200
        .size:           2
        .value_kind:     hidden_group_size_z
      - .offset:         202
        .size:           2
        .value_kind:     hidden_remainder_x
      - .offset:         204
        .size:           2
        .value_kind:     hidden_remainder_y
      - .offset:         206
        .size:           2
        .value_kind:     hidden_remainder_z
      - .offset:         224
        .size:           8
        .value_kind:     hidden_global_offset_x
      - .offset:         232
        .size:           8
        .value_kind:     hidden_global_offset_y
      - .offset:         240
        .size:           8
        .value_kind:     hidden_global_offset_z
      - .offset:         248
        .size:           2
        .value_kind:     hidden_grid_dims
      - .offset:         304
        .size:           4
        .value_kind:     hidden_dynamic_lds_size
    .group_segment_fixed_size: 0
    .kernarg_segment_align: 8
    .kernarg_segment_size: 440
    .language:       OpenCL C
    .language_version:
      - 2
      - 0
    .max_flat_workgroup_size: 512
    .name:           _Z8mega_fwd6Params
    .private_segment_fixed_size: 0
    .sgpr_count:     108
    .sgpr_spill_count: 0
    .symbol:         _Z8mega_fwd6Params.kd
    .uniform_work_group_size: 1
    .uses_dynamic_stack: false
    .vgpr_count:     232
    .vgpr_spill_count: 0
    .wavefront_size: 64
